# K-loop load segments: the two back-to-back waits merged into one instruction, hazard pads after m0 writes replaced by reordered address adds
# baseline (speedup 1.0000x reference)
; #define PG8_STAGE(bufoff, gbase, voff) do { _Pragma("unroll") for (int _i = 0; _i < 2; ++_i) \
;         __builtin_amdgcn_global_load_lds((const unsigned*)((const char*)(gbase) + (voff)[_i]), (PG8_LAS unsigned*)(lds + (bufoff) + ldsw + _i * 8192), 16, 0, 0); } while (0)
; #define PG8_LDA(dst, b, h) do { _Pragma("unroll") for (int m = 0; m < 4; ++m) _Pragma("unroll") for (int k = 0; k < 2; ++k) dst[m][k] = *(const PG8_LAS bf16x8*)(lds + PG8_SA(b, h) + aoff + m * 2048 + k * 1024); } while (0)
; #define PG8_LDB(dst, b, h) do { _Pragma("unroll") for (int n = 0; n < 2; ++n) _Pragma("unroll") for (int k = 0; k < 2; ++k) dst[n][k] = *(const PG8_LAS bf16x8*)(lds + PG8_SB(b, h) + boff + n * 2048 + k * 1024); } while (0)
; #define PG8_MMA(ai, bj, At, Bt) do { __builtin_amdgcn_s_setprio(1); _Pragma("unroll") for (int m = 0; m < 4; ++m) _Pragma("unroll") for (int n = 0; n < 2; ++n) _Pragma("unroll") for (int k = 0; k < 2; ++k) \
;         acc[ai][bj][m][n] = __builtin_amdgcn_mfma_f32_16x16x32_bf16(Bt[n][k], At[m][k], acc[ai][bj][m][n], 0, 0, 0); __builtin_amdgcn_s_setprio(0); } while (0)
; #define PG8_WAIT_V(n) asm volatile("s_waitcnt vmcnt(" #n ")" ::: "memory")
; template <class Epi, class Sched, bool ALIGN_EPI = false, bool SP2 = false>
; __device__ __forceinline__ void gemm_phase(PG8_LAS unsigned char* lds, const Gemm g, const Sched& S, const Epi& E) {
;     ...
;         const char* nA = has_next ? (const char*)g.A + (size_t)nxt.pm * tstep : cA; const char* nB = has_next ? (const char*)g.Bt + (size_t)nxt.pn * tstep : cB;
;         for (int t = 0; t < nt; t += 2) {
;             const bool last = (t == nt - 2);
;             const char* a1 = cA + (size_t)(t + 1) * kstep;
;             const char* a2 = last ? nA : cA + (size_t)(t + 2) * kstep; const char* b2 = last ? nB : cB + (size_t)(t + 2) * kstep;
;             const char* a3 = a2 + kstep; const char* b3 = b2 + kstep;
;             if (last && has_next) S.a_ready(nxt);
;             if constexpr (SP2) {
;             PG8_LDB(B0, 0, 0); PG8_LDB(B1, 0, 1); PG8_SCHED; PG8_LDA(At, 0, 0); PG8_STAGE(PG8_SA(1, 1), a1 + hstep, voffA);
;             PG8_WAIT_V(8); PG8_WAIT_L(0); PG8_BAR; PG8_MMA(0, 0, At, B0); PG8_MMA(0, 1, At, B1); PG8_BAR; PG8_SCHED;
;             PG8_LDA(At, 0, 1); PG8_STAGE(PG8_SB(0, 0), b2, voffB); PG8_STAGE(PG8_SB(0, 1), b2 + hstep, voffB); PG8_STAGE(PG8_SA(0, 0), a2, voffA);
.LBB0_128:
	s_ashr_i32 s25, s24, 31
	s_lshl_b64 s[28:29], s[24:25], 20
	v_readlane_b32 s30, v254, 51
	v_readlane_b32 s31, v254, 52
	s_add_u32 s28, s30, s28
	s_addc_u32 s29, s31, s29
	s_and_b64 s[30:31], s[26:27], exec
	s_cselect_b32 s25, s29, s9
	s_cselect_b32 s35, s28, s8
	s_ashr_i32 s23, s22, 31
	s_lshl_b64 s[30:31], s[22:23], 20
	s_add_u32 s30, s94, s30
	s_addc_u32 s31, s95, s31
	s_and_b64 s[46:47], s[26:27], exec
	s_cselect_b32 s23, s31, s45
	s_cselect_b32 s43, s30, s44
	s_add_u32 s8, s8, 0x80080
	s_addc_u32 s9, s9, 0
	s_add_u32 s48, s44, 0x100
	s_addc_u32 s49, s45, 0
	s_mov_b32 s54, -2
	s_waitcnt lgkmcnt(0)
	ds_read_b128 v[96:99], v173
	ds_read_b128 v[100:103], v173 offset:1024
	ds_read_b128 v[104:107], v173 offset:2048
	ds_read_b128 v[112:115], v173 offset:3072
	ds_read_b128 v[178:181], v175
	ds_read_b128 v[182:185], v175 offset:1024
	ds_read_b128 v[186:189], v175 offset:2048
	ds_read_b128 v[190:193], v175 offset:3072
	s_add_u32 s44, s8, 0xfff80080
	s_addc_u32 s45, s9, -1
	s_cmp_eq_u32 s54, 28
	s_cselect_b32 s47, s25, s45
	s_cselect_b32 s46, s35, s44
	s_cselect_b32 s45, s23, s49
	s_cselect_b32 s44, s43, s48
	v_lshl_add_u64 v[160:161], s[8:9], 0, v[154:155]
	s_add_i32 m0, s63, 0xc000
	ds_read_b128 v[198:201], v177
	ds_read_b128 v[202:205], v177 offset:1024
	ds_read_b128 v[206:209], v177 offset:2048
	ds_read_b128 v[210:213], v177 offset:3072
	ds_read_b128 v[214:217], v177 offset:4096
	ds_read_b128 v[218:221], v177 offset:5120
	ds_read_b128 v[222:225], v177 offset:6144
	ds_read_b128 v[226:229], v177 offset:7168
	global_load_lds_dwordx4 v[160:161], off
	s_add_i32 m0, s63, 0xe000
	v_lshl_add_u64 v[160:161], s[8:9], 0, v[156:157]
	global_load_lds_dwordx4 v[160:161], off
	s_waitcnt lgkmcnt(0)
	s_setprio 1
	s_barrier
	v_mfma_f32_16x16x32_bf16 v[140:143], v[96:99], v[198:201], 0
	v_mfma_f32_16x16x32_bf16 v[132:135], v[104:107], v[198:201], 0
	v_mfma_f32_16x16x32_bf16 v[116:119], v[96:99], v[206:209], 0
	v_mfma_f32_16x16x32_bf16 v[124:127], v[104:107], v[206:209], 0
	v_mfma_f32_16x16x32_bf16 v[84:87], v[96:99], v[214:217], 0
	v_mfma_f32_16x16x32_bf16 v[92:95], v[104:107], v[214:217], 0
	v_mfma_f32_16x16x32_bf16 v[68:71], v[96:99], v[222:225], 0
	v_mfma_f32_16x16x32_bf16 v[76:79], v[104:107], v[222:225], 0
	v_mfma_f32_16x16x32_bf16 v[140:143], v[100:103], v[202:205], v[140:143]
	v_mfma_f32_16x16x32_bf16 v[132:135], v[112:115], v[202:205], v[132:135]
	v_mfma_f32_16x16x32_bf16 v[116:119], v[100:103], v[210:213], v[116:119]
	v_mfma_f32_16x16x32_bf16 v[124:127], v[112:115], v[210:213], v[124:127]
	v_mfma_f32_16x16x32_bf16 v[84:87], v[100:103], v[218:221], v[84:87]
	v_mfma_f32_16x16x32_bf16 v[92:95], v[112:115], v[218:221], v[92:95]
	v_mfma_f32_16x16x32_bf16 v[68:71], v[100:103], v[226:229], v[68:71]
	v_mfma_f32_16x16x32_bf16 v[76:79], v[112:115], v[226:229], v[76:79]
	v_mfma_f32_16x16x32_bf16 v[128:131], v[178:181], v[198:201], 0
	v_mfma_f32_16x16x32_bf16 v[136:139], v[186:189], v[198:201], 0
	v_mfma_f32_16x16x32_bf16 v[120:123], v[178:181], v[206:209], 0
	v_mfma_f32_16x16x32_bf16 v[108:111], v[186:189], v[206:209], 0
	v_mfma_f32_16x16x32_bf16 v[88:91], v[178:181], v[214:217], 0
	v_mfma_f32_16x16x32_bf16 v[80:83], v[186:189], v[214:217], 0
	v_mfma_f32_16x16x32_bf16 v[72:75], v[178:181], v[222:225], 0
	v_mfma_f32_16x16x32_bf16 v[64:67], v[186:189], v[222:225], 0
	v_mfma_f32_16x16x32_bf16 v[128:131], v[182:185], v[202:205], v[128:131]
	v_mfma_f32_16x16x32_bf16 v[136:139], v[190:193], v[202:205], v[136:139]
	v_mfma_f32_16x16x32_bf16 v[120:123], v[182:185], v[210:213], v[120:123]
	v_mfma_f32_16x16x32_bf16 v[108:111], v[190:193], v[210:213], v[108:111]
	v_mfma_f32_16x16x32_bf16 v[88:91], v[182:185], v[218:221], v[88:91]
	v_mfma_f32_16x16x32_bf16 v[80:83], v[190:193], v[218:221], v[80:83]
	v_mfma_f32_16x16x32_bf16 v[72:75], v[182:185], v[226:229], v[72:75]
	v_mfma_f32_16x16x32_bf16 v[64:67], v[190:193], v[226:229], v[64:67]
	s_barrier
	s_setprio 0
	s_add_i32 s55, s52, s62
	v_lshl_add_u64 v[160:161], s[44:45], 0, v[144:145]
	s_mov_b32 m0, s55
	ds_read_b128 v[198:201], v177 offset:16384
	ds_read_b128 v[202:205], v177 offset:17408
	ds_read_b128 v[206:209], v177 offset:18432
	ds_read_b128 v[210:213], v177 offset:19456
	ds_read_b128 v[214:217], v177 offset:20480
	ds_read_b128 v[218:221], v177 offset:21504
	ds_read_b128 v[222:225], v177 offset:22528
	ds_read_b128 v[226:229], v177 offset:23552
	global_load_lds_dwordx4 v[160:161], off
	s_add_i32 m0, s55, 0x2000
	s_add_u32 s56, s44, 0x80000
	v_lshl_add_u64 v[164:165], s[44:45], 0, v[146:147]
	s_addc_u32 s57, s45, 0
	s_add_i32 s55, s53, s62
	global_load_lds_dwordx4 v[164:165], off
	v_lshl_add_u64 v[170:171], s[56:57], 0, v[144:145]
	s_mov_b32 m0, s55
	v_lshl_add_u64 v[194:195], s[46:47], 0, v[146:147]
	global_load_lds_dwordx4 v[170:171], off
	s_add_i32 m0, s55, 0x2000
	v_lshl_add_u64 v[170:171], s[56:57], 0, v[146:147]
	global_load_lds_dwordx4 v[170:171], off
	s_mov_b32 m0, s63
	v_lshl_add_u64 v[170:171], s[46:47], 0, v[144:145]
	global_load_lds_dwordx4 v[170:171], off
	s_mov_b32 m0, s64
	s_nop 0
	global_load_lds_dwordx4 v[194:195], off
	s_waitcnt lgkmcnt(0)
	s_setprio 1
	s_barrier
; #define PG8_STAGE(bufoff, gbase, voff) do { _Pragma("unroll") for (int _i = 0; _i < 2; ++_i) \
;         __builtin_amdgcn_global_load_lds((const unsigned*)((const char*)(gbase) + (voff)[_i]), (PG8_LAS unsigned*)(lds + (bufoff) + ldsw + _i * 8192), 16, 0, 0); } while (0)
; #define PG8_LDA(dst, b, h) do { _Pragma("unroll") for (int m = 0; m < 4; ++m) _Pragma("unroll") for (int k = 0; k < 2; ++k) dst[m][k] = *(const PG8_LAS bf16x8*)(lds + PG8_SA(b, h) + aoff + m * 2048 + k * 1024); } while (0)
; #define PG8_LDB(dst, b, h) do { _Pragma("unroll") for (int n = 0; n < 2; ++n) _Pragma("unroll") for (int k = 0; k < 2; ++k) dst[n][k] = *(const PG8_LAS bf16x8*)(lds + PG8_SB(b, h) + boff + n * 2048 + k * 1024); } while (0)
; #define PG8_MMA(ai, bj, At, Bt) do { __builtin_amdgcn_s_setprio(1); _Pragma("unroll") for (int m = 0; m < 4; ++m) _Pragma("unroll") for (int n = 0; n < 2; ++n) _Pragma("unroll") for (int k = 0; k < 2; ++k) \
;         acc[ai][bj][m][n] = __builtin_amdgcn_mfma_f32_16x16x32_bf16(Bt[n][k], At[m][k], acc[ai][bj][m][n], 0, 0, 0); __builtin_amdgcn_s_setprio(0); } while (0)
; #define PG8_WAIT_V(n) asm volatile("s_waitcnt vmcnt(" #n ")" ::: "memory")
; #define PG8_WAIT_L(n) asm volatile("s_waitcnt lgkmcnt(" #n ")" ::: "memory")
; #define PG8_BAR __builtin_amdgcn_s_barrier()
; #define PG8_SCHED __builtin_amdgcn_sched_barrier(0)
; template <class Epi, class Sched, bool ALIGN_EPI = false, bool SP2 = false>
; __device__ __forceinline__ void gemm_phase(PG8_LAS unsigned char* lds, const Gemm g, const Sched& S, const Epi& E) {
;     ...
;             PG8_WAIT_V(8); PG8_WAIT_L(0); PG8_BAR; PG8_MMA(1, 0, At, B0); PG8_MMA(1, 1, At, B1); PG8_BAR; PG8_SCHED;
;             PG8_LDB(B0, 1, 0); PG8_LDB(B1, 1, 1); PG8_SCHED; PG8_LDA(At, 1, 0); PG8_STAGE(PG8_SA(0, 1), a2 + hstep, voffA);
;             PG8_WAIT_V(8); PG8_WAIT_L(0); PG8_BAR; PG8_MMA(0, 0, At, B0); PG8_MMA(0, 1, At, B1); PG8_BAR; PG8_SCHED;
	v_mfma_f32_16x16x32_bf16 v[60:63], v[96:99], v[198:201], 0
	v_mfma_f32_16x16x32_bf16 v[52:55], v[104:107], v[198:201], 0
	v_mfma_f32_16x16x32_bf16 v[36:39], v[96:99], v[206:209], 0
	v_mfma_f32_16x16x32_bf16 v[44:47], v[104:107], v[206:209], 0
	v_mfma_f32_16x16x32_bf16 v[20:23], v[96:99], v[214:217], 0
	v_mfma_f32_16x16x32_bf16 v[28:31], v[104:107], v[214:217], 0
	v_mfma_f32_16x16x32_bf16 v[4:7], v[96:99], v[222:225], 0
	v_mfma_f32_16x16x32_bf16 v[12:15], v[104:107], v[222:225], 0
	v_mfma_f32_16x16x32_bf16 v[60:63], v[100:103], v[202:205], v[60:63]
	v_mfma_f32_16x16x32_bf16 v[52:55], v[112:115], v[202:205], v[52:55]
	v_mfma_f32_16x16x32_bf16 v[36:39], v[100:103], v[210:213], v[36:39]
	v_mfma_f32_16x16x32_bf16 v[44:47], v[112:115], v[210:213], v[44:47]
	v_mfma_f32_16x16x32_bf16 v[20:23], v[100:103], v[218:221], v[20:23]
	v_mfma_f32_16x16x32_bf16 v[28:31], v[112:115], v[218:221], v[28:31]
	v_mfma_f32_16x16x32_bf16 v[4:7], v[100:103], v[226:229], v[4:7]
	v_mfma_f32_16x16x32_bf16 v[12:15], v[112:115], v[226:229], v[12:15]
	v_mfma_f32_16x16x32_bf16 v[48:51], v[178:181], v[198:201], 0
	v_mfma_f32_16x16x32_bf16 v[56:59], v[186:189], v[198:201], 0
	v_mfma_f32_16x16x32_bf16 v[40:43], v[178:181], v[206:209], 0
	v_mfma_f32_16x16x32_bf16 v[32:35], v[186:189], v[206:209], 0
	v_mfma_f32_16x16x32_bf16 v[24:27], v[178:181], v[214:217], 0
	v_mfma_f32_16x16x32_bf16 v[16:19], v[186:189], v[214:217], 0
	v_mfma_f32_16x16x32_bf16 v[8:11], v[178:181], v[222:225], 0
	v_mfma_f32_16x16x32_bf16 v[0:3], v[186:189], v[222:225], 0
	v_mfma_f32_16x16x32_bf16 v[48:51], v[182:185], v[202:205], v[48:51]
	v_mfma_f32_16x16x32_bf16 v[56:59], v[190:193], v[202:205], v[56:59]
	v_mfma_f32_16x16x32_bf16 v[40:43], v[182:185], v[210:213], v[40:43]
	v_mfma_f32_16x16x32_bf16 v[32:35], v[190:193], v[210:213], v[32:35]
	v_mfma_f32_16x16x32_bf16 v[24:27], v[182:185], v[218:221], v[24:27]
	v_mfma_f32_16x16x32_bf16 v[16:19], v[190:193], v[218:221], v[16:19]
	v_mfma_f32_16x16x32_bf16 v[8:11], v[182:185], v[226:229], v[8:11]
	v_mfma_f32_16x16x32_bf16 v[0:3], v[190:193], v[226:229], v[0:3]
	s_barrier
	s_setprio 0
	s_add_i32 s55, 0, 0x18000
	s_add_i32 s56, 0, 0x1c000
	v_add_u32_e32 v112, s55, v167
	v_add_u32_e32 v162, s56, v167
	ds_read_b128 v[96:99], v112
	ds_read_b128 v[100:103], v112 offset:1024
	ds_read_b128 v[104:107], v112 offset:2048
	ds_read_b128 v[112:115], v112 offset:3072
	ds_read_b128 v[178:181], v162
	ds_read_b128 v[182:185], v162 offset:1024
	ds_read_b128 v[186:189], v162 offset:2048
	ds_read_b128 v[190:193], v162 offset:3072
	s_add_u32 s46, s46, 0x80000
	s_addc_u32 s47, s47, 0
	s_mov_b32 m0, s65
	v_lshl_add_u64 v[230:231], s[46:47], 0, v[144:145]
	ds_read_b128 v[198:201], v177 offset:32768
	ds_read_b128 v[202:205], v177 offset:33792
	ds_read_b128 v[206:209], v177 offset:34816
	ds_read_b128 v[210:213], v177 offset:35840
	ds_read_b128 v[214:217], v177 offset:36864
	ds_read_b128 v[218:221], v177 offset:37888
	ds_read_b128 v[222:225], v177 offset:38912
	ds_read_b128 v[226:229], v177 offset:39936
	global_load_lds_dwordx4 v[230:231], off
	s_mov_b32 m0, s66
	v_lshl_add_u64 v[230:231], s[46:47], 0, v[146:147]
	global_load_lds_dwordx4 v[230:231], off
	s_waitcnt vmcnt(8) lgkmcnt(0)
	s_setprio 1
	s_barrier
	v_mfma_f32_16x16x32_bf16 v[140:143], v[96:99], v[198:201], v[140:143]
	v_mfma_f32_16x16x32_bf16 v[132:135], v[104:107], v[198:201], v[132:135]
	v_mfma_f32_16x16x32_bf16 v[116:119], v[96:99], v[206:209], v[116:119]
	v_mfma_f32_16x16x32_bf16 v[124:127], v[104:107], v[206:209], v[124:127]
	v_mfma_f32_16x16x32_bf16 v[84:87], v[96:99], v[214:217], v[84:87]
	v_mfma_f32_16x16x32_bf16 v[92:95], v[104:107], v[214:217], v[92:95]
	v_mfma_f32_16x16x32_bf16 v[68:71], v[96:99], v[222:225], v[68:71]
	v_mfma_f32_16x16x32_bf16 v[76:79], v[104:107], v[222:225], v[76:79]
	v_mfma_f32_16x16x32_bf16 v[140:143], v[100:103], v[202:205], v[140:143]
	v_mfma_f32_16x16x32_bf16 v[132:135], v[112:115], v[202:205], v[132:135]
	v_mfma_f32_16x16x32_bf16 v[116:119], v[100:103], v[210:213], v[116:119]
	v_mfma_f32_16x16x32_bf16 v[124:127], v[112:115], v[210:213], v[124:127]
	v_mfma_f32_16x16x32_bf16 v[84:87], v[100:103], v[218:221], v[84:87]
	v_mfma_f32_16x16x32_bf16 v[92:95], v[112:115], v[218:221], v[92:95]
	v_mfma_f32_16x16x32_bf16 v[68:71], v[100:103], v[226:229], v[68:71]
	v_mfma_f32_16x16x32_bf16 v[76:79], v[112:115], v[226:229], v[76:79]
	v_mfma_f32_16x16x32_bf16 v[128:131], v[178:181], v[198:201], v[128:131]
	v_mfma_f32_16x16x32_bf16 v[136:139], v[186:189], v[198:201], v[136:139]
	v_mfma_f32_16x16x32_bf16 v[120:123], v[178:181], v[206:209], v[120:123]
	v_mfma_f32_16x16x32_bf16 v[108:111], v[186:189], v[206:209], v[108:111]
	v_mfma_f32_16x16x32_bf16 v[88:91], v[178:181], v[214:217], v[88:91]
	v_mfma_f32_16x16x32_bf16 v[80:83], v[186:189], v[214:217], v[80:83]
	v_mfma_f32_16x16x32_bf16 v[72:75], v[178:181], v[222:225], v[72:75]
	v_mfma_f32_16x16x32_bf16 v[64:67], v[186:189], v[222:225], v[64:67]
	v_mfma_f32_16x16x32_bf16 v[128:131], v[182:185], v[202:205], v[128:131]
	v_mfma_f32_16x16x32_bf16 v[136:139], v[190:193], v[202:205], v[136:139]
	v_mfma_f32_16x16x32_bf16 v[120:123], v[182:185], v[210:213], v[120:123]
	v_mfma_f32_16x16x32_bf16 v[108:111], v[190:193], v[210:213], v[108:111]
	v_mfma_f32_16x16x32_bf16 v[88:91], v[182:185], v[218:221], v[88:91]
	v_mfma_f32_16x16x32_bf16 v[80:83], v[190:193], v[218:221], v[80:83]
	v_mfma_f32_16x16x32_bf16 v[72:75], v[182:185], v[226:229], v[72:75]
	v_mfma_f32_16x16x32_bf16 v[64:67], v[190:193], v[226:229], v[64:67]
	s_barrier
; #define PG8_STAGE(bufoff, gbase, voff) do { _Pragma("unroll") for (int _i = 0; _i < 2; ++_i) \
;         __builtin_amdgcn_global_load_lds((const unsigned*)((const char*)(gbase) + (voff)[_i]), (PG8_LAS unsigned*)(lds + (bufoff) + ldsw + _i * 8192), 16, 0, 0); } while (0)
; #define PG8_LDA(dst, b, h) do { _Pragma("unroll") for (int m = 0; m < 4; ++m) _Pragma("unroll") for (int k = 0; k < 2; ++k) dst[m][k] = *(const PG8_LAS bf16x8*)(lds + PG8_SA(b, h) + aoff + m * 2048 + k * 1024); } while (0)
; #define PG8_LDB(dst, b, h) do { _Pragma("unroll") for (int n = 0; n < 2; ++n) _Pragma("unroll") for (int k = 0; k < 2; ++k) dst[n][k] = *(const PG8_LAS bf16x8*)(lds + PG8_SB(b, h) + boff + n * 2048 + k * 1024); } while (0)
; #define PG8_MMA(ai, bj, At, Bt) do { __builtin_amdgcn_s_setprio(1); _Pragma("unroll") for (int m = 0; m < 4; ++m) _Pragma("unroll") for (int n = 0; n < 2; ++n) _Pragma("unroll") for (int k = 0; k < 2; ++k) \
;         acc[ai][bj][m][n] = __builtin_amdgcn_mfma_f32_16x16x32_bf16(Bt[n][k], At[m][k], acc[ai][bj][m][n], 0, 0, 0); __builtin_amdgcn_s_setprio(0); } while (0)
; #define PG8_WAIT_V(n) asm volatile("s_waitcnt vmcnt(" #n ")" ::: "memory")
; template <class Epi, class Sched, bool ALIGN_EPI = false, bool SP2 = false>
; __device__ __forceinline__ void gemm_phase(PG8_LAS unsigned char* lds, const Gemm g, const Sched& S, const Epi& E) {
;     ...
;             PG8_LDB(B0, 0, 0); PG8_LDB(B1, 0, 1); PG8_SCHED; PG8_LDA(At, 0, 0); PG8_STAGE(PG8_SA(1, 1), a1 + hstep, voffA);
;             PG8_WAIT_V(8); PG8_WAIT_L(0); PG8_BAR; PG8_MMA(0, 0, At, B0); PG8_MMA(0, 1, At, B1); PG8_BAR; PG8_SCHED;
;             PG8_LDA(At, 0, 1); PG8_STAGE(PG8_SB(0, 0), b2, voffB); PG8_STAGE(PG8_SB(0, 1), b2 + hstep, voffB); PG8_STAGE(PG8_SA(0, 0), a2, voffA);
;             PG8_WAIT_V(8); PG8_WAIT_L(0); PG8_BAR; PG8_MMA(1, 0, At, B0); PG8_MMA(1, 1, At, B1); PG8_BAR; PG8_SCHED;
;             PG8_LDB(B0, 1, 0); PG8_LDB(B1, 1, 1); PG8_SCHED; PG8_LDA(At, 1, 0); PG8_STAGE(PG8_SA(0, 1), a2 + hstep, voffA);
;             PG8_WAIT_V(8); PG8_WAIT_L(0); PG8_BAR; PG8_MMA(0, 0, At, B0); PG8_MMA(0, 1, At, B1); PG8_BAR; PG8_SCHED;
;             PG8_LDA(At, 1, 1); PG8_STAGE(PG8_SB(1, 0), b3, voffB); PG8_STAGE(PG8_SB(1, 1), b3 + hstep, voffB); PG8_STAGE(PG8_SA(1, 0), a3, voffA);
;             PG8_WAIT_V(8); PG8_WAIT_L(0); PG8_BAR; PG8_MMA(1, 0, At, B0); PG8_MMA(1, 1, At, B1); PG8_BAR; PG8_SCHED;
	s_setprio 0
	s_add_i32 s46, s55, s62
	v_lshl_add_u64 v[160:161], v[160:161], 0, s[12:13]
	s_mov_b32 m0, s46
	ds_read_b128 v[198:201], v177 offset:49152
	ds_read_b128 v[202:205], v177 offset:50176
	ds_read_b128 v[206:209], v177 offset:51200
	ds_read_b128 v[210:213], v177 offset:52224
	ds_read_b128 v[214:217], v177 offset:53248
	ds_read_b128 v[218:221], v177 offset:54272
	ds_read_b128 v[222:225], v177 offset:55296
	ds_read_b128 v[226:229], v177 offset:56320
	global_load_lds_dwordx4 v[160:161], off
	s_add_i32 m0, s46, 0x2000
	s_add_u32 s44, s44, 0x80080
	v_lshl_add_u64 v[160:161], v[164:165], 0, s[12:13]
	s_addc_u32 s45, s45, 0
	s_add_i32 s46, s56, s62
	global_load_lds_dwordx4 v[160:161], off
	s_mov_b32 m0, s46
	v_lshl_add_u64 v[160:161], s[44:45], 0, v[144:145]
	global_load_lds_dwordx4 v[160:161], off
	s_add_i32 m0, s46, 0x2000
	v_lshl_add_u64 v[160:161], s[44:45], 0, v[146:147]
	global_load_lds_dwordx4 v[160:161], off
	s_mov_b32 m0, s68
	v_lshl_add_u64 v[160:161], v[170:171], 0, s[12:13]
	global_load_lds_dwordx4 v[160:161], off
	s_mov_b32 m0, s69
	v_lshl_add_u64 v[160:161], v[194:195], 0, s[12:13]
	global_load_lds_dwordx4 v[160:161], off
	s_waitcnt vmcnt(8) lgkmcnt(0)
	s_setprio 1
	s_barrier
	v_mfma_f32_16x16x32_bf16 v[60:63], v[96:99], v[198:201], v[60:63]
	v_mfma_f32_16x16x32_bf16 v[52:55], v[104:107], v[198:201], v[52:55]
	v_mfma_f32_16x16x32_bf16 v[36:39], v[96:99], v[206:209], v[36:39]
	v_mfma_f32_16x16x32_bf16 v[44:47], v[104:107], v[206:209], v[44:47]
	v_mfma_f32_16x16x32_bf16 v[20:23], v[96:99], v[214:217], v[20:23]
	v_mfma_f32_16x16x32_bf16 v[28:31], v[104:107], v[214:217], v[28:31]
	v_mfma_f32_16x16x32_bf16 v[4:7], v[96:99], v[222:225], v[4:7]
	v_mfma_f32_16x16x32_bf16 v[12:15], v[104:107], v[222:225], v[12:15]
	v_mfma_f32_16x16x32_bf16 v[60:63], v[100:103], v[202:205], v[60:63]
	v_mfma_f32_16x16x32_bf16 v[52:55], v[112:115], v[202:205], v[52:55]
	v_mfma_f32_16x16x32_bf16 v[36:39], v[100:103], v[210:213], v[36:39]
	v_mfma_f32_16x16x32_bf16 v[44:47], v[112:115], v[210:213], v[44:47]
	v_mfma_f32_16x16x32_bf16 v[20:23], v[100:103], v[218:221], v[20:23]
	v_mfma_f32_16x16x32_bf16 v[28:31], v[112:115], v[218:221], v[28:31]
	v_mfma_f32_16x16x32_bf16 v[4:7], v[100:103], v[226:229], v[4:7]
	v_mfma_f32_16x16x32_bf16 v[12:15], v[112:115], v[226:229], v[12:15]
	v_mfma_f32_16x16x32_bf16 v[48:51], v[178:181], v[198:201], v[48:51]
	v_mfma_f32_16x16x32_bf16 v[56:59], v[186:189], v[198:201], v[56:59]
	v_mfma_f32_16x16x32_bf16 v[40:43], v[178:181], v[206:209], v[40:43]
	v_mfma_f32_16x16x32_bf16 v[32:35], v[186:189], v[206:209], v[32:35]
	v_mfma_f32_16x16x32_bf16 v[24:27], v[178:181], v[214:217], v[24:27]
	v_mfma_f32_16x16x32_bf16 v[16:19], v[186:189], v[214:217], v[16:19]
	v_mfma_f32_16x16x32_bf16 v[8:11], v[178:181], v[222:225], v[8:11]
	v_mfma_f32_16x16x32_bf16 v[0:3], v[186:189], v[222:225], v[0:3]
	v_mfma_f32_16x16x32_bf16 v[48:51], v[182:185], v[202:205], v[48:51]
	v_mfma_f32_16x16x32_bf16 v[56:59], v[190:193], v[202:205], v[56:59]
	v_mfma_f32_16x16x32_bf16 v[40:43], v[182:185], v[210:213], v[40:43]
	v_mfma_f32_16x16x32_bf16 v[32:35], v[190:193], v[210:213], v[32:35]
	v_mfma_f32_16x16x32_bf16 v[24:27], v[182:185], v[218:221], v[24:27]
	v_mfma_f32_16x16x32_bf16 v[16:19], v[190:193], v[218:221], v[16:19]
	v_mfma_f32_16x16x32_bf16 v[8:11], v[182:185], v[226:229], v[8:11]
	v_mfma_f32_16x16x32_bf16 v[0:3], v[190:193], v[226:229], v[0:3]
	s_barrier
	s_setprio 0
	s_add_i32 s54, s54, 2
	s_add_u32 s8, s8, 0x100
	s_addc_u32 s9, s9, 0
	s_add_u32 s48, s48, 0x100
	s_addc_u32 s49, s49, 0
.LBB0_129:
	ds_read_b128 v[96:99], v173
	ds_read_b128 v[100:103], v173 offset:1024
	ds_read_b128 v[104:107], v173 offset:2048
	ds_read_b128 v[112:115], v173 offset:3072
	ds_read_b128 v[178:181], v175
	ds_read_b128 v[182:185], v175 offset:1024
	ds_read_b128 v[186:189], v175 offset:2048
	ds_read_b128 v[190:193], v175 offset:3072
	s_add_u32 s44, s8, 0xfff80080
	s_addc_u32 s45, s9, -1
	s_cmp_eq_u32 s54, 28
	s_cselect_b32 s47, s25, s45
	s_cselect_b32 s46, s35, s44
	s_cselect_b32 s45, s23, s49
	s_cselect_b32 s44, s43, s48
	v_lshl_add_u64 v[160:161], s[8:9], 0, v[154:155]
	s_add_i32 m0, s63, 0xc000
	ds_read_b128 v[198:201], v177
	ds_read_b128 v[202:205], v177 offset:1024
	ds_read_b128 v[206:209], v177 offset:2048
	ds_read_b128 v[210:213], v177 offset:3072
	ds_read_b128 v[214:217], v177 offset:4096
	ds_read_b128 v[218:221], v177 offset:5120
	ds_read_b128 v[222:225], v177 offset:6144
	ds_read_b128 v[226:229], v177 offset:7168
	global_load_lds_dwordx4 v[160:161], off
	s_add_i32 m0, s63, 0xe000
	v_lshl_add_u64 v[160:161], s[8:9], 0, v[156:157]
	global_load_lds_dwordx4 v[160:161], off
	s_waitcnt vmcnt(8) lgkmcnt(0)
	s_setprio 1
	s_barrier
; #define PG8_STAGE(bufoff, gbase, voff) do { _Pragma("unroll") for (int _i = 0; _i < 2; ++_i) \
;         __builtin_amdgcn_global_load_lds((const unsigned*)((const char*)(gbase) + (voff)[_i]), (PG8_LAS unsigned*)(lds + (bufoff) + ldsw + _i * 8192), 16, 0, 0); } while (0)
; #define PG8_LDA(dst, b, h) do { _Pragma("unroll") for (int m = 0; m < 4; ++m) _Pragma("unroll") for (int k = 0; k < 2; ++k) dst[m][k] = *(const PG8_LAS bf16x8*)(lds + PG8_SA(b, h) + aoff + m * 2048 + k * 1024); } while (0)
; #define PG8_MMA(ai, bj, At, Bt) do { __builtin_amdgcn_s_setprio(1); _Pragma("unroll") for (int m = 0; m < 4; ++m) _Pragma("unroll") for (int n = 0; n < 2; ++n) _Pragma("unroll") for (int k = 0; k < 2; ++k) \
;         acc[ai][bj][m][n] = __builtin_amdgcn_mfma_f32_16x16x32_bf16(Bt[n][k], At[m][k], acc[ai][bj][m][n], 0, 0, 0); __builtin_amdgcn_s_setprio(0); } while (0)
; #define PG8_WAIT_V(n) asm volatile("s_waitcnt vmcnt(" #n ")" ::: "memory")
; #define PG8_WAIT_L(n) asm volatile("s_waitcnt lgkmcnt(" #n ")" ::: "memory")
; #define PG8_BAR __builtin_amdgcn_s_barrier()
; #define PG8_SCHED __builtin_amdgcn_sched_barrier(0)
; template <class Epi, class Sched, bool ALIGN_EPI = false, bool SP2 = false>
; __device__ __forceinline__ void gemm_phase(PG8_LAS unsigned char* lds, const Gemm g, const Sched& S, const Epi& E) {
;     ...
;             PG8_WAIT_V(8); PG8_WAIT_L(0); PG8_BAR; PG8_MMA(0, 0, At, B0); PG8_MMA(0, 1, At, B1); PG8_BAR; PG8_SCHED;
;             PG8_LDA(At, 0, 1); PG8_STAGE(PG8_SB(0, 0), b2, voffB); PG8_STAGE(PG8_SB(0, 1), b2 + hstep, voffB); PG8_STAGE(PG8_SA(0, 0), a2, voffA);
;             PG8_WAIT_V(8); PG8_WAIT_L(0); PG8_BAR; PG8_MMA(1, 0, At, B0); PG8_MMA(1, 1, At, B1); PG8_BAR; PG8_SCHED;
	v_mfma_f32_16x16x32_bf16 v[140:143], v[96:99], v[198:201], v[140:143]
	v_mfma_f32_16x16x32_bf16 v[132:135], v[104:107], v[198:201], v[132:135]
	v_mfma_f32_16x16x32_bf16 v[116:119], v[96:99], v[206:209], v[116:119]
	v_mfma_f32_16x16x32_bf16 v[124:127], v[104:107], v[206:209], v[124:127]
	v_mfma_f32_16x16x32_bf16 v[84:87], v[96:99], v[214:217], v[84:87]
	v_mfma_f32_16x16x32_bf16 v[92:95], v[104:107], v[214:217], v[92:95]
	v_mfma_f32_16x16x32_bf16 v[68:71], v[96:99], v[222:225], v[68:71]
	v_mfma_f32_16x16x32_bf16 v[76:79], v[104:107], v[222:225], v[76:79]
	v_mfma_f32_16x16x32_bf16 v[140:143], v[100:103], v[202:205], v[140:143]
	v_mfma_f32_16x16x32_bf16 v[132:135], v[112:115], v[202:205], v[132:135]
	v_mfma_f32_16x16x32_bf16 v[116:119], v[100:103], v[210:213], v[116:119]
	v_mfma_f32_16x16x32_bf16 v[124:127], v[112:115], v[210:213], v[124:127]
	v_mfma_f32_16x16x32_bf16 v[84:87], v[100:103], v[218:221], v[84:87]
	v_mfma_f32_16x16x32_bf16 v[92:95], v[112:115], v[218:221], v[92:95]
	v_mfma_f32_16x16x32_bf16 v[68:71], v[100:103], v[226:229], v[68:71]
	v_mfma_f32_16x16x32_bf16 v[76:79], v[112:115], v[226:229], v[76:79]
	v_mfma_f32_16x16x32_bf16 v[128:131], v[178:181], v[198:201], v[128:131]
	v_mfma_f32_16x16x32_bf16 v[136:139], v[186:189], v[198:201], v[136:139]
	v_mfma_f32_16x16x32_bf16 v[120:123], v[178:181], v[206:209], v[120:123]
	v_mfma_f32_16x16x32_bf16 v[108:111], v[186:189], v[206:209], v[108:111]
	v_mfma_f32_16x16x32_bf16 v[88:91], v[178:181], v[214:217], v[88:91]
	v_mfma_f32_16x16x32_bf16 v[80:83], v[186:189], v[214:217], v[80:83]
	v_mfma_f32_16x16x32_bf16 v[72:75], v[178:181], v[222:225], v[72:75]
	v_mfma_f32_16x16x32_bf16 v[64:67], v[186:189], v[222:225], v[64:67]
	v_mfma_f32_16x16x32_bf16 v[128:131], v[182:185], v[202:205], v[128:131]
	v_mfma_f32_16x16x32_bf16 v[136:139], v[190:193], v[202:205], v[136:139]
	v_mfma_f32_16x16x32_bf16 v[120:123], v[182:185], v[210:213], v[120:123]
	v_mfma_f32_16x16x32_bf16 v[108:111], v[190:193], v[210:213], v[108:111]
	v_mfma_f32_16x16x32_bf16 v[88:91], v[182:185], v[218:221], v[88:91]
	v_mfma_f32_16x16x32_bf16 v[80:83], v[190:193], v[218:221], v[80:83]
	v_mfma_f32_16x16x32_bf16 v[72:75], v[182:185], v[226:229], v[72:75]
	v_mfma_f32_16x16x32_bf16 v[64:67], v[190:193], v[226:229], v[64:67]
	s_barrier
	s_setprio 0
	s_add_i32 s55, s52, s62
	v_lshl_add_u64 v[160:161], s[44:45], 0, v[144:145]
	s_mov_b32 m0, s55
	ds_read_b128 v[198:201], v177 offset:16384
	ds_read_b128 v[202:205], v177 offset:17408
	ds_read_b128 v[206:209], v177 offset:18432
	ds_read_b128 v[210:213], v177 offset:19456
	ds_read_b128 v[214:217], v177 offset:20480
	ds_read_b128 v[218:221], v177 offset:21504
	ds_read_b128 v[222:225], v177 offset:22528
	ds_read_b128 v[226:229], v177 offset:23552
	global_load_lds_dwordx4 v[160:161], off
	s_add_i32 m0, s55, 0x2000
	s_add_u32 s56, s44, 0x80000
	v_lshl_add_u64 v[164:165], s[44:45], 0, v[146:147]
	s_addc_u32 s57, s45, 0
	s_add_i32 s55, s53, s62
	global_load_lds_dwordx4 v[164:165], off
	v_lshl_add_u64 v[170:171], s[56:57], 0, v[144:145]
	s_mov_b32 m0, s55
	v_lshl_add_u64 v[194:195], s[46:47], 0, v[146:147]
	global_load_lds_dwordx4 v[170:171], off
	s_add_i32 m0, s55, 0x2000
	v_lshl_add_u64 v[170:171], s[56:57], 0, v[146:147]
	global_load_lds_dwordx4 v[170:171], off
	s_mov_b32 m0, s63
	v_lshl_add_u64 v[170:171], s[46:47], 0, v[144:145]
	global_load_lds_dwordx4 v[170:171], off
	s_mov_b32 m0, s64
	s_nop 0
	global_load_lds_dwordx4 v[194:195], off
	s_waitcnt vmcnt(8) lgkmcnt(0)
	s_setprio 1
	s_barrier
	v_mfma_f32_16x16x32_bf16 v[60:63], v[96:99], v[198:201], v[60:63]
	v_mfma_f32_16x16x32_bf16 v[52:55], v[104:107], v[198:201], v[52:55]
	v_mfma_f32_16x16x32_bf16 v[36:39], v[96:99], v[206:209], v[36:39]
	v_mfma_f32_16x16x32_bf16 v[44:47], v[104:107], v[206:209], v[44:47]
	v_mfma_f32_16x16x32_bf16 v[20:23], v[96:99], v[214:217], v[20:23]
	v_mfma_f32_16x16x32_bf16 v[28:31], v[104:107], v[214:217], v[28:31]
	v_mfma_f32_16x16x32_bf16 v[4:7], v[96:99], v[222:225], v[4:7]
	v_mfma_f32_16x16x32_bf16 v[12:15], v[104:107], v[222:225], v[12:15]
	v_mfma_f32_16x16x32_bf16 v[60:63], v[100:103], v[202:205], v[60:63]
	v_mfma_f32_16x16x32_bf16 v[52:55], v[112:115], v[202:205], v[52:55]
	v_mfma_f32_16x16x32_bf16 v[36:39], v[100:103], v[210:213], v[36:39]
	v_mfma_f32_16x16x32_bf16 v[44:47], v[112:115], v[210:213], v[44:47]
	v_mfma_f32_16x16x32_bf16 v[20:23], v[100:103], v[218:221], v[20:23]
	v_mfma_f32_16x16x32_bf16 v[28:31], v[112:115], v[218:221], v[28:31]
	v_mfma_f32_16x16x32_bf16 v[4:7], v[100:103], v[226:229], v[4:7]
	v_mfma_f32_16x16x32_bf16 v[12:15], v[112:115], v[226:229], v[12:15]
	v_mfma_f32_16x16x32_bf16 v[48:51], v[178:181], v[198:201], v[48:51]
	v_mfma_f32_16x16x32_bf16 v[56:59], v[186:189], v[198:201], v[56:59]
	v_mfma_f32_16x16x32_bf16 v[40:43], v[178:181], v[206:209], v[40:43]
	v_mfma_f32_16x16x32_bf16 v[32:35], v[186:189], v[206:209], v[32:35]
	v_mfma_f32_16x16x32_bf16 v[24:27], v[178:181], v[214:217], v[24:27]
	v_mfma_f32_16x16x32_bf16 v[16:19], v[186:189], v[214:217], v[16:19]
	v_mfma_f32_16x16x32_bf16 v[8:11], v[178:181], v[222:225], v[8:11]
	v_mfma_f32_16x16x32_bf16 v[0:3], v[186:189], v[222:225], v[0:3]
	v_mfma_f32_16x16x32_bf16 v[48:51], v[182:185], v[202:205], v[48:51]
	v_mfma_f32_16x16x32_bf16 v[56:59], v[190:193], v[202:205], v[56:59]
	v_mfma_f32_16x16x32_bf16 v[40:43], v[182:185], v[210:213], v[40:43]
	v_mfma_f32_16x16x32_bf16 v[32:35], v[190:193], v[210:213], v[32:35]
	v_mfma_f32_16x16x32_bf16 v[24:27], v[182:185], v[218:221], v[24:27]
	v_mfma_f32_16x16x32_bf16 v[16:19], v[190:193], v[218:221], v[16:19]
	v_mfma_f32_16x16x32_bf16 v[8:11], v[182:185], v[226:229], v[8:11]
	v_mfma_f32_16x16x32_bf16 v[0:3], v[190:193], v[226:229], v[0:3]
	s_barrier
; #define PG8_STAGE(bufoff, gbase, voff) do { _Pragma("unroll") for (int _i = 0; _i < 2; ++_i) \
;         __builtin_amdgcn_global_load_lds((const unsigned*)((const char*)(gbase) + (voff)[_i]), (PG8_LAS unsigned*)(lds + (bufoff) + ldsw + _i * 8192), 16, 0, 0); } while (0)
; #define PG8_LDA(dst, b, h) do { _Pragma("unroll") for (int m = 0; m < 4; ++m) _Pragma("unroll") for (int k = 0; k < 2; ++k) dst[m][k] = *(const PG8_LAS bf16x8*)(lds + PG8_SA(b, h) + aoff + m * 2048 + k * 1024); } while (0)
; #define PG8_LDB(dst, b, h) do { _Pragma("unroll") for (int n = 0; n < 2; ++n) _Pragma("unroll") for (int k = 0; k < 2; ++k) dst[n][k] = *(const PG8_LAS bf16x8*)(lds + PG8_SB(b, h) + boff + n * 2048 + k * 1024); } while (0)
; #define PG8_MMA(ai, bj, At, Bt) do { __builtin_amdgcn_s_setprio(1); _Pragma("unroll") for (int m = 0; m < 4; ++m) _Pragma("unroll") for (int n = 0; n < 2; ++n) _Pragma("unroll") for (int k = 0; k < 2; ++k) \
;         acc[ai][bj][m][n] = __builtin_amdgcn_mfma_f32_16x16x32_bf16(Bt[n][k], At[m][k], acc[ai][bj][m][n], 0, 0, 0); __builtin_amdgcn_s_setprio(0); } while (0)
; #define PG8_WAIT_V(n) asm volatile("s_waitcnt vmcnt(" #n ")" ::: "memory")
; #define PG8_WAIT_L(n) asm volatile("s_waitcnt lgkmcnt(" #n ")" ::: "memory")
; #define PG8_BAR __builtin_amdgcn_s_barrier()
; #define PG8_SCHED __builtin_amdgcn_sched_barrier(0)
; template <class Epi, class Sched, bool ALIGN_EPI = false, bool SP2 = false>
; __device__ __forceinline__ void gemm_phase(PG8_LAS unsigned char* lds, const Gemm g, const Sched& S, const Epi& E) {
;     ...
;             PG8_LDB(B0, 1, 0); PG8_LDB(B1, 1, 1); PG8_SCHED; PG8_LDA(At, 1, 0); PG8_STAGE(PG8_SA(0, 1), a2 + hstep, voffA);
;             PG8_WAIT_V(8); PG8_WAIT_L(0); PG8_BAR; PG8_MMA(0, 0, At, B0); PG8_MMA(0, 1, At, B1); PG8_BAR; PG8_SCHED;
	s_setprio 0
	s_add_i32 s55, 0, 0x18000
	s_add_i32 s56, 0, 0x1c000
	v_add_u32_e32 v112, s55, v167
	v_add_u32_e32 v162, s56, v167
	ds_read_b128 v[96:99], v112
	ds_read_b128 v[100:103], v112 offset:1024
	ds_read_b128 v[104:107], v112 offset:2048
	ds_read_b128 v[112:115], v112 offset:3072
	ds_read_b128 v[178:181], v162
	ds_read_b128 v[182:185], v162 offset:1024
	ds_read_b128 v[186:189], v162 offset:2048
	ds_read_b128 v[190:193], v162 offset:3072
	s_add_u32 s46, s46, 0x80000
	s_addc_u32 s47, s47, 0
	s_mov_b32 m0, s65
	v_lshl_add_u64 v[230:231], s[46:47], 0, v[144:145]
	ds_read_b128 v[198:201], v177 offset:32768
	ds_read_b128 v[202:205], v177 offset:33792
	ds_read_b128 v[206:209], v177 offset:34816
	ds_read_b128 v[210:213], v177 offset:35840
	ds_read_b128 v[214:217], v177 offset:36864
	ds_read_b128 v[218:221], v177 offset:37888
	ds_read_b128 v[222:225], v177 offset:38912
	ds_read_b128 v[226:229], v177 offset:39936
	global_load_lds_dwordx4 v[230:231], off
	s_mov_b32 m0, s66
	v_lshl_add_u64 v[230:231], s[46:47], 0, v[146:147]
	global_load_lds_dwordx4 v[230:231], off
	s_waitcnt vmcnt(8) lgkmcnt(0)
	s_setprio 1
	s_barrier
	v_mfma_f32_16x16x32_bf16 v[140:143], v[96:99], v[198:201], v[140:143]
	v_mfma_f32_16x16x32_bf16 v[132:135], v[104:107], v[198:201], v[132:135]
	v_mfma_f32_16x16x32_bf16 v[116:119], v[96:99], v[206:209], v[116:119]
	v_mfma_f32_16x16x32_bf16 v[124:127], v[104:107], v[206:209], v[124:127]
	v_mfma_f32_16x16x32_bf16 v[84:87], v[96:99], v[214:217], v[84:87]
	v_mfma_f32_16x16x32_bf16 v[92:95], v[104:107], v[214:217], v[92:95]
	v_mfma_f32_16x16x32_bf16 v[68:71], v[96:99], v[222:225], v[68:71]
	v_mfma_f32_16x16x32_bf16 v[76:79], v[104:107], v[222:225], v[76:79]
	v_mfma_f32_16x16x32_bf16 v[140:143], v[100:103], v[202:205], v[140:143]
	v_mfma_f32_16x16x32_bf16 v[132:135], v[112:115], v[202:205], v[132:135]
	v_mfma_f32_16x16x32_bf16 v[116:119], v[100:103], v[210:213], v[116:119]
	v_mfma_f32_16x16x32_bf16 v[124:127], v[112:115], v[210:213], v[124:127]
	v_mfma_f32_16x16x32_bf16 v[84:87], v[100:103], v[218:221], v[84:87]
	v_mfma_f32_16x16x32_bf16 v[92:95], v[112:115], v[218:221], v[92:95]
	v_mfma_f32_16x16x32_bf16 v[68:71], v[100:103], v[226:229], v[68:71]
	v_mfma_f32_16x16x32_bf16 v[76:79], v[112:115], v[226:229], v[76:79]
	v_mfma_f32_16x16x32_bf16 v[128:131], v[178:181], v[198:201], v[128:131]
	v_mfma_f32_16x16x32_bf16 v[136:139], v[186:189], v[198:201], v[136:139]
	v_mfma_f32_16x16x32_bf16 v[120:123], v[178:181], v[206:209], v[120:123]
	v_mfma_f32_16x16x32_bf16 v[108:111], v[186:189], v[206:209], v[108:111]
	v_mfma_f32_16x16x32_bf16 v[88:91], v[178:181], v[214:217], v[88:91]
	v_mfma_f32_16x16x32_bf16 v[80:83], v[186:189], v[214:217], v[80:83]
	v_mfma_f32_16x16x32_bf16 v[72:75], v[178:181], v[222:225], v[72:75]
	v_mfma_f32_16x16x32_bf16 v[64:67], v[186:189], v[222:225], v[64:67]
	v_mfma_f32_16x16x32_bf16 v[128:131], v[182:185], v[202:205], v[128:131]
	v_mfma_f32_16x16x32_bf16 v[136:139], v[190:193], v[202:205], v[136:139]
	v_mfma_f32_16x16x32_bf16 v[120:123], v[182:185], v[210:213], v[120:123]
	v_mfma_f32_16x16x32_bf16 v[108:111], v[190:193], v[210:213], v[108:111]
	v_mfma_f32_16x16x32_bf16 v[88:91], v[182:185], v[218:221], v[88:91]
	v_mfma_f32_16x16x32_bf16 v[80:83], v[190:193], v[218:221], v[80:83]
	v_mfma_f32_16x16x32_bf16 v[72:75], v[182:185], v[226:229], v[72:75]
	v_mfma_f32_16x16x32_bf16 v[64:67], v[190:193], v[226:229], v[64:67]
	s_barrier
; #define PG8_STAGE(bufoff, gbase, voff) do { _Pragma("unroll") for (int _i = 0; _i < 2; ++_i) \
;         __builtin_amdgcn_global_load_lds((const unsigned*)((const char*)(gbase) + (voff)[_i]), (PG8_LAS unsigned*)(lds + (bufoff) + ldsw + _i * 8192), 16, 0, 0); } while (0)
; #define PG8_LDA(dst, b, h) do { _Pragma("unroll") for (int m = 0; m < 4; ++m) _Pragma("unroll") for (int k = 0; k < 2; ++k) dst[m][k] = *(const PG8_LAS bf16x8*)(lds + PG8_SA(b, h) + aoff + m * 2048 + k * 1024); } while (0)
; #define PG8_MMA(ai, bj, At, Bt) do { __builtin_amdgcn_s_setprio(1); _Pragma("unroll") for (int m = 0; m < 4; ++m) _Pragma("unroll") for (int n = 0; n < 2; ++n) _Pragma("unroll") for (int k = 0; k < 2; ++k) \
;         acc[ai][bj][m][n] = __builtin_amdgcn_mfma_f32_16x16x32_bf16(Bt[n][k], At[m][k], acc[ai][bj][m][n], 0, 0, 0); __builtin_amdgcn_s_setprio(0); } while (0)
; #define PG8_WAIT_V(n) asm volatile("s_waitcnt vmcnt(" #n ")" ::: "memory")
; #define PG8_WAIT_L(n) asm volatile("s_waitcnt lgkmcnt(" #n ")" ::: "memory")
; #define PG8_BAR __builtin_amdgcn_s_barrier()
; #define PG8_SCHED __builtin_amdgcn_sched_barrier(0)
; template <class Epi, class Sched, bool ALIGN_EPI = false, bool SP2 = false>
; __device__ __forceinline__ void gemm_phase(PG8_LAS unsigned char* lds, const Gemm g, const Sched& S, const Epi& E) {
;     ...
;         for (int t = 0; t < nt; t += 2) {
;     ...
;             PG8_LDA(At, 1, 1); PG8_STAGE(PG8_SB(1, 0), b3, voffB); PG8_STAGE(PG8_SB(1, 1), b3 + hstep, voffB); PG8_STAGE(PG8_SA(1, 0), a3, voffA);
;             PG8_WAIT_V(8); PG8_WAIT_L(0); PG8_BAR; PG8_MMA(1, 0, At, B0); PG8_MMA(1, 1, At, B1); PG8_BAR; PG8_SCHED;
	s_setprio 0
	s_add_i32 s46, s55, s62
	v_lshl_add_u64 v[160:161], v[160:161], 0, s[12:13]
	s_mov_b32 m0, s46
	ds_read_b128 v[198:201], v177 offset:49152
	ds_read_b128 v[202:205], v177 offset:50176
	ds_read_b128 v[206:209], v177 offset:51200
	ds_read_b128 v[210:213], v177 offset:52224
	ds_read_b128 v[214:217], v177 offset:53248
	ds_read_b128 v[218:221], v177 offset:54272
	ds_read_b128 v[222:225], v177 offset:55296
	ds_read_b128 v[226:229], v177 offset:56320
	global_load_lds_dwordx4 v[160:161], off
	s_add_i32 m0, s46, 0x2000
	s_add_u32 s44, s44, 0x80080
	v_lshl_add_u64 v[160:161], v[164:165], 0, s[12:13]
	s_addc_u32 s45, s45, 0
	s_add_i32 s46, s56, s62
	global_load_lds_dwordx4 v[160:161], off
	s_mov_b32 m0, s46
	v_lshl_add_u64 v[160:161], s[44:45], 0, v[144:145]
	global_load_lds_dwordx4 v[160:161], off
	s_add_i32 m0, s46, 0x2000
	v_lshl_add_u64 v[160:161], s[44:45], 0, v[146:147]
	global_load_lds_dwordx4 v[160:161], off
	s_mov_b32 m0, s68
	v_lshl_add_u64 v[160:161], v[170:171], 0, s[12:13]
	global_load_lds_dwordx4 v[160:161], off
	s_mov_b32 m0, s69
	v_lshl_add_u64 v[160:161], v[194:195], 0, s[12:13]
	global_load_lds_dwordx4 v[160:161], off
	s_waitcnt vmcnt(8) lgkmcnt(0)
	s_setprio 1
	s_barrier
	v_mfma_f32_16x16x32_bf16 v[60:63], v[96:99], v[198:201], v[60:63]
	v_mfma_f32_16x16x32_bf16 v[52:55], v[104:107], v[198:201], v[52:55]
	v_mfma_f32_16x16x32_bf16 v[36:39], v[96:99], v[206:209], v[36:39]
	v_mfma_f32_16x16x32_bf16 v[44:47], v[104:107], v[206:209], v[44:47]
	v_mfma_f32_16x16x32_bf16 v[20:23], v[96:99], v[214:217], v[20:23]
	v_mfma_f32_16x16x32_bf16 v[28:31], v[104:107], v[214:217], v[28:31]
	v_mfma_f32_16x16x32_bf16 v[4:7], v[96:99], v[222:225], v[4:7]
	v_mfma_f32_16x16x32_bf16 v[12:15], v[104:107], v[222:225], v[12:15]
	v_mfma_f32_16x16x32_bf16 v[60:63], v[100:103], v[202:205], v[60:63]
	v_mfma_f32_16x16x32_bf16 v[52:55], v[112:115], v[202:205], v[52:55]
	v_mfma_f32_16x16x32_bf16 v[36:39], v[100:103], v[210:213], v[36:39]
	v_mfma_f32_16x16x32_bf16 v[44:47], v[112:115], v[210:213], v[44:47]
	v_mfma_f32_16x16x32_bf16 v[20:23], v[100:103], v[218:221], v[20:23]
	v_mfma_f32_16x16x32_bf16 v[28:31], v[112:115], v[218:221], v[28:31]
	v_mfma_f32_16x16x32_bf16 v[4:7], v[100:103], v[226:229], v[4:7]
	v_mfma_f32_16x16x32_bf16 v[12:15], v[112:115], v[226:229], v[12:15]
	v_mfma_f32_16x16x32_bf16 v[48:51], v[178:181], v[198:201], v[48:51]
	v_mfma_f32_16x16x32_bf16 v[56:59], v[186:189], v[198:201], v[56:59]
	v_mfma_f32_16x16x32_bf16 v[40:43], v[178:181], v[206:209], v[40:43]
	v_mfma_f32_16x16x32_bf16 v[32:35], v[186:189], v[206:209], v[32:35]
	v_mfma_f32_16x16x32_bf16 v[24:27], v[178:181], v[214:217], v[24:27]
	v_mfma_f32_16x16x32_bf16 v[16:19], v[186:189], v[214:217], v[16:19]
	v_mfma_f32_16x16x32_bf16 v[8:11], v[178:181], v[222:225], v[8:11]
	v_mfma_f32_16x16x32_bf16 v[0:3], v[186:189], v[222:225], v[0:3]
	v_mfma_f32_16x16x32_bf16 v[48:51], v[182:185], v[202:205], v[48:51]
	v_mfma_f32_16x16x32_bf16 v[56:59], v[190:193], v[202:205], v[56:59]
	v_mfma_f32_16x16x32_bf16 v[40:43], v[182:185], v[210:213], v[40:43]
	v_mfma_f32_16x16x32_bf16 v[32:35], v[190:193], v[210:213], v[32:35]
	v_mfma_f32_16x16x32_bf16 v[24:27], v[182:185], v[218:221], v[24:27]
	v_mfma_f32_16x16x32_bf16 v[16:19], v[190:193], v[218:221], v[16:19]
	v_mfma_f32_16x16x32_bf16 v[8:11], v[182:185], v[226:229], v[8:11]
	v_mfma_f32_16x16x32_bf16 v[0:3], v[190:193], v[226:229], v[0:3]
	s_barrier
	s_setprio 0
	s_add_i32 s54, s54, 2
	s_add_u32 s8, s8, 0x100
	s_addc_u32 s9, s9, 0
	s_add_u32 s48, s48, 0x100
	s_addc_u32 s49, s49, 0
	s_cmp_gt_u32 s54, 29
	s_cbranch_scc0 .LBB0_129
	s_and_b64 vcc, exec, s[14:15]
	s_cbranch_vccz .LBB0_132
	s_barrier

; #define PG8_STAGE(bufoff, gbase, voff) do { _Pragma("unroll") for (int _i = 0; _i < 2; ++_i) \
;         __builtin_amdgcn_global_load_lds((const unsigned*)((const char*)(gbase) + (voff)[_i]), (PG8_LAS unsigned*)(lds + (bufoff) + ldsw + _i * 8192), 16, 0, 0); } while (0)
; #define PG8_LDA(dst, b, h) do { _Pragma("unroll") for (int m = 0; m < 4; ++m) _Pragma("unroll") for (int k = 0; k < 2; ++k) dst[m][k] = *(const PG8_LAS bf16x8*)(lds + PG8_SA(b, h) + aoff + m * 2048 + k * 1024); } while (0)
; #define PG8_LDB(dst, b, h) do { _Pragma("unroll") for (int n = 0; n < 2; ++n) _Pragma("unroll") for (int k = 0; k < 2; ++k) dst[n][k] = *(const PG8_LAS bf16x8*)(lds + PG8_SB(b, h) + boff + n * 2048 + k * 1024); } while (0)
; #define PG8_MMA(ai, bj, At, Bt) do { __builtin_amdgcn_s_setprio(1); _Pragma("unroll") for (int m = 0; m < 4; ++m) _Pragma("unroll") for (int n = 0; n < 2; ++n) _Pragma("unroll") for (int k = 0; k < 2; ++k) \
;         acc[ai][bj][m][n] = __builtin_amdgcn_mfma_f32_16x16x32_bf16(Bt[n][k], At[m][k], acc[ai][bj][m][n], 0, 0, 0); __builtin_amdgcn_s_setprio(0); } while (0)
; #define PG8_WAIT_V(n) asm volatile("s_waitcnt vmcnt(" #n ")" ::: "memory")
; template <class Epi, class Sched, bool ALIGN_EPI = false, bool SP2 = false>
; __device__ __forceinline__ void gemm_phase(PG8_LAS unsigned char* lds, const Gemm g, const Sched& S, const Epi& E) {
;     ...
;         const char* nA = has_next ? (const char*)g.A + (size_t)nxt.pm * tstep : cA; const char* nB = has_next ? (const char*)g.Bt + (size_t)nxt.pn * tstep : cB;
;         for (int t = 0; t < nt; t += 2) {
;             const bool last = (t == nt - 2);
;             const char* a1 = cA + (size_t)(t + 1) * kstep;
;             const char* a2 = last ? nA : cA + (size_t)(t + 2) * kstep; const char* b2 = last ? nB : cB + (size_t)(t + 2) * kstep;
;             const char* a3 = a2 + kstep; const char* b3 = b2 + kstep;
;             if (last && has_next) S.a_ready(nxt);
;             if constexpr (SP2) {
;             PG8_LDB(B0, 0, 0); PG8_LDB(B1, 0, 1); PG8_SCHED; PG8_LDA(At, 0, 0); PG8_STAGE(PG8_SA(1, 1), a1 + hstep, voffA);
;             PG8_WAIT_V(8); PG8_WAIT_L(0); PG8_BAR; PG8_MMA(0, 0, At, B0); PG8_MMA(0, 1, At, B1); PG8_BAR; PG8_SCHED;
;             PG8_LDA(At, 0, 1); PG8_STAGE(PG8_SB(0, 0), b2, voffB); PG8_STAGE(PG8_SB(0, 1), b2 + hstep, voffB); PG8_STAGE(PG8_SA(0, 0), a2, voffA);
.LBB0_306:
	s_ashr_i32 s21, s20, 31
	s_lshl_b64 s[22:23], s[20:21], 20
	s_add_u32 s22, s60, s22
	s_addc_u32 s23, s61, s23
	s_and_b64 s[24:25], s[4:5], exec
	s_cselect_b32 s7, s23, s27
	s_cselect_b32 s21, s22, s26
	s_ashr_i32 s19, s18, 31
	s_lshl_b64 s[24:25], s[18:19], 20
	s_add_u32 s24, s68, s24
	s_addc_u32 s25, s69, s25
	s_and_b64 s[30:31], s[4:5], exec
	s_cselect_b32 s19, s25, s29
	s_cselect_b32 s33, s24, s28
	s_add_u32 s26, s26, 0x80080
	s_addc_u32 s27, s27, 0
	s_add_u32 s48, s28, 0x100
	s_addc_u32 s49, s29, 0
	s_mov_b32 s50, -2
	s_waitcnt lgkmcnt(0)
	s_waitcnt lgkmcnt(0)
	ds_read_b128 v[128:131], v181
	ds_read_b128 v[132:135], v181 offset:1024
	ds_read_b128 v[136:139], v181 offset:2048
	ds_read_b128 v[140:143], v181 offset:3072
	ds_read_b128 v[144:147], v182
	ds_read_b128 v[148:151], v182 offset:1024
	ds_read_b128 v[168:171], v182 offset:2048
	ds_read_b128 v[172:175], v182 offset:3072
	s_add_u32 s28, s26, 0xfff80080
	s_addc_u32 s29, s27, -1
	s_cmp_eq_u32 s50, 28
	s_cselect_b32 s31, s7, s29
	s_cselect_b32 s30, s21, s28
	s_cselect_b32 s29, s19, s49
	s_cselect_b32 s28, s33, s48
	v_lshl_add_u64 v[176:177], s[26:27], 0, v[160:161]
	s_add_i32 m0, s35, 0xc000
	ds_read_b128 v[186:189], v183
	ds_read_b128 v[190:193], v183 offset:1024
	ds_read_b128 v[198:201], v183 offset:2048
	ds_read_b128 v[202:205], v183 offset:3072
	ds_read_b128 v[206:209], v183 offset:4096
	ds_read_b128 v[210:213], v183 offset:5120
	ds_read_b128 v[214:217], v183 offset:6144
	ds_read_b128 v[218:221], v183 offset:7168
	global_load_lds_dwordx4 v[176:177], off
	s_add_i32 m0, s35, 0xe000
	v_lshl_add_u64 v[176:177], s[26:27], 0, v[162:163]
	global_load_lds_dwordx4 v[176:177], off
	s_waitcnt lgkmcnt(0)
	s_setprio 1
	s_barrier
	v_mfma_f32_16x16x32_bf16 v[124:127], v[128:131], v[186:189], 0
	v_mfma_f32_16x16x32_bf16 v[120:123], v[136:139], v[186:189], 0
	v_mfma_f32_16x16x32_bf16 v[104:107], v[128:131], v[198:201], 0
	v_mfma_f32_16x16x32_bf16 v[108:111], v[136:139], v[198:201], 0
	v_mfma_f32_16x16x32_bf16 v[88:91], v[128:131], v[206:209], 0
	v_mfma_f32_16x16x32_bf16 v[92:95], v[136:139], v[206:209], 0
	v_mfma_f32_16x16x32_bf16 v[72:75], v[128:131], v[214:217], 0
	v_mfma_f32_16x16x32_bf16 v[76:79], v[136:139], v[214:217], 0
	v_mfma_f32_16x16x32_bf16 v[124:127], v[132:135], v[190:193], v[124:127]
	v_mfma_f32_16x16x32_bf16 v[120:123], v[140:143], v[190:193], v[120:123]
	v_mfma_f32_16x16x32_bf16 v[104:107], v[132:135], v[202:205], v[104:107]
	v_mfma_f32_16x16x32_bf16 v[108:111], v[140:143], v[202:205], v[108:111]
	v_mfma_f32_16x16x32_bf16 v[88:91], v[132:135], v[210:213], v[88:91]
	v_mfma_f32_16x16x32_bf16 v[92:95], v[140:143], v[210:213], v[92:95]
	v_mfma_f32_16x16x32_bf16 v[72:75], v[132:135], v[218:221], v[72:75]
	v_mfma_f32_16x16x32_bf16 v[76:79], v[140:143], v[218:221], v[76:79]
	v_mfma_f32_16x16x32_bf16 v[116:119], v[144:147], v[186:189], 0
	v_mfma_f32_16x16x32_bf16 v[112:115], v[168:171], v[186:189], 0
	v_mfma_f32_16x16x32_bf16 v[100:103], v[144:147], v[198:201], 0
	v_mfma_f32_16x16x32_bf16 v[96:99], v[168:171], v[198:201], 0
	v_mfma_f32_16x16x32_bf16 v[84:87], v[144:147], v[206:209], 0
	v_mfma_f32_16x16x32_bf16 v[80:83], v[168:171], v[206:209], 0
	v_mfma_f32_16x16x32_bf16 v[68:71], v[144:147], v[214:217], 0
	v_mfma_f32_16x16x32_bf16 v[64:67], v[168:171], v[214:217], 0
	v_mfma_f32_16x16x32_bf16 v[116:119], v[148:151], v[190:193], v[116:119]
	v_mfma_f32_16x16x32_bf16 v[112:115], v[172:175], v[190:193], v[112:115]
	v_mfma_f32_16x16x32_bf16 v[100:103], v[148:151], v[202:205], v[100:103]
	v_mfma_f32_16x16x32_bf16 v[96:99], v[172:175], v[202:205], v[96:99]
	v_mfma_f32_16x16x32_bf16 v[84:87], v[148:151], v[210:213], v[84:87]
	v_mfma_f32_16x16x32_bf16 v[80:83], v[172:175], v[210:213], v[80:83]
	v_mfma_f32_16x16x32_bf16 v[68:71], v[148:151], v[218:221], v[68:71]
	v_mfma_f32_16x16x32_bf16 v[64:67], v[172:175], v[218:221], v[64:67]
	s_barrier
	s_setprio 0
	s_add_i32 s51, s62, s34
	v_lshl_add_u64 v[176:177], s[28:29], 0, v[154:155]
	s_mov_b32 m0, s51
	ds_read_b128 v[186:189], v183 offset:16384
	ds_read_b128 v[190:193], v183 offset:17408
	ds_read_b128 v[198:201], v183 offset:18432
	ds_read_b128 v[202:205], v183 offset:19456
	ds_read_b128 v[206:209], v183 offset:20480
	ds_read_b128 v[210:213], v183 offset:21504
	ds_read_b128 v[214:217], v183 offset:22528
	ds_read_b128 v[218:221], v183 offset:23552
	global_load_lds_dwordx4 v[176:177], off
	s_add_i32 m0, s51, 0x2000
	s_add_u32 s52, s28, 0x80000
	v_lshl_add_u64 v[194:195], s[28:29], 0, v[158:159]
	s_addc_u32 s53, s29, 0
	s_add_i32 s51, s63, s34
	global_load_lds_dwordx4 v[194:195], off
	v_lshl_add_u64 v[222:223], s[52:53], 0, v[154:155]
	s_mov_b32 m0, s51
	v_lshl_add_u64 v[224:225], s[30:31], 0, v[156:157]
	global_load_lds_dwordx4 v[222:223], off
	s_add_i32 m0, s51, 0x2000
	v_lshl_add_u64 v[222:223], s[52:53], 0, v[158:159]
	global_load_lds_dwordx4 v[222:223], off
	s_mov_b32 m0, s35
	v_lshl_add_u64 v[222:223], s[30:31], 0, v[152:153]
	global_load_lds_dwordx4 v[222:223], off
	s_mov_b32 m0, s37
	s_nop 0
	global_load_lds_dwordx4 v[224:225], off
	s_waitcnt lgkmcnt(0)
	s_setprio 1
	s_barrier
; #define PG8_STAGE(bufoff, gbase, voff) do { _Pragma("unroll") for (int _i = 0; _i < 2; ++_i) \
;         __builtin_amdgcn_global_load_lds((const unsigned*)((const char*)(gbase) + (voff)[_i]), (PG8_LAS unsigned*)(lds + (bufoff) + ldsw + _i * 8192), 16, 0, 0); } while (0)
; #define PG8_LDA(dst, b, h) do { _Pragma("unroll") for (int m = 0; m < 4; ++m) _Pragma("unroll") for (int k = 0; k < 2; ++k) dst[m][k] = *(const PG8_LAS bf16x8*)(lds + PG8_SA(b, h) + aoff + m * 2048 + k * 1024); } while (0)
; #define PG8_LDB(dst, b, h) do { _Pragma("unroll") for (int n = 0; n < 2; ++n) _Pragma("unroll") for (int k = 0; k < 2; ++k) dst[n][k] = *(const PG8_LAS bf16x8*)(lds + PG8_SB(b, h) + boff + n * 2048 + k * 1024); } while (0)
; #define PG8_MMA(ai, bj, At, Bt) do { __builtin_amdgcn_s_setprio(1); _Pragma("unroll") for (int m = 0; m < 4; ++m) _Pragma("unroll") for (int n = 0; n < 2; ++n) _Pragma("unroll") for (int k = 0; k < 2; ++k) \
;         acc[ai][bj][m][n] = __builtin_amdgcn_mfma_f32_16x16x32_bf16(Bt[n][k], At[m][k], acc[ai][bj][m][n], 0, 0, 0); __builtin_amdgcn_s_setprio(0); } while (0)
; #define PG8_WAIT_V(n) asm volatile("s_waitcnt vmcnt(" #n ")" ::: "memory")
; #define PG8_WAIT_L(n) asm volatile("s_waitcnt lgkmcnt(" #n ")" ::: "memory")
; #define PG8_BAR __builtin_amdgcn_s_barrier()
; #define PG8_SCHED __builtin_amdgcn_sched_barrier(0)
; template <class Epi, class Sched, bool ALIGN_EPI = false, bool SP2 = false>
; __device__ __forceinline__ void gemm_phase(PG8_LAS unsigned char* lds, const Gemm g, const Sched& S, const Epi& E) {
;     ...
;             PG8_WAIT_V(8); PG8_WAIT_L(0); PG8_BAR; PG8_MMA(1, 0, At, B0); PG8_MMA(1, 1, At, B1); PG8_BAR; PG8_SCHED;
;             PG8_LDB(B0, 1, 0); PG8_LDB(B1, 1, 1); PG8_SCHED; PG8_LDA(At, 1, 0); PG8_STAGE(PG8_SA(0, 1), a2 + hstep, voffA);
;             PG8_WAIT_V(8); PG8_WAIT_L(0); PG8_BAR; PG8_MMA(0, 0, At, B0); PG8_MMA(0, 1, At, B1); PG8_BAR; PG8_SCHED;
	v_mfma_f32_16x16x32_bf16 v[56:59], v[128:131], v[186:189], 0
	v_mfma_f32_16x16x32_bf16 v[60:63], v[136:139], v[186:189], 0
	v_mfma_f32_16x16x32_bf16 v[40:43], v[128:131], v[198:201], 0
	v_mfma_f32_16x16x32_bf16 v[44:47], v[136:139], v[198:201], 0
	v_mfma_f32_16x16x32_bf16 v[24:27], v[128:131], v[206:209], 0
	v_mfma_f32_16x16x32_bf16 v[28:31], v[136:139], v[206:209], 0
	v_mfma_f32_16x16x32_bf16 v[8:11], v[128:131], v[214:217], 0
	v_mfma_f32_16x16x32_bf16 v[12:15], v[136:139], v[214:217], 0
	v_mfma_f32_16x16x32_bf16 v[56:59], v[132:135], v[190:193], v[56:59]
	v_mfma_f32_16x16x32_bf16 v[60:63], v[140:143], v[190:193], v[60:63]
	v_mfma_f32_16x16x32_bf16 v[40:43], v[132:135], v[202:205], v[40:43]
	v_mfma_f32_16x16x32_bf16 v[44:47], v[140:143], v[202:205], v[44:47]
	v_mfma_f32_16x16x32_bf16 v[24:27], v[132:135], v[210:213], v[24:27]
	v_mfma_f32_16x16x32_bf16 v[28:31], v[140:143], v[210:213], v[28:31]
	v_mfma_f32_16x16x32_bf16 v[8:11], v[132:135], v[218:221], v[8:11]
	v_mfma_f32_16x16x32_bf16 v[12:15], v[140:143], v[218:221], v[12:15]
	v_mfma_f32_16x16x32_bf16 v[52:55], v[144:147], v[186:189], 0
	v_mfma_f32_16x16x32_bf16 v[48:51], v[168:171], v[186:189], 0
	v_mfma_f32_16x16x32_bf16 v[36:39], v[144:147], v[198:201], 0
	v_mfma_f32_16x16x32_bf16 v[32:35], v[168:171], v[198:201], 0
	v_mfma_f32_16x16x32_bf16 v[20:23], v[144:147], v[206:209], 0
	v_mfma_f32_16x16x32_bf16 v[16:19], v[168:171], v[206:209], 0
	v_mfma_f32_16x16x32_bf16 v[4:7], v[144:147], v[214:217], 0
	v_mfma_f32_16x16x32_bf16 v[0:3], v[168:171], v[214:217], 0
	v_mfma_f32_16x16x32_bf16 v[52:55], v[148:151], v[190:193], v[52:55]
	v_mfma_f32_16x16x32_bf16 v[48:51], v[172:175], v[190:193], v[48:51]
	v_mfma_f32_16x16x32_bf16 v[36:39], v[148:151], v[202:205], v[36:39]
	v_mfma_f32_16x16x32_bf16 v[32:35], v[172:175], v[202:205], v[32:35]
	v_mfma_f32_16x16x32_bf16 v[20:23], v[148:151], v[210:213], v[20:23]
	v_mfma_f32_16x16x32_bf16 v[16:19], v[172:175], v[210:213], v[16:19]
	v_mfma_f32_16x16x32_bf16 v[4:7], v[148:151], v[218:221], v[4:7]
	v_mfma_f32_16x16x32_bf16 v[0:3], v[172:175], v[218:221], v[0:3]
	s_barrier
	s_setprio 0
	s_add_i32 s51, 0, 0x18000
	s_add_i32 s52, 0, 0x1c000
	v_add_u32_e32 v140, s51, v179
	v_add_u32_e32 v172, s52, v179
	ds_read_b128 v[128:131], v140
	ds_read_b128 v[132:135], v140 offset:1024
	ds_read_b128 v[136:139], v140 offset:2048
	ds_read_b128 v[140:143], v140 offset:3072
	ds_read_b128 v[144:147], v172
	ds_read_b128 v[148:151], v172 offset:1024
	ds_read_b128 v[168:171], v172 offset:2048
	ds_read_b128 v[172:175], v172 offset:3072
	s_add_u32 s30, s30, 0x80000
	s_addc_u32 s31, s31, 0
	s_mov_b32 m0, s39
	v_lshl_add_u64 v[226:227], s[30:31], 0, v[152:153]
	ds_read_b128 v[186:189], v183 offset:32768
	ds_read_b128 v[190:193], v183 offset:33792
	ds_read_b128 v[198:201], v183 offset:34816
	ds_read_b128 v[202:205], v183 offset:35840
	ds_read_b128 v[206:209], v183 offset:36864
	ds_read_b128 v[210:213], v183 offset:37888
	ds_read_b128 v[214:217], v183 offset:38912
	ds_read_b128 v[218:221], v183 offset:39936
	global_load_lds_dwordx4 v[226:227], off
	s_mov_b32 m0, s42
	v_lshl_add_u64 v[226:227], s[30:31], 0, v[156:157]
	global_load_lds_dwordx4 v[226:227], off
	s_waitcnt vmcnt(8) lgkmcnt(0)
	s_setprio 1
	s_barrier
	v_mfma_f32_16x16x32_bf16 v[124:127], v[128:131], v[186:189], v[124:127]
	v_mfma_f32_16x16x32_bf16 v[120:123], v[136:139], v[186:189], v[120:123]
	v_mfma_f32_16x16x32_bf16 v[104:107], v[128:131], v[198:201], v[104:107]
	v_mfma_f32_16x16x32_bf16 v[108:111], v[136:139], v[198:201], v[108:111]
	v_mfma_f32_16x16x32_bf16 v[88:91], v[128:131], v[206:209], v[88:91]
	v_mfma_f32_16x16x32_bf16 v[92:95], v[136:139], v[206:209], v[92:95]
	v_mfma_f32_16x16x32_bf16 v[72:75], v[128:131], v[214:217], v[72:75]
	v_mfma_f32_16x16x32_bf16 v[76:79], v[136:139], v[214:217], v[76:79]
	v_mfma_f32_16x16x32_bf16 v[124:127], v[132:135], v[190:193], v[124:127]
	v_mfma_f32_16x16x32_bf16 v[120:123], v[140:143], v[190:193], v[120:123]
	v_mfma_f32_16x16x32_bf16 v[104:107], v[132:135], v[202:205], v[104:107]
	v_mfma_f32_16x16x32_bf16 v[108:111], v[140:143], v[202:205], v[108:111]
	v_mfma_f32_16x16x32_bf16 v[88:91], v[132:135], v[210:213], v[88:91]
	v_mfma_f32_16x16x32_bf16 v[92:95], v[140:143], v[210:213], v[92:95]
	v_mfma_f32_16x16x32_bf16 v[72:75], v[132:135], v[218:221], v[72:75]
	v_mfma_f32_16x16x32_bf16 v[76:79], v[140:143], v[218:221], v[76:79]
	v_mfma_f32_16x16x32_bf16 v[116:119], v[144:147], v[186:189], v[116:119]
	v_mfma_f32_16x16x32_bf16 v[112:115], v[168:171], v[186:189], v[112:115]
	v_mfma_f32_16x16x32_bf16 v[100:103], v[144:147], v[198:201], v[100:103]
	v_mfma_f32_16x16x32_bf16 v[96:99], v[168:171], v[198:201], v[96:99]
	v_mfma_f32_16x16x32_bf16 v[84:87], v[144:147], v[206:209], v[84:87]
	v_mfma_f32_16x16x32_bf16 v[80:83], v[168:171], v[206:209], v[80:83]
	v_mfma_f32_16x16x32_bf16 v[68:71], v[144:147], v[214:217], v[68:71]
	v_mfma_f32_16x16x32_bf16 v[64:67], v[168:171], v[214:217], v[64:67]
	v_mfma_f32_16x16x32_bf16 v[116:119], v[148:151], v[190:193], v[116:119]
	v_mfma_f32_16x16x32_bf16 v[112:115], v[172:175], v[190:193], v[112:115]
	v_mfma_f32_16x16x32_bf16 v[100:103], v[148:151], v[202:205], v[100:103]
	v_mfma_f32_16x16x32_bf16 v[96:99], v[172:175], v[202:205], v[96:99]
	v_mfma_f32_16x16x32_bf16 v[84:87], v[148:151], v[210:213], v[84:87]
	v_mfma_f32_16x16x32_bf16 v[80:83], v[172:175], v[210:213], v[80:83]
	v_mfma_f32_16x16x32_bf16 v[68:71], v[148:151], v[218:221], v[68:71]
	v_mfma_f32_16x16x32_bf16 v[64:67], v[172:175], v[218:221], v[64:67]
	s_barrier
; #define PG8_STAGE(bufoff, gbase, voff) do { _Pragma("unroll") for (int _i = 0; _i < 2; ++_i) \
;         __builtin_amdgcn_global_load_lds((const unsigned*)((const char*)(gbase) + (voff)[_i]), (PG8_LAS unsigned*)(lds + (bufoff) + ldsw + _i * 8192), 16, 0, 0); } while (0)
; #define PG8_LDA(dst, b, h) do { _Pragma("unroll") for (int m = 0; m < 4; ++m) _Pragma("unroll") for (int k = 0; k < 2; ++k) dst[m][k] = *(const PG8_LAS bf16x8*)(lds + PG8_SA(b, h) + aoff + m * 2048 + k * 1024); } while (0)
; #define PG8_LDB(dst, b, h) do { _Pragma("unroll") for (int n = 0; n < 2; ++n) _Pragma("unroll") for (int k = 0; k < 2; ++k) dst[n][k] = *(const PG8_LAS bf16x8*)(lds + PG8_SB(b, h) + boff + n * 2048 + k * 1024); } while (0)
; #define PG8_MMA(ai, bj, At, Bt) do { __builtin_amdgcn_s_setprio(1); _Pragma("unroll") for (int m = 0; m < 4; ++m) _Pragma("unroll") for (int n = 0; n < 2; ++n) _Pragma("unroll") for (int k = 0; k < 2; ++k) \
;         acc[ai][bj][m][n] = __builtin_amdgcn_mfma_f32_16x16x32_bf16(Bt[n][k], At[m][k], acc[ai][bj][m][n], 0, 0, 0); __builtin_amdgcn_s_setprio(0); } while (0)
; #define PG8_WAIT_V(n) asm volatile("s_waitcnt vmcnt(" #n ")" ::: "memory")
; template <class Epi, class Sched, bool ALIGN_EPI = false, bool SP2 = false>
; __device__ __forceinline__ void gemm_phase(PG8_LAS unsigned char* lds, const Gemm g, const Sched& S, const Epi& E) {
;     ...
;             PG8_LDB(B0, 0, 0); PG8_LDB(B1, 0, 1); PG8_SCHED; PG8_LDA(At, 0, 0); PG8_STAGE(PG8_SA(1, 1), a1 + hstep, voffA);
;             PG8_WAIT_V(8); PG8_WAIT_L(0); PG8_BAR; PG8_MMA(0, 0, At, B0); PG8_MMA(0, 1, At, B1); PG8_BAR; PG8_SCHED;
;             PG8_LDA(At, 0, 1); PG8_STAGE(PG8_SB(0, 0), b2, voffB); PG8_STAGE(PG8_SB(0, 1), b2 + hstep, voffB); PG8_STAGE(PG8_SA(0, 0), a2, voffA);
;             PG8_WAIT_V(8); PG8_WAIT_L(0); PG8_BAR; PG8_MMA(1, 0, At, B0); PG8_MMA(1, 1, At, B1); PG8_BAR; PG8_SCHED;
;             PG8_LDB(B0, 1, 0); PG8_LDB(B1, 1, 1); PG8_SCHED; PG8_LDA(At, 1, 0); PG8_STAGE(PG8_SA(0, 1), a2 + hstep, voffA);
;             PG8_WAIT_V(8); PG8_WAIT_L(0); PG8_BAR; PG8_MMA(0, 0, At, B0); PG8_MMA(0, 1, At, B1); PG8_BAR; PG8_SCHED;
;             PG8_LDA(At, 1, 1); PG8_STAGE(PG8_SB(1, 0), b3, voffB); PG8_STAGE(PG8_SB(1, 1), b3 + hstep, voffB); PG8_STAGE(PG8_SA(1, 0), a3, voffA);
;             PG8_WAIT_V(8); PG8_WAIT_L(0); PG8_BAR; PG8_MMA(1, 0, At, B0); PG8_MMA(1, 1, At, B1); PG8_BAR; PG8_SCHED;
	s_setprio 0
	s_add_i32 s30, s51, s34
	v_lshl_add_u64 v[176:177], v[176:177], 0, s[12:13]
	s_mov_b32 m0, s30
	ds_read_b128 v[186:189], v183 offset:49152
	ds_read_b128 v[190:193], v183 offset:50176
	ds_read_b128 v[198:201], v183 offset:51200
	ds_read_b128 v[202:205], v183 offset:52224
	ds_read_b128 v[206:209], v183 offset:53248
	ds_read_b128 v[210:213], v183 offset:54272
	ds_read_b128 v[214:217], v183 offset:55296
	ds_read_b128 v[218:221], v183 offset:56320
	global_load_lds_dwordx4 v[176:177], off
	s_add_i32 m0, s30, 0x2000
	s_add_u32 s28, s28, 0x80080
	v_lshl_add_u64 v[176:177], v[194:195], 0, s[12:13]
	s_addc_u32 s29, s29, 0
	s_add_i32 s30, s52, s34
	global_load_lds_dwordx4 v[176:177], off
	s_mov_b32 m0, s30
	v_lshl_add_u64 v[176:177], s[28:29], 0, v[154:155]
	global_load_lds_dwordx4 v[176:177], off
	s_add_i32 m0, s30, 0x2000
	v_lshl_add_u64 v[176:177], s[28:29], 0, v[158:159]
	global_load_lds_dwordx4 v[176:177], off
	s_mov_b32 m0, s44
	v_lshl_add_u64 v[176:177], v[222:223], 0, s[12:13]
	global_load_lds_dwordx4 v[176:177], off
	s_mov_b32 m0, s45
	v_lshl_add_u64 v[176:177], v[224:225], 0, s[12:13]
	global_load_lds_dwordx4 v[176:177], off
	s_waitcnt vmcnt(8) lgkmcnt(0)
	s_setprio 1
	s_barrier
	v_mfma_f32_16x16x32_bf16 v[56:59], v[128:131], v[186:189], v[56:59]
	v_mfma_f32_16x16x32_bf16 v[60:63], v[136:139], v[186:189], v[60:63]
	v_mfma_f32_16x16x32_bf16 v[40:43], v[128:131], v[198:201], v[40:43]
	v_mfma_f32_16x16x32_bf16 v[44:47], v[136:139], v[198:201], v[44:47]
	v_mfma_f32_16x16x32_bf16 v[24:27], v[128:131], v[206:209], v[24:27]
	v_mfma_f32_16x16x32_bf16 v[28:31], v[136:139], v[206:209], v[28:31]
	v_mfma_f32_16x16x32_bf16 v[8:11], v[128:131], v[214:217], v[8:11]
	v_mfma_f32_16x16x32_bf16 v[12:15], v[136:139], v[214:217], v[12:15]
	v_mfma_f32_16x16x32_bf16 v[56:59], v[132:135], v[190:193], v[56:59]
	v_mfma_f32_16x16x32_bf16 v[60:63], v[140:143], v[190:193], v[60:63]
	v_mfma_f32_16x16x32_bf16 v[40:43], v[132:135], v[202:205], v[40:43]
	v_mfma_f32_16x16x32_bf16 v[44:47], v[140:143], v[202:205], v[44:47]
	v_mfma_f32_16x16x32_bf16 v[24:27], v[132:135], v[210:213], v[24:27]
	v_mfma_f32_16x16x32_bf16 v[28:31], v[140:143], v[210:213], v[28:31]
	v_mfma_f32_16x16x32_bf16 v[8:11], v[132:135], v[218:221], v[8:11]
	v_mfma_f32_16x16x32_bf16 v[12:15], v[140:143], v[218:221], v[12:15]
	v_mfma_f32_16x16x32_bf16 v[52:55], v[144:147], v[186:189], v[52:55]
	v_mfma_f32_16x16x32_bf16 v[48:51], v[168:171], v[186:189], v[48:51]
	v_mfma_f32_16x16x32_bf16 v[36:39], v[144:147], v[198:201], v[36:39]
	v_mfma_f32_16x16x32_bf16 v[32:35], v[168:171], v[198:201], v[32:35]
	v_mfma_f32_16x16x32_bf16 v[20:23], v[144:147], v[206:209], v[20:23]
	v_mfma_f32_16x16x32_bf16 v[16:19], v[168:171], v[206:209], v[16:19]
	v_mfma_f32_16x16x32_bf16 v[4:7], v[144:147], v[214:217], v[4:7]
	v_mfma_f32_16x16x32_bf16 v[0:3], v[168:171], v[214:217], v[0:3]
	v_mfma_f32_16x16x32_bf16 v[52:55], v[148:151], v[190:193], v[52:55]
	v_mfma_f32_16x16x32_bf16 v[48:51], v[172:175], v[190:193], v[48:51]
	v_mfma_f32_16x16x32_bf16 v[36:39], v[148:151], v[202:205], v[36:39]
	v_mfma_f32_16x16x32_bf16 v[32:35], v[172:175], v[202:205], v[32:35]
	v_mfma_f32_16x16x32_bf16 v[20:23], v[148:151], v[210:213], v[20:23]
	v_mfma_f32_16x16x32_bf16 v[16:19], v[172:175], v[210:213], v[16:19]
	v_mfma_f32_16x16x32_bf16 v[4:7], v[148:151], v[218:221], v[4:7]
	v_mfma_f32_16x16x32_bf16 v[0:3], v[172:175], v[218:221], v[0:3]
	s_barrier
	s_setprio 0
	s_add_i32 s50, s50, 2
	s_add_u32 s26, s26, 0x100
	s_addc_u32 s27, s27, 0
	s_add_u32 s48, s48, 0x100
	s_addc_u32 s49, s49, 0
.LBB0_307:
	ds_read_b128 v[128:131], v181
	ds_read_b128 v[132:135], v181 offset:1024
	ds_read_b128 v[136:139], v181 offset:2048
	ds_read_b128 v[140:143], v181 offset:3072
	ds_read_b128 v[144:147], v182
	ds_read_b128 v[148:151], v182 offset:1024
	ds_read_b128 v[168:171], v182 offset:2048
	ds_read_b128 v[172:175], v182 offset:3072
	s_add_u32 s28, s26, 0xfff80080
	s_addc_u32 s29, s27, -1
	s_cmp_eq_u32 s50, 28
	s_cselect_b32 s31, s7, s29
	s_cselect_b32 s30, s21, s28
	s_cselect_b32 s29, s19, s49
	s_cselect_b32 s28, s33, s48
	v_lshl_add_u64 v[176:177], s[26:27], 0, v[160:161]
	s_add_i32 m0, s35, 0xc000
	ds_read_b128 v[186:189], v183
	ds_read_b128 v[190:193], v183 offset:1024
	ds_read_b128 v[198:201], v183 offset:2048
	ds_read_b128 v[202:205], v183 offset:3072
	ds_read_b128 v[206:209], v183 offset:4096
	ds_read_b128 v[210:213], v183 offset:5120
	ds_read_b128 v[214:217], v183 offset:6144
	ds_read_b128 v[218:221], v183 offset:7168
	global_load_lds_dwordx4 v[176:177], off
	s_add_i32 m0, s35, 0xe000
	v_lshl_add_u64 v[176:177], s[26:27], 0, v[162:163]
	global_load_lds_dwordx4 v[176:177], off
	s_waitcnt vmcnt(8) lgkmcnt(0)
	s_setprio 1
	s_barrier
; #define PG8_STAGE(bufoff, gbase, voff) do { _Pragma("unroll") for (int _i = 0; _i < 2; ++_i) \
;         __builtin_amdgcn_global_load_lds((const unsigned*)((const char*)(gbase) + (voff)[_i]), (PG8_LAS unsigned*)(lds + (bufoff) + ldsw + _i * 8192), 16, 0, 0); } while (0)
; #define PG8_LDA(dst, b, h) do { _Pragma("unroll") for (int m = 0; m < 4; ++m) _Pragma("unroll") for (int k = 0; k < 2; ++k) dst[m][k] = *(const PG8_LAS bf16x8*)(lds + PG8_SA(b, h) + aoff + m * 2048 + k * 1024); } while (0)
; #define PG8_MMA(ai, bj, At, Bt) do { __builtin_amdgcn_s_setprio(1); _Pragma("unroll") for (int m = 0; m < 4; ++m) _Pragma("unroll") for (int n = 0; n < 2; ++n) _Pragma("unroll") for (int k = 0; k < 2; ++k) \
;         acc[ai][bj][m][n] = __builtin_amdgcn_mfma_f32_16x16x32_bf16(Bt[n][k], At[m][k], acc[ai][bj][m][n], 0, 0, 0); __builtin_amdgcn_s_setprio(0); } while (0)
; #define PG8_WAIT_V(n) asm volatile("s_waitcnt vmcnt(" #n ")" ::: "memory")
; #define PG8_WAIT_L(n) asm volatile("s_waitcnt lgkmcnt(" #n ")" ::: "memory")
; #define PG8_BAR __builtin_amdgcn_s_barrier()
; #define PG8_SCHED __builtin_amdgcn_sched_barrier(0)
; template <class Epi, class Sched, bool ALIGN_EPI = false, bool SP2 = false>
; __device__ __forceinline__ void gemm_phase(PG8_LAS unsigned char* lds, const Gemm g, const Sched& S, const Epi& E) {
;     ...
;             PG8_WAIT_V(8); PG8_WAIT_L(0); PG8_BAR; PG8_MMA(0, 0, At, B0); PG8_MMA(0, 1, At, B1); PG8_BAR; PG8_SCHED;
;             PG8_LDA(At, 0, 1); PG8_STAGE(PG8_SB(0, 0), b2, voffB); PG8_STAGE(PG8_SB(0, 1), b2 + hstep, voffB); PG8_STAGE(PG8_SA(0, 0), a2, voffA);
;             PG8_WAIT_V(8); PG8_WAIT_L(0); PG8_BAR; PG8_MMA(1, 0, At, B0); PG8_MMA(1, 1, At, B1); PG8_BAR; PG8_SCHED;
	v_mfma_f32_16x16x32_bf16 v[124:127], v[128:131], v[186:189], v[124:127]
	v_mfma_f32_16x16x32_bf16 v[120:123], v[136:139], v[186:189], v[120:123]
	v_mfma_f32_16x16x32_bf16 v[104:107], v[128:131], v[198:201], v[104:107]
	v_mfma_f32_16x16x32_bf16 v[108:111], v[136:139], v[198:201], v[108:111]
	v_mfma_f32_16x16x32_bf16 v[88:91], v[128:131], v[206:209], v[88:91]
	v_mfma_f32_16x16x32_bf16 v[92:95], v[136:139], v[206:209], v[92:95]
	v_mfma_f32_16x16x32_bf16 v[72:75], v[128:131], v[214:217], v[72:75]
	v_mfma_f32_16x16x32_bf16 v[76:79], v[136:139], v[214:217], v[76:79]
	v_mfma_f32_16x16x32_bf16 v[124:127], v[132:135], v[190:193], v[124:127]
	v_mfma_f32_16x16x32_bf16 v[120:123], v[140:143], v[190:193], v[120:123]
	v_mfma_f32_16x16x32_bf16 v[104:107], v[132:135], v[202:205], v[104:107]
	v_mfma_f32_16x16x32_bf16 v[108:111], v[140:143], v[202:205], v[108:111]
	v_mfma_f32_16x16x32_bf16 v[88:91], v[132:135], v[210:213], v[88:91]
	v_mfma_f32_16x16x32_bf16 v[92:95], v[140:143], v[210:213], v[92:95]
	v_mfma_f32_16x16x32_bf16 v[72:75], v[132:135], v[218:221], v[72:75]
	v_mfma_f32_16x16x32_bf16 v[76:79], v[140:143], v[218:221], v[76:79]
	v_mfma_f32_16x16x32_bf16 v[116:119], v[144:147], v[186:189], v[116:119]
	v_mfma_f32_16x16x32_bf16 v[112:115], v[168:171], v[186:189], v[112:115]
	v_mfma_f32_16x16x32_bf16 v[100:103], v[144:147], v[198:201], v[100:103]
	v_mfma_f32_16x16x32_bf16 v[96:99], v[168:171], v[198:201], v[96:99]
	v_mfma_f32_16x16x32_bf16 v[84:87], v[144:147], v[206:209], v[84:87]
	v_mfma_f32_16x16x32_bf16 v[80:83], v[168:171], v[206:209], v[80:83]
	v_mfma_f32_16x16x32_bf16 v[68:71], v[144:147], v[214:217], v[68:71]
	v_mfma_f32_16x16x32_bf16 v[64:67], v[168:171], v[214:217], v[64:67]
	v_mfma_f32_16x16x32_bf16 v[116:119], v[148:151], v[190:193], v[116:119]
	v_mfma_f32_16x16x32_bf16 v[112:115], v[172:175], v[190:193], v[112:115]
	v_mfma_f32_16x16x32_bf16 v[100:103], v[148:151], v[202:205], v[100:103]
	v_mfma_f32_16x16x32_bf16 v[96:99], v[172:175], v[202:205], v[96:99]
	v_mfma_f32_16x16x32_bf16 v[84:87], v[148:151], v[210:213], v[84:87]
	v_mfma_f32_16x16x32_bf16 v[80:83], v[172:175], v[210:213], v[80:83]
	v_mfma_f32_16x16x32_bf16 v[68:71], v[148:151], v[218:221], v[68:71]
	v_mfma_f32_16x16x32_bf16 v[64:67], v[172:175], v[218:221], v[64:67]
	s_barrier
	s_setprio 0
	s_add_i32 s51, s62, s34
	v_lshl_add_u64 v[176:177], s[28:29], 0, v[154:155]
	s_mov_b32 m0, s51
	ds_read_b128 v[186:189], v183 offset:16384
	ds_read_b128 v[190:193], v183 offset:17408
	ds_read_b128 v[198:201], v183 offset:18432
	ds_read_b128 v[202:205], v183 offset:19456
	ds_read_b128 v[206:209], v183 offset:20480
	ds_read_b128 v[210:213], v183 offset:21504
	ds_read_b128 v[214:217], v183 offset:22528
	ds_read_b128 v[218:221], v183 offset:23552
	global_load_lds_dwordx4 v[176:177], off
	s_add_i32 m0, s51, 0x2000
	s_add_u32 s52, s28, 0x80000
	v_lshl_add_u64 v[194:195], s[28:29], 0, v[158:159]
	s_addc_u32 s53, s29, 0
	s_add_i32 s51, s63, s34
	global_load_lds_dwordx4 v[194:195], off
	v_lshl_add_u64 v[222:223], s[52:53], 0, v[154:155]
	s_mov_b32 m0, s51
	v_lshl_add_u64 v[224:225], s[30:31], 0, v[156:157]
	global_load_lds_dwordx4 v[222:223], off
	s_add_i32 m0, s51, 0x2000
	v_lshl_add_u64 v[222:223], s[52:53], 0, v[158:159]
	global_load_lds_dwordx4 v[222:223], off
	s_mov_b32 m0, s35
	v_lshl_add_u64 v[222:223], s[30:31], 0, v[152:153]
	global_load_lds_dwordx4 v[222:223], off
	s_mov_b32 m0, s37
	s_nop 0
	global_load_lds_dwordx4 v[224:225], off
	s_waitcnt vmcnt(8) lgkmcnt(0)
	s_setprio 1
	s_barrier
	v_mfma_f32_16x16x32_bf16 v[56:59], v[128:131], v[186:189], v[56:59]
	v_mfma_f32_16x16x32_bf16 v[60:63], v[136:139], v[186:189], v[60:63]
	v_mfma_f32_16x16x32_bf16 v[40:43], v[128:131], v[198:201], v[40:43]
	v_mfma_f32_16x16x32_bf16 v[44:47], v[136:139], v[198:201], v[44:47]
	v_mfma_f32_16x16x32_bf16 v[24:27], v[128:131], v[206:209], v[24:27]
	v_mfma_f32_16x16x32_bf16 v[28:31], v[136:139], v[206:209], v[28:31]
	v_mfma_f32_16x16x32_bf16 v[8:11], v[128:131], v[214:217], v[8:11]
	v_mfma_f32_16x16x32_bf16 v[12:15], v[136:139], v[214:217], v[12:15]
	v_mfma_f32_16x16x32_bf16 v[56:59], v[132:135], v[190:193], v[56:59]
	v_mfma_f32_16x16x32_bf16 v[60:63], v[140:143], v[190:193], v[60:63]
	v_mfma_f32_16x16x32_bf16 v[40:43], v[132:135], v[202:205], v[40:43]
	v_mfma_f32_16x16x32_bf16 v[44:47], v[140:143], v[202:205], v[44:47]
	v_mfma_f32_16x16x32_bf16 v[24:27], v[132:135], v[210:213], v[24:27]
	v_mfma_f32_16x16x32_bf16 v[28:31], v[140:143], v[210:213], v[28:31]
	v_mfma_f32_16x16x32_bf16 v[8:11], v[132:135], v[218:221], v[8:11]
	v_mfma_f32_16x16x32_bf16 v[12:15], v[140:143], v[218:221], v[12:15]
	v_mfma_f32_16x16x32_bf16 v[52:55], v[144:147], v[186:189], v[52:55]
	v_mfma_f32_16x16x32_bf16 v[48:51], v[168:171], v[186:189], v[48:51]
	v_mfma_f32_16x16x32_bf16 v[36:39], v[144:147], v[198:201], v[36:39]
	v_mfma_f32_16x16x32_bf16 v[32:35], v[168:171], v[198:201], v[32:35]
	v_mfma_f32_16x16x32_bf16 v[20:23], v[144:147], v[206:209], v[20:23]
	v_mfma_f32_16x16x32_bf16 v[16:19], v[168:171], v[206:209], v[16:19]
	v_mfma_f32_16x16x32_bf16 v[4:7], v[144:147], v[214:217], v[4:7]
	v_mfma_f32_16x16x32_bf16 v[0:3], v[168:171], v[214:217], v[0:3]
	v_mfma_f32_16x16x32_bf16 v[52:55], v[148:151], v[190:193], v[52:55]
	v_mfma_f32_16x16x32_bf16 v[48:51], v[172:175], v[190:193], v[48:51]
	v_mfma_f32_16x16x32_bf16 v[36:39], v[148:151], v[202:205], v[36:39]
	v_mfma_f32_16x16x32_bf16 v[32:35], v[172:175], v[202:205], v[32:35]
	v_mfma_f32_16x16x32_bf16 v[20:23], v[148:151], v[210:213], v[20:23]
	v_mfma_f32_16x16x32_bf16 v[16:19], v[172:175], v[210:213], v[16:19]
	v_mfma_f32_16x16x32_bf16 v[4:7], v[148:151], v[218:221], v[4:7]
	v_mfma_f32_16x16x32_bf16 v[0:3], v[172:175], v[218:221], v[0:3]
	s_barrier
; #define PG8_STAGE(bufoff, gbase, voff) do { _Pragma("unroll") for (int _i = 0; _i < 2; ++_i) \
;         __builtin_amdgcn_global_load_lds((const unsigned*)((const char*)(gbase) + (voff)[_i]), (PG8_LAS unsigned*)(lds + (bufoff) + ldsw + _i * 8192), 16, 0, 0); } while (0)
; #define PG8_LDA(dst, b, h) do { _Pragma("unroll") for (int m = 0; m < 4; ++m) _Pragma("unroll") for (int k = 0; k < 2; ++k) dst[m][k] = *(const PG8_LAS bf16x8*)(lds + PG8_SA(b, h) + aoff + m * 2048 + k * 1024); } while (0)
; #define PG8_LDB(dst, b, h) do { _Pragma("unroll") for (int n = 0; n < 2; ++n) _Pragma("unroll") for (int k = 0; k < 2; ++k) dst[n][k] = *(const PG8_LAS bf16x8*)(lds + PG8_SB(b, h) + boff + n * 2048 + k * 1024); } while (0)
; #define PG8_MMA(ai, bj, At, Bt) do { __builtin_amdgcn_s_setprio(1); _Pragma("unroll") for (int m = 0; m < 4; ++m) _Pragma("unroll") for (int n = 0; n < 2; ++n) _Pragma("unroll") for (int k = 0; k < 2; ++k) \
;         acc[ai][bj][m][n] = __builtin_amdgcn_mfma_f32_16x16x32_bf16(Bt[n][k], At[m][k], acc[ai][bj][m][n], 0, 0, 0); __builtin_amdgcn_s_setprio(0); } while (0)
; #define PG8_WAIT_V(n) asm volatile("s_waitcnt vmcnt(" #n ")" ::: "memory")
; #define PG8_WAIT_L(n) asm volatile("s_waitcnt lgkmcnt(" #n ")" ::: "memory")
; #define PG8_BAR __builtin_amdgcn_s_barrier()
; #define PG8_SCHED __builtin_amdgcn_sched_barrier(0)
; template <class Epi, class Sched, bool ALIGN_EPI = false, bool SP2 = false>
; __device__ __forceinline__ void gemm_phase(PG8_LAS unsigned char* lds, const Gemm g, const Sched& S, const Epi& E) {
;     ...
;             PG8_LDB(B0, 1, 0); PG8_LDB(B1, 1, 1); PG8_SCHED; PG8_LDA(At, 1, 0); PG8_STAGE(PG8_SA(0, 1), a2 + hstep, voffA);
;             PG8_WAIT_V(8); PG8_WAIT_L(0); PG8_BAR; PG8_MMA(0, 0, At, B0); PG8_MMA(0, 1, At, B1); PG8_BAR; PG8_SCHED;
	s_setprio 0
	s_add_i32 s51, 0, 0x18000
	s_add_i32 s52, 0, 0x1c000
	v_add_u32_e32 v140, s51, v179
	v_add_u32_e32 v172, s52, v179
	ds_read_b128 v[128:131], v140
	ds_read_b128 v[132:135], v140 offset:1024
	ds_read_b128 v[136:139], v140 offset:2048
	ds_read_b128 v[140:143], v140 offset:3072
	ds_read_b128 v[144:147], v172
	ds_read_b128 v[148:151], v172 offset:1024
	ds_read_b128 v[168:171], v172 offset:2048
	ds_read_b128 v[172:175], v172 offset:3072
	s_add_u32 s30, s30, 0x80000
	s_addc_u32 s31, s31, 0
	s_mov_b32 m0, s39
	v_lshl_add_u64 v[226:227], s[30:31], 0, v[152:153]
	ds_read_b128 v[186:189], v183 offset:32768
	ds_read_b128 v[190:193], v183 offset:33792
	ds_read_b128 v[198:201], v183 offset:34816
	ds_read_b128 v[202:205], v183 offset:35840
	ds_read_b128 v[206:209], v183 offset:36864
	ds_read_b128 v[210:213], v183 offset:37888
	ds_read_b128 v[214:217], v183 offset:38912
	ds_read_b128 v[218:221], v183 offset:39936
	global_load_lds_dwordx4 v[226:227], off
	s_mov_b32 m0, s42
	v_lshl_add_u64 v[226:227], s[30:31], 0, v[156:157]
	global_load_lds_dwordx4 v[226:227], off
	s_waitcnt vmcnt(8) lgkmcnt(0)
	s_setprio 1
	s_barrier
	v_mfma_f32_16x16x32_bf16 v[124:127], v[128:131], v[186:189], v[124:127]
	v_mfma_f32_16x16x32_bf16 v[120:123], v[136:139], v[186:189], v[120:123]
	v_mfma_f32_16x16x32_bf16 v[104:107], v[128:131], v[198:201], v[104:107]
	v_mfma_f32_16x16x32_bf16 v[108:111], v[136:139], v[198:201], v[108:111]
	v_mfma_f32_16x16x32_bf16 v[88:91], v[128:131], v[206:209], v[88:91]
	v_mfma_f32_16x16x32_bf16 v[92:95], v[136:139], v[206:209], v[92:95]
	v_mfma_f32_16x16x32_bf16 v[72:75], v[128:131], v[214:217], v[72:75]
	v_mfma_f32_16x16x32_bf16 v[76:79], v[136:139], v[214:217], v[76:79]
	v_mfma_f32_16x16x32_bf16 v[124:127], v[132:135], v[190:193], v[124:127]
	v_mfma_f32_16x16x32_bf16 v[120:123], v[140:143], v[190:193], v[120:123]
	v_mfma_f32_16x16x32_bf16 v[104:107], v[132:135], v[202:205], v[104:107]
	v_mfma_f32_16x16x32_bf16 v[108:111], v[140:143], v[202:205], v[108:111]
	v_mfma_f32_16x16x32_bf16 v[88:91], v[132:135], v[210:213], v[88:91]
	v_mfma_f32_16x16x32_bf16 v[92:95], v[140:143], v[210:213], v[92:95]
	v_mfma_f32_16x16x32_bf16 v[72:75], v[132:135], v[218:221], v[72:75]
	v_mfma_f32_16x16x32_bf16 v[76:79], v[140:143], v[218:221], v[76:79]
	v_mfma_f32_16x16x32_bf16 v[116:119], v[144:147], v[186:189], v[116:119]
	v_mfma_f32_16x16x32_bf16 v[112:115], v[168:171], v[186:189], v[112:115]
	v_mfma_f32_16x16x32_bf16 v[100:103], v[144:147], v[198:201], v[100:103]
	v_mfma_f32_16x16x32_bf16 v[96:99], v[168:171], v[198:201], v[96:99]
	v_mfma_f32_16x16x32_bf16 v[84:87], v[144:147], v[206:209], v[84:87]
	v_mfma_f32_16x16x32_bf16 v[80:83], v[168:171], v[206:209], v[80:83]
	v_mfma_f32_16x16x32_bf16 v[68:71], v[144:147], v[214:217], v[68:71]
	v_mfma_f32_16x16x32_bf16 v[64:67], v[168:171], v[214:217], v[64:67]
	v_mfma_f32_16x16x32_bf16 v[116:119], v[148:151], v[190:193], v[116:119]
	v_mfma_f32_16x16x32_bf16 v[112:115], v[172:175], v[190:193], v[112:115]
	v_mfma_f32_16x16x32_bf16 v[100:103], v[148:151], v[202:205], v[100:103]
	v_mfma_f32_16x16x32_bf16 v[96:99], v[172:175], v[202:205], v[96:99]
	v_mfma_f32_16x16x32_bf16 v[84:87], v[148:151], v[210:213], v[84:87]
	v_mfma_f32_16x16x32_bf16 v[80:83], v[172:175], v[210:213], v[80:83]
	v_mfma_f32_16x16x32_bf16 v[68:71], v[148:151], v[218:221], v[68:71]
	v_mfma_f32_16x16x32_bf16 v[64:67], v[172:175], v[218:221], v[64:67]
	s_barrier
; #define PG8_STAGE(bufoff, gbase, voff) do { _Pragma("unroll") for (int _i = 0; _i < 2; ++_i) \
;         __builtin_amdgcn_global_load_lds((const unsigned*)((const char*)(gbase) + (voff)[_i]), (PG8_LAS unsigned*)(lds + (bufoff) + ldsw + _i * 8192), 16, 0, 0); } while (0)
; #define PG8_LDA(dst, b, h) do { _Pragma("unroll") for (int m = 0; m < 4; ++m) _Pragma("unroll") for (int k = 0; k < 2; ++k) dst[m][k] = *(const PG8_LAS bf16x8*)(lds + PG8_SA(b, h) + aoff + m * 2048 + k * 1024); } while (0)
; #define PG8_MMA(ai, bj, At, Bt) do { __builtin_amdgcn_s_setprio(1); _Pragma("unroll") for (int m = 0; m < 4; ++m) _Pragma("unroll") for (int n = 0; n < 2; ++n) _Pragma("unroll") for (int k = 0; k < 2; ++k) \
;         acc[ai][bj][m][n] = __builtin_amdgcn_mfma_f32_16x16x32_bf16(Bt[n][k], At[m][k], acc[ai][bj][m][n], 0, 0, 0); __builtin_amdgcn_s_setprio(0); } while (0)
; #define PG8_WAIT_V(n) asm volatile("s_waitcnt vmcnt(" #n ")" ::: "memory")
; #define PG8_WAIT_L(n) asm volatile("s_waitcnt lgkmcnt(" #n ")" ::: "memory")
; #define PG8_BAR __builtin_amdgcn_s_barrier()
; #define PG8_SCHED __builtin_amdgcn_sched_barrier(0)
; template <class Epi, class Sched, bool ALIGN_EPI = false, bool SP2 = false>
; __device__ __forceinline__ void gemm_phase(PG8_LAS unsigned char* lds, const Gemm g, const Sched& S, const Epi& E) {
;     ...
;         for (int t = 0; t < nt; t += 2) {
;     ...
;             PG8_LDA(At, 1, 1); PG8_STAGE(PG8_SB(1, 0), b3, voffB); PG8_STAGE(PG8_SB(1, 1), b3 + hstep, voffB); PG8_STAGE(PG8_SA(1, 0), a3, voffA);
;             PG8_WAIT_V(8); PG8_WAIT_L(0); PG8_BAR; PG8_MMA(1, 0, At, B0); PG8_MMA(1, 1, At, B1); PG8_BAR; PG8_SCHED;
	s_setprio 0
	s_add_i32 s30, s51, s34
	v_lshl_add_u64 v[176:177], v[176:177], 0, s[12:13]
	s_mov_b32 m0, s30
	ds_read_b128 v[186:189], v183 offset:49152
	ds_read_b128 v[190:193], v183 offset:50176
	ds_read_b128 v[198:201], v183 offset:51200
	ds_read_b128 v[202:205], v183 offset:52224
	ds_read_b128 v[206:209], v183 offset:53248
	ds_read_b128 v[210:213], v183 offset:54272
	ds_read_b128 v[214:217], v183 offset:55296
	ds_read_b128 v[218:221], v183 offset:56320
	global_load_lds_dwordx4 v[176:177], off
	s_add_i32 m0, s30, 0x2000
	s_add_u32 s28, s28, 0x80080
	v_lshl_add_u64 v[176:177], v[194:195], 0, s[12:13]
	s_addc_u32 s29, s29, 0
	s_add_i32 s30, s52, s34
	global_load_lds_dwordx4 v[176:177], off
	s_mov_b32 m0, s30
	v_lshl_add_u64 v[176:177], s[28:29], 0, v[154:155]
	global_load_lds_dwordx4 v[176:177], off
	s_add_i32 m0, s30, 0x2000
	v_lshl_add_u64 v[176:177], s[28:29], 0, v[158:159]
	global_load_lds_dwordx4 v[176:177], off
	s_mov_b32 m0, s44
	v_lshl_add_u64 v[176:177], v[222:223], 0, s[12:13]
	global_load_lds_dwordx4 v[176:177], off
	s_mov_b32 m0, s45
	v_lshl_add_u64 v[176:177], v[224:225], 0, s[12:13]
	global_load_lds_dwordx4 v[176:177], off
	s_waitcnt vmcnt(8) lgkmcnt(0)
	s_setprio 1
	s_barrier
	v_mfma_f32_16x16x32_bf16 v[56:59], v[128:131], v[186:189], v[56:59]
	v_mfma_f32_16x16x32_bf16 v[60:63], v[136:139], v[186:189], v[60:63]
	v_mfma_f32_16x16x32_bf16 v[40:43], v[128:131], v[198:201], v[40:43]
	v_mfma_f32_16x16x32_bf16 v[44:47], v[136:139], v[198:201], v[44:47]
	v_mfma_f32_16x16x32_bf16 v[24:27], v[128:131], v[206:209], v[24:27]
	v_mfma_f32_16x16x32_bf16 v[28:31], v[136:139], v[206:209], v[28:31]
	v_mfma_f32_16x16x32_bf16 v[8:11], v[128:131], v[214:217], v[8:11]
	v_mfma_f32_16x16x32_bf16 v[12:15], v[136:139], v[214:217], v[12:15]
	v_mfma_f32_16x16x32_bf16 v[56:59], v[132:135], v[190:193], v[56:59]
	v_mfma_f32_16x16x32_bf16 v[60:63], v[140:143], v[190:193], v[60:63]
	v_mfma_f32_16x16x32_bf16 v[40:43], v[132:135], v[202:205], v[40:43]
	v_mfma_f32_16x16x32_bf16 v[44:47], v[140:143], v[202:205], v[44:47]
	v_mfma_f32_16x16x32_bf16 v[24:27], v[132:135], v[210:213], v[24:27]
	v_mfma_f32_16x16x32_bf16 v[28:31], v[140:143], v[210:213], v[28:31]
	v_mfma_f32_16x16x32_bf16 v[8:11], v[132:135], v[218:221], v[8:11]
	v_mfma_f32_16x16x32_bf16 v[12:15], v[140:143], v[218:221], v[12:15]
	v_mfma_f32_16x16x32_bf16 v[52:55], v[144:147], v[186:189], v[52:55]
	v_mfma_f32_16x16x32_bf16 v[48:51], v[168:171], v[186:189], v[48:51]
	v_mfma_f32_16x16x32_bf16 v[36:39], v[144:147], v[198:201], v[36:39]
	v_mfma_f32_16x16x32_bf16 v[32:35], v[168:171], v[198:201], v[32:35]
	v_mfma_f32_16x16x32_bf16 v[20:23], v[144:147], v[206:209], v[20:23]
	v_mfma_f32_16x16x32_bf16 v[16:19], v[168:171], v[206:209], v[16:19]
	v_mfma_f32_16x16x32_bf16 v[4:7], v[144:147], v[214:217], v[4:7]
	v_mfma_f32_16x16x32_bf16 v[0:3], v[168:171], v[214:217], v[0:3]
	v_mfma_f32_16x16x32_bf16 v[52:55], v[148:151], v[190:193], v[52:55]
	v_mfma_f32_16x16x32_bf16 v[48:51], v[172:175], v[190:193], v[48:51]
	v_mfma_f32_16x16x32_bf16 v[36:39], v[148:151], v[202:205], v[36:39]
	v_mfma_f32_16x16x32_bf16 v[32:35], v[172:175], v[202:205], v[32:35]
	v_mfma_f32_16x16x32_bf16 v[20:23], v[148:151], v[210:213], v[20:23]
	v_mfma_f32_16x16x32_bf16 v[16:19], v[172:175], v[210:213], v[16:19]
	v_mfma_f32_16x16x32_bf16 v[4:7], v[148:151], v[218:221], v[4:7]
	v_mfma_f32_16x16x32_bf16 v[0:3], v[172:175], v[218:221], v[0:3]
	s_barrier
	s_setprio 0
	s_add_i32 s50, s50, 2
	s_add_u32 s26, s26, 0x100
	s_addc_u32 s27, s27, 0
	s_add_u32 s48, s48, 0x100
	s_addc_u32 s49, s49, 0
	s_cmp_gt_u32 s50, 29
	s_cbranch_scc0 .LBB0_307
	s_and_b64 vcc, exec, s[14:15]
	s_cbranch_vccz .LBB0_310
	s_barrier

; #define PG8_STAGE(bufoff, gbase, voff) do { _Pragma("unroll") for (int _i = 0; _i < 2; ++_i) \
;         __builtin_amdgcn_global_load_lds((const unsigned*)((const char*)(gbase) + (voff)[_i]), (PG8_LAS unsigned*)(lds + (bufoff) + ldsw + _i * 8192), 16, 0, 0); } while (0)
; #define PG8_LDA(dst, b, h) do { _Pragma("unroll") for (int m = 0; m < 4; ++m) _Pragma("unroll") for (int k = 0; k < 2; ++k) dst[m][k] = *(const PG8_LAS bf16x8*)(lds + PG8_SA(b, h) + aoff + m * 2048 + k * 1024); } while (0)
; #define PG8_LDB(dst, b, h) do { _Pragma("unroll") for (int n = 0; n < 2; ++n) _Pragma("unroll") for (int k = 0; k < 2; ++k) dst[n][k] = *(const PG8_LAS bf16x8*)(lds + PG8_SB(b, h) + boff + n * 2048 + k * 1024); } while (0)
; #define PG8_MMA(ai, bj, At, Bt) do { __builtin_amdgcn_s_setprio(1); _Pragma("unroll") for (int m = 0; m < 4; ++m) _Pragma("unroll") for (int n = 0; n < 2; ++n) _Pragma("unroll") for (int k = 0; k < 2; ++k) \
;         acc[ai][bj][m][n] = __builtin_amdgcn_mfma_f32_16x16x32_bf16(Bt[n][k], At[m][k], acc[ai][bj][m][n], 0, 0, 0); __builtin_amdgcn_s_setprio(0); } while (0)
; #define PG8_WAIT_V(n) asm volatile("s_waitcnt vmcnt(" #n ")" ::: "memory")
; template <class Epi, class Sched, bool ALIGN_EPI = false, bool SP2 = false>
; __device__ __forceinline__ void gemm_phase(PG8_LAS unsigned char* lds, const Gemm g, const Sched& S, const Epi& E) {
;     ...
;         const char* nA = has_next ? (const char*)g.A + (size_t)nxt.pm * tstep : cA; const char* nB = has_next ? (const char*)g.Bt + (size_t)nxt.pn * tstep : cB;
;         for (int t = 0; t < nt; t += 2) {
;             const bool last = (t == nt - 2);
;             const char* a1 = cA + (size_t)(t + 1) * kstep;
;             const char* a2 = last ? nA : cA + (size_t)(t + 2) * kstep; const char* b2 = last ? nB : cB + (size_t)(t + 2) * kstep;
;             const char* a3 = a2 + kstep; const char* b3 = b2 + kstep;
;             if (last && has_next) S.a_ready(nxt);
;             if constexpr (SP2) {
;             PG8_LDB(B0, 0, 0); PG8_LDB(B1, 0, 1); PG8_SCHED; PG8_LDA(At, 0, 0); PG8_STAGE(PG8_SA(1, 1), a1 + hstep, voffA);
;             PG8_WAIT_V(8); PG8_WAIT_L(0); PG8_BAR; PG8_MMA(0, 0, At, B0); PG8_MMA(0, 1, At, B1); PG8_BAR; PG8_SCHED;
;             PG8_LDA(At, 0, 1); PG8_STAGE(PG8_SB(0, 0), b2, voffB); PG8_STAGE(PG8_SB(0, 1), b2 + hstep, voffB); PG8_STAGE(PG8_SA(0, 0), a2, voffA);
.LBB0_490:
	s_ashr_i32 s21, s20, 31
	s_lshl_b64 s[0:1], s[20:21], 20
	v_readlane_b32 s24, v254, 51
	v_readlane_b32 s25, v254, 52
	s_add_u32 s24, s24, s0
	s_addc_u32 s25, s25, s1
	s_and_b64 s[0:1], s[22:23], exec
	s_cselect_b32 s5, s25, s31
	s_cselect_b32 s21, s24, s30
	s_ashr_i32 s19, s18, 31
	s_lshl_b64 s[0:1], s[18:19], 20
	v_readlane_b32 s26, v254, 22
	v_readlane_b32 s27, v254, 23
	s_add_u32 s26, s26, s0
	s_addc_u32 s27, s27, s1
	s_and_b64 s[0:1], s[22:23], exec
	s_cselect_b32 s19, s27, s29
	s_cselect_b32 s33, s26, s28
	s_add_u32 s0, s30, 0x80080
	s_addc_u32 s1, s31, 0
	s_add_u32 s44, s28, 0x100
	s_addc_u32 s45, s29, 0
	s_mov_b32 s48, -2
	v_add_u32_e32 v140, s68, v163
	v_add_u32_e32 v152, s69, v163
	ds_read_b128 v[128:131], v140
	ds_read_b128 v[132:135], v140 offset:1024
	ds_read_b128 v[136:139], v140 offset:2048
	ds_read_b128 v[140:143], v140 offset:3072
	ds_read_b128 v[184:187], v152
	ds_read_b128 v[218:221], v152 offset:1024
	ds_read_b128 v[222:225], v152 offset:2048
	ds_read_b128 v[226:229], v152 offset:3072
	s_add_u32 s28, s0, 0xfff80080
	s_addc_u32 s29, s1, -1
	s_cmp_eq_u32 s48, 28
	s_cselect_b32 s31, s5, s29
	s_cselect_b32 s30, s21, s28
	s_cselect_b32 s29, s19, s45
	s_cselect_b32 s28, s33, s44
	v_lshl_add_u64 v[172:173], s[0:1], 0, v[156:157]
	s_add_i32 m0, s17, 0xc000
	ds_read_b128 v[230:233], v214
	ds_read_b128 v[234:237], v214 offset:1024
	ds_read_b128 v[238:241], v214 offset:2048
	ds_read_b128 v[242:245], v214 offset:3072
	ds_read_b128 v[246:249], v214 offset:4096
	ds_read_b128 v[250:253], v214 offset:5120
	ds_read_b128 v[206:209], v214 offset:6144
	ds_read_b128 v[210:213], v214 offset:7168
	global_load_lds_dwordx4 v[172:173], off
	s_add_i32 m0, s17, 0xe000
	v_lshl_add_u64 v[172:173], s[0:1], 0, v[158:159]
	global_load_lds_dwordx4 v[172:173], off
	s_waitcnt lgkmcnt(0)
	s_setprio 1
	s_barrier
	v_mfma_f32_16x16x32_bf16 v[124:127], v[128:131], v[230:233], 0
	v_mfma_f32_16x16x32_bf16 v[120:123], v[136:139], v[230:233], 0
	v_mfma_f32_16x16x32_bf16 v[116:119], v[128:131], v[238:241], 0
	v_mfma_f32_16x16x32_bf16 v[108:111], v[136:139], v[238:241], 0
	v_mfma_f32_16x16x32_bf16 v[100:103], v[128:131], v[246:249], 0
	v_mfma_f32_16x16x32_bf16 v[92:95], v[136:139], v[246:249], 0
	v_mfma_f32_16x16x32_bf16 v[84:87], v[128:131], v[206:209], 0
	v_mfma_f32_16x16x32_bf16 v[76:79], v[136:139], v[206:209], 0
	v_mfma_f32_16x16x32_bf16 v[124:127], v[132:135], v[234:237], v[124:127]
	v_mfma_f32_16x16x32_bf16 v[120:123], v[140:143], v[234:237], v[120:123]
	v_mfma_f32_16x16x32_bf16 v[116:119], v[132:135], v[242:245], v[116:119]
	v_mfma_f32_16x16x32_bf16 v[108:111], v[140:143], v[242:245], v[108:111]
	v_mfma_f32_16x16x32_bf16 v[100:103], v[132:135], v[250:253], v[100:103]
	v_mfma_f32_16x16x32_bf16 v[92:95], v[140:143], v[250:253], v[92:95]
	v_mfma_f32_16x16x32_bf16 v[84:87], v[132:135], v[210:213], v[84:87]
	v_mfma_f32_16x16x32_bf16 v[76:79], v[140:143], v[210:213], v[76:79]
	v_mfma_f32_16x16x32_bf16 v[112:115], v[184:187], v[230:233], 0
	v_mfma_f32_16x16x32_bf16 v[104:107], v[222:225], v[230:233], 0
	v_mfma_f32_16x16x32_bf16 v[96:99], v[184:187], v[238:241], 0
	v_mfma_f32_16x16x32_bf16 v[88:91], v[222:225], v[238:241], 0
	v_mfma_f32_16x16x32_bf16 v[80:83], v[184:187], v[246:249], 0
	v_mfma_f32_16x16x32_bf16 v[72:75], v[222:225], v[246:249], 0
	v_mfma_f32_16x16x32_bf16 v[68:71], v[184:187], v[206:209], 0
	v_mfma_f32_16x16x32_bf16 v[64:67], v[222:225], v[206:209], 0
	v_mfma_f32_16x16x32_bf16 v[112:115], v[218:221], v[234:237], v[112:115]
	v_mfma_f32_16x16x32_bf16 v[104:107], v[226:229], v[234:237], v[104:107]
	v_mfma_f32_16x16x32_bf16 v[96:99], v[218:221], v[242:245], v[96:99]
	v_mfma_f32_16x16x32_bf16 v[88:91], v[226:229], v[242:245], v[88:91]
	v_mfma_f32_16x16x32_bf16 v[80:83], v[218:221], v[250:253], v[80:83]
	v_mfma_f32_16x16x32_bf16 v[72:75], v[226:229], v[250:253], v[72:75]
	v_mfma_f32_16x16x32_bf16 v[68:71], v[218:221], v[210:213], v[68:71]
	v_mfma_f32_16x16x32_bf16 v[64:67], v[226:229], v[210:213], v[64:67]
	s_barrier
	s_setprio 0
	s_add_i32 s49, s68, s34
	v_lshl_add_u64 v[172:173], s[28:29], 0, v[146:147]
	s_mov_b32 m0, s49
	ds_read_b128 v[206:209], v214 offset:16384
	ds_read_b128 v[210:213], v214 offset:17408
	ds_read_b128 v[230:233], v214 offset:18432
	ds_read_b128 v[234:237], v214 offset:19456
	ds_read_b128 v[238:241], v214 offset:20480
	ds_read_b128 v[242:245], v214 offset:21504
	ds_read_b128 v[246:249], v214 offset:22528
	ds_read_b128 v[250:253], v214 offset:23552
	global_load_lds_dwordx4 v[172:173], off
	s_add_i32 m0, s49, 0x2000
	s_add_u32 s50, s28, 0x80000
	v_lshl_add_u64 v[176:177], s[28:29], 0, v[150:151]
	s_addc_u32 s51, s29, 0
	s_add_i32 s49, s69, s34
	global_load_lds_dwordx4 v[176:177], off
	v_lshl_add_u64 v[180:181], s[50:51], 0, v[146:147]
	s_mov_b32 m0, s49
	v_lshl_add_u64 v[188:189], s[30:31], 0, v[148:149]
	global_load_lds_dwordx4 v[180:181], off
	s_add_i32 m0, s49, 0x2000
	v_lshl_add_u64 v[180:181], s[50:51], 0, v[150:151]
	global_load_lds_dwordx4 v[180:181], off
	s_mov_b32 m0, s17
	v_lshl_add_u64 v[180:181], s[30:31], 0, v[144:145]
	global_load_lds_dwordx4 v[180:181], off
	s_mov_b32 m0, s35
	s_nop 0
	global_load_lds_dwordx4 v[188:189], off
	s_waitcnt lgkmcnt(0)
	s_setprio 1
	s_barrier
; #define PG8_STAGE(bufoff, gbase, voff) do { _Pragma("unroll") for (int _i = 0; _i < 2; ++_i) \
;         __builtin_amdgcn_global_load_lds((const unsigned*)((const char*)(gbase) + (voff)[_i]), (PG8_LAS unsigned*)(lds + (bufoff) + ldsw + _i * 8192), 16, 0, 0); } while (0)
; #define PG8_LDA(dst, b, h) do { _Pragma("unroll") for (int m = 0; m < 4; ++m) _Pragma("unroll") for (int k = 0; k < 2; ++k) dst[m][k] = *(const PG8_LAS bf16x8*)(lds + PG8_SA(b, h) + aoff + m * 2048 + k * 1024); } while (0)
; #define PG8_LDB(dst, b, h) do { _Pragma("unroll") for (int n = 0; n < 2; ++n) _Pragma("unroll") for (int k = 0; k < 2; ++k) dst[n][k] = *(const PG8_LAS bf16x8*)(lds + PG8_SB(b, h) + boff + n * 2048 + k * 1024); } while (0)
; #define PG8_MMA(ai, bj, At, Bt) do { __builtin_amdgcn_s_setprio(1); _Pragma("unroll") for (int m = 0; m < 4; ++m) _Pragma("unroll") for (int n = 0; n < 2; ++n) _Pragma("unroll") for (int k = 0; k < 2; ++k) \
;         acc[ai][bj][m][n] = __builtin_amdgcn_mfma_f32_16x16x32_bf16(Bt[n][k], At[m][k], acc[ai][bj][m][n], 0, 0, 0); __builtin_amdgcn_s_setprio(0); } while (0)
; #define PG8_WAIT_V(n) asm volatile("s_waitcnt vmcnt(" #n ")" ::: "memory")
; #define PG8_WAIT_L(n) asm volatile("s_waitcnt lgkmcnt(" #n ")" ::: "memory")
; #define PG8_BAR __builtin_amdgcn_s_barrier()
; #define PG8_SCHED __builtin_amdgcn_sched_barrier(0)
; template <class Epi, class Sched, bool ALIGN_EPI = false, bool SP2 = false>
; __device__ __forceinline__ void gemm_phase(PG8_LAS unsigned char* lds, const Gemm g, const Sched& S, const Epi& E) {
;     ...
;             PG8_WAIT_V(8); PG8_WAIT_L(0); PG8_BAR; PG8_MMA(1, 0, At, B0); PG8_MMA(1, 1, At, B1); PG8_BAR; PG8_SCHED;
;             PG8_LDB(B0, 1, 0); PG8_LDB(B1, 1, 1); PG8_SCHED; PG8_LDA(At, 1, 0); PG8_STAGE(PG8_SA(0, 1), a2 + hstep, voffA);
;             PG8_WAIT_V(8); PG8_WAIT_L(0); PG8_BAR; PG8_MMA(0, 0, At, B0); PG8_MMA(0, 1, At, B1); PG8_BAR; PG8_SCHED;
	v_mfma_f32_16x16x32_bf16 v[60:63], v[128:131], v[206:209], 0
	v_mfma_f32_16x16x32_bf16 v[56:59], v[136:139], v[206:209], 0
	v_mfma_f32_16x16x32_bf16 v[52:55], v[128:131], v[230:233], 0
	v_mfma_f32_16x16x32_bf16 v[44:47], v[136:139], v[230:233], 0
	v_mfma_f32_16x16x32_bf16 v[36:39], v[128:131], v[238:241], 0
	v_mfma_f32_16x16x32_bf16 v[28:31], v[136:139], v[238:241], 0
	v_mfma_f32_16x16x32_bf16 v[20:23], v[128:131], v[246:249], 0
	v_mfma_f32_16x16x32_bf16 v[12:15], v[136:139], v[246:249], 0
	v_mfma_f32_16x16x32_bf16 v[60:63], v[132:135], v[210:213], v[60:63]
	v_mfma_f32_16x16x32_bf16 v[56:59], v[140:143], v[210:213], v[56:59]
	v_mfma_f32_16x16x32_bf16 v[52:55], v[132:135], v[234:237], v[52:55]
	v_mfma_f32_16x16x32_bf16 v[44:47], v[140:143], v[234:237], v[44:47]
	v_mfma_f32_16x16x32_bf16 v[36:39], v[132:135], v[242:245], v[36:39]
	v_mfma_f32_16x16x32_bf16 v[28:31], v[140:143], v[242:245], v[28:31]
	v_mfma_f32_16x16x32_bf16 v[20:23], v[132:135], v[250:253], v[20:23]
	v_mfma_f32_16x16x32_bf16 v[12:15], v[140:143], v[250:253], v[12:15]
	v_mfma_f32_16x16x32_bf16 v[48:51], v[184:187], v[206:209], 0
	v_mfma_f32_16x16x32_bf16 v[40:43], v[222:225], v[206:209], 0
	v_mfma_f32_16x16x32_bf16 v[32:35], v[184:187], v[230:233], 0
	v_mfma_f32_16x16x32_bf16 v[24:27], v[222:225], v[230:233], 0
	v_mfma_f32_16x16x32_bf16 v[16:19], v[184:187], v[238:241], 0
	v_mfma_f32_16x16x32_bf16 v[8:11], v[222:225], v[238:241], 0
	v_mfma_f32_16x16x32_bf16 v[4:7], v[184:187], v[246:249], 0
	v_mfma_f32_16x16x32_bf16 v[0:3], v[222:225], v[246:249], 0
	v_mfma_f32_16x16x32_bf16 v[48:51], v[218:221], v[210:213], v[48:51]
	v_mfma_f32_16x16x32_bf16 v[40:43], v[226:229], v[210:213], v[40:43]
	v_mfma_f32_16x16x32_bf16 v[32:35], v[218:221], v[234:237], v[32:35]
	v_mfma_f32_16x16x32_bf16 v[24:27], v[226:229], v[234:237], v[24:27]
	v_mfma_f32_16x16x32_bf16 v[16:19], v[218:221], v[242:245], v[16:19]
	v_mfma_f32_16x16x32_bf16 v[8:11], v[226:229], v[242:245], v[8:11]
	v_mfma_f32_16x16x32_bf16 v[4:7], v[218:221], v[250:253], v[4:7]
	v_mfma_f32_16x16x32_bf16 v[0:3], v[226:229], v[250:253], v[0:3]
	s_barrier
	s_setprio 0
	s_add_i32 s49, 0, 0x18000
	s_add_i32 s50, 0, 0x1c000
	v_add_u32_e32 v140, s49, v163
	v_add_u32_e32 v152, s50, v163
	ds_read_b128 v[128:131], v140
	ds_read_b128 v[132:135], v140 offset:1024
	ds_read_b128 v[136:139], v140 offset:2048
	ds_read_b128 v[140:143], v140 offset:3072
	ds_read_b128 v[184:187], v152
	ds_read_b128 v[206:209], v152 offset:1024
	ds_read_b128 v[210:213], v152 offset:2048
	ds_read_b128 v[218:221], v152 offset:3072
	s_add_u32 s30, s30, 0x80000
	s_addc_u32 s31, s31, 0
	s_mov_b32 m0, s37
	v_lshl_add_u64 v[216:217], s[30:31], 0, v[144:145]
	ds_read_b128 v[222:225], v214 offset:32768
	ds_read_b128 v[226:229], v214 offset:33792
	ds_read_b128 v[230:233], v214 offset:34816
	ds_read_b128 v[234:237], v214 offset:35840
	ds_read_b128 v[238:241], v214 offset:36864
	ds_read_b128 v[242:245], v214 offset:37888
	ds_read_b128 v[246:249], v214 offset:38912
	ds_read_b128 v[250:253], v214 offset:39936
	global_load_lds_dwordx4 v[216:217], off
	s_mov_b32 m0, s39
	v_lshl_add_u64 v[216:217], s[30:31], 0, v[148:149]
	global_load_lds_dwordx4 v[216:217], off
	s_waitcnt vmcnt(8) lgkmcnt(0)
	s_setprio 1
	s_barrier
	v_mfma_f32_16x16x32_bf16 v[124:127], v[128:131], v[222:225], v[124:127]
	v_mfma_f32_16x16x32_bf16 v[120:123], v[136:139], v[222:225], v[120:123]
	v_mfma_f32_16x16x32_bf16 v[116:119], v[128:131], v[230:233], v[116:119]
	v_mfma_f32_16x16x32_bf16 v[108:111], v[136:139], v[230:233], v[108:111]
	v_mfma_f32_16x16x32_bf16 v[100:103], v[128:131], v[238:241], v[100:103]
	v_mfma_f32_16x16x32_bf16 v[92:95], v[136:139], v[238:241], v[92:95]
	v_mfma_f32_16x16x32_bf16 v[84:87], v[128:131], v[246:249], v[84:87]
	v_mfma_f32_16x16x32_bf16 v[76:79], v[136:139], v[246:249], v[76:79]
	v_mfma_f32_16x16x32_bf16 v[124:127], v[132:135], v[226:229], v[124:127]
	v_mfma_f32_16x16x32_bf16 v[120:123], v[140:143], v[226:229], v[120:123]
	v_mfma_f32_16x16x32_bf16 v[116:119], v[132:135], v[234:237], v[116:119]
	v_mfma_f32_16x16x32_bf16 v[108:111], v[140:143], v[234:237], v[108:111]
	v_mfma_f32_16x16x32_bf16 v[100:103], v[132:135], v[242:245], v[100:103]
	v_mfma_f32_16x16x32_bf16 v[92:95], v[140:143], v[242:245], v[92:95]
	v_mfma_f32_16x16x32_bf16 v[84:87], v[132:135], v[250:253], v[84:87]
	v_mfma_f32_16x16x32_bf16 v[76:79], v[140:143], v[250:253], v[76:79]
	v_mfma_f32_16x16x32_bf16 v[112:115], v[184:187], v[222:225], v[112:115]
	v_mfma_f32_16x16x32_bf16 v[104:107], v[210:213], v[222:225], v[104:107]
	v_mfma_f32_16x16x32_bf16 v[96:99], v[184:187], v[230:233], v[96:99]
	v_mfma_f32_16x16x32_bf16 v[88:91], v[210:213], v[230:233], v[88:91]
	v_mfma_f32_16x16x32_bf16 v[80:83], v[184:187], v[238:241], v[80:83]
	v_mfma_f32_16x16x32_bf16 v[72:75], v[210:213], v[238:241], v[72:75]
	v_mfma_f32_16x16x32_bf16 v[68:71], v[184:187], v[246:249], v[68:71]
	v_mfma_f32_16x16x32_bf16 v[64:67], v[210:213], v[246:249], v[64:67]
	v_mfma_f32_16x16x32_bf16 v[112:115], v[206:209], v[226:229], v[112:115]
	v_mfma_f32_16x16x32_bf16 v[104:107], v[218:221], v[226:229], v[104:107]
	v_mfma_f32_16x16x32_bf16 v[96:99], v[206:209], v[234:237], v[96:99]
	v_mfma_f32_16x16x32_bf16 v[88:91], v[218:221], v[234:237], v[88:91]
	v_mfma_f32_16x16x32_bf16 v[80:83], v[206:209], v[242:245], v[80:83]
	v_mfma_f32_16x16x32_bf16 v[72:75], v[218:221], v[242:245], v[72:75]
	v_mfma_f32_16x16x32_bf16 v[68:71], v[206:209], v[250:253], v[68:71]
	v_mfma_f32_16x16x32_bf16 v[64:67], v[218:221], v[250:253], v[64:67]
	s_barrier
; #define PG8_STAGE(bufoff, gbase, voff) do { _Pragma("unroll") for (int _i = 0; _i < 2; ++_i) \
;         __builtin_amdgcn_global_load_lds((const unsigned*)((const char*)(gbase) + (voff)[_i]), (PG8_LAS unsigned*)(lds + (bufoff) + ldsw + _i * 8192), 16, 0, 0); } while (0)
; #define PG8_LDA(dst, b, h) do { _Pragma("unroll") for (int m = 0; m < 4; ++m) _Pragma("unroll") for (int k = 0; k < 2; ++k) dst[m][k] = *(const PG8_LAS bf16x8*)(lds + PG8_SA(b, h) + aoff + m * 2048 + k * 1024); } while (0)
; #define PG8_LDB(dst, b, h) do { _Pragma("unroll") for (int n = 0; n < 2; ++n) _Pragma("unroll") for (int k = 0; k < 2; ++k) dst[n][k] = *(const PG8_LAS bf16x8*)(lds + PG8_SB(b, h) + boff + n * 2048 + k * 1024); } while (0)
; #define PG8_MMA(ai, bj, At, Bt) do { __builtin_amdgcn_s_setprio(1); _Pragma("unroll") for (int m = 0; m < 4; ++m) _Pragma("unroll") for (int n = 0; n < 2; ++n) _Pragma("unroll") for (int k = 0; k < 2; ++k) \
;         acc[ai][bj][m][n] = __builtin_amdgcn_mfma_f32_16x16x32_bf16(Bt[n][k], At[m][k], acc[ai][bj][m][n], 0, 0, 0); __builtin_amdgcn_s_setprio(0); } while (0)
; #define PG8_WAIT_V(n) asm volatile("s_waitcnt vmcnt(" #n ")" ::: "memory")
; template <class Epi, class Sched, bool ALIGN_EPI = false, bool SP2 = false>
; __device__ __forceinline__ void gemm_phase(PG8_LAS unsigned char* lds, const Gemm g, const Sched& S, const Epi& E) {
;     ...
;             PG8_LDB(B0, 0, 0); PG8_LDB(B1, 0, 1); PG8_SCHED; PG8_LDA(At, 0, 0); PG8_STAGE(PG8_SA(1, 1), a1 + hstep, voffA);
;             PG8_WAIT_V(8); PG8_WAIT_L(0); PG8_BAR; PG8_MMA(0, 0, At, B0); PG8_MMA(0, 1, At, B1); PG8_BAR; PG8_SCHED;
;             PG8_LDA(At, 0, 1); PG8_STAGE(PG8_SB(0, 0), b2, voffB); PG8_STAGE(PG8_SB(0, 1), b2 + hstep, voffB); PG8_STAGE(PG8_SA(0, 0), a2, voffA);
;             PG8_WAIT_V(8); PG8_WAIT_L(0); PG8_BAR; PG8_MMA(1, 0, At, B0); PG8_MMA(1, 1, At, B1); PG8_BAR; PG8_SCHED;
;             PG8_LDB(B0, 1, 0); PG8_LDB(B1, 1, 1); PG8_SCHED; PG8_LDA(At, 1, 0); PG8_STAGE(PG8_SA(0, 1), a2 + hstep, voffA);
;             PG8_WAIT_V(8); PG8_WAIT_L(0); PG8_BAR; PG8_MMA(0, 0, At, B0); PG8_MMA(0, 1, At, B1); PG8_BAR; PG8_SCHED;
;             PG8_LDA(At, 1, 1); PG8_STAGE(PG8_SB(1, 0), b3, voffB); PG8_STAGE(PG8_SB(1, 1), b3 + hstep, voffB); PG8_STAGE(PG8_SA(1, 0), a3, voffA);
;             PG8_WAIT_V(8); PG8_WAIT_L(0); PG8_BAR; PG8_MMA(1, 0, At, B0); PG8_MMA(1, 1, At, B1); PG8_BAR; PG8_SCHED;
	s_setprio 0
	s_add_i32 s30, s49, s34
	v_lshl_add_u64 v[172:173], v[172:173], 0, s[10:11]
	s_mov_b32 m0, s30
	ds_read_b128 v[222:225], v214 offset:49152
	ds_read_b128 v[226:229], v214 offset:50176
	ds_read_b128 v[230:233], v214 offset:51200
	ds_read_b128 v[234:237], v214 offset:52224
	ds_read_b128 v[238:241], v214 offset:53248
	ds_read_b128 v[242:245], v214 offset:54272
	ds_read_b128 v[246:249], v214 offset:55296
	ds_read_b128 v[250:253], v214 offset:56320
	global_load_lds_dwordx4 v[172:173], off
	s_add_i32 m0, s30, 0x2000
	s_add_u32 s28, s28, 0x80080
	v_lshl_add_u64 v[172:173], v[176:177], 0, s[10:11]
	s_addc_u32 s29, s29, 0
	s_add_i32 s30, s50, s34
	global_load_lds_dwordx4 v[172:173], off
	s_mov_b32 m0, s30
	v_lshl_add_u64 v[172:173], s[28:29], 0, v[146:147]
	global_load_lds_dwordx4 v[172:173], off
	s_add_i32 m0, s30, 0x2000
	v_lshl_add_u64 v[172:173], s[28:29], 0, v[150:151]
	global_load_lds_dwordx4 v[172:173], off
	s_mov_b32 m0, s43
	v_lshl_add_u64 v[172:173], v[180:181], 0, s[10:11]
	global_load_lds_dwordx4 v[172:173], off
	s_mov_b32 m0, s46
	v_lshl_add_u64 v[172:173], v[188:189], 0, s[10:11]
	global_load_lds_dwordx4 v[172:173], off
	s_waitcnt vmcnt(8) lgkmcnt(0)
	s_setprio 1
	s_barrier
	v_mfma_f32_16x16x32_bf16 v[60:63], v[128:131], v[222:225], v[60:63]
	v_mfma_f32_16x16x32_bf16 v[56:59], v[136:139], v[222:225], v[56:59]
	v_mfma_f32_16x16x32_bf16 v[52:55], v[128:131], v[230:233], v[52:55]
	v_mfma_f32_16x16x32_bf16 v[44:47], v[136:139], v[230:233], v[44:47]
	v_mfma_f32_16x16x32_bf16 v[36:39], v[128:131], v[238:241], v[36:39]
	v_mfma_f32_16x16x32_bf16 v[28:31], v[136:139], v[238:241], v[28:31]
	v_mfma_f32_16x16x32_bf16 v[20:23], v[128:131], v[246:249], v[20:23]
	v_mfma_f32_16x16x32_bf16 v[12:15], v[136:139], v[246:249], v[12:15]
	v_mfma_f32_16x16x32_bf16 v[60:63], v[132:135], v[226:229], v[60:63]
	v_mfma_f32_16x16x32_bf16 v[56:59], v[140:143], v[226:229], v[56:59]
	v_mfma_f32_16x16x32_bf16 v[52:55], v[132:135], v[234:237], v[52:55]
	v_mfma_f32_16x16x32_bf16 v[44:47], v[140:143], v[234:237], v[44:47]
	v_mfma_f32_16x16x32_bf16 v[36:39], v[132:135], v[242:245], v[36:39]
	v_mfma_f32_16x16x32_bf16 v[28:31], v[140:143], v[242:245], v[28:31]
	v_mfma_f32_16x16x32_bf16 v[20:23], v[132:135], v[250:253], v[20:23]
	v_mfma_f32_16x16x32_bf16 v[12:15], v[140:143], v[250:253], v[12:15]
	v_mfma_f32_16x16x32_bf16 v[48:51], v[184:187], v[222:225], v[48:51]
	v_mfma_f32_16x16x32_bf16 v[40:43], v[210:213], v[222:225], v[40:43]
	v_mfma_f32_16x16x32_bf16 v[32:35], v[184:187], v[230:233], v[32:35]
	v_mfma_f32_16x16x32_bf16 v[24:27], v[210:213], v[230:233], v[24:27]
	v_mfma_f32_16x16x32_bf16 v[16:19], v[184:187], v[238:241], v[16:19]
	v_mfma_f32_16x16x32_bf16 v[8:11], v[210:213], v[238:241], v[8:11]
	v_mfma_f32_16x16x32_bf16 v[4:7], v[184:187], v[246:249], v[4:7]
	v_mfma_f32_16x16x32_bf16 v[0:3], v[210:213], v[246:249], v[0:3]
	v_mfma_f32_16x16x32_bf16 v[48:51], v[206:209], v[226:229], v[48:51]
	v_mfma_f32_16x16x32_bf16 v[40:43], v[218:221], v[226:229], v[40:43]
	v_mfma_f32_16x16x32_bf16 v[32:35], v[206:209], v[234:237], v[32:35]
	v_mfma_f32_16x16x32_bf16 v[24:27], v[218:221], v[234:237], v[24:27]
	v_mfma_f32_16x16x32_bf16 v[16:19], v[206:209], v[242:245], v[16:19]
	v_mfma_f32_16x16x32_bf16 v[8:11], v[218:221], v[242:245], v[8:11]
	v_mfma_f32_16x16x32_bf16 v[4:7], v[206:209], v[250:253], v[4:7]
	v_mfma_f32_16x16x32_bf16 v[0:3], v[218:221], v[250:253], v[0:3]
	s_barrier
	s_setprio 0
	s_add_i32 s48, s48, 2
	s_add_u32 s0, s0, 0x100
	s_addc_u32 s1, s1, 0
	s_add_u32 s44, s44, 0x100
	s_addc_u32 s45, s45, 0
.LBB0_491:
	v_add_u32_e32 v140, s68, v163
	v_add_u32_e32 v152, s69, v163
	ds_read_b128 v[128:131], v140
	ds_read_b128 v[132:135], v140 offset:1024
	ds_read_b128 v[136:139], v140 offset:2048
	ds_read_b128 v[140:143], v140 offset:3072
	ds_read_b128 v[184:187], v152
	ds_read_b128 v[218:221], v152 offset:1024
	ds_read_b128 v[222:225], v152 offset:2048
	ds_read_b128 v[226:229], v152 offset:3072
	s_add_u32 s28, s0, 0xfff80080
	s_addc_u32 s29, s1, -1
	s_cmp_eq_u32 s48, 28
	s_cselect_b32 s31, s5, s29
	s_cselect_b32 s30, s21, s28
	s_cselect_b32 s29, s19, s45
	s_cselect_b32 s28, s33, s44
	v_lshl_add_u64 v[172:173], s[0:1], 0, v[156:157]
	s_add_i32 m0, s17, 0xc000
	ds_read_b128 v[230:233], v214
	ds_read_b128 v[234:237], v214 offset:1024
	ds_read_b128 v[238:241], v214 offset:2048
	ds_read_b128 v[242:245], v214 offset:3072
	ds_read_b128 v[246:249], v214 offset:4096
	ds_read_b128 v[250:253], v214 offset:5120
	ds_read_b128 v[206:209], v214 offset:6144
	ds_read_b128 v[210:213], v214 offset:7168
	global_load_lds_dwordx4 v[172:173], off
	s_add_i32 m0, s17, 0xe000
	v_lshl_add_u64 v[172:173], s[0:1], 0, v[158:159]
	global_load_lds_dwordx4 v[172:173], off
	s_waitcnt vmcnt(8) lgkmcnt(0)
	s_setprio 1
	s_barrier
; #define PG8_STAGE(bufoff, gbase, voff) do { _Pragma("unroll") for (int _i = 0; _i < 2; ++_i) \
;         __builtin_amdgcn_global_load_lds((const unsigned*)((const char*)(gbase) + (voff)[_i]), (PG8_LAS unsigned*)(lds + (bufoff) + ldsw + _i * 8192), 16, 0, 0); } while (0)
; #define PG8_LDA(dst, b, h) do { _Pragma("unroll") for (int m = 0; m < 4; ++m) _Pragma("unroll") for (int k = 0; k < 2; ++k) dst[m][k] = *(const PG8_LAS bf16x8*)(lds + PG8_SA(b, h) + aoff + m * 2048 + k * 1024); } while (0)
; #define PG8_LDB(dst, b, h) do { _Pragma("unroll") for (int n = 0; n < 2; ++n) _Pragma("unroll") for (int k = 0; k < 2; ++k) dst[n][k] = *(const PG8_LAS bf16x8*)(lds + PG8_SB(b, h) + boff + n * 2048 + k * 1024); } while (0)
; #define PG8_MMA(ai, bj, At, Bt) do { __builtin_amdgcn_s_setprio(1); _Pragma("unroll") for (int m = 0; m < 4; ++m) _Pragma("unroll") for (int n = 0; n < 2; ++n) _Pragma("unroll") for (int k = 0; k < 2; ++k) \
;         acc[ai][bj][m][n] = __builtin_amdgcn_mfma_f32_16x16x32_bf16(Bt[n][k], At[m][k], acc[ai][bj][m][n], 0, 0, 0); __builtin_amdgcn_s_setprio(0); } while (0)
; #define PG8_WAIT_V(n) asm volatile("s_waitcnt vmcnt(" #n ")" ::: "memory")
; #define PG8_WAIT_L(n) asm volatile("s_waitcnt lgkmcnt(" #n ")" ::: "memory")
; #define PG8_BAR __builtin_amdgcn_s_barrier()
; #define PG8_SCHED __builtin_amdgcn_sched_barrier(0)
; template <class Epi, class Sched, bool ALIGN_EPI = false, bool SP2 = false>
; __device__ __forceinline__ void gemm_phase(PG8_LAS unsigned char* lds, const Gemm g, const Sched& S, const Epi& E) {
;     ...
;             PG8_LDB(B0, 0, 0); PG8_LDB(B1, 0, 1); PG8_SCHED; PG8_LDA(At, 0, 0); PG8_STAGE(PG8_SA(1, 1), a1 + hstep, voffA);
;             PG8_WAIT_V(8); PG8_WAIT_L(0); PG8_BAR; PG8_MMA(0, 0, At, B0); PG8_MMA(0, 1, At, B1); PG8_BAR; PG8_SCHED;
;             PG8_LDA(At, 0, 1); PG8_STAGE(PG8_SB(0, 0), b2, voffB); PG8_STAGE(PG8_SB(0, 1), b2 + hstep, voffB); PG8_STAGE(PG8_SA(0, 0), a2, voffA);
;             PG8_WAIT_V(8); PG8_WAIT_L(0); PG8_BAR; PG8_MMA(1, 0, At, B0); PG8_MMA(1, 1, At, B1); PG8_BAR; PG8_SCHED;
	v_mfma_f32_16x16x32_bf16 v[124:127], v[128:131], v[230:233], v[124:127]
	v_mfma_f32_16x16x32_bf16 v[120:123], v[136:139], v[230:233], v[120:123]
	v_mfma_f32_16x16x32_bf16 v[116:119], v[128:131], v[238:241], v[116:119]
	v_mfma_f32_16x16x32_bf16 v[108:111], v[136:139], v[238:241], v[108:111]
	v_mfma_f32_16x16x32_bf16 v[100:103], v[128:131], v[246:249], v[100:103]
	v_mfma_f32_16x16x32_bf16 v[92:95], v[136:139], v[246:249], v[92:95]
	v_mfma_f32_16x16x32_bf16 v[84:87], v[128:131], v[206:209], v[84:87]
	v_mfma_f32_16x16x32_bf16 v[76:79], v[136:139], v[206:209], v[76:79]
	v_mfma_f32_16x16x32_bf16 v[124:127], v[132:135], v[234:237], v[124:127]
	v_mfma_f32_16x16x32_bf16 v[120:123], v[140:143], v[234:237], v[120:123]
	v_mfma_f32_16x16x32_bf16 v[116:119], v[132:135], v[242:245], v[116:119]
	v_mfma_f32_16x16x32_bf16 v[108:111], v[140:143], v[242:245], v[108:111]
	v_mfma_f32_16x16x32_bf16 v[100:103], v[132:135], v[250:253], v[100:103]
	v_mfma_f32_16x16x32_bf16 v[92:95], v[140:143], v[250:253], v[92:95]
	v_mfma_f32_16x16x32_bf16 v[84:87], v[132:135], v[210:213], v[84:87]
	v_mfma_f32_16x16x32_bf16 v[76:79], v[140:143], v[210:213], v[76:79]
	v_mfma_f32_16x16x32_bf16 v[112:115], v[184:187], v[230:233], v[112:115]
	v_mfma_f32_16x16x32_bf16 v[104:107], v[222:225], v[230:233], v[104:107]
	v_mfma_f32_16x16x32_bf16 v[96:99], v[184:187], v[238:241], v[96:99]
	v_mfma_f32_16x16x32_bf16 v[88:91], v[222:225], v[238:241], v[88:91]
	v_mfma_f32_16x16x32_bf16 v[80:83], v[184:187], v[246:249], v[80:83]
	v_mfma_f32_16x16x32_bf16 v[72:75], v[222:225], v[246:249], v[72:75]
	v_mfma_f32_16x16x32_bf16 v[68:71], v[184:187], v[206:209], v[68:71]
	v_mfma_f32_16x16x32_bf16 v[64:67], v[222:225], v[206:209], v[64:67]
	v_mfma_f32_16x16x32_bf16 v[112:115], v[218:221], v[234:237], v[112:115]
	v_mfma_f32_16x16x32_bf16 v[104:107], v[226:229], v[234:237], v[104:107]
	v_mfma_f32_16x16x32_bf16 v[96:99], v[218:221], v[242:245], v[96:99]
	v_mfma_f32_16x16x32_bf16 v[88:91], v[226:229], v[242:245], v[88:91]
	v_mfma_f32_16x16x32_bf16 v[80:83], v[218:221], v[250:253], v[80:83]
	v_mfma_f32_16x16x32_bf16 v[72:75], v[226:229], v[250:253], v[72:75]
	v_mfma_f32_16x16x32_bf16 v[68:71], v[218:221], v[210:213], v[68:71]
	v_mfma_f32_16x16x32_bf16 v[64:67], v[226:229], v[210:213], v[64:67]
	s_barrier
	s_setprio 0
	s_add_i32 s49, s68, s34
	v_lshl_add_u64 v[172:173], s[28:29], 0, v[146:147]
	s_mov_b32 m0, s49
	ds_read_b128 v[206:209], v214 offset:16384
	ds_read_b128 v[210:213], v214 offset:17408
	ds_read_b128 v[230:233], v214 offset:18432
	ds_read_b128 v[234:237], v214 offset:19456
	ds_read_b128 v[238:241], v214 offset:20480
	ds_read_b128 v[242:245], v214 offset:21504
	ds_read_b128 v[246:249], v214 offset:22528
	ds_read_b128 v[250:253], v214 offset:23552
	global_load_lds_dwordx4 v[172:173], off
	s_add_i32 m0, s49, 0x2000
	s_add_u32 s50, s28, 0x80000
	v_lshl_add_u64 v[176:177], s[28:29], 0, v[150:151]
	s_addc_u32 s51, s29, 0
	s_add_i32 s49, s69, s34
	global_load_lds_dwordx4 v[176:177], off
	v_lshl_add_u64 v[180:181], s[50:51], 0, v[146:147]
	s_mov_b32 m0, s49
	v_lshl_add_u64 v[188:189], s[30:31], 0, v[148:149]
	global_load_lds_dwordx4 v[180:181], off
	s_add_i32 m0, s49, 0x2000
	v_lshl_add_u64 v[180:181], s[50:51], 0, v[150:151]
	global_load_lds_dwordx4 v[180:181], off
	s_mov_b32 m0, s17
	v_lshl_add_u64 v[180:181], s[30:31], 0, v[144:145]
	global_load_lds_dwordx4 v[180:181], off
	s_mov_b32 m0, s35
	s_nop 0
	global_load_lds_dwordx4 v[188:189], off
	s_waitcnt vmcnt(8) lgkmcnt(0)
	s_setprio 1
	s_barrier
	v_mfma_f32_16x16x32_bf16 v[60:63], v[128:131], v[206:209], v[60:63]
	v_mfma_f32_16x16x32_bf16 v[56:59], v[136:139], v[206:209], v[56:59]
	v_mfma_f32_16x16x32_bf16 v[52:55], v[128:131], v[230:233], v[52:55]
	v_mfma_f32_16x16x32_bf16 v[44:47], v[136:139], v[230:233], v[44:47]
	v_mfma_f32_16x16x32_bf16 v[36:39], v[128:131], v[238:241], v[36:39]
	v_mfma_f32_16x16x32_bf16 v[28:31], v[136:139], v[238:241], v[28:31]
	v_mfma_f32_16x16x32_bf16 v[20:23], v[128:131], v[246:249], v[20:23]
	v_mfma_f32_16x16x32_bf16 v[12:15], v[136:139], v[246:249], v[12:15]
	v_mfma_f32_16x16x32_bf16 v[60:63], v[132:135], v[210:213], v[60:63]
	v_mfma_f32_16x16x32_bf16 v[56:59], v[140:143], v[210:213], v[56:59]
	v_mfma_f32_16x16x32_bf16 v[52:55], v[132:135], v[234:237], v[52:55]
	v_mfma_f32_16x16x32_bf16 v[44:47], v[140:143], v[234:237], v[44:47]
	v_mfma_f32_16x16x32_bf16 v[36:39], v[132:135], v[242:245], v[36:39]
	v_mfma_f32_16x16x32_bf16 v[28:31], v[140:143], v[242:245], v[28:31]
	v_mfma_f32_16x16x32_bf16 v[20:23], v[132:135], v[250:253], v[20:23]
	v_mfma_f32_16x16x32_bf16 v[12:15], v[140:143], v[250:253], v[12:15]
	v_mfma_f32_16x16x32_bf16 v[48:51], v[184:187], v[206:209], v[48:51]
	v_mfma_f32_16x16x32_bf16 v[40:43], v[222:225], v[206:209], v[40:43]
	v_mfma_f32_16x16x32_bf16 v[32:35], v[184:187], v[230:233], v[32:35]
	v_mfma_f32_16x16x32_bf16 v[24:27], v[222:225], v[230:233], v[24:27]
	v_mfma_f32_16x16x32_bf16 v[16:19], v[184:187], v[238:241], v[16:19]
	v_mfma_f32_16x16x32_bf16 v[8:11], v[222:225], v[238:241], v[8:11]
	v_mfma_f32_16x16x32_bf16 v[4:7], v[184:187], v[246:249], v[4:7]
	v_mfma_f32_16x16x32_bf16 v[0:3], v[222:225], v[246:249], v[0:3]
	v_mfma_f32_16x16x32_bf16 v[48:51], v[218:221], v[210:213], v[48:51]
	v_mfma_f32_16x16x32_bf16 v[40:43], v[226:229], v[210:213], v[40:43]
	v_mfma_f32_16x16x32_bf16 v[32:35], v[218:221], v[234:237], v[32:35]
	v_mfma_f32_16x16x32_bf16 v[24:27], v[226:229], v[234:237], v[24:27]
	v_mfma_f32_16x16x32_bf16 v[16:19], v[218:221], v[242:245], v[16:19]
	v_mfma_f32_16x16x32_bf16 v[8:11], v[226:229], v[242:245], v[8:11]
	v_mfma_f32_16x16x32_bf16 v[4:7], v[218:221], v[250:253], v[4:7]
	v_mfma_f32_16x16x32_bf16 v[0:3], v[226:229], v[250:253], v[0:3]
	s_barrier
; #define PG8_STAGE(bufoff, gbase, voff) do { _Pragma("unroll") for (int _i = 0; _i < 2; ++_i) \
;         __builtin_amdgcn_global_load_lds((const unsigned*)((const char*)(gbase) + (voff)[_i]), (PG8_LAS unsigned*)(lds + (bufoff) + ldsw + _i * 8192), 16, 0, 0); } while (0)
; #define PG8_LDA(dst, b, h) do { _Pragma("unroll") for (int m = 0; m < 4; ++m) _Pragma("unroll") for (int k = 0; k < 2; ++k) dst[m][k] = *(const PG8_LAS bf16x8*)(lds + PG8_SA(b, h) + aoff + m * 2048 + k * 1024); } while (0)
; #define PG8_LDB(dst, b, h) do { _Pragma("unroll") for (int n = 0; n < 2; ++n) _Pragma("unroll") for (int k = 0; k < 2; ++k) dst[n][k] = *(const PG8_LAS bf16x8*)(lds + PG8_SB(b, h) + boff + n * 2048 + k * 1024); } while (0)
; #define PG8_MMA(ai, bj, At, Bt) do { __builtin_amdgcn_s_setprio(1); _Pragma("unroll") for (int m = 0; m < 4; ++m) _Pragma("unroll") for (int n = 0; n < 2; ++n) _Pragma("unroll") for (int k = 0; k < 2; ++k) \
;         acc[ai][bj][m][n] = __builtin_amdgcn_mfma_f32_16x16x32_bf16(Bt[n][k], At[m][k], acc[ai][bj][m][n], 0, 0, 0); __builtin_amdgcn_s_setprio(0); } while (0)
; #define PG8_WAIT_V(n) asm volatile("s_waitcnt vmcnt(" #n ")" ::: "memory")
; #define PG8_WAIT_L(n) asm volatile("s_waitcnt lgkmcnt(" #n ")" ::: "memory")
; #define PG8_BAR __builtin_amdgcn_s_barrier()
; #define PG8_SCHED __builtin_amdgcn_sched_barrier(0)
; template <class Epi, class Sched, bool ALIGN_EPI = false, bool SP2 = false>
; __device__ __forceinline__ void gemm_phase(PG8_LAS unsigned char* lds, const Gemm g, const Sched& S, const Epi& E) {
;     ...
;             PG8_LDB(B0, 1, 0); PG8_LDB(B1, 1, 1); PG8_SCHED; PG8_LDA(At, 1, 0); PG8_STAGE(PG8_SA(0, 1), a2 + hstep, voffA);
;             PG8_WAIT_V(8); PG8_WAIT_L(0); PG8_BAR; PG8_MMA(0, 0, At, B0); PG8_MMA(0, 1, At, B1); PG8_BAR; PG8_SCHED;
	s_setprio 0
	s_add_i32 s49, 0, 0x18000
	s_add_i32 s50, 0, 0x1c000
	v_add_u32_e32 v140, s49, v163
	v_add_u32_e32 v152, s50, v163
	ds_read_b128 v[128:131], v140
	ds_read_b128 v[132:135], v140 offset:1024
	ds_read_b128 v[136:139], v140 offset:2048
	ds_read_b128 v[140:143], v140 offset:3072
	ds_read_b128 v[184:187], v152
	ds_read_b128 v[206:209], v152 offset:1024
	ds_read_b128 v[210:213], v152 offset:2048
	ds_read_b128 v[218:221], v152 offset:3072
	s_add_u32 s30, s30, 0x80000
	s_addc_u32 s31, s31, 0
	s_mov_b32 m0, s37
	v_lshl_add_u64 v[216:217], s[30:31], 0, v[144:145]
	ds_read_b128 v[222:225], v214 offset:32768
	ds_read_b128 v[226:229], v214 offset:33792
	ds_read_b128 v[230:233], v214 offset:34816
	ds_read_b128 v[234:237], v214 offset:35840
	ds_read_b128 v[238:241], v214 offset:36864
	ds_read_b128 v[242:245], v214 offset:37888
	ds_read_b128 v[246:249], v214 offset:38912
	ds_read_b128 v[250:253], v214 offset:39936
	global_load_lds_dwordx4 v[216:217], off
	s_mov_b32 m0, s39
	v_lshl_add_u64 v[216:217], s[30:31], 0, v[148:149]
	global_load_lds_dwordx4 v[216:217], off
	s_waitcnt vmcnt(8) lgkmcnt(0)
	s_setprio 1
	s_barrier
	v_mfma_f32_16x16x32_bf16 v[124:127], v[128:131], v[222:225], v[124:127]
	v_mfma_f32_16x16x32_bf16 v[120:123], v[136:139], v[222:225], v[120:123]
	v_mfma_f32_16x16x32_bf16 v[116:119], v[128:131], v[230:233], v[116:119]
	v_mfma_f32_16x16x32_bf16 v[108:111], v[136:139], v[230:233], v[108:111]
	v_mfma_f32_16x16x32_bf16 v[100:103], v[128:131], v[238:241], v[100:103]
	v_mfma_f32_16x16x32_bf16 v[92:95], v[136:139], v[238:241], v[92:95]
	v_mfma_f32_16x16x32_bf16 v[84:87], v[128:131], v[246:249], v[84:87]
	v_mfma_f32_16x16x32_bf16 v[76:79], v[136:139], v[246:249], v[76:79]
	v_mfma_f32_16x16x32_bf16 v[124:127], v[132:135], v[226:229], v[124:127]
	v_mfma_f32_16x16x32_bf16 v[120:123], v[140:143], v[226:229], v[120:123]
	v_mfma_f32_16x16x32_bf16 v[116:119], v[132:135], v[234:237], v[116:119]
	v_mfma_f32_16x16x32_bf16 v[108:111], v[140:143], v[234:237], v[108:111]
	v_mfma_f32_16x16x32_bf16 v[100:103], v[132:135], v[242:245], v[100:103]
	v_mfma_f32_16x16x32_bf16 v[92:95], v[140:143], v[242:245], v[92:95]
	v_mfma_f32_16x16x32_bf16 v[84:87], v[132:135], v[250:253], v[84:87]
	v_mfma_f32_16x16x32_bf16 v[76:79], v[140:143], v[250:253], v[76:79]
	v_mfma_f32_16x16x32_bf16 v[112:115], v[184:187], v[222:225], v[112:115]
	v_mfma_f32_16x16x32_bf16 v[104:107], v[210:213], v[222:225], v[104:107]
	v_mfma_f32_16x16x32_bf16 v[96:99], v[184:187], v[230:233], v[96:99]
	v_mfma_f32_16x16x32_bf16 v[88:91], v[210:213], v[230:233], v[88:91]
	v_mfma_f32_16x16x32_bf16 v[80:83], v[184:187], v[238:241], v[80:83]
	v_mfma_f32_16x16x32_bf16 v[72:75], v[210:213], v[238:241], v[72:75]
	v_mfma_f32_16x16x32_bf16 v[68:71], v[184:187], v[246:249], v[68:71]
	v_mfma_f32_16x16x32_bf16 v[64:67], v[210:213], v[246:249], v[64:67]
	v_mfma_f32_16x16x32_bf16 v[112:115], v[206:209], v[226:229], v[112:115]
	v_mfma_f32_16x16x32_bf16 v[104:107], v[218:221], v[226:229], v[104:107]
	v_mfma_f32_16x16x32_bf16 v[96:99], v[206:209], v[234:237], v[96:99]
	v_mfma_f32_16x16x32_bf16 v[88:91], v[218:221], v[234:237], v[88:91]
	v_mfma_f32_16x16x32_bf16 v[80:83], v[206:209], v[242:245], v[80:83]
	v_mfma_f32_16x16x32_bf16 v[72:75], v[218:221], v[242:245], v[72:75]
	v_mfma_f32_16x16x32_bf16 v[68:71], v[206:209], v[250:253], v[68:71]
	v_mfma_f32_16x16x32_bf16 v[64:67], v[218:221], v[250:253], v[64:67]
	s_barrier
; #define PG8_STAGE(bufoff, gbase, voff) do { _Pragma("unroll") for (int _i = 0; _i < 2; ++_i) \
;         __builtin_amdgcn_global_load_lds((const unsigned*)((const char*)(gbase) + (voff)[_i]), (PG8_LAS unsigned*)(lds + (bufoff) + ldsw + _i * 8192), 16, 0, 0); } while (0)
; #define PG8_LDA(dst, b, h) do { _Pragma("unroll") for (int m = 0; m < 4; ++m) _Pragma("unroll") for (int k = 0; k < 2; ++k) dst[m][k] = *(const PG8_LAS bf16x8*)(lds + PG8_SA(b, h) + aoff + m * 2048 + k * 1024); } while (0)
; #define PG8_MMA(ai, bj, At, Bt) do { __builtin_amdgcn_s_setprio(1); _Pragma("unroll") for (int m = 0; m < 4; ++m) _Pragma("unroll") for (int n = 0; n < 2; ++n) _Pragma("unroll") for (int k = 0; k < 2; ++k) \
;         acc[ai][bj][m][n] = __builtin_amdgcn_mfma_f32_16x16x32_bf16(Bt[n][k], At[m][k], acc[ai][bj][m][n], 0, 0, 0); __builtin_amdgcn_s_setprio(0); } while (0)
; #define PG8_WAIT_V(n) asm volatile("s_waitcnt vmcnt(" #n ")" ::: "memory")
; #define PG8_WAIT_L(n) asm volatile("s_waitcnt lgkmcnt(" #n ")" ::: "memory")
; #define PG8_BAR __builtin_amdgcn_s_barrier()
; #define PG8_SCHED __builtin_amdgcn_sched_barrier(0)
; template <class Epi, class Sched, bool ALIGN_EPI = false, bool SP2 = false>
; __device__ __forceinline__ void gemm_phase(PG8_LAS unsigned char* lds, const Gemm g, const Sched& S, const Epi& E) {
;     ...
;             PG8_LDA(At, 1, 1); PG8_STAGE(PG8_SB(1, 0), b3, voffB); PG8_STAGE(PG8_SB(1, 1), b3 + hstep, voffB); PG8_STAGE(PG8_SA(1, 0), a3, voffA);
;             PG8_WAIT_V(8); PG8_WAIT_L(0); PG8_BAR; PG8_MMA(1, 0, At, B0); PG8_MMA(1, 1, At, B1); PG8_BAR; PG8_SCHED;
;     ...
;         if constexpr (ALIGN_EPI) { if (wr == 0) PG8_BAR; }
	s_setprio 0
	s_add_i32 s30, s49, s34
	v_lshl_add_u64 v[172:173], v[172:173], 0, s[10:11]
	s_mov_b32 m0, s30
	ds_read_b128 v[222:225], v214 offset:49152
	ds_read_b128 v[226:229], v214 offset:50176
	ds_read_b128 v[230:233], v214 offset:51200
	ds_read_b128 v[234:237], v214 offset:52224
	ds_read_b128 v[238:241], v214 offset:53248
	ds_read_b128 v[242:245], v214 offset:54272
	ds_read_b128 v[246:249], v214 offset:55296
	ds_read_b128 v[250:253], v214 offset:56320
	global_load_lds_dwordx4 v[172:173], off
	s_add_i32 m0, s30, 0x2000
	s_add_u32 s28, s28, 0x80080
	v_lshl_add_u64 v[172:173], v[176:177], 0, s[10:11]
	s_addc_u32 s29, s29, 0
	s_add_i32 s30, s50, s34
	global_load_lds_dwordx4 v[172:173], off
	s_mov_b32 m0, s30
	v_lshl_add_u64 v[172:173], s[28:29], 0, v[146:147]
	global_load_lds_dwordx4 v[172:173], off
	s_add_i32 m0, s30, 0x2000
	v_lshl_add_u64 v[172:173], s[28:29], 0, v[150:151]
	global_load_lds_dwordx4 v[172:173], off
	s_mov_b32 m0, s43
	v_lshl_add_u64 v[172:173], v[180:181], 0, s[10:11]
	global_load_lds_dwordx4 v[172:173], off
	s_mov_b32 m0, s46
	v_lshl_add_u64 v[172:173], v[188:189], 0, s[10:11]
	global_load_lds_dwordx4 v[172:173], off
	s_waitcnt vmcnt(8) lgkmcnt(0)
	s_setprio 1
	s_barrier
	v_mfma_f32_16x16x32_bf16 v[60:63], v[128:131], v[222:225], v[60:63]
	v_mfma_f32_16x16x32_bf16 v[56:59], v[136:139], v[222:225], v[56:59]
	v_mfma_f32_16x16x32_bf16 v[52:55], v[128:131], v[230:233], v[52:55]
	v_mfma_f32_16x16x32_bf16 v[44:47], v[136:139], v[230:233], v[44:47]
	v_mfma_f32_16x16x32_bf16 v[36:39], v[128:131], v[238:241], v[36:39]
	v_mfma_f32_16x16x32_bf16 v[28:31], v[136:139], v[238:241], v[28:31]
	v_mfma_f32_16x16x32_bf16 v[20:23], v[128:131], v[246:249], v[20:23]
	v_mfma_f32_16x16x32_bf16 v[12:15], v[136:139], v[246:249], v[12:15]
	v_mfma_f32_16x16x32_bf16 v[60:63], v[132:135], v[226:229], v[60:63]
	v_mfma_f32_16x16x32_bf16 v[56:59], v[140:143], v[226:229], v[56:59]
	v_mfma_f32_16x16x32_bf16 v[52:55], v[132:135], v[234:237], v[52:55]
	v_mfma_f32_16x16x32_bf16 v[44:47], v[140:143], v[234:237], v[44:47]
	v_mfma_f32_16x16x32_bf16 v[36:39], v[132:135], v[242:245], v[36:39]
	v_mfma_f32_16x16x32_bf16 v[28:31], v[140:143], v[242:245], v[28:31]
	v_mfma_f32_16x16x32_bf16 v[20:23], v[132:135], v[250:253], v[20:23]
	v_mfma_f32_16x16x32_bf16 v[12:15], v[140:143], v[250:253], v[12:15]
	v_mfma_f32_16x16x32_bf16 v[48:51], v[184:187], v[222:225], v[48:51]
	v_mfma_f32_16x16x32_bf16 v[40:43], v[210:213], v[222:225], v[40:43]
	v_mfma_f32_16x16x32_bf16 v[32:35], v[184:187], v[230:233], v[32:35]
	v_mfma_f32_16x16x32_bf16 v[24:27], v[210:213], v[230:233], v[24:27]
	v_mfma_f32_16x16x32_bf16 v[16:19], v[184:187], v[238:241], v[16:19]
	v_mfma_f32_16x16x32_bf16 v[8:11], v[210:213], v[238:241], v[8:11]
	v_mfma_f32_16x16x32_bf16 v[4:7], v[184:187], v[246:249], v[4:7]
	v_mfma_f32_16x16x32_bf16 v[0:3], v[210:213], v[246:249], v[0:3]
	v_mfma_f32_16x16x32_bf16 v[48:51], v[206:209], v[226:229], v[48:51]
	v_mfma_f32_16x16x32_bf16 v[40:43], v[218:221], v[226:229], v[40:43]
	v_mfma_f32_16x16x32_bf16 v[32:35], v[206:209], v[234:237], v[32:35]
	v_mfma_f32_16x16x32_bf16 v[24:27], v[218:221], v[234:237], v[24:27]
	v_mfma_f32_16x16x32_bf16 v[16:19], v[206:209], v[242:245], v[16:19]
	v_mfma_f32_16x16x32_bf16 v[8:11], v[218:221], v[242:245], v[8:11]
	v_mfma_f32_16x16x32_bf16 v[4:7], v[206:209], v[250:253], v[4:7]
	v_mfma_f32_16x16x32_bf16 v[0:3], v[218:221], v[250:253], v[0:3]
	s_barrier
	s_setprio 0
	s_add_i32 s48, s48, 2
	s_add_u32 s0, s0, 0x100
	s_addc_u32 s1, s1, 0
	s_add_u32 s44, s44, 0x100
	s_addc_u32 s45, s45, 0
	s_cmp_gt_u32 s48, 29
	s_cbranch_scc0 .LBB0_491
	s_and_b64 vcc, exec, s[12:13]
	s_cbranch_vccz .LBB0_494
	s_barrier

; #define PG8_STAGE(bufoff, gbase, voff) do { _Pragma("unroll") for (int _i = 0; _i < 2; ++_i) \
;         __builtin_amdgcn_global_load_lds((const unsigned*)((const char*)(gbase) + (voff)[_i]), (PG8_LAS unsigned*)(lds + (bufoff) + ldsw + _i * 8192), 16, 0, 0); } while (0)
; #define PG8_LDA(dst, b, h) do { _Pragma("unroll") for (int m = 0; m < 4; ++m) _Pragma("unroll") for (int k = 0; k < 2; ++k) dst[m][k] = *(const PG8_LAS bf16x8*)(lds + PG8_SA(b, h) + aoff + m * 2048 + k * 1024); } while (0)
; #define PG8_LDB(dst, b, h) do { _Pragma("unroll") for (int n = 0; n < 2; ++n) _Pragma("unroll") for (int k = 0; k < 2; ++k) dst[n][k] = *(const PG8_LAS bf16x8*)(lds + PG8_SB(b, h) + boff + n * 2048 + k * 1024); } while (0)
; #define PG8_WAIT_V(n) asm volatile("s_waitcnt vmcnt(" #n ")" ::: "memory")
; #define PG8_WAIT_L(n) asm volatile("s_waitcnt lgkmcnt(" #n ")" ::: "memory")
; #define PG8_BAR __builtin_amdgcn_s_barrier()
; #define PG8_SCHED __builtin_amdgcn_sched_barrier(0)
; template <class Epi, class Sched, bool ALIGN_EPI = false, bool SP2 = false>
; __device__ __forceinline__ void gemm_phase(PG8_LAS unsigned char* lds, const Gemm g, const Sched& S, const Epi& E) {
;     ...
;         const bool has_next = S.next(ui + 1, nxt);
;         const char* nA = has_next ? (const char*)g.A + (size_t)nxt.pm * tstep : cA; const char* nB = has_next ? (const char*)g.Bt + (size_t)nxt.pn * tstep : cB;
;         for (int t = 0; t < nt; t += 2) {
;             const bool last = (t == nt - 2);
;             const char* a1 = cA + (size_t)(t + 1) * kstep;
;             const char* a2 = last ? nA : cA + (size_t)(t + 2) * kstep; const char* b2 = last ? nB : cB + (size_t)(t + 2) * kstep;
;             const char* a3 = a2 + kstep; const char* b3 = b2 + kstep;
;             if (last && has_next) S.a_ready(nxt);
;             if constexpr (SP2) {
;             PG8_LDB(B0, 0, 0); PG8_LDB(B1, 0, 1); PG8_SCHED; PG8_LDA(At, 0, 0); PG8_STAGE(PG8_SA(1, 1), a1 + hstep, voffA);
;             PG8_WAIT_V(8); PG8_WAIT_L(0); PG8_BAR; PG8_MMA(0, 0, At, B0); PG8_MMA(0, 1, At, B1); PG8_BAR; PG8_SCHED;
;             PG8_LDA(At, 0, 1); PG8_STAGE(PG8_SB(0, 0), b2, voffB); PG8_STAGE(PG8_SB(0, 1), b2 + hstep, voffB); PG8_STAGE(PG8_SA(0, 0), a2, voffA);
;             PG8_WAIT_V(8); PG8_WAIT_L(0); PG8_BAR; PG8_MMA(1, 0, At, B0); PG8_MMA(1, 1, At, B1); PG8_BAR; PG8_SCHED;
.LBB0_762:
	s_ashr_i32 s21, s20, 31
	s_lshl_b64 s[22:23], s[20:21], 21
	s_add_u32 s22, s60, s22
	s_addc_u32 s23, s61, s23
	s_and_b64 s[24:25], s[4:5], exec
	s_cselect_b32 s7, s23, s27
	s_cselect_b32 s21, s22, s26
	s_ashr_i32 s19, s18, 31
	s_lshl_b64 s[24:25], s[18:19], 21
	v_readlane_b32 s30, v254, 32
	v_readlane_b32 s31, v254, 33
	s_add_u32 s24, s30, s24
	s_addc_u32 s25, s31, s25
	s_and_b64 s[30:31], s[4:5], exec
	s_cselect_b32 s19, s25, s29
	s_cselect_b32 s48, s24, s28
	s_add_u32 s26, s26, 0x100080
	s_addc_u32 s27, s27, 0
	s_add_u32 s49, s28, 0x100
	s_addc_u32 s52, s29, 0
	s_mov_b32 s53, -2
	s_waitcnt lgkmcnt(0)
	ds_read_b128 v[128:131], v181
	ds_read_b128 v[132:135], v181 offset:1024
	ds_read_b128 v[136:139], v181 offset:2048
	ds_read_b128 v[140:143], v181 offset:3072
	ds_read_b128 v[144:147], v182
	ds_read_b128 v[148:151], v182 offset:1024
	ds_read_b128 v[168:171], v182 offset:2048
	ds_read_b128 v[172:175], v182 offset:3072
	s_add_u32 s28, s26, 0xfff00080
	s_addc_u32 s29, s27, -1
	s_cmp_eq_u32 s53, 60
	s_cselect_b32 s31, s7, s29
	s_cselect_b32 s30, s21, s28
	s_cselect_b32 s29, s19, s52
	s_cselect_b32 s28, s48, s49
	v_lshl_add_u64 v[176:177], s[26:27], 0, v[160:161]
	s_add_i32 m0, s35, 0xc000
	ds_read_b128 v[186:189], v183
	ds_read_b128 v[190:193], v183 offset:1024
	ds_read_b128 v[198:201], v183 offset:2048
	ds_read_b128 v[202:205], v183 offset:3072
	ds_read_b128 v[206:209], v183 offset:4096
	ds_read_b128 v[210:213], v183 offset:5120
	ds_read_b128 v[214:217], v183 offset:6144
	ds_read_b128 v[218:221], v183 offset:7168
	global_load_lds_dwordx4 v[176:177], off
	s_add_i32 m0, s35, 0xe000
	v_lshl_add_u64 v[176:177], s[26:27], 0, v[162:163]
	global_load_lds_dwordx4 v[176:177], off
	s_waitcnt lgkmcnt(0)
	s_setprio 1
	s_barrier
	v_mfma_f32_16x16x32_bf16 v[124:127], v[128:131], v[186:189], 0
	v_mfma_f32_16x16x32_bf16 v[120:123], v[136:139], v[186:189], 0
	v_mfma_f32_16x16x32_bf16 v[104:107], v[128:131], v[198:201], 0
	v_mfma_f32_16x16x32_bf16 v[108:111], v[136:139], v[198:201], 0
	v_mfma_f32_16x16x32_bf16 v[88:91], v[128:131], v[206:209], 0
	v_mfma_f32_16x16x32_bf16 v[92:95], v[136:139], v[206:209], 0
	v_mfma_f32_16x16x32_bf16 v[72:75], v[128:131], v[214:217], 0
	v_mfma_f32_16x16x32_bf16 v[76:79], v[136:139], v[214:217], 0
	v_mfma_f32_16x16x32_bf16 v[124:127], v[132:135], v[190:193], v[124:127]
	v_mfma_f32_16x16x32_bf16 v[120:123], v[140:143], v[190:193], v[120:123]
	v_mfma_f32_16x16x32_bf16 v[104:107], v[132:135], v[202:205], v[104:107]
	v_mfma_f32_16x16x32_bf16 v[108:111], v[140:143], v[202:205], v[108:111]
	v_mfma_f32_16x16x32_bf16 v[88:91], v[132:135], v[210:213], v[88:91]
	v_mfma_f32_16x16x32_bf16 v[92:95], v[140:143], v[210:213], v[92:95]
	v_mfma_f32_16x16x32_bf16 v[72:75], v[132:135], v[218:221], v[72:75]
	v_mfma_f32_16x16x32_bf16 v[76:79], v[140:143], v[218:221], v[76:79]
	v_mfma_f32_16x16x32_bf16 v[116:119], v[144:147], v[186:189], 0
	v_mfma_f32_16x16x32_bf16 v[112:115], v[168:171], v[186:189], 0
	v_mfma_f32_16x16x32_bf16 v[100:103], v[144:147], v[198:201], 0
	v_mfma_f32_16x16x32_bf16 v[96:99], v[168:171], v[198:201], 0
	v_mfma_f32_16x16x32_bf16 v[84:87], v[144:147], v[206:209], 0
	v_mfma_f32_16x16x32_bf16 v[80:83], v[168:171], v[206:209], 0
	v_mfma_f32_16x16x32_bf16 v[68:71], v[144:147], v[214:217], 0
	v_mfma_f32_16x16x32_bf16 v[64:67], v[168:171], v[214:217], 0
	v_mfma_f32_16x16x32_bf16 v[116:119], v[148:151], v[190:193], v[116:119]
	v_mfma_f32_16x16x32_bf16 v[112:115], v[172:175], v[190:193], v[112:115]
	v_mfma_f32_16x16x32_bf16 v[100:103], v[148:151], v[202:205], v[100:103]
	v_mfma_f32_16x16x32_bf16 v[96:99], v[172:175], v[202:205], v[96:99]
	v_mfma_f32_16x16x32_bf16 v[84:87], v[148:151], v[210:213], v[84:87]
	v_mfma_f32_16x16x32_bf16 v[80:83], v[172:175], v[210:213], v[80:83]
	v_mfma_f32_16x16x32_bf16 v[68:71], v[148:151], v[218:221], v[68:71]
	v_mfma_f32_16x16x32_bf16 v[64:67], v[172:175], v[218:221], v[64:67]
	s_barrier
	s_setprio 0
	s_add_i32 s54, s47, s34
	v_lshl_add_u64 v[176:177], s[28:29], 0, v[154:155]
	s_mov_b32 m0, s54
	ds_read_b128 v[186:189], v183 offset:16384
	ds_read_b128 v[190:193], v183 offset:17408
	ds_read_b128 v[198:201], v183 offset:18432
	ds_read_b128 v[202:205], v183 offset:19456
	ds_read_b128 v[206:209], v183 offset:20480
	ds_read_b128 v[210:213], v183 offset:21504
	ds_read_b128 v[214:217], v183 offset:22528
	ds_read_b128 v[218:221], v183 offset:23552
	global_load_lds_dwordx4 v[176:177], off
	s_add_i32 m0, s54, 0x2000
	s_add_u32 s54, s28, 0x100000
	v_lshl_add_u64 v[194:195], s[28:29], 0, v[158:159]
	s_addc_u32 s55, s29, 0
	s_add_i32 s56, s50, s34
	global_load_lds_dwordx4 v[194:195], off
	v_lshl_add_u64 v[222:223], s[54:55], 0, v[154:155]
	s_mov_b32 m0, s56
	v_lshl_add_u64 v[224:225], s[30:31], 0, v[156:157]
	global_load_lds_dwordx4 v[222:223], off
	s_add_i32 m0, s56, 0x2000
	v_lshl_add_u64 v[222:223], s[54:55], 0, v[158:159]
	global_load_lds_dwordx4 v[222:223], off
	s_mov_b32 m0, s35
	v_lshl_add_u64 v[222:223], s[30:31], 0, v[152:153]
	global_load_lds_dwordx4 v[222:223], off
	s_mov_b32 m0, s33
	s_nop 0
	global_load_lds_dwordx4 v[224:225], off
	s_waitcnt lgkmcnt(0)
	s_setprio 1
	s_barrier
; #define PG8_STAGE(bufoff, gbase, voff) do { _Pragma("unroll") for (int _i = 0; _i < 2; ++_i) \
;         __builtin_amdgcn_global_load_lds((const unsigned*)((const char*)(gbase) + (voff)[_i]), (PG8_LAS unsigned*)(lds + (bufoff) + ldsw + _i * 8192), 16, 0, 0); } while (0)
; #define PG8_LDA(dst, b, h) do { _Pragma("unroll") for (int m = 0; m < 4; ++m) _Pragma("unroll") for (int k = 0; k < 2; ++k) dst[m][k] = *(const PG8_LAS bf16x8*)(lds + PG8_SA(b, h) + aoff + m * 2048 + k * 1024); } while (0)
; #define PG8_LDB(dst, b, h) do { _Pragma("unroll") for (int n = 0; n < 2; ++n) _Pragma("unroll") for (int k = 0; k < 2; ++k) dst[n][k] = *(const PG8_LAS bf16x8*)(lds + PG8_SB(b, h) + boff + n * 2048 + k * 1024); } while (0)
; #define PG8_MMA(ai, bj, At, Bt) do { __builtin_amdgcn_s_setprio(1); _Pragma("unroll") for (int m = 0; m < 4; ++m) _Pragma("unroll") for (int n = 0; n < 2; ++n) _Pragma("unroll") for (int k = 0; k < 2; ++k) \
;         acc[ai][bj][m][n] = __builtin_amdgcn_mfma_f32_16x16x32_bf16(Bt[n][k], At[m][k], acc[ai][bj][m][n], 0, 0, 0); __builtin_amdgcn_s_setprio(0); } while (0)
; #define PG8_WAIT_V(n) asm volatile("s_waitcnt vmcnt(" #n ")" ::: "memory")
; #define PG8_WAIT_L(n) asm volatile("s_waitcnt lgkmcnt(" #n ")" ::: "memory")
; #define PG8_BAR __builtin_amdgcn_s_barrier()
; #define PG8_SCHED __builtin_amdgcn_sched_barrier(0)
; template <class Epi, class Sched, bool ALIGN_EPI = false, bool SP2 = false>
; __device__ __forceinline__ void gemm_phase(PG8_LAS unsigned char* lds, const Gemm g, const Sched& S, const Epi& E) {
;     ...
;             PG8_WAIT_V(8); PG8_WAIT_L(0); PG8_BAR; PG8_MMA(1, 0, At, B0); PG8_MMA(1, 1, At, B1); PG8_BAR; PG8_SCHED;
;             PG8_LDB(B0, 1, 0); PG8_LDB(B1, 1, 1); PG8_SCHED; PG8_LDA(At, 1, 0); PG8_STAGE(PG8_SA(0, 1), a2 + hstep, voffA);
;             PG8_WAIT_V(8); PG8_WAIT_L(0); PG8_BAR; PG8_MMA(0, 0, At, B0); PG8_MMA(0, 1, At, B1); PG8_BAR; PG8_SCHED;
	v_mfma_f32_16x16x32_bf16 v[56:59], v[128:131], v[186:189], 0
	v_mfma_f32_16x16x32_bf16 v[60:63], v[136:139], v[186:189], 0
	v_mfma_f32_16x16x32_bf16 v[40:43], v[128:131], v[198:201], 0
	v_mfma_f32_16x16x32_bf16 v[44:47], v[136:139], v[198:201], 0
	v_mfma_f32_16x16x32_bf16 v[24:27], v[128:131], v[206:209], 0
	v_mfma_f32_16x16x32_bf16 v[28:31], v[136:139], v[206:209], 0
	v_mfma_f32_16x16x32_bf16 v[8:11], v[128:131], v[214:217], 0
	v_mfma_f32_16x16x32_bf16 v[12:15], v[136:139], v[214:217], 0
	v_mfma_f32_16x16x32_bf16 v[56:59], v[132:135], v[190:193], v[56:59]
	v_mfma_f32_16x16x32_bf16 v[60:63], v[140:143], v[190:193], v[60:63]
	v_mfma_f32_16x16x32_bf16 v[40:43], v[132:135], v[202:205], v[40:43]
	v_mfma_f32_16x16x32_bf16 v[44:47], v[140:143], v[202:205], v[44:47]
	v_mfma_f32_16x16x32_bf16 v[24:27], v[132:135], v[210:213], v[24:27]
	v_mfma_f32_16x16x32_bf16 v[28:31], v[140:143], v[210:213], v[28:31]
	v_mfma_f32_16x16x32_bf16 v[8:11], v[132:135], v[218:221], v[8:11]
	v_mfma_f32_16x16x32_bf16 v[12:15], v[140:143], v[218:221], v[12:15]
	v_mfma_f32_16x16x32_bf16 v[52:55], v[144:147], v[186:189], 0
	v_mfma_f32_16x16x32_bf16 v[48:51], v[168:171], v[186:189], 0
	v_mfma_f32_16x16x32_bf16 v[36:39], v[144:147], v[198:201], 0
	v_mfma_f32_16x16x32_bf16 v[32:35], v[168:171], v[198:201], 0
	v_mfma_f32_16x16x32_bf16 v[20:23], v[144:147], v[206:209], 0
	v_mfma_f32_16x16x32_bf16 v[16:19], v[168:171], v[206:209], 0
	v_mfma_f32_16x16x32_bf16 v[4:7], v[144:147], v[214:217], 0
	v_mfma_f32_16x16x32_bf16 v[0:3], v[168:171], v[214:217], 0
	v_mfma_f32_16x16x32_bf16 v[52:55], v[148:151], v[190:193], v[52:55]
	v_mfma_f32_16x16x32_bf16 v[48:51], v[172:175], v[190:193], v[48:51]
	v_mfma_f32_16x16x32_bf16 v[36:39], v[148:151], v[202:205], v[36:39]
	v_mfma_f32_16x16x32_bf16 v[32:35], v[172:175], v[202:205], v[32:35]
	v_mfma_f32_16x16x32_bf16 v[20:23], v[148:151], v[210:213], v[20:23]
	v_mfma_f32_16x16x32_bf16 v[16:19], v[172:175], v[210:213], v[16:19]
	v_mfma_f32_16x16x32_bf16 v[4:7], v[148:151], v[218:221], v[4:7]
	v_mfma_f32_16x16x32_bf16 v[0:3], v[172:175], v[218:221], v[0:3]
	s_barrier
	s_setprio 0
	s_add_i32 s54, 0, 0x18000
	s_add_i32 s55, 0, 0x1c000
	v_add_u32_e32 v140, s54, v179
	v_add_u32_e32 v172, s55, v179
	ds_read_b128 v[128:131], v140
	ds_read_b128 v[132:135], v140 offset:1024
	ds_read_b128 v[136:139], v140 offset:2048
	ds_read_b128 v[140:143], v140 offset:3072
	ds_read_b128 v[144:147], v172
	ds_read_b128 v[148:151], v172 offset:1024
	ds_read_b128 v[168:171], v172 offset:2048
	ds_read_b128 v[172:175], v172 offset:3072
	s_add_u32 s30, s30, 0x100000
	s_addc_u32 s31, s31, 0
	s_mov_b32 m0, s37
	v_lshl_add_u64 v[226:227], s[30:31], 0, v[152:153]
	ds_read_b128 v[186:189], v183 offset:32768
	ds_read_b128 v[190:193], v183 offset:33792
	ds_read_b128 v[198:201], v183 offset:34816
	ds_read_b128 v[202:205], v183 offset:35840
	ds_read_b128 v[206:209], v183 offset:36864
	ds_read_b128 v[210:213], v183 offset:37888
	ds_read_b128 v[214:217], v183 offset:38912
	ds_read_b128 v[218:221], v183 offset:39936
	global_load_lds_dwordx4 v[226:227], off
	s_mov_b32 m0, s39
	v_lshl_add_u64 v[226:227], s[30:31], 0, v[156:157]
	global_load_lds_dwordx4 v[226:227], off
	s_waitcnt vmcnt(8) lgkmcnt(0)
	s_setprio 1
	s_barrier
	v_mfma_f32_16x16x32_bf16 v[124:127], v[128:131], v[186:189], v[124:127]
	v_mfma_f32_16x16x32_bf16 v[120:123], v[136:139], v[186:189], v[120:123]
	v_mfma_f32_16x16x32_bf16 v[104:107], v[128:131], v[198:201], v[104:107]
	v_mfma_f32_16x16x32_bf16 v[108:111], v[136:139], v[198:201], v[108:111]
	v_mfma_f32_16x16x32_bf16 v[88:91], v[128:131], v[206:209], v[88:91]
	v_mfma_f32_16x16x32_bf16 v[92:95], v[136:139], v[206:209], v[92:95]
	v_mfma_f32_16x16x32_bf16 v[72:75], v[128:131], v[214:217], v[72:75]
	v_mfma_f32_16x16x32_bf16 v[76:79], v[136:139], v[214:217], v[76:79]
	v_mfma_f32_16x16x32_bf16 v[124:127], v[132:135], v[190:193], v[124:127]
	v_mfma_f32_16x16x32_bf16 v[120:123], v[140:143], v[190:193], v[120:123]
	v_mfma_f32_16x16x32_bf16 v[104:107], v[132:135], v[202:205], v[104:107]
	v_mfma_f32_16x16x32_bf16 v[108:111], v[140:143], v[202:205], v[108:111]
	v_mfma_f32_16x16x32_bf16 v[88:91], v[132:135], v[210:213], v[88:91]
	v_mfma_f32_16x16x32_bf16 v[92:95], v[140:143], v[210:213], v[92:95]
	v_mfma_f32_16x16x32_bf16 v[72:75], v[132:135], v[218:221], v[72:75]
	v_mfma_f32_16x16x32_bf16 v[76:79], v[140:143], v[218:221], v[76:79]
	v_mfma_f32_16x16x32_bf16 v[116:119], v[144:147], v[186:189], v[116:119]
	v_mfma_f32_16x16x32_bf16 v[112:115], v[168:171], v[186:189], v[112:115]
	v_mfma_f32_16x16x32_bf16 v[100:103], v[144:147], v[198:201], v[100:103]
	v_mfma_f32_16x16x32_bf16 v[96:99], v[168:171], v[198:201], v[96:99]
	v_mfma_f32_16x16x32_bf16 v[84:87], v[144:147], v[206:209], v[84:87]
	v_mfma_f32_16x16x32_bf16 v[80:83], v[168:171], v[206:209], v[80:83]
	v_mfma_f32_16x16x32_bf16 v[68:71], v[144:147], v[214:217], v[68:71]
	v_mfma_f32_16x16x32_bf16 v[64:67], v[168:171], v[214:217], v[64:67]
	v_mfma_f32_16x16x32_bf16 v[116:119], v[148:151], v[190:193], v[116:119]
	v_mfma_f32_16x16x32_bf16 v[112:115], v[172:175], v[190:193], v[112:115]
	v_mfma_f32_16x16x32_bf16 v[100:103], v[148:151], v[202:205], v[100:103]
	v_mfma_f32_16x16x32_bf16 v[96:99], v[172:175], v[202:205], v[96:99]
	v_mfma_f32_16x16x32_bf16 v[84:87], v[148:151], v[210:213], v[84:87]
	v_mfma_f32_16x16x32_bf16 v[80:83], v[172:175], v[210:213], v[80:83]
	v_mfma_f32_16x16x32_bf16 v[68:71], v[148:151], v[218:221], v[68:71]
	v_mfma_f32_16x16x32_bf16 v[64:67], v[172:175], v[218:221], v[64:67]
	s_barrier
; #define PG8_STAGE(bufoff, gbase, voff) do { _Pragma("unroll") for (int _i = 0; _i < 2; ++_i) \
;         __builtin_amdgcn_global_load_lds((const unsigned*)((const char*)(gbase) + (voff)[_i]), (PG8_LAS unsigned*)(lds + (bufoff) + ldsw + _i * 8192), 16, 0, 0); } while (0)
; #define PG8_LDA(dst, b, h) do { _Pragma("unroll") for (int m = 0; m < 4; ++m) _Pragma("unroll") for (int k = 0; k < 2; ++k) dst[m][k] = *(const PG8_LAS bf16x8*)(lds + PG8_SA(b, h) + aoff + m * 2048 + k * 1024); } while (0)
; #define PG8_LDB(dst, b, h) do { _Pragma("unroll") for (int n = 0; n < 2; ++n) _Pragma("unroll") for (int k = 0; k < 2; ++k) dst[n][k] = *(const PG8_LAS bf16x8*)(lds + PG8_SB(b, h) + boff + n * 2048 + k * 1024); } while (0)
; template <class Epi, class Sched, bool ALIGN_EPI = false, bool SP2 = false>
; __device__ __forceinline__ void gemm_phase(PG8_LAS unsigned char* lds, const Gemm g, const Sched& S, const Epi& E) {
;     ...
;         for (int t = 0; t < nt; t += 2) {
;             const bool last = (t == nt - 2);
;             const char* a1 = cA + (size_t)(t + 1) * kstep;
;             const char* a2 = last ? nA : cA + (size_t)(t + 2) * kstep; const char* b2 = last ? nB : cB + (size_t)(t + 2) * kstep;
;             const char* a3 = a2 + kstep; const char* b3 = b2 + kstep;
;             if (last && has_next) S.a_ready(nxt);
;             if constexpr (SP2) {
;             PG8_LDB(B0, 0, 0); PG8_LDB(B1, 0, 1); PG8_SCHED; PG8_LDA(At, 0, 0); PG8_STAGE(PG8_SA(1, 1), a1 + hstep, voffA);
;             PG8_WAIT_V(8); PG8_WAIT_L(0); PG8_BAR; PG8_MMA(0, 0, At, B0); PG8_MMA(0, 1, At, B1); PG8_BAR; PG8_SCHED;
;             PG8_LDA(At, 0, 1); PG8_STAGE(PG8_SB(0, 0), b2, voffB); PG8_STAGE(PG8_SB(0, 1), b2 + hstep, voffB); PG8_STAGE(PG8_SA(0, 0), a2, voffA);
;             PG8_WAIT_V(8); PG8_WAIT_L(0); PG8_BAR; PG8_MMA(1, 0, At, B0); PG8_MMA(1, 1, At, B1); PG8_BAR; PG8_SCHED;
;             PG8_LDB(B0, 1, 0); PG8_LDB(B1, 1, 1); PG8_SCHED; PG8_LDA(At, 1, 0); PG8_STAGE(PG8_SA(0, 1), a2 + hstep, voffA);
;             PG8_WAIT_V(8); PG8_WAIT_L(0); PG8_BAR; PG8_MMA(0, 0, At, B0); PG8_MMA(0, 1, At, B1); PG8_BAR; PG8_SCHED;
;             PG8_LDA(At, 1, 1); PG8_STAGE(PG8_SB(1, 0), b3, voffB); PG8_STAGE(PG8_SB(1, 1), b3 + hstep, voffB); PG8_STAGE(PG8_SA(1, 0), a3, voffA);
;             PG8_WAIT_V(8); PG8_WAIT_L(0); PG8_BAR; PG8_MMA(1, 0, At, B0); PG8_MMA(1, 1, At, B1); PG8_BAR; PG8_SCHED;
	s_setprio 0
	s_add_i32 s30, s54, s34
	v_lshl_add_u64 v[176:177], v[176:177], 0, s[12:13]
	s_mov_b32 m0, s30
	ds_read_b128 v[186:189], v183 offset:49152
	ds_read_b128 v[190:193], v183 offset:50176
	ds_read_b128 v[198:201], v183 offset:51200
	ds_read_b128 v[202:205], v183 offset:52224
	ds_read_b128 v[206:209], v183 offset:53248
	ds_read_b128 v[210:213], v183 offset:54272
	ds_read_b128 v[214:217], v183 offset:55296
	ds_read_b128 v[218:221], v183 offset:56320
	global_load_lds_dwordx4 v[176:177], off
	s_add_i32 m0, s30, 0x2000
	s_add_u32 s28, s28, 0x100080
	v_lshl_add_u64 v[176:177], v[194:195], 0, s[12:13]
	s_addc_u32 s29, s29, 0
	s_add_i32 s30, s55, s34
	global_load_lds_dwordx4 v[176:177], off
	s_mov_b32 m0, s30
	v_lshl_add_u64 v[176:177], s[28:29], 0, v[154:155]
	global_load_lds_dwordx4 v[176:177], off
	s_add_i32 m0, s30, 0x2000
	v_lshl_add_u64 v[176:177], s[28:29], 0, v[158:159]
	global_load_lds_dwordx4 v[176:177], off
	s_mov_b32 m0, s43
	v_lshl_add_u64 v[176:177], v[222:223], 0, s[12:13]
	global_load_lds_dwordx4 v[176:177], off
	s_mov_b32 m0, s44
	v_lshl_add_u64 v[176:177], v[224:225], 0, s[12:13]
	global_load_lds_dwordx4 v[176:177], off
	s_waitcnt vmcnt(8) lgkmcnt(0)
	s_setprio 1
	s_barrier
	v_mfma_f32_16x16x32_bf16 v[56:59], v[128:131], v[186:189], v[56:59]
	v_mfma_f32_16x16x32_bf16 v[60:63], v[136:139], v[186:189], v[60:63]
	v_mfma_f32_16x16x32_bf16 v[40:43], v[128:131], v[198:201], v[40:43]
	v_mfma_f32_16x16x32_bf16 v[44:47], v[136:139], v[198:201], v[44:47]
	v_mfma_f32_16x16x32_bf16 v[24:27], v[128:131], v[206:209], v[24:27]
	v_mfma_f32_16x16x32_bf16 v[28:31], v[136:139], v[206:209], v[28:31]
	v_mfma_f32_16x16x32_bf16 v[8:11], v[128:131], v[214:217], v[8:11]
	v_mfma_f32_16x16x32_bf16 v[12:15], v[136:139], v[214:217], v[12:15]
	v_mfma_f32_16x16x32_bf16 v[56:59], v[132:135], v[190:193], v[56:59]
	v_mfma_f32_16x16x32_bf16 v[60:63], v[140:143], v[190:193], v[60:63]
	v_mfma_f32_16x16x32_bf16 v[40:43], v[132:135], v[202:205], v[40:43]
	v_mfma_f32_16x16x32_bf16 v[44:47], v[140:143], v[202:205], v[44:47]
	v_mfma_f32_16x16x32_bf16 v[24:27], v[132:135], v[210:213], v[24:27]
	v_mfma_f32_16x16x32_bf16 v[28:31], v[140:143], v[210:213], v[28:31]
	v_mfma_f32_16x16x32_bf16 v[8:11], v[132:135], v[218:221], v[8:11]
	v_mfma_f32_16x16x32_bf16 v[12:15], v[140:143], v[218:221], v[12:15]
	v_mfma_f32_16x16x32_bf16 v[52:55], v[144:147], v[186:189], v[52:55]
	v_mfma_f32_16x16x32_bf16 v[48:51], v[168:171], v[186:189], v[48:51]
	v_mfma_f32_16x16x32_bf16 v[36:39], v[144:147], v[198:201], v[36:39]
	v_mfma_f32_16x16x32_bf16 v[32:35], v[168:171], v[198:201], v[32:35]
	v_mfma_f32_16x16x32_bf16 v[20:23], v[144:147], v[206:209], v[20:23]
	v_mfma_f32_16x16x32_bf16 v[16:19], v[168:171], v[206:209], v[16:19]
	v_mfma_f32_16x16x32_bf16 v[4:7], v[144:147], v[214:217], v[4:7]
	v_mfma_f32_16x16x32_bf16 v[0:3], v[168:171], v[214:217], v[0:3]
	v_mfma_f32_16x16x32_bf16 v[52:55], v[148:151], v[190:193], v[52:55]
	v_mfma_f32_16x16x32_bf16 v[48:51], v[172:175], v[190:193], v[48:51]
	v_mfma_f32_16x16x32_bf16 v[36:39], v[148:151], v[202:205], v[36:39]
	v_mfma_f32_16x16x32_bf16 v[32:35], v[172:175], v[202:205], v[32:35]
	v_mfma_f32_16x16x32_bf16 v[20:23], v[148:151], v[210:213], v[20:23]
	v_mfma_f32_16x16x32_bf16 v[16:19], v[172:175], v[210:213], v[16:19]
	v_mfma_f32_16x16x32_bf16 v[4:7], v[148:151], v[218:221], v[4:7]
	v_mfma_f32_16x16x32_bf16 v[0:3], v[172:175], v[218:221], v[0:3]
	s_barrier
	s_setprio 0
	s_add_i32 s53, s53, 2
	s_add_u32 s26, s26, 0x100
	s_addc_u32 s27, s27, 0
	s_add_u32 s49, s49, 0x100
	s_addc_u32 s52, s52, 0
.LBB0_763:
	ds_read_b128 v[128:131], v181
	ds_read_b128 v[132:135], v181 offset:1024
	ds_read_b128 v[136:139], v181 offset:2048
	ds_read_b128 v[140:143], v181 offset:3072
	ds_read_b128 v[144:147], v182
	ds_read_b128 v[148:151], v182 offset:1024
	ds_read_b128 v[168:171], v182 offset:2048
	ds_read_b128 v[172:175], v182 offset:3072
	s_add_u32 s28, s26, 0xfff00080
	s_addc_u32 s29, s27, -1
	s_cmp_eq_u32 s53, 60
	s_cselect_b32 s31, s7, s29
	s_cselect_b32 s30, s21, s28
	s_cselect_b32 s29, s19, s52
	s_cselect_b32 s28, s48, s49
	v_lshl_add_u64 v[176:177], s[26:27], 0, v[160:161]
	s_add_i32 m0, s35, 0xc000
	ds_read_b128 v[186:189], v183
	ds_read_b128 v[190:193], v183 offset:1024
	ds_read_b128 v[198:201], v183 offset:2048
	ds_read_b128 v[202:205], v183 offset:3072
	ds_read_b128 v[206:209], v183 offset:4096
	ds_read_b128 v[210:213], v183 offset:5120
	ds_read_b128 v[214:217], v183 offset:6144
	ds_read_b128 v[218:221], v183 offset:7168
	global_load_lds_dwordx4 v[176:177], off
	s_add_i32 m0, s35, 0xe000
	v_lshl_add_u64 v[176:177], s[26:27], 0, v[162:163]
	global_load_lds_dwordx4 v[176:177], off
	s_waitcnt vmcnt(8) lgkmcnt(0)
	s_setprio 1
	s_barrier
; #define PG8_STAGE(bufoff, gbase, voff) do { _Pragma("unroll") for (int _i = 0; _i < 2; ++_i) \
;         __builtin_amdgcn_global_load_lds((const unsigned*)((const char*)(gbase) + (voff)[_i]), (PG8_LAS unsigned*)(lds + (bufoff) + ldsw + _i * 8192), 16, 0, 0); } while (0)
; #define PG8_LDA(dst, b, h) do { _Pragma("unroll") for (int m = 0; m < 4; ++m) _Pragma("unroll") for (int k = 0; k < 2; ++k) dst[m][k] = *(const PG8_LAS bf16x8*)(lds + PG8_SA(b, h) + aoff + m * 2048 + k * 1024); } while (0)
; #define PG8_LDB(dst, b, h) do { _Pragma("unroll") for (int n = 0; n < 2; ++n) _Pragma("unroll") for (int k = 0; k < 2; ++k) dst[n][k] = *(const PG8_LAS bf16x8*)(lds + PG8_SB(b, h) + boff + n * 2048 + k * 1024); } while (0)
; #define PG8_MMA(ai, bj, At, Bt) do { __builtin_amdgcn_s_setprio(1); _Pragma("unroll") for (int m = 0; m < 4; ++m) _Pragma("unroll") for (int n = 0; n < 2; ++n) _Pragma("unroll") for (int k = 0; k < 2; ++k) \
;         acc[ai][bj][m][n] = __builtin_amdgcn_mfma_f32_16x16x32_bf16(Bt[n][k], At[m][k], acc[ai][bj][m][n], 0, 0, 0); __builtin_amdgcn_s_setprio(0); } while (0)
; #define PG8_WAIT_V(n) asm volatile("s_waitcnt vmcnt(" #n ")" ::: "memory")
; #define PG8_WAIT_L(n) asm volatile("s_waitcnt lgkmcnt(" #n ")" ::: "memory")
; #define PG8_BAR __builtin_amdgcn_s_barrier()
; #define PG8_SCHED __builtin_amdgcn_sched_barrier(0)
; template <class Epi, class Sched, bool ALIGN_EPI = false, bool SP2 = false>
; __device__ __forceinline__ void gemm_phase(PG8_LAS unsigned char* lds, const Gemm g, const Sched& S, const Epi& E) {
;     ...
;             PG8_LDB(B0, 0, 0); PG8_LDB(B1, 0, 1); PG8_SCHED; PG8_LDA(At, 0, 0); PG8_STAGE(PG8_SA(1, 1), a1 + hstep, voffA);
;             PG8_WAIT_V(8); PG8_WAIT_L(0); PG8_BAR; PG8_MMA(0, 0, At, B0); PG8_MMA(0, 1, At, B1); PG8_BAR; PG8_SCHED;
;             PG8_LDA(At, 0, 1); PG8_STAGE(PG8_SB(0, 0), b2, voffB); PG8_STAGE(PG8_SB(0, 1), b2 + hstep, voffB); PG8_STAGE(PG8_SA(0, 0), a2, voffA);
;             PG8_WAIT_V(8); PG8_WAIT_L(0); PG8_BAR; PG8_MMA(1, 0, At, B0); PG8_MMA(1, 1, At, B1); PG8_BAR; PG8_SCHED;
	v_mfma_f32_16x16x32_bf16 v[124:127], v[128:131], v[186:189], v[124:127]
	v_mfma_f32_16x16x32_bf16 v[120:123], v[136:139], v[186:189], v[120:123]
	v_mfma_f32_16x16x32_bf16 v[104:107], v[128:131], v[198:201], v[104:107]
	v_mfma_f32_16x16x32_bf16 v[108:111], v[136:139], v[198:201], v[108:111]
	v_mfma_f32_16x16x32_bf16 v[88:91], v[128:131], v[206:209], v[88:91]
	v_mfma_f32_16x16x32_bf16 v[92:95], v[136:139], v[206:209], v[92:95]
	v_mfma_f32_16x16x32_bf16 v[72:75], v[128:131], v[214:217], v[72:75]
	v_mfma_f32_16x16x32_bf16 v[76:79], v[136:139], v[214:217], v[76:79]
	v_mfma_f32_16x16x32_bf16 v[124:127], v[132:135], v[190:193], v[124:127]
	v_mfma_f32_16x16x32_bf16 v[120:123], v[140:143], v[190:193], v[120:123]
	v_mfma_f32_16x16x32_bf16 v[104:107], v[132:135], v[202:205], v[104:107]
	v_mfma_f32_16x16x32_bf16 v[108:111], v[140:143], v[202:205], v[108:111]
	v_mfma_f32_16x16x32_bf16 v[88:91], v[132:135], v[210:213], v[88:91]
	v_mfma_f32_16x16x32_bf16 v[92:95], v[140:143], v[210:213], v[92:95]
	v_mfma_f32_16x16x32_bf16 v[72:75], v[132:135], v[218:221], v[72:75]
	v_mfma_f32_16x16x32_bf16 v[76:79], v[140:143], v[218:221], v[76:79]
	v_mfma_f32_16x16x32_bf16 v[116:119], v[144:147], v[186:189], v[116:119]
	v_mfma_f32_16x16x32_bf16 v[112:115], v[168:171], v[186:189], v[112:115]
	v_mfma_f32_16x16x32_bf16 v[100:103], v[144:147], v[198:201], v[100:103]
	v_mfma_f32_16x16x32_bf16 v[96:99], v[168:171], v[198:201], v[96:99]
	v_mfma_f32_16x16x32_bf16 v[84:87], v[144:147], v[206:209], v[84:87]
	v_mfma_f32_16x16x32_bf16 v[80:83], v[168:171], v[206:209], v[80:83]
	v_mfma_f32_16x16x32_bf16 v[68:71], v[144:147], v[214:217], v[68:71]
	v_mfma_f32_16x16x32_bf16 v[64:67], v[168:171], v[214:217], v[64:67]
	v_mfma_f32_16x16x32_bf16 v[116:119], v[148:151], v[190:193], v[116:119]
	v_mfma_f32_16x16x32_bf16 v[112:115], v[172:175], v[190:193], v[112:115]
	v_mfma_f32_16x16x32_bf16 v[100:103], v[148:151], v[202:205], v[100:103]
	v_mfma_f32_16x16x32_bf16 v[96:99], v[172:175], v[202:205], v[96:99]
	v_mfma_f32_16x16x32_bf16 v[84:87], v[148:151], v[210:213], v[84:87]
	v_mfma_f32_16x16x32_bf16 v[80:83], v[172:175], v[210:213], v[80:83]
	v_mfma_f32_16x16x32_bf16 v[68:71], v[148:151], v[218:221], v[68:71]
	v_mfma_f32_16x16x32_bf16 v[64:67], v[172:175], v[218:221], v[64:67]
	s_barrier
	s_setprio 0
	s_add_i32 s54, s47, s34
	v_lshl_add_u64 v[176:177], s[28:29], 0, v[154:155]
	s_mov_b32 m0, s54
	ds_read_b128 v[186:189], v183 offset:16384
	ds_read_b128 v[190:193], v183 offset:17408
	ds_read_b128 v[198:201], v183 offset:18432
	ds_read_b128 v[202:205], v183 offset:19456
	ds_read_b128 v[206:209], v183 offset:20480
	ds_read_b128 v[210:213], v183 offset:21504
	ds_read_b128 v[214:217], v183 offset:22528
	ds_read_b128 v[218:221], v183 offset:23552
	global_load_lds_dwordx4 v[176:177], off
	s_add_i32 m0, s54, 0x2000
	s_add_u32 s54, s28, 0x100000
	v_lshl_add_u64 v[194:195], s[28:29], 0, v[158:159]
	s_addc_u32 s55, s29, 0
	s_add_i32 s56, s50, s34
	global_load_lds_dwordx4 v[194:195], off
	v_lshl_add_u64 v[222:223], s[54:55], 0, v[154:155]
	s_mov_b32 m0, s56
	v_lshl_add_u64 v[224:225], s[30:31], 0, v[156:157]
	global_load_lds_dwordx4 v[222:223], off
	s_add_i32 m0, s56, 0x2000
	v_lshl_add_u64 v[222:223], s[54:55], 0, v[158:159]
	global_load_lds_dwordx4 v[222:223], off
	s_mov_b32 m0, s35
	v_lshl_add_u64 v[222:223], s[30:31], 0, v[152:153]
	global_load_lds_dwordx4 v[222:223], off
	s_mov_b32 m0, s33
	s_nop 0
	global_load_lds_dwordx4 v[224:225], off
	s_waitcnt vmcnt(8) lgkmcnt(0)
	s_setprio 1
	s_barrier
	v_mfma_f32_16x16x32_bf16 v[56:59], v[128:131], v[186:189], v[56:59]
	v_mfma_f32_16x16x32_bf16 v[60:63], v[136:139], v[186:189], v[60:63]
	v_mfma_f32_16x16x32_bf16 v[40:43], v[128:131], v[198:201], v[40:43]
	v_mfma_f32_16x16x32_bf16 v[44:47], v[136:139], v[198:201], v[44:47]
	v_mfma_f32_16x16x32_bf16 v[24:27], v[128:131], v[206:209], v[24:27]
	v_mfma_f32_16x16x32_bf16 v[28:31], v[136:139], v[206:209], v[28:31]
	v_mfma_f32_16x16x32_bf16 v[8:11], v[128:131], v[214:217], v[8:11]
	v_mfma_f32_16x16x32_bf16 v[12:15], v[136:139], v[214:217], v[12:15]
	v_mfma_f32_16x16x32_bf16 v[56:59], v[132:135], v[190:193], v[56:59]
	v_mfma_f32_16x16x32_bf16 v[60:63], v[140:143], v[190:193], v[60:63]
	v_mfma_f32_16x16x32_bf16 v[40:43], v[132:135], v[202:205], v[40:43]
	v_mfma_f32_16x16x32_bf16 v[44:47], v[140:143], v[202:205], v[44:47]
	v_mfma_f32_16x16x32_bf16 v[24:27], v[132:135], v[210:213], v[24:27]
	v_mfma_f32_16x16x32_bf16 v[28:31], v[140:143], v[210:213], v[28:31]
	v_mfma_f32_16x16x32_bf16 v[8:11], v[132:135], v[218:221], v[8:11]
	v_mfma_f32_16x16x32_bf16 v[12:15], v[140:143], v[218:221], v[12:15]
	v_mfma_f32_16x16x32_bf16 v[52:55], v[144:147], v[186:189], v[52:55]
	v_mfma_f32_16x16x32_bf16 v[48:51], v[168:171], v[186:189], v[48:51]
	v_mfma_f32_16x16x32_bf16 v[36:39], v[144:147], v[198:201], v[36:39]
	v_mfma_f32_16x16x32_bf16 v[32:35], v[168:171], v[198:201], v[32:35]
	v_mfma_f32_16x16x32_bf16 v[20:23], v[144:147], v[206:209], v[20:23]
	v_mfma_f32_16x16x32_bf16 v[16:19], v[168:171], v[206:209], v[16:19]
	v_mfma_f32_16x16x32_bf16 v[4:7], v[144:147], v[214:217], v[4:7]
	v_mfma_f32_16x16x32_bf16 v[0:3], v[168:171], v[214:217], v[0:3]
	v_mfma_f32_16x16x32_bf16 v[52:55], v[148:151], v[190:193], v[52:55]
	v_mfma_f32_16x16x32_bf16 v[48:51], v[172:175], v[190:193], v[48:51]
	v_mfma_f32_16x16x32_bf16 v[36:39], v[148:151], v[202:205], v[36:39]
	v_mfma_f32_16x16x32_bf16 v[32:35], v[172:175], v[202:205], v[32:35]
	v_mfma_f32_16x16x32_bf16 v[20:23], v[148:151], v[210:213], v[20:23]
	v_mfma_f32_16x16x32_bf16 v[16:19], v[172:175], v[210:213], v[16:19]
	v_mfma_f32_16x16x32_bf16 v[4:7], v[148:151], v[218:221], v[4:7]
	v_mfma_f32_16x16x32_bf16 v[0:3], v[172:175], v[218:221], v[0:3]
	s_barrier
; #define PG8_STAGE(bufoff, gbase, voff) do { _Pragma("unroll") for (int _i = 0; _i < 2; ++_i) \
;         __builtin_amdgcn_global_load_lds((const unsigned*)((const char*)(gbase) + (voff)[_i]), (PG8_LAS unsigned*)(lds + (bufoff) + ldsw + _i * 8192), 16, 0, 0); } while (0)
; #define PG8_LDA(dst, b, h) do { _Pragma("unroll") for (int m = 0; m < 4; ++m) _Pragma("unroll") for (int k = 0; k < 2; ++k) dst[m][k] = *(const PG8_LAS bf16x8*)(lds + PG8_SA(b, h) + aoff + m * 2048 + k * 1024); } while (0)
; #define PG8_LDB(dst, b, h) do { _Pragma("unroll") for (int n = 0; n < 2; ++n) _Pragma("unroll") for (int k = 0; k < 2; ++k) dst[n][k] = *(const PG8_LAS bf16x8*)(lds + PG8_SB(b, h) + boff + n * 2048 + k * 1024); } while (0)
; #define PG8_MMA(ai, bj, At, Bt) do { __builtin_amdgcn_s_setprio(1); _Pragma("unroll") for (int m = 0; m < 4; ++m) _Pragma("unroll") for (int n = 0; n < 2; ++n) _Pragma("unroll") for (int k = 0; k < 2; ++k) \
;         acc[ai][bj][m][n] = __builtin_amdgcn_mfma_f32_16x16x32_bf16(Bt[n][k], At[m][k], acc[ai][bj][m][n], 0, 0, 0); __builtin_amdgcn_s_setprio(0); } while (0)
; #define PG8_WAIT_V(n) asm volatile("s_waitcnt vmcnt(" #n ")" ::: "memory")
; #define PG8_WAIT_L(n) asm volatile("s_waitcnt lgkmcnt(" #n ")" ::: "memory")
; #define PG8_BAR __builtin_amdgcn_s_barrier()
; #define PG8_SCHED __builtin_amdgcn_sched_barrier(0)
; template <class Epi, class Sched, bool ALIGN_EPI = false, bool SP2 = false>
; __device__ __forceinline__ void gemm_phase(PG8_LAS unsigned char* lds, const Gemm g, const Sched& S, const Epi& E) {
;     ...
;             PG8_LDB(B0, 1, 0); PG8_LDB(B1, 1, 1); PG8_SCHED; PG8_LDA(At, 1, 0); PG8_STAGE(PG8_SA(0, 1), a2 + hstep, voffA);
;             PG8_WAIT_V(8); PG8_WAIT_L(0); PG8_BAR; PG8_MMA(0, 0, At, B0); PG8_MMA(0, 1, At, B1); PG8_BAR; PG8_SCHED;
	s_setprio 0
	s_add_i32 s54, 0, 0x18000
	s_add_i32 s55, 0, 0x1c000
	v_add_u32_e32 v140, s54, v179
	v_add_u32_e32 v172, s55, v179
	ds_read_b128 v[128:131], v140
	ds_read_b128 v[132:135], v140 offset:1024
	ds_read_b128 v[136:139], v140 offset:2048
	ds_read_b128 v[140:143], v140 offset:3072
	ds_read_b128 v[144:147], v172
	ds_read_b128 v[148:151], v172 offset:1024
	ds_read_b128 v[168:171], v172 offset:2048
	ds_read_b128 v[172:175], v172 offset:3072
	s_add_u32 s30, s30, 0x100000
	s_addc_u32 s31, s31, 0
	s_mov_b32 m0, s37
	v_lshl_add_u64 v[226:227], s[30:31], 0, v[152:153]
	ds_read_b128 v[186:189], v183 offset:32768
	ds_read_b128 v[190:193], v183 offset:33792
	ds_read_b128 v[198:201], v183 offset:34816
	ds_read_b128 v[202:205], v183 offset:35840
	ds_read_b128 v[206:209], v183 offset:36864
	ds_read_b128 v[210:213], v183 offset:37888
	ds_read_b128 v[214:217], v183 offset:38912
	ds_read_b128 v[218:221], v183 offset:39936
	global_load_lds_dwordx4 v[226:227], off
	s_mov_b32 m0, s39
	v_lshl_add_u64 v[226:227], s[30:31], 0, v[156:157]
	global_load_lds_dwordx4 v[226:227], off
	s_waitcnt vmcnt(8) lgkmcnt(0)
	s_setprio 1
	s_barrier
	v_mfma_f32_16x16x32_bf16 v[124:127], v[128:131], v[186:189], v[124:127]
	v_mfma_f32_16x16x32_bf16 v[120:123], v[136:139], v[186:189], v[120:123]
	v_mfma_f32_16x16x32_bf16 v[104:107], v[128:131], v[198:201], v[104:107]
	v_mfma_f32_16x16x32_bf16 v[108:111], v[136:139], v[198:201], v[108:111]
	v_mfma_f32_16x16x32_bf16 v[88:91], v[128:131], v[206:209], v[88:91]
	v_mfma_f32_16x16x32_bf16 v[92:95], v[136:139], v[206:209], v[92:95]
	v_mfma_f32_16x16x32_bf16 v[72:75], v[128:131], v[214:217], v[72:75]
	v_mfma_f32_16x16x32_bf16 v[76:79], v[136:139], v[214:217], v[76:79]
	v_mfma_f32_16x16x32_bf16 v[124:127], v[132:135], v[190:193], v[124:127]
	v_mfma_f32_16x16x32_bf16 v[120:123], v[140:143], v[190:193], v[120:123]
	v_mfma_f32_16x16x32_bf16 v[104:107], v[132:135], v[202:205], v[104:107]
	v_mfma_f32_16x16x32_bf16 v[108:111], v[140:143], v[202:205], v[108:111]
	v_mfma_f32_16x16x32_bf16 v[88:91], v[132:135], v[210:213], v[88:91]
	v_mfma_f32_16x16x32_bf16 v[92:95], v[140:143], v[210:213], v[92:95]
	v_mfma_f32_16x16x32_bf16 v[72:75], v[132:135], v[218:221], v[72:75]
	v_mfma_f32_16x16x32_bf16 v[76:79], v[140:143], v[218:221], v[76:79]
	v_mfma_f32_16x16x32_bf16 v[116:119], v[144:147], v[186:189], v[116:119]
	v_mfma_f32_16x16x32_bf16 v[112:115], v[168:171], v[186:189], v[112:115]
	v_mfma_f32_16x16x32_bf16 v[100:103], v[144:147], v[198:201], v[100:103]
	v_mfma_f32_16x16x32_bf16 v[96:99], v[168:171], v[198:201], v[96:99]
	v_mfma_f32_16x16x32_bf16 v[84:87], v[144:147], v[206:209], v[84:87]
	v_mfma_f32_16x16x32_bf16 v[80:83], v[168:171], v[206:209], v[80:83]
	v_mfma_f32_16x16x32_bf16 v[68:71], v[144:147], v[214:217], v[68:71]
	v_mfma_f32_16x16x32_bf16 v[64:67], v[168:171], v[214:217], v[64:67]
	v_mfma_f32_16x16x32_bf16 v[116:119], v[148:151], v[190:193], v[116:119]
	v_mfma_f32_16x16x32_bf16 v[112:115], v[172:175], v[190:193], v[112:115]
	v_mfma_f32_16x16x32_bf16 v[100:103], v[148:151], v[202:205], v[100:103]
	v_mfma_f32_16x16x32_bf16 v[96:99], v[172:175], v[202:205], v[96:99]
	v_mfma_f32_16x16x32_bf16 v[84:87], v[148:151], v[210:213], v[84:87]
	v_mfma_f32_16x16x32_bf16 v[80:83], v[172:175], v[210:213], v[80:83]
	v_mfma_f32_16x16x32_bf16 v[68:71], v[148:151], v[218:221], v[68:71]
	v_mfma_f32_16x16x32_bf16 v[64:67], v[172:175], v[218:221], v[64:67]
	s_barrier
; #define PG8_STAGE(bufoff, gbase, voff) do { _Pragma("unroll") for (int _i = 0; _i < 2; ++_i) \
;         __builtin_amdgcn_global_load_lds((const unsigned*)((const char*)(gbase) + (voff)[_i]), (PG8_LAS unsigned*)(lds + (bufoff) + ldsw + _i * 8192), 16, 0, 0); } while (0)
; #define PG8_LDA(dst, b, h) do { _Pragma("unroll") for (int m = 0; m < 4; ++m) _Pragma("unroll") for (int k = 0; k < 2; ++k) dst[m][k] = *(const PG8_LAS bf16x8*)(lds + PG8_SA(b, h) + aoff + m * 2048 + k * 1024); } while (0)
; #define PG8_MMA(ai, bj, At, Bt) do { __builtin_amdgcn_s_setprio(1); _Pragma("unroll") for (int m = 0; m < 4; ++m) _Pragma("unroll") for (int n = 0; n < 2; ++n) _Pragma("unroll") for (int k = 0; k < 2; ++k) \
;         acc[ai][bj][m][n] = __builtin_amdgcn_mfma_f32_16x16x32_bf16(Bt[n][k], At[m][k], acc[ai][bj][m][n], 0, 0, 0); __builtin_amdgcn_s_setprio(0); } while (0)
; #define PG8_WAIT_V(n) asm volatile("s_waitcnt vmcnt(" #n ")" ::: "memory")
; #define PG8_WAIT_L(n) asm volatile("s_waitcnt lgkmcnt(" #n ")" ::: "memory")
; #define PG8_BAR __builtin_amdgcn_s_barrier()
; #define PG8_SCHED __builtin_amdgcn_sched_barrier(0)
; template <class Epi, class Sched, bool ALIGN_EPI = false, bool SP2 = false>
; __device__ __forceinline__ void gemm_phase(PG8_LAS unsigned char* lds, const Gemm g, const Sched& S, const Epi& E) {
;     ...
;             PG8_LDA(At, 1, 1); PG8_STAGE(PG8_SB(1, 0), b3, voffB); PG8_STAGE(PG8_SB(1, 1), b3 + hstep, voffB); PG8_STAGE(PG8_SA(1, 0), a3, voffA);
;             PG8_WAIT_V(8); PG8_WAIT_L(0); PG8_BAR; PG8_MMA(1, 0, At, B0); PG8_MMA(1, 1, At, B1); PG8_BAR; PG8_SCHED;
;     ...
;         if constexpr (ALIGN_EPI) { if (wr == 0) PG8_BAR; }
	s_setprio 0
	s_add_i32 s30, s54, s34
	v_lshl_add_u64 v[176:177], v[176:177], 0, s[12:13]
	s_mov_b32 m0, s30
	ds_read_b128 v[186:189], v183 offset:49152
	ds_read_b128 v[190:193], v183 offset:50176
	ds_read_b128 v[198:201], v183 offset:51200
	ds_read_b128 v[202:205], v183 offset:52224
	ds_read_b128 v[206:209], v183 offset:53248
	ds_read_b128 v[210:213], v183 offset:54272
	ds_read_b128 v[214:217], v183 offset:55296
	ds_read_b128 v[218:221], v183 offset:56320
	global_load_lds_dwordx4 v[176:177], off
	s_add_i32 m0, s30, 0x2000
	s_add_u32 s28, s28, 0x100080
	v_lshl_add_u64 v[176:177], v[194:195], 0, s[12:13]
	s_addc_u32 s29, s29, 0
	s_add_i32 s30, s55, s34
	global_load_lds_dwordx4 v[176:177], off
	s_mov_b32 m0, s30
	v_lshl_add_u64 v[176:177], s[28:29], 0, v[154:155]
	global_load_lds_dwordx4 v[176:177], off
	s_add_i32 m0, s30, 0x2000
	v_lshl_add_u64 v[176:177], s[28:29], 0, v[158:159]
	global_load_lds_dwordx4 v[176:177], off
	s_mov_b32 m0, s43
	v_lshl_add_u64 v[176:177], v[222:223], 0, s[12:13]
	global_load_lds_dwordx4 v[176:177], off
	s_mov_b32 m0, s44
	v_lshl_add_u64 v[176:177], v[224:225], 0, s[12:13]
	global_load_lds_dwordx4 v[176:177], off
	s_waitcnt vmcnt(8) lgkmcnt(0)
	s_setprio 1
	s_barrier
	v_mfma_f32_16x16x32_bf16 v[56:59], v[128:131], v[186:189], v[56:59]
	v_mfma_f32_16x16x32_bf16 v[60:63], v[136:139], v[186:189], v[60:63]
	v_mfma_f32_16x16x32_bf16 v[40:43], v[128:131], v[198:201], v[40:43]
	v_mfma_f32_16x16x32_bf16 v[44:47], v[136:139], v[198:201], v[44:47]
	v_mfma_f32_16x16x32_bf16 v[24:27], v[128:131], v[206:209], v[24:27]
	v_mfma_f32_16x16x32_bf16 v[28:31], v[136:139], v[206:209], v[28:31]
	v_mfma_f32_16x16x32_bf16 v[8:11], v[128:131], v[214:217], v[8:11]
	v_mfma_f32_16x16x32_bf16 v[12:15], v[136:139], v[214:217], v[12:15]
	v_mfma_f32_16x16x32_bf16 v[56:59], v[132:135], v[190:193], v[56:59]
	v_mfma_f32_16x16x32_bf16 v[60:63], v[140:143], v[190:193], v[60:63]
	v_mfma_f32_16x16x32_bf16 v[40:43], v[132:135], v[202:205], v[40:43]
	v_mfma_f32_16x16x32_bf16 v[44:47], v[140:143], v[202:205], v[44:47]
	v_mfma_f32_16x16x32_bf16 v[24:27], v[132:135], v[210:213], v[24:27]
	v_mfma_f32_16x16x32_bf16 v[28:31], v[140:143], v[210:213], v[28:31]
	v_mfma_f32_16x16x32_bf16 v[8:11], v[132:135], v[218:221], v[8:11]
	v_mfma_f32_16x16x32_bf16 v[12:15], v[140:143], v[218:221], v[12:15]
	v_mfma_f32_16x16x32_bf16 v[52:55], v[144:147], v[186:189], v[52:55]
	v_mfma_f32_16x16x32_bf16 v[48:51], v[168:171], v[186:189], v[48:51]
	v_mfma_f32_16x16x32_bf16 v[36:39], v[144:147], v[198:201], v[36:39]
	v_mfma_f32_16x16x32_bf16 v[32:35], v[168:171], v[198:201], v[32:35]
	v_mfma_f32_16x16x32_bf16 v[20:23], v[144:147], v[206:209], v[20:23]
	v_mfma_f32_16x16x32_bf16 v[16:19], v[168:171], v[206:209], v[16:19]
	v_mfma_f32_16x16x32_bf16 v[4:7], v[144:147], v[214:217], v[4:7]
	v_mfma_f32_16x16x32_bf16 v[0:3], v[168:171], v[214:217], v[0:3]
	v_mfma_f32_16x16x32_bf16 v[52:55], v[148:151], v[190:193], v[52:55]
	v_mfma_f32_16x16x32_bf16 v[48:51], v[172:175], v[190:193], v[48:51]
	v_mfma_f32_16x16x32_bf16 v[36:39], v[148:151], v[202:205], v[36:39]
	v_mfma_f32_16x16x32_bf16 v[32:35], v[172:175], v[202:205], v[32:35]
	v_mfma_f32_16x16x32_bf16 v[20:23], v[148:151], v[210:213], v[20:23]
	v_mfma_f32_16x16x32_bf16 v[16:19], v[172:175], v[210:213], v[16:19]
	v_mfma_f32_16x16x32_bf16 v[4:7], v[148:151], v[218:221], v[4:7]
	v_mfma_f32_16x16x32_bf16 v[0:3], v[172:175], v[218:221], v[0:3]
	s_barrier
	s_setprio 0
	s_add_i32 s53, s53, 2
	s_add_u32 s26, s26, 0x100
	s_addc_u32 s27, s27, 0
	s_add_u32 s49, s49, 0x100
	s_addc_u32 s52, s52, 0
	s_cmp_gt_u32 s53, 61
	s_cbranch_scc0 .LBB0_763
	s_and_b64 vcc, exec, s[14:15]
	s_cbranch_vccz .LBB0_766
	s_barrier

; #define PG8_STAGE(bufoff, gbase, voff) do { _Pragma("unroll") for (int _i = 0; _i < 2; ++_i) \
;         __builtin_amdgcn_global_load_lds((const unsigned*)((const char*)(gbase) + (voff)[_i]), (PG8_LAS unsigned*)(lds + (bufoff) + ldsw + _i * 8192), 16, 0, 0); } while (0)
; #define PG8_LDA(dst, b, h) do { _Pragma("unroll") for (int m = 0; m < 4; ++m) _Pragma("unroll") for (int k = 0; k < 2; ++k) dst[m][k] = *(const PG8_LAS bf16x8*)(lds + PG8_SA(b, h) + aoff + m * 2048 + k * 1024); } while (0)
; #define PG8_LDB(dst, b, h) do { _Pragma("unroll") for (int n = 0; n < 2; ++n) _Pragma("unroll") for (int k = 0; k < 2; ++k) dst[n][k] = *(const PG8_LAS bf16x8*)(lds + PG8_SB(b, h) + boff + n * 2048 + k * 1024); } while (0)
; #define PG8_WAIT_V(n) asm volatile("s_waitcnt vmcnt(" #n ")" ::: "memory")
; #define PG8_WAIT_L(n) asm volatile("s_waitcnt lgkmcnt(" #n ")" ::: "memory")
; #define PG8_BAR __builtin_amdgcn_s_barrier()
; #define PG8_SCHED __builtin_amdgcn_sched_barrier(0)
; template <class Epi, class Sched, bool ALIGN_EPI = false, bool SP2 = false>
; __device__ __forceinline__ void gemm_phase(PG8_LAS unsigned char* lds, const Gemm g, const Sched& S, const Epi& E) {
;     ...
;         const bool has_next = S.next(ui + 1, nxt);
;         const char* nA = has_next ? (const char*)g.A + (size_t)nxt.pm * tstep : cA; const char* nB = has_next ? (const char*)g.Bt + (size_t)nxt.pn * tstep : cB;
;         for (int t = 0; t < nt; t += 2) {
;             const bool last = (t == nt - 2);
;             const char* a1 = cA + (size_t)(t + 1) * kstep;
;             const char* a2 = last ? nA : cA + (size_t)(t + 2) * kstep; const char* b2 = last ? nB : cB + (size_t)(t + 2) * kstep;
;             const char* a3 = a2 + kstep; const char* b3 = b2 + kstep;
;             if (last && has_next) S.a_ready(nxt);
;             if constexpr (SP2) {
;             PG8_LDB(B0, 0, 0); PG8_LDB(B1, 0, 1); PG8_SCHED; PG8_LDA(At, 0, 0); PG8_STAGE(PG8_SA(1, 1), a1 + hstep, voffA);
;             PG8_WAIT_V(8); PG8_WAIT_L(0); PG8_BAR; PG8_MMA(0, 0, At, B0); PG8_MMA(0, 1, At, B1); PG8_BAR; PG8_SCHED;
;             PG8_LDA(At, 0, 1); PG8_STAGE(PG8_SB(0, 0), b2, voffB); PG8_STAGE(PG8_SB(0, 1), b2 + hstep, voffB); PG8_STAGE(PG8_SA(0, 0), a2, voffA);
;             PG8_WAIT_V(8); PG8_WAIT_L(0); PG8_BAR; PG8_MMA(1, 0, At, B0); PG8_MMA(1, 1, At, B1); PG8_BAR; PG8_SCHED;
.LBB0_954:
	s_ashr_i32 s53, s52, 31
	s_lshl_b64 s[22:23], s[52:53], 20
	s_add_u32 s54, s74, s22
	s_addc_u32 s55, s75, s23
	s_and_b64 s[24:25], s[62:63], exec
	s_cselect_b32 s1, s55, s27
	s_cselect_b32 s5, s54, s26
	s_ashr_i32 s41, s40, 31
	s_lshl_b64 s[24:25], s[40:41], 20
	s_add_u32 s56, s94, s24
	s_addc_u32 s57, s95, s25
	s_and_b64 s[30:31], s[62:63], exec
	s_cselect_b32 s17, s57, s29
	s_cselect_b32 s19, s56, s28
	s_add_u32 s26, s26, 0x80080
	s_addc_u32 s27, s27, 0
	s_add_u32 s33, s28, 0x100
	s_addc_u32 s44, s29, 0
	s_mov_b32 s45, -2
	s_waitcnt vmcnt(0)
	ds_read_b128 v[128:131], v209
	ds_read_b128 v[132:135], v209 offset:1024
	ds_read_b128 v[136:139], v209 offset:2048
	ds_read_b128 v[178:181], v209 offset:3072
	ds_read_b128 v[182:185], v210
	ds_read_b128 v[186:189], v210 offset:1024
	ds_read_b128 v[190:193], v210 offset:2048
	ds_read_b128 v[222:225], v210 offset:3072
	s_add_u32 s28, s26, 0xfff80080
	s_addc_u32 s29, s27, -1
	s_cmp_eq_u32 s45, 28
	s_cselect_b32 s31, s1, s29
	s_cselect_b32 s30, s5, s28
	s_cselect_b32 s29, s17, s44
	s_cselect_b32 s28, s19, s33
	v_lshl_add_u64 v[166:167], s[26:27], 0, v[150:151]
	s_add_i32 m0, s35, 0xc000
	ds_read_b128 v[226:229], v211
	ds_read_b128 v[230:233], v211 offset:1024
	ds_read_b128 v[234:237], v211 offset:2048
	ds_read_b128 v[238:241], v211 offset:3072
	ds_read_b128 v[242:245], v211 offset:4096
	ds_read_b128 v[246:249], v211 offset:5120
	ds_read_b128 v[250:253], v211 offset:6144
	ds_read_b128 v[160:163], v211 offset:7168
	global_load_lds_dwordx4 v[166:167], off
	s_add_i32 m0, s35, 0xe000
	v_lshl_add_u64 v[166:167], s[26:27], 0, v[152:153]
	global_load_lds_dwordx4 v[166:167], off
	s_waitcnt lgkmcnt(0)
	s_setprio 1
	s_barrier
	v_mfma_f32_16x16x32_bf16 v[124:127], v[128:131], v[226:229], 0
	v_mfma_f32_16x16x32_bf16 v[120:123], v[136:139], v[226:229], 0
	v_mfma_f32_16x16x32_bf16 v[116:119], v[128:131], v[234:237], 0
	v_mfma_f32_16x16x32_bf16 v[108:111], v[136:139], v[234:237], 0
	v_mfma_f32_16x16x32_bf16 v[100:103], v[128:131], v[242:245], 0
	v_mfma_f32_16x16x32_bf16 v[92:95], v[136:139], v[242:245], 0
	v_mfma_f32_16x16x32_bf16 v[84:87], v[128:131], v[250:253], 0
	v_mfma_f32_16x16x32_bf16 v[76:79], v[136:139], v[250:253], 0
	v_mfma_f32_16x16x32_bf16 v[124:127], v[132:135], v[230:233], v[124:127]
	v_mfma_f32_16x16x32_bf16 v[120:123], v[178:181], v[230:233], v[120:123]
	v_mfma_f32_16x16x32_bf16 v[116:119], v[132:135], v[238:241], v[116:119]
	v_mfma_f32_16x16x32_bf16 v[108:111], v[178:181], v[238:241], v[108:111]
	v_mfma_f32_16x16x32_bf16 v[100:103], v[132:135], v[246:249], v[100:103]
	v_mfma_f32_16x16x32_bf16 v[92:95], v[178:181], v[246:249], v[92:95]
	v_mfma_f32_16x16x32_bf16 v[84:87], v[132:135], v[160:163], v[84:87]
	v_mfma_f32_16x16x32_bf16 v[76:79], v[178:181], v[160:163], v[76:79]
	v_mfma_f32_16x16x32_bf16 v[112:115], v[182:185], v[226:229], 0
	v_mfma_f32_16x16x32_bf16 v[104:107], v[190:193], v[226:229], 0
	v_mfma_f32_16x16x32_bf16 v[96:99], v[182:185], v[234:237], 0
	v_mfma_f32_16x16x32_bf16 v[88:91], v[190:193], v[234:237], 0
	v_mfma_f32_16x16x32_bf16 v[80:83], v[182:185], v[242:245], 0
	v_mfma_f32_16x16x32_bf16 v[72:75], v[190:193], v[242:245], 0
	v_mfma_f32_16x16x32_bf16 v[68:71], v[182:185], v[250:253], 0
	v_mfma_f32_16x16x32_bf16 v[64:67], v[190:193], v[250:253], 0
	v_mfma_f32_16x16x32_bf16 v[112:115], v[186:189], v[230:233], v[112:115]
	v_mfma_f32_16x16x32_bf16 v[104:107], v[222:225], v[230:233], v[104:107]
	v_mfma_f32_16x16x32_bf16 v[96:99], v[186:189], v[238:241], v[96:99]
	v_mfma_f32_16x16x32_bf16 v[88:91], v[222:225], v[238:241], v[88:91]
	v_mfma_f32_16x16x32_bf16 v[80:83], v[186:189], v[246:249], v[80:83]
	v_mfma_f32_16x16x32_bf16 v[72:75], v[222:225], v[246:249], v[72:75]
	v_mfma_f32_16x16x32_bf16 v[68:71], v[186:189], v[160:163], v[68:71]
	v_mfma_f32_16x16x32_bf16 v[64:67], v[222:225], v[160:163], v[64:67]
	s_barrier
	s_setprio 0
	s_add_i32 s48, s69, s34
	v_lshl_add_u64 v[166:167], s[28:29], 0, v[142:143]
	s_mov_b32 m0, s48
	ds_read_b128 v[160:163], v211 offset:16384
	ds_read_b128 v[226:229], v211 offset:17408
	ds_read_b128 v[230:233], v211 offset:18432
	ds_read_b128 v[234:237], v211 offset:19456
	ds_read_b128 v[238:241], v211 offset:20480
	ds_read_b128 v[242:245], v211 offset:21504
	ds_read_b128 v[246:249], v211 offset:22528
	ds_read_b128 v[250:253], v211 offset:23552
	global_load_lds_dwordx4 v[166:167], off
	s_add_i32 m0, s48, 0x2000
	s_add_u32 s48, s28, 0x80000
	v_lshl_add_u64 v[170:171], s[28:29], 0, v[146:147]
	s_addc_u32 s49, s29, 0
	s_add_i32 s50, s70, s34
	global_load_lds_dwordx4 v[170:171], off
	v_lshl_add_u64 v[174:175], s[48:49], 0, v[142:143]
	s_mov_b32 m0, s50
	v_lshl_add_u64 v[194:195], s[30:31], 0, v[144:145]
	global_load_lds_dwordx4 v[174:175], off
	s_add_i32 m0, s50, 0x2000
	v_lshl_add_u64 v[174:175], s[48:49], 0, v[146:147]
	global_load_lds_dwordx4 v[174:175], off
	s_mov_b32 m0, s35
	v_lshl_add_u64 v[174:175], s[30:31], 0, v[140:141]
	global_load_lds_dwordx4 v[174:175], off
	s_mov_b32 m0, s37
	s_nop 0
	global_load_lds_dwordx4 v[194:195], off
	s_waitcnt lgkmcnt(0)
	s_setprio 1
	s_barrier
; #define PG8_STAGE(bufoff, gbase, voff) do { _Pragma("unroll") for (int _i = 0; _i < 2; ++_i) \
;         __builtin_amdgcn_global_load_lds((const unsigned*)((const char*)(gbase) + (voff)[_i]), (PG8_LAS unsigned*)(lds + (bufoff) + ldsw + _i * 8192), 16, 0, 0); } while (0)
; #define PG8_LDA(dst, b, h) do { _Pragma("unroll") for (int m = 0; m < 4; ++m) _Pragma("unroll") for (int k = 0; k < 2; ++k) dst[m][k] = *(const PG8_LAS bf16x8*)(lds + PG8_SA(b, h) + aoff + m * 2048 + k * 1024); } while (0)
; #define PG8_LDB(dst, b, h) do { _Pragma("unroll") for (int n = 0; n < 2; ++n) _Pragma("unroll") for (int k = 0; k < 2; ++k) dst[n][k] = *(const PG8_LAS bf16x8*)(lds + PG8_SB(b, h) + boff + n * 2048 + k * 1024); } while (0)
; #define PG8_MMA(ai, bj, At, Bt) do { __builtin_amdgcn_s_setprio(1); _Pragma("unroll") for (int m = 0; m < 4; ++m) _Pragma("unroll") for (int n = 0; n < 2; ++n) _Pragma("unroll") for (int k = 0; k < 2; ++k) \
;         acc[ai][bj][m][n] = __builtin_amdgcn_mfma_f32_16x16x32_bf16(Bt[n][k], At[m][k], acc[ai][bj][m][n], 0, 0, 0); __builtin_amdgcn_s_setprio(0); } while (0)
; #define PG8_WAIT_V(n) asm volatile("s_waitcnt vmcnt(" #n ")" ::: "memory")
; #define PG8_WAIT_L(n) asm volatile("s_waitcnt lgkmcnt(" #n ")" ::: "memory")
; #define PG8_BAR __builtin_amdgcn_s_barrier()
; #define PG8_SCHED __builtin_amdgcn_sched_barrier(0)
; template <class Epi, class Sched, bool ALIGN_EPI = false, bool SP2 = false>
; __device__ __forceinline__ void gemm_phase(PG8_LAS unsigned char* lds, const Gemm g, const Sched& S, const Epi& E) {
;     ...
;             PG8_WAIT_V(8); PG8_WAIT_L(0); PG8_BAR; PG8_MMA(1, 0, At, B0); PG8_MMA(1, 1, At, B1); PG8_BAR; PG8_SCHED;
;             PG8_LDB(B0, 1, 0); PG8_LDB(B1, 1, 1); PG8_SCHED; PG8_LDA(At, 1, 0); PG8_STAGE(PG8_SA(0, 1), a2 + hstep, voffA);
;             PG8_WAIT_V(8); PG8_WAIT_L(0); PG8_BAR; PG8_MMA(0, 0, At, B0); PG8_MMA(0, 1, At, B1); PG8_BAR; PG8_SCHED;
	v_mfma_f32_16x16x32_bf16 v[60:63], v[128:131], v[160:163], 0
	v_mfma_f32_16x16x32_bf16 v[56:59], v[136:139], v[160:163], 0
	v_mfma_f32_16x16x32_bf16 v[52:55], v[128:131], v[230:233], 0
	v_mfma_f32_16x16x32_bf16 v[44:47], v[136:139], v[230:233], 0
	v_mfma_f32_16x16x32_bf16 v[36:39], v[128:131], v[238:241], 0
	v_mfma_f32_16x16x32_bf16 v[28:31], v[136:139], v[238:241], 0
	v_mfma_f32_16x16x32_bf16 v[20:23], v[128:131], v[246:249], 0
	v_mfma_f32_16x16x32_bf16 v[12:15], v[136:139], v[246:249], 0
	v_mfma_f32_16x16x32_bf16 v[60:63], v[132:135], v[226:229], v[60:63]
	v_mfma_f32_16x16x32_bf16 v[56:59], v[178:181], v[226:229], v[56:59]
	v_mfma_f32_16x16x32_bf16 v[52:55], v[132:135], v[234:237], v[52:55]
	v_mfma_f32_16x16x32_bf16 v[44:47], v[178:181], v[234:237], v[44:47]
	v_mfma_f32_16x16x32_bf16 v[36:39], v[132:135], v[242:245], v[36:39]
	v_mfma_f32_16x16x32_bf16 v[28:31], v[178:181], v[242:245], v[28:31]
	v_mfma_f32_16x16x32_bf16 v[20:23], v[132:135], v[250:253], v[20:23]
	v_mfma_f32_16x16x32_bf16 v[12:15], v[178:181], v[250:253], v[12:15]
	v_mfma_f32_16x16x32_bf16 v[48:51], v[182:185], v[160:163], 0
	v_mfma_f32_16x16x32_bf16 v[40:43], v[190:193], v[160:163], 0
	v_mfma_f32_16x16x32_bf16 v[32:35], v[182:185], v[230:233], 0
	v_mfma_f32_16x16x32_bf16 v[24:27], v[190:193], v[230:233], 0
	v_mfma_f32_16x16x32_bf16 v[16:19], v[182:185], v[238:241], 0
	v_mfma_f32_16x16x32_bf16 v[8:11], v[190:193], v[238:241], 0
	v_mfma_f32_16x16x32_bf16 v[4:7], v[182:185], v[246:249], 0
	v_mfma_f32_16x16x32_bf16 v[0:3], v[190:193], v[246:249], 0
	v_mfma_f32_16x16x32_bf16 v[48:51], v[186:189], v[226:229], v[48:51]
	v_mfma_f32_16x16x32_bf16 v[40:43], v[222:225], v[226:229], v[40:43]
	v_mfma_f32_16x16x32_bf16 v[32:35], v[186:189], v[234:237], v[32:35]
	v_mfma_f32_16x16x32_bf16 v[24:27], v[222:225], v[234:237], v[24:27]
	v_mfma_f32_16x16x32_bf16 v[16:19], v[186:189], v[242:245], v[16:19]
	v_mfma_f32_16x16x32_bf16 v[8:11], v[222:225], v[242:245], v[8:11]
	v_mfma_f32_16x16x32_bf16 v[4:7], v[186:189], v[250:253], v[4:7]
	v_mfma_f32_16x16x32_bf16 v[0:3], v[222:225], v[250:253], v[0:3]
	s_barrier
	s_setprio 0
	s_add_i32 s48, 0, 0x18000
	v_add_u32_e32 v148, s48, v159
	s_add_i32 s49, 0, 0x1c000
	ds_read_b128 v[128:131], v148
	ds_read_b128 v[132:135], v148 offset:1024
	ds_read_b128 v[136:139], v148 offset:2048
	ds_read_b128 v[160:163], v148 offset:3072
	v_add_u32_e32 v148, s49, v159
	ds_read_b128 v[178:181], v148
	ds_read_b128 v[182:185], v148 offset:1024
	ds_read_b128 v[186:189], v148 offset:2048
	ds_read_b128 v[190:193], v148 offset:3072
	s_add_u32 s30, s30, 0x80000
	s_addc_u32 s31, s31, 0
	s_mov_b32 m0, s39
	v_lshl_add_u64 v[154:155], s[30:31], 0, v[140:141]
	ds_read_b128 v[222:225], v211 offset:32768
	ds_read_b128 v[226:229], v211 offset:33792
	ds_read_b128 v[230:233], v211 offset:34816
	ds_read_b128 v[234:237], v211 offset:35840
	ds_read_b128 v[238:241], v211 offset:36864
	ds_read_b128 v[242:245], v211 offset:37888
	ds_read_b128 v[246:249], v211 offset:38912
	ds_read_b128 v[250:253], v211 offset:39936
	global_load_lds_dwordx4 v[154:155], off
	s_mov_b32 m0, s42
	v_lshl_add_u64 v[154:155], s[30:31], 0, v[144:145]
	global_load_lds_dwordx4 v[154:155], off
	s_waitcnt vmcnt(8) lgkmcnt(0)
	s_setprio 1
	s_barrier
	v_mfma_f32_16x16x32_bf16 v[124:127], v[128:131], v[222:225], v[124:127]
	v_mfma_f32_16x16x32_bf16 v[120:123], v[136:139], v[222:225], v[120:123]
	v_mfma_f32_16x16x32_bf16 v[116:119], v[128:131], v[230:233], v[116:119]
	v_mfma_f32_16x16x32_bf16 v[108:111], v[136:139], v[230:233], v[108:111]
	v_mfma_f32_16x16x32_bf16 v[100:103], v[128:131], v[238:241], v[100:103]
	v_mfma_f32_16x16x32_bf16 v[92:95], v[136:139], v[238:241], v[92:95]
	v_mfma_f32_16x16x32_bf16 v[84:87], v[128:131], v[246:249], v[84:87]
	v_mfma_f32_16x16x32_bf16 v[76:79], v[136:139], v[246:249], v[76:79]
	v_mfma_f32_16x16x32_bf16 v[124:127], v[132:135], v[226:229], v[124:127]
	v_mfma_f32_16x16x32_bf16 v[120:123], v[160:163], v[226:229], v[120:123]
	v_mfma_f32_16x16x32_bf16 v[116:119], v[132:135], v[234:237], v[116:119]
	v_mfma_f32_16x16x32_bf16 v[108:111], v[160:163], v[234:237], v[108:111]
	v_mfma_f32_16x16x32_bf16 v[100:103], v[132:135], v[242:245], v[100:103]
	v_mfma_f32_16x16x32_bf16 v[92:95], v[160:163], v[242:245], v[92:95]
	v_mfma_f32_16x16x32_bf16 v[84:87], v[132:135], v[250:253], v[84:87]
	v_mfma_f32_16x16x32_bf16 v[76:79], v[160:163], v[250:253], v[76:79]
	v_mfma_f32_16x16x32_bf16 v[112:115], v[178:181], v[222:225], v[112:115]
	v_mfma_f32_16x16x32_bf16 v[104:107], v[186:189], v[222:225], v[104:107]
	v_mfma_f32_16x16x32_bf16 v[96:99], v[178:181], v[230:233], v[96:99]
	v_mfma_f32_16x16x32_bf16 v[88:91], v[186:189], v[230:233], v[88:91]
	v_mfma_f32_16x16x32_bf16 v[80:83], v[178:181], v[238:241], v[80:83]
	v_mfma_f32_16x16x32_bf16 v[72:75], v[186:189], v[238:241], v[72:75]
	v_mfma_f32_16x16x32_bf16 v[68:71], v[178:181], v[246:249], v[68:71]
	v_mfma_f32_16x16x32_bf16 v[64:67], v[186:189], v[246:249], v[64:67]
	v_mfma_f32_16x16x32_bf16 v[112:115], v[182:185], v[226:229], v[112:115]
	v_mfma_f32_16x16x32_bf16 v[104:107], v[190:193], v[226:229], v[104:107]
	v_mfma_f32_16x16x32_bf16 v[96:99], v[182:185], v[234:237], v[96:99]
	v_mfma_f32_16x16x32_bf16 v[88:91], v[190:193], v[234:237], v[88:91]
	v_mfma_f32_16x16x32_bf16 v[80:83], v[182:185], v[242:245], v[80:83]
	v_mfma_f32_16x16x32_bf16 v[72:75], v[190:193], v[242:245], v[72:75]
	v_mfma_f32_16x16x32_bf16 v[68:71], v[182:185], v[250:253], v[68:71]
	v_mfma_f32_16x16x32_bf16 v[64:67], v[190:193], v[250:253], v[64:67]
	s_barrier
; #define PG8_STAGE(bufoff, gbase, voff) do { _Pragma("unroll") for (int _i = 0; _i < 2; ++_i) \
;         __builtin_amdgcn_global_load_lds((const unsigned*)((const char*)(gbase) + (voff)[_i]), (PG8_LAS unsigned*)(lds + (bufoff) + ldsw + _i * 8192), 16, 0, 0); } while (0)
; #define PG8_LDA(dst, b, h) do { _Pragma("unroll") for (int m = 0; m < 4; ++m) _Pragma("unroll") for (int k = 0; k < 2; ++k) dst[m][k] = *(const PG8_LAS bf16x8*)(lds + PG8_SA(b, h) + aoff + m * 2048 + k * 1024); } while (0)
; #define PG8_LDB(dst, b, h) do { _Pragma("unroll") for (int n = 0; n < 2; ++n) _Pragma("unroll") for (int k = 0; k < 2; ++k) dst[n][k] = *(const PG8_LAS bf16x8*)(lds + PG8_SB(b, h) + boff + n * 2048 + k * 1024); } while (0)
; template <class Epi, class Sched, bool ALIGN_EPI = false, bool SP2 = false>
; __device__ __forceinline__ void gemm_phase(PG8_LAS unsigned char* lds, const Gemm g, const Sched& S, const Epi& E) {
;     ...
;         for (int t = 0; t < nt; t += 2) {
;             const bool last = (t == nt - 2);
;             const char* a1 = cA + (size_t)(t + 1) * kstep;
;             const char* a2 = last ? nA : cA + (size_t)(t + 2) * kstep; const char* b2 = last ? nB : cB + (size_t)(t + 2) * kstep;
;             const char* a3 = a2 + kstep; const char* b3 = b2 + kstep;
;             if (last && has_next) S.a_ready(nxt);
;             if constexpr (SP2) {
;             PG8_LDB(B0, 0, 0); PG8_LDB(B1, 0, 1); PG8_SCHED; PG8_LDA(At, 0, 0); PG8_STAGE(PG8_SA(1, 1), a1 + hstep, voffA);
;             PG8_WAIT_V(8); PG8_WAIT_L(0); PG8_BAR; PG8_MMA(0, 0, At, B0); PG8_MMA(0, 1, At, B1); PG8_BAR; PG8_SCHED;
;             PG8_LDA(At, 0, 1); PG8_STAGE(PG8_SB(0, 0), b2, voffB); PG8_STAGE(PG8_SB(0, 1), b2 + hstep, voffB); PG8_STAGE(PG8_SA(0, 0), a2, voffA);
;             PG8_WAIT_V(8); PG8_WAIT_L(0); PG8_BAR; PG8_MMA(1, 0, At, B0); PG8_MMA(1, 1, At, B1); PG8_BAR; PG8_SCHED;
;             PG8_LDB(B0, 1, 0); PG8_LDB(B1, 1, 1); PG8_SCHED; PG8_LDA(At, 1, 0); PG8_STAGE(PG8_SA(0, 1), a2 + hstep, voffA);
;             PG8_WAIT_V(8); PG8_WAIT_L(0); PG8_BAR; PG8_MMA(0, 0, At, B0); PG8_MMA(0, 1, At, B1); PG8_BAR; PG8_SCHED;
;             PG8_LDA(At, 1, 1); PG8_STAGE(PG8_SB(1, 0), b3, voffB); PG8_STAGE(PG8_SB(1, 1), b3 + hstep, voffB); PG8_STAGE(PG8_SA(1, 0), a3, voffA);
;             PG8_WAIT_V(8); PG8_WAIT_L(0); PG8_BAR; PG8_MMA(1, 0, At, B0); PG8_MMA(1, 1, At, B1); PG8_BAR; PG8_SCHED;
	s_setprio 0
	s_add_i32 s30, s48, s34
	v_lshl_add_u64 v[154:155], v[166:167], 0, s[10:11]
	s_mov_b32 m0, s30
	ds_read_b128 v[222:225], v211 offset:49152
	ds_read_b128 v[226:229], v211 offset:50176
	ds_read_b128 v[230:233], v211 offset:51200
	ds_read_b128 v[234:237], v211 offset:52224
	ds_read_b128 v[238:241], v211 offset:53248
	ds_read_b128 v[242:245], v211 offset:54272
	ds_read_b128 v[246:249], v211 offset:55296
	ds_read_b128 v[250:253], v211 offset:56320
	global_load_lds_dwordx4 v[154:155], off
	s_add_i32 m0, s30, 0x2000
	s_add_u32 s28, s28, 0x80080
	v_lshl_add_u64 v[154:155], v[170:171], 0, s[10:11]
	s_addc_u32 s29, s29, 0
	s_add_i32 s30, s49, s34
	global_load_lds_dwordx4 v[154:155], off
	s_mov_b32 m0, s30
	v_lshl_add_u64 v[154:155], s[28:29], 0, v[142:143]
	global_load_lds_dwordx4 v[154:155], off
	s_add_i32 m0, s30, 0x2000
	v_lshl_add_u64 v[154:155], s[28:29], 0, v[146:147]
	global_load_lds_dwordx4 v[154:155], off
	s_mov_b32 m0, s46
	v_lshl_add_u64 v[154:155], v[174:175], 0, s[10:11]
	global_load_lds_dwordx4 v[154:155], off
	s_mov_b32 m0, s47
	v_lshl_add_u64 v[154:155], v[194:195], 0, s[10:11]
	global_load_lds_dwordx4 v[154:155], off
	s_waitcnt vmcnt(8) lgkmcnt(0)
	s_setprio 1
	s_barrier
	v_mfma_f32_16x16x32_bf16 v[60:63], v[128:131], v[222:225], v[60:63]
	v_mfma_f32_16x16x32_bf16 v[56:59], v[136:139], v[222:225], v[56:59]
	v_mfma_f32_16x16x32_bf16 v[52:55], v[128:131], v[230:233], v[52:55]
	v_mfma_f32_16x16x32_bf16 v[44:47], v[136:139], v[230:233], v[44:47]
	v_mfma_f32_16x16x32_bf16 v[36:39], v[128:131], v[238:241], v[36:39]
	v_mfma_f32_16x16x32_bf16 v[28:31], v[136:139], v[238:241], v[28:31]
	v_mfma_f32_16x16x32_bf16 v[20:23], v[128:131], v[246:249], v[20:23]
	v_mfma_f32_16x16x32_bf16 v[12:15], v[136:139], v[246:249], v[12:15]
	v_mfma_f32_16x16x32_bf16 v[60:63], v[132:135], v[226:229], v[60:63]
	v_mfma_f32_16x16x32_bf16 v[56:59], v[160:163], v[226:229], v[56:59]
	v_mfma_f32_16x16x32_bf16 v[52:55], v[132:135], v[234:237], v[52:55]
	v_mfma_f32_16x16x32_bf16 v[44:47], v[160:163], v[234:237], v[44:47]
	v_mfma_f32_16x16x32_bf16 v[36:39], v[132:135], v[242:245], v[36:39]
	v_mfma_f32_16x16x32_bf16 v[28:31], v[160:163], v[242:245], v[28:31]
	v_mfma_f32_16x16x32_bf16 v[20:23], v[132:135], v[250:253], v[20:23]
	v_mfma_f32_16x16x32_bf16 v[12:15], v[160:163], v[250:253], v[12:15]
	v_mfma_f32_16x16x32_bf16 v[48:51], v[178:181], v[222:225], v[48:51]
	v_mfma_f32_16x16x32_bf16 v[40:43], v[186:189], v[222:225], v[40:43]
	v_mfma_f32_16x16x32_bf16 v[32:35], v[178:181], v[230:233], v[32:35]
	v_mfma_f32_16x16x32_bf16 v[24:27], v[186:189], v[230:233], v[24:27]
	v_mfma_f32_16x16x32_bf16 v[16:19], v[178:181], v[238:241], v[16:19]
	v_mfma_f32_16x16x32_bf16 v[8:11], v[186:189], v[238:241], v[8:11]
	v_mfma_f32_16x16x32_bf16 v[4:7], v[178:181], v[246:249], v[4:7]
	v_mfma_f32_16x16x32_bf16 v[0:3], v[186:189], v[246:249], v[0:3]
	v_mfma_f32_16x16x32_bf16 v[48:51], v[182:185], v[226:229], v[48:51]
	v_mfma_f32_16x16x32_bf16 v[40:43], v[190:193], v[226:229], v[40:43]
	v_mfma_f32_16x16x32_bf16 v[32:35], v[182:185], v[234:237], v[32:35]
	v_mfma_f32_16x16x32_bf16 v[24:27], v[190:193], v[234:237], v[24:27]
	v_mfma_f32_16x16x32_bf16 v[16:19], v[182:185], v[242:245], v[16:19]
	v_mfma_f32_16x16x32_bf16 v[8:11], v[190:193], v[242:245], v[8:11]
	v_mfma_f32_16x16x32_bf16 v[4:7], v[182:185], v[250:253], v[4:7]
	v_mfma_f32_16x16x32_bf16 v[0:3], v[190:193], v[250:253], v[0:3]
	s_barrier
	s_setprio 0
	s_add_i32 s45, s45, 2
	s_add_u32 s26, s26, 0x100
	s_addc_u32 s27, s27, 0
	s_add_u32 s33, s33, 0x100
	s_addc_u32 s44, s44, 0
.LBB0_955:
	ds_read_b128 v[128:131], v209
	ds_read_b128 v[132:135], v209 offset:1024
	ds_read_b128 v[136:139], v209 offset:2048
	ds_read_b128 v[178:181], v209 offset:3072
	ds_read_b128 v[182:185], v210
	ds_read_b128 v[186:189], v210 offset:1024
	ds_read_b128 v[190:193], v210 offset:2048
	ds_read_b128 v[222:225], v210 offset:3072
	s_add_u32 s28, s26, 0xfff80080
	s_addc_u32 s29, s27, -1
	s_cmp_eq_u32 s45, 28
	s_cselect_b32 s31, s1, s29
	s_cselect_b32 s30, s5, s28
	s_cselect_b32 s29, s17, s44
	s_cselect_b32 s28, s19, s33
	v_lshl_add_u64 v[166:167], s[26:27], 0, v[150:151]
	s_add_i32 m0, s35, 0xc000
	ds_read_b128 v[226:229], v211
	ds_read_b128 v[230:233], v211 offset:1024
	ds_read_b128 v[234:237], v211 offset:2048
	ds_read_b128 v[238:241], v211 offset:3072
	ds_read_b128 v[242:245], v211 offset:4096
	ds_read_b128 v[246:249], v211 offset:5120
	ds_read_b128 v[250:253], v211 offset:6144
	ds_read_b128 v[160:163], v211 offset:7168
	global_load_lds_dwordx4 v[166:167], off
	s_add_i32 m0, s35, 0xe000
	v_lshl_add_u64 v[166:167], s[26:27], 0, v[152:153]
	global_load_lds_dwordx4 v[166:167], off
	s_waitcnt vmcnt(8) lgkmcnt(0)
	s_setprio 1
	s_barrier
; #define PG8_STAGE(bufoff, gbase, voff) do { _Pragma("unroll") for (int _i = 0; _i < 2; ++_i) \
;         __builtin_amdgcn_global_load_lds((const unsigned*)((const char*)(gbase) + (voff)[_i]), (PG8_LAS unsigned*)(lds + (bufoff) + ldsw + _i * 8192), 16, 0, 0); } while (0)
; #define PG8_LDA(dst, b, h) do { _Pragma("unroll") for (int m = 0; m < 4; ++m) _Pragma("unroll") for (int k = 0; k < 2; ++k) dst[m][k] = *(const PG8_LAS bf16x8*)(lds + PG8_SA(b, h) + aoff + m * 2048 + k * 1024); } while (0)
; #define PG8_LDB(dst, b, h) do { _Pragma("unroll") for (int n = 0; n < 2; ++n) _Pragma("unroll") for (int k = 0; k < 2; ++k) dst[n][k] = *(const PG8_LAS bf16x8*)(lds + PG8_SB(b, h) + boff + n * 2048 + k * 1024); } while (0)
; #define PG8_MMA(ai, bj, At, Bt) do { __builtin_amdgcn_s_setprio(1); _Pragma("unroll") for (int m = 0; m < 4; ++m) _Pragma("unroll") for (int n = 0; n < 2; ++n) _Pragma("unroll") for (int k = 0; k < 2; ++k) \
;         acc[ai][bj][m][n] = __builtin_amdgcn_mfma_f32_16x16x32_bf16(Bt[n][k], At[m][k], acc[ai][bj][m][n], 0, 0, 0); __builtin_amdgcn_s_setprio(0); } while (0)
; #define PG8_WAIT_V(n) asm volatile("s_waitcnt vmcnt(" #n ")" ::: "memory")
; #define PG8_WAIT_L(n) asm volatile("s_waitcnt lgkmcnt(" #n ")" ::: "memory")
; #define PG8_BAR __builtin_amdgcn_s_barrier()
; #define PG8_SCHED __builtin_amdgcn_sched_barrier(0)
; template <class Epi, class Sched, bool ALIGN_EPI = false, bool SP2 = false>
; __device__ __forceinline__ void gemm_phase(PG8_LAS unsigned char* lds, const Gemm g, const Sched& S, const Epi& E) {
;     ...
;             PG8_LDB(B0, 0, 0); PG8_LDB(B1, 0, 1); PG8_SCHED; PG8_LDA(At, 0, 0); PG8_STAGE(PG8_SA(1, 1), a1 + hstep, voffA);
;             PG8_WAIT_V(8); PG8_WAIT_L(0); PG8_BAR; PG8_MMA(0, 0, At, B0); PG8_MMA(0, 1, At, B1); PG8_BAR; PG8_SCHED;
;             PG8_LDA(At, 0, 1); PG8_STAGE(PG8_SB(0, 0), b2, voffB); PG8_STAGE(PG8_SB(0, 1), b2 + hstep, voffB); PG8_STAGE(PG8_SA(0, 0), a2, voffA);
;             PG8_WAIT_V(8); PG8_WAIT_L(0); PG8_BAR; PG8_MMA(1, 0, At, B0); PG8_MMA(1, 1, At, B1); PG8_BAR; PG8_SCHED;
	v_mfma_f32_16x16x32_bf16 v[124:127], v[128:131], v[226:229], v[124:127]
	v_mfma_f32_16x16x32_bf16 v[120:123], v[136:139], v[226:229], v[120:123]
	v_mfma_f32_16x16x32_bf16 v[116:119], v[128:131], v[234:237], v[116:119]
	v_mfma_f32_16x16x32_bf16 v[108:111], v[136:139], v[234:237], v[108:111]
	v_mfma_f32_16x16x32_bf16 v[100:103], v[128:131], v[242:245], v[100:103]
	v_mfma_f32_16x16x32_bf16 v[92:95], v[136:139], v[242:245], v[92:95]
	v_mfma_f32_16x16x32_bf16 v[84:87], v[128:131], v[250:253], v[84:87]
	v_mfma_f32_16x16x32_bf16 v[76:79], v[136:139], v[250:253], v[76:79]
	v_mfma_f32_16x16x32_bf16 v[124:127], v[132:135], v[230:233], v[124:127]
	v_mfma_f32_16x16x32_bf16 v[120:123], v[178:181], v[230:233], v[120:123]
	v_mfma_f32_16x16x32_bf16 v[116:119], v[132:135], v[238:241], v[116:119]
	v_mfma_f32_16x16x32_bf16 v[108:111], v[178:181], v[238:241], v[108:111]
	v_mfma_f32_16x16x32_bf16 v[100:103], v[132:135], v[246:249], v[100:103]
	v_mfma_f32_16x16x32_bf16 v[92:95], v[178:181], v[246:249], v[92:95]
	v_mfma_f32_16x16x32_bf16 v[84:87], v[132:135], v[160:163], v[84:87]
	v_mfma_f32_16x16x32_bf16 v[76:79], v[178:181], v[160:163], v[76:79]
	v_mfma_f32_16x16x32_bf16 v[112:115], v[182:185], v[226:229], v[112:115]
	v_mfma_f32_16x16x32_bf16 v[104:107], v[190:193], v[226:229], v[104:107]
	v_mfma_f32_16x16x32_bf16 v[96:99], v[182:185], v[234:237], v[96:99]
	v_mfma_f32_16x16x32_bf16 v[88:91], v[190:193], v[234:237], v[88:91]
	v_mfma_f32_16x16x32_bf16 v[80:83], v[182:185], v[242:245], v[80:83]
	v_mfma_f32_16x16x32_bf16 v[72:75], v[190:193], v[242:245], v[72:75]
	v_mfma_f32_16x16x32_bf16 v[68:71], v[182:185], v[250:253], v[68:71]
	v_mfma_f32_16x16x32_bf16 v[64:67], v[190:193], v[250:253], v[64:67]
	v_mfma_f32_16x16x32_bf16 v[112:115], v[186:189], v[230:233], v[112:115]
	v_mfma_f32_16x16x32_bf16 v[104:107], v[222:225], v[230:233], v[104:107]
	v_mfma_f32_16x16x32_bf16 v[96:99], v[186:189], v[238:241], v[96:99]
	v_mfma_f32_16x16x32_bf16 v[88:91], v[222:225], v[238:241], v[88:91]
	v_mfma_f32_16x16x32_bf16 v[80:83], v[186:189], v[246:249], v[80:83]
	v_mfma_f32_16x16x32_bf16 v[72:75], v[222:225], v[246:249], v[72:75]
	v_mfma_f32_16x16x32_bf16 v[68:71], v[186:189], v[160:163], v[68:71]
	v_mfma_f32_16x16x32_bf16 v[64:67], v[222:225], v[160:163], v[64:67]
	s_barrier
	s_setprio 0
	s_add_i32 s48, s69, s34
	v_lshl_add_u64 v[166:167], s[28:29], 0, v[142:143]
	s_mov_b32 m0, s48
	ds_read_b128 v[160:163], v211 offset:16384
	ds_read_b128 v[226:229], v211 offset:17408
	ds_read_b128 v[230:233], v211 offset:18432
	ds_read_b128 v[234:237], v211 offset:19456
	ds_read_b128 v[238:241], v211 offset:20480
	ds_read_b128 v[242:245], v211 offset:21504
	ds_read_b128 v[246:249], v211 offset:22528
	ds_read_b128 v[250:253], v211 offset:23552
	global_load_lds_dwordx4 v[166:167], off
	s_add_i32 m0, s48, 0x2000
	s_add_u32 s48, s28, 0x80000
	v_lshl_add_u64 v[170:171], s[28:29], 0, v[146:147]
	s_addc_u32 s49, s29, 0
	s_add_i32 s50, s70, s34
	global_load_lds_dwordx4 v[170:171], off
	v_lshl_add_u64 v[174:175], s[48:49], 0, v[142:143]
	s_mov_b32 m0, s50
	v_lshl_add_u64 v[194:195], s[30:31], 0, v[144:145]
	global_load_lds_dwordx4 v[174:175], off
	s_add_i32 m0, s50, 0x2000
	v_lshl_add_u64 v[174:175], s[48:49], 0, v[146:147]
	global_load_lds_dwordx4 v[174:175], off
	s_mov_b32 m0, s35
	v_lshl_add_u64 v[174:175], s[30:31], 0, v[140:141]
	global_load_lds_dwordx4 v[174:175], off
	s_mov_b32 m0, s37
	s_nop 0
	global_load_lds_dwordx4 v[194:195], off
	s_waitcnt vmcnt(8) lgkmcnt(0)
	s_setprio 1
	s_barrier
	v_mfma_f32_16x16x32_bf16 v[60:63], v[128:131], v[160:163], v[60:63]
	v_mfma_f32_16x16x32_bf16 v[56:59], v[136:139], v[160:163], v[56:59]
	v_mfma_f32_16x16x32_bf16 v[52:55], v[128:131], v[230:233], v[52:55]
	v_mfma_f32_16x16x32_bf16 v[44:47], v[136:139], v[230:233], v[44:47]
	v_mfma_f32_16x16x32_bf16 v[36:39], v[128:131], v[238:241], v[36:39]
	v_mfma_f32_16x16x32_bf16 v[28:31], v[136:139], v[238:241], v[28:31]
	v_mfma_f32_16x16x32_bf16 v[20:23], v[128:131], v[246:249], v[20:23]
	v_mfma_f32_16x16x32_bf16 v[12:15], v[136:139], v[246:249], v[12:15]
	v_mfma_f32_16x16x32_bf16 v[60:63], v[132:135], v[226:229], v[60:63]
	v_mfma_f32_16x16x32_bf16 v[56:59], v[178:181], v[226:229], v[56:59]
	v_mfma_f32_16x16x32_bf16 v[52:55], v[132:135], v[234:237], v[52:55]
	v_mfma_f32_16x16x32_bf16 v[44:47], v[178:181], v[234:237], v[44:47]
	v_mfma_f32_16x16x32_bf16 v[36:39], v[132:135], v[242:245], v[36:39]
	v_mfma_f32_16x16x32_bf16 v[28:31], v[178:181], v[242:245], v[28:31]
	v_mfma_f32_16x16x32_bf16 v[20:23], v[132:135], v[250:253], v[20:23]
	v_mfma_f32_16x16x32_bf16 v[12:15], v[178:181], v[250:253], v[12:15]
	v_mfma_f32_16x16x32_bf16 v[48:51], v[182:185], v[160:163], v[48:51]
	v_mfma_f32_16x16x32_bf16 v[40:43], v[190:193], v[160:163], v[40:43]
	v_mfma_f32_16x16x32_bf16 v[32:35], v[182:185], v[230:233], v[32:35]
	v_mfma_f32_16x16x32_bf16 v[24:27], v[190:193], v[230:233], v[24:27]
	v_mfma_f32_16x16x32_bf16 v[16:19], v[182:185], v[238:241], v[16:19]
	v_mfma_f32_16x16x32_bf16 v[8:11], v[190:193], v[238:241], v[8:11]
	v_mfma_f32_16x16x32_bf16 v[4:7], v[182:185], v[246:249], v[4:7]
	v_mfma_f32_16x16x32_bf16 v[0:3], v[190:193], v[246:249], v[0:3]
	v_mfma_f32_16x16x32_bf16 v[48:51], v[186:189], v[226:229], v[48:51]
	v_mfma_f32_16x16x32_bf16 v[40:43], v[222:225], v[226:229], v[40:43]
	v_mfma_f32_16x16x32_bf16 v[32:35], v[186:189], v[234:237], v[32:35]
	v_mfma_f32_16x16x32_bf16 v[24:27], v[222:225], v[234:237], v[24:27]
	v_mfma_f32_16x16x32_bf16 v[16:19], v[186:189], v[242:245], v[16:19]
	v_mfma_f32_16x16x32_bf16 v[8:11], v[222:225], v[242:245], v[8:11]
	v_mfma_f32_16x16x32_bf16 v[4:7], v[186:189], v[250:253], v[4:7]
	v_mfma_f32_16x16x32_bf16 v[0:3], v[222:225], v[250:253], v[0:3]
	s_barrier
; #define PG8_STAGE(bufoff, gbase, voff) do { _Pragma("unroll") for (int _i = 0; _i < 2; ++_i) \
;         __builtin_amdgcn_global_load_lds((const unsigned*)((const char*)(gbase) + (voff)[_i]), (PG8_LAS unsigned*)(lds + (bufoff) + ldsw + _i * 8192), 16, 0, 0); } while (0)
; #define PG8_LDA(dst, b, h) do { _Pragma("unroll") for (int m = 0; m < 4; ++m) _Pragma("unroll") for (int k = 0; k < 2; ++k) dst[m][k] = *(const PG8_LAS bf16x8*)(lds + PG8_SA(b, h) + aoff + m * 2048 + k * 1024); } while (0)
; #define PG8_LDB(dst, b, h) do { _Pragma("unroll") for (int n = 0; n < 2; ++n) _Pragma("unroll") for (int k = 0; k < 2; ++k) dst[n][k] = *(const PG8_LAS bf16x8*)(lds + PG8_SB(b, h) + boff + n * 2048 + k * 1024); } while (0)
; #define PG8_MMA(ai, bj, At, Bt) do { __builtin_amdgcn_s_setprio(1); _Pragma("unroll") for (int m = 0; m < 4; ++m) _Pragma("unroll") for (int n = 0; n < 2; ++n) _Pragma("unroll") for (int k = 0; k < 2; ++k) \
;         acc[ai][bj][m][n] = __builtin_amdgcn_mfma_f32_16x16x32_bf16(Bt[n][k], At[m][k], acc[ai][bj][m][n], 0, 0, 0); __builtin_amdgcn_s_setprio(0); } while (0)
; #define PG8_WAIT_V(n) asm volatile("s_waitcnt vmcnt(" #n ")" ::: "memory")
; #define PG8_WAIT_L(n) asm volatile("s_waitcnt lgkmcnt(" #n ")" ::: "memory")
; #define PG8_BAR __builtin_amdgcn_s_barrier()
; #define PG8_SCHED __builtin_amdgcn_sched_barrier(0)
; template <class Epi, class Sched, bool ALIGN_EPI = false, bool SP2 = false>
; __device__ __forceinline__ void gemm_phase(PG8_LAS unsigned char* lds, const Gemm g, const Sched& S, const Epi& E) {
;     ...
;             PG8_LDB(B0, 1, 0); PG8_LDB(B1, 1, 1); PG8_SCHED; PG8_LDA(At, 1, 0); PG8_STAGE(PG8_SA(0, 1), a2 + hstep, voffA);
;             PG8_WAIT_V(8); PG8_WAIT_L(0); PG8_BAR; PG8_MMA(0, 0, At, B0); PG8_MMA(0, 1, At, B1); PG8_BAR; PG8_SCHED;
	s_setprio 0
	s_add_i32 s48, 0, 0x18000
	v_add_u32_e32 v148, s48, v159
	s_add_i32 s49, 0, 0x1c000
	ds_read_b128 v[128:131], v148
	ds_read_b128 v[132:135], v148 offset:1024
	ds_read_b128 v[136:139], v148 offset:2048
	ds_read_b128 v[160:163], v148 offset:3072
	v_add_u32_e32 v148, s49, v159
	ds_read_b128 v[178:181], v148
	ds_read_b128 v[182:185], v148 offset:1024
	ds_read_b128 v[186:189], v148 offset:2048
	ds_read_b128 v[190:193], v148 offset:3072
	s_add_u32 s30, s30, 0x80000
	s_addc_u32 s31, s31, 0
	s_mov_b32 m0, s39
	v_lshl_add_u64 v[154:155], s[30:31], 0, v[140:141]
	ds_read_b128 v[222:225], v211 offset:32768
	ds_read_b128 v[226:229], v211 offset:33792
	ds_read_b128 v[230:233], v211 offset:34816
	ds_read_b128 v[234:237], v211 offset:35840
	ds_read_b128 v[238:241], v211 offset:36864
	ds_read_b128 v[242:245], v211 offset:37888
	ds_read_b128 v[246:249], v211 offset:38912
	ds_read_b128 v[250:253], v211 offset:39936
	global_load_lds_dwordx4 v[154:155], off
	s_mov_b32 m0, s42
	v_lshl_add_u64 v[154:155], s[30:31], 0, v[144:145]
	global_load_lds_dwordx4 v[154:155], off
	s_waitcnt vmcnt(8) lgkmcnt(0)
	s_setprio 1
	s_barrier
	v_mfma_f32_16x16x32_bf16 v[124:127], v[128:131], v[222:225], v[124:127]
	v_mfma_f32_16x16x32_bf16 v[120:123], v[136:139], v[222:225], v[120:123]
	v_mfma_f32_16x16x32_bf16 v[116:119], v[128:131], v[230:233], v[116:119]
	v_mfma_f32_16x16x32_bf16 v[108:111], v[136:139], v[230:233], v[108:111]
	v_mfma_f32_16x16x32_bf16 v[100:103], v[128:131], v[238:241], v[100:103]
	v_mfma_f32_16x16x32_bf16 v[92:95], v[136:139], v[238:241], v[92:95]
	v_mfma_f32_16x16x32_bf16 v[84:87], v[128:131], v[246:249], v[84:87]
	v_mfma_f32_16x16x32_bf16 v[76:79], v[136:139], v[246:249], v[76:79]
	v_mfma_f32_16x16x32_bf16 v[124:127], v[132:135], v[226:229], v[124:127]
	v_mfma_f32_16x16x32_bf16 v[120:123], v[160:163], v[226:229], v[120:123]
	v_mfma_f32_16x16x32_bf16 v[116:119], v[132:135], v[234:237], v[116:119]
	v_mfma_f32_16x16x32_bf16 v[108:111], v[160:163], v[234:237], v[108:111]
	v_mfma_f32_16x16x32_bf16 v[100:103], v[132:135], v[242:245], v[100:103]
	v_mfma_f32_16x16x32_bf16 v[92:95], v[160:163], v[242:245], v[92:95]
	v_mfma_f32_16x16x32_bf16 v[84:87], v[132:135], v[250:253], v[84:87]
	v_mfma_f32_16x16x32_bf16 v[76:79], v[160:163], v[250:253], v[76:79]
	v_mfma_f32_16x16x32_bf16 v[112:115], v[178:181], v[222:225], v[112:115]
	v_mfma_f32_16x16x32_bf16 v[104:107], v[186:189], v[222:225], v[104:107]
	v_mfma_f32_16x16x32_bf16 v[96:99], v[178:181], v[230:233], v[96:99]
	v_mfma_f32_16x16x32_bf16 v[88:91], v[186:189], v[230:233], v[88:91]
	v_mfma_f32_16x16x32_bf16 v[80:83], v[178:181], v[238:241], v[80:83]
	v_mfma_f32_16x16x32_bf16 v[72:75], v[186:189], v[238:241], v[72:75]
	v_mfma_f32_16x16x32_bf16 v[68:71], v[178:181], v[246:249], v[68:71]
	v_mfma_f32_16x16x32_bf16 v[64:67], v[186:189], v[246:249], v[64:67]
	v_mfma_f32_16x16x32_bf16 v[112:115], v[182:185], v[226:229], v[112:115]
	v_mfma_f32_16x16x32_bf16 v[104:107], v[190:193], v[226:229], v[104:107]
	v_mfma_f32_16x16x32_bf16 v[96:99], v[182:185], v[234:237], v[96:99]
	v_mfma_f32_16x16x32_bf16 v[88:91], v[190:193], v[234:237], v[88:91]
	v_mfma_f32_16x16x32_bf16 v[80:83], v[182:185], v[242:245], v[80:83]
	v_mfma_f32_16x16x32_bf16 v[72:75], v[190:193], v[242:245], v[72:75]
	v_mfma_f32_16x16x32_bf16 v[68:71], v[182:185], v[250:253], v[68:71]
	v_mfma_f32_16x16x32_bf16 v[64:67], v[190:193], v[250:253], v[64:67]
	s_barrier
; #define PG8_STAGE(bufoff, gbase, voff) do { _Pragma("unroll") for (int _i = 0; _i < 2; ++_i) \
;         __builtin_amdgcn_global_load_lds((const unsigned*)((const char*)(gbase) + (voff)[_i]), (PG8_LAS unsigned*)(lds + (bufoff) + ldsw + _i * 8192), 16, 0, 0); } while (0)
; #define PG8_LDA(dst, b, h) do { _Pragma("unroll") for (int m = 0; m < 4; ++m) _Pragma("unroll") for (int k = 0; k < 2; ++k) dst[m][k] = *(const PG8_LAS bf16x8*)(lds + PG8_SA(b, h) + aoff + m * 2048 + k * 1024); } while (0)
; #define PG8_MMA(ai, bj, At, Bt) do { __builtin_amdgcn_s_setprio(1); _Pragma("unroll") for (int m = 0; m < 4; ++m) _Pragma("unroll") for (int n = 0; n < 2; ++n) _Pragma("unroll") for (int k = 0; k < 2; ++k) \
;         acc[ai][bj][m][n] = __builtin_amdgcn_mfma_f32_16x16x32_bf16(Bt[n][k], At[m][k], acc[ai][bj][m][n], 0, 0, 0); __builtin_amdgcn_s_setprio(0); } while (0)
; #define PG8_WAIT_V(n) asm volatile("s_waitcnt vmcnt(" #n ")" ::: "memory")
; #define PG8_WAIT_L(n) asm volatile("s_waitcnt lgkmcnt(" #n ")" ::: "memory")
; #define PG8_BAR __builtin_amdgcn_s_barrier()
; #define PG8_SCHED __builtin_amdgcn_sched_barrier(0)
; template <class Epi, class Sched, bool ALIGN_EPI = false, bool SP2 = false>
; __device__ __forceinline__ void gemm_phase(PG8_LAS unsigned char* lds, const Gemm g, const Sched& S, const Epi& E) {
;     ...
;             PG8_LDA(At, 1, 1); PG8_STAGE(PG8_SB(1, 0), b3, voffB); PG8_STAGE(PG8_SB(1, 1), b3 + hstep, voffB); PG8_STAGE(PG8_SA(1, 0), a3, voffA);
;             PG8_WAIT_V(8); PG8_WAIT_L(0); PG8_BAR; PG8_MMA(1, 0, At, B0); PG8_MMA(1, 1, At, B1); PG8_BAR; PG8_SCHED;
;     ...
;         if constexpr (ALIGN_EPI) { if (wr == 0) PG8_BAR; }
	s_setprio 0
	s_add_i32 s30, s48, s34
	v_lshl_add_u64 v[154:155], v[166:167], 0, s[10:11]
	s_mov_b32 m0, s30
	ds_read_b128 v[222:225], v211 offset:49152
	ds_read_b128 v[226:229], v211 offset:50176
	ds_read_b128 v[230:233], v211 offset:51200
	ds_read_b128 v[234:237], v211 offset:52224
	ds_read_b128 v[238:241], v211 offset:53248
	ds_read_b128 v[242:245], v211 offset:54272
	ds_read_b128 v[246:249], v211 offset:55296
	ds_read_b128 v[250:253], v211 offset:56320
	global_load_lds_dwordx4 v[154:155], off
	s_add_i32 m0, s30, 0x2000
	s_add_u32 s28, s28, 0x80080
	v_lshl_add_u64 v[154:155], v[170:171], 0, s[10:11]
	s_addc_u32 s29, s29, 0
	s_add_i32 s30, s49, s34
	global_load_lds_dwordx4 v[154:155], off
	s_mov_b32 m0, s30
	v_lshl_add_u64 v[154:155], s[28:29], 0, v[142:143]
	global_load_lds_dwordx4 v[154:155], off
	s_add_i32 m0, s30, 0x2000
	v_lshl_add_u64 v[154:155], s[28:29], 0, v[146:147]
	global_load_lds_dwordx4 v[154:155], off
	s_mov_b32 m0, s46
	v_lshl_add_u64 v[154:155], v[174:175], 0, s[10:11]
	global_load_lds_dwordx4 v[154:155], off
	s_mov_b32 m0, s47
	v_lshl_add_u64 v[154:155], v[194:195], 0, s[10:11]
	global_load_lds_dwordx4 v[154:155], off
	s_waitcnt vmcnt(8) lgkmcnt(0)
	s_setprio 1
	s_barrier
	v_mfma_f32_16x16x32_bf16 v[60:63], v[128:131], v[222:225], v[60:63]
	v_mfma_f32_16x16x32_bf16 v[56:59], v[136:139], v[222:225], v[56:59]
	v_mfma_f32_16x16x32_bf16 v[52:55], v[128:131], v[230:233], v[52:55]
	v_mfma_f32_16x16x32_bf16 v[44:47], v[136:139], v[230:233], v[44:47]
	v_mfma_f32_16x16x32_bf16 v[36:39], v[128:131], v[238:241], v[36:39]
	v_mfma_f32_16x16x32_bf16 v[28:31], v[136:139], v[238:241], v[28:31]
	v_mfma_f32_16x16x32_bf16 v[20:23], v[128:131], v[246:249], v[20:23]
	v_mfma_f32_16x16x32_bf16 v[12:15], v[136:139], v[246:249], v[12:15]
	v_mfma_f32_16x16x32_bf16 v[60:63], v[132:135], v[226:229], v[60:63]
	v_mfma_f32_16x16x32_bf16 v[56:59], v[160:163], v[226:229], v[56:59]
	v_mfma_f32_16x16x32_bf16 v[52:55], v[132:135], v[234:237], v[52:55]
	v_mfma_f32_16x16x32_bf16 v[44:47], v[160:163], v[234:237], v[44:47]
	v_mfma_f32_16x16x32_bf16 v[36:39], v[132:135], v[242:245], v[36:39]
	v_mfma_f32_16x16x32_bf16 v[28:31], v[160:163], v[242:245], v[28:31]
	v_mfma_f32_16x16x32_bf16 v[20:23], v[132:135], v[250:253], v[20:23]
	v_mfma_f32_16x16x32_bf16 v[12:15], v[160:163], v[250:253], v[12:15]
	v_mfma_f32_16x16x32_bf16 v[48:51], v[178:181], v[222:225], v[48:51]
	v_mfma_f32_16x16x32_bf16 v[40:43], v[186:189], v[222:225], v[40:43]
	v_mfma_f32_16x16x32_bf16 v[32:35], v[178:181], v[230:233], v[32:35]
	v_mfma_f32_16x16x32_bf16 v[24:27], v[186:189], v[230:233], v[24:27]
	v_mfma_f32_16x16x32_bf16 v[16:19], v[178:181], v[238:241], v[16:19]
	v_mfma_f32_16x16x32_bf16 v[8:11], v[186:189], v[238:241], v[8:11]
	v_mfma_f32_16x16x32_bf16 v[4:7], v[178:181], v[246:249], v[4:7]
	v_mfma_f32_16x16x32_bf16 v[0:3], v[186:189], v[246:249], v[0:3]
	v_mfma_f32_16x16x32_bf16 v[48:51], v[182:185], v[226:229], v[48:51]
	v_mfma_f32_16x16x32_bf16 v[40:43], v[190:193], v[226:229], v[40:43]
	v_mfma_f32_16x16x32_bf16 v[32:35], v[182:185], v[234:237], v[32:35]
	v_mfma_f32_16x16x32_bf16 v[24:27], v[190:193], v[234:237], v[24:27]
	v_mfma_f32_16x16x32_bf16 v[16:19], v[182:185], v[242:245], v[16:19]
	v_mfma_f32_16x16x32_bf16 v[8:11], v[190:193], v[242:245], v[8:11]
	v_mfma_f32_16x16x32_bf16 v[4:7], v[182:185], v[250:253], v[4:7]
	v_mfma_f32_16x16x32_bf16 v[0:3], v[190:193], v[250:253], v[0:3]
	s_barrier
	s_setprio 0
	s_add_i32 s45, s45, 2
	s_add_u32 s26, s26, 0x100
	s_addc_u32 s27, s27, 0
	s_add_u32 s33, s33, 0x100
	s_addc_u32 s44, s44, 0
	s_cmp_gt_u32 s45, 29
	s_cbranch_scc0 .LBB0_955
	s_and_b64 vcc, exec, s[12:13]
	s_cbranch_vccz .LBB0_958
	s_barrier

; #define PG8_STAGE(bufoff, gbase, voff) do { _Pragma("unroll") for (int _i = 0; _i < 2; ++_i) \
;         __builtin_amdgcn_global_load_lds((const unsigned*)((const char*)(gbase) + (voff)[_i]), (PG8_LAS unsigned*)(lds + (bufoff) + ldsw + _i * 8192), 16, 0, 0); } while (0)
; #define PG8_LDA(dst, b, h) do { _Pragma("unroll") for (int m = 0; m < 4; ++m) _Pragma("unroll") for (int k = 0; k < 2; ++k) dst[m][k] = *(const PG8_LAS bf16x8*)(lds + PG8_SA(b, h) + aoff + m * 2048 + k * 1024); } while (0)
; #define PG8_LDB(dst, b, h) do { _Pragma("unroll") for (int n = 0; n < 2; ++n) _Pragma("unroll") for (int k = 0; k < 2; ++k) dst[n][k] = *(const PG8_LAS bf16x8*)(lds + PG8_SB(b, h) + boff + n * 2048 + k * 1024); } while (0)
; #define PG8_WAIT_V(n) asm volatile("s_waitcnt vmcnt(" #n ")" ::: "memory")
; #define PG8_WAIT_L(n) asm volatile("s_waitcnt lgkmcnt(" #n ")" ::: "memory")
; #define PG8_BAR __builtin_amdgcn_s_barrier()
; #define PG8_SCHED __builtin_amdgcn_sched_barrier(0)
; template <class Epi, class Sched, bool ALIGN_EPI = false, bool SP2 = false>
; __device__ __forceinline__ void gemm_phase(PG8_LAS unsigned char* lds, const Gemm g, const Sched& S, const Epi& E) {
;     ...
;         const bool has_next = S.next(ui + 1, nxt);
;         const char* nA = has_next ? (const char*)g.A + (size_t)nxt.pm * tstep : cA; const char* nB = has_next ? (const char*)g.Bt + (size_t)nxt.pn * tstep : cB;
;         for (int t = 0; t < nt; t += 2) {
;             const bool last = (t == nt - 2);
;             const char* a1 = cA + (size_t)(t + 1) * kstep;
;             const char* a2 = last ? nA : cA + (size_t)(t + 2) * kstep; const char* b2 = last ? nB : cB + (size_t)(t + 2) * kstep;
;             const char* a3 = a2 + kstep; const char* b3 = b2 + kstep;
;             if (last && has_next) S.a_ready(nxt);
;             if constexpr (SP2) {
;             PG8_LDB(B0, 0, 0); PG8_LDB(B1, 0, 1); PG8_SCHED; PG8_LDA(At, 0, 0); PG8_STAGE(PG8_SA(1, 1), a1 + hstep, voffA);
;             PG8_WAIT_V(8); PG8_WAIT_L(0); PG8_BAR; PG8_MMA(0, 0, At, B0); PG8_MMA(0, 1, At, B1); PG8_BAR; PG8_SCHED;
;             PG8_LDA(At, 0, 1); PG8_STAGE(PG8_SB(0, 0), b2, voffB); PG8_STAGE(PG8_SB(0, 1), b2 + hstep, voffB); PG8_STAGE(PG8_SA(0, 0), a2, voffA);
;             PG8_WAIT_V(8); PG8_WAIT_L(0); PG8_BAR; PG8_MMA(1, 0, At, B0); PG8_MMA(1, 1, At, B1); PG8_BAR; PG8_SCHED;
.LBB0_1179:
	s_ashr_i32 s21, s20, 31
	s_lshl_b64 s[22:23], s[20:21], 20
	s_add_u32 s22, s56, s22
	s_addc_u32 s23, s57, s23
	s_and_b64 s[24:25], s[4:5], exec
	s_cselect_b32 s7, s23, s27
	s_cselect_b32 s21, s22, s26
	s_ashr_i32 s19, s18, 31
	s_lshl_b64 s[24:25], s[18:19], 20
	s_add_u32 s24, s68, s24
	s_addc_u32 s25, s69, s25
	s_and_b64 s[30:31], s[4:5], exec
	s_cselect_b32 s19, s25, s29
	s_cselect_b32 s46, s24, s28
	s_add_u32 s26, s26, 0x80080
	s_addc_u32 s27, s27, 0
	s_add_u32 s47, s28, 0x100
	s_addc_u32 s48, s29, 0
	s_mov_b32 s49, -2
	s_waitcnt lgkmcnt(0)
	ds_read_b128 v[128:131], v181
	ds_read_b128 v[132:135], v181 offset:1024
	ds_read_b128 v[136:139], v181 offset:2048
	ds_read_b128 v[140:143], v181 offset:3072
	ds_read_b128 v[144:147], v182
	ds_read_b128 v[148:151], v182 offset:1024
	ds_read_b128 v[168:171], v182 offset:2048
	ds_read_b128 v[172:175], v182 offset:3072
	s_add_u32 s28, s26, 0xfff80080
	s_addc_u32 s29, s27, -1
	s_cmp_eq_u32 s49, 28
	s_cselect_b32 s31, s7, s29
	s_cselect_b32 s30, s21, s28
	s_cselect_b32 s29, s19, s48
	s_cselect_b32 s28, s46, s47
	v_lshl_add_u64 v[176:177], s[26:27], 0, v[160:161]
	s_add_i32 m0, s35, 0xc000
	ds_read_b128 v[186:189], v183
	ds_read_b128 v[190:193], v183 offset:1024
	ds_read_b128 v[198:201], v183 offset:2048
	ds_read_b128 v[202:205], v183 offset:3072
	ds_read_b128 v[206:209], v183 offset:4096
	ds_read_b128 v[210:213], v183 offset:5120
	ds_read_b128 v[214:217], v183 offset:6144
	ds_read_b128 v[218:221], v183 offset:7168
	global_load_lds_dwordx4 v[176:177], off
	s_add_i32 m0, s35, 0xe000
	v_lshl_add_u64 v[176:177], s[26:27], 0, v[162:163]
	global_load_lds_dwordx4 v[176:177], off
	s_waitcnt lgkmcnt(0)
	s_setprio 1
	s_barrier
	v_mfma_f32_16x16x32_bf16 v[124:127], v[128:131], v[186:189], 0
	v_mfma_f32_16x16x32_bf16 v[120:123], v[136:139], v[186:189], 0
	v_mfma_f32_16x16x32_bf16 v[104:107], v[128:131], v[198:201], 0
	v_mfma_f32_16x16x32_bf16 v[108:111], v[136:139], v[198:201], 0
	v_mfma_f32_16x16x32_bf16 v[88:91], v[128:131], v[206:209], 0
	v_mfma_f32_16x16x32_bf16 v[92:95], v[136:139], v[206:209], 0
	v_mfma_f32_16x16x32_bf16 v[72:75], v[128:131], v[214:217], 0
	v_mfma_f32_16x16x32_bf16 v[76:79], v[136:139], v[214:217], 0
	v_mfma_f32_16x16x32_bf16 v[124:127], v[132:135], v[190:193], v[124:127]
	v_mfma_f32_16x16x32_bf16 v[120:123], v[140:143], v[190:193], v[120:123]
	v_mfma_f32_16x16x32_bf16 v[104:107], v[132:135], v[202:205], v[104:107]
	v_mfma_f32_16x16x32_bf16 v[108:111], v[140:143], v[202:205], v[108:111]
	v_mfma_f32_16x16x32_bf16 v[88:91], v[132:135], v[210:213], v[88:91]
	v_mfma_f32_16x16x32_bf16 v[92:95], v[140:143], v[210:213], v[92:95]
	v_mfma_f32_16x16x32_bf16 v[72:75], v[132:135], v[218:221], v[72:75]
	v_mfma_f32_16x16x32_bf16 v[76:79], v[140:143], v[218:221], v[76:79]
	v_mfma_f32_16x16x32_bf16 v[116:119], v[144:147], v[186:189], 0
	v_mfma_f32_16x16x32_bf16 v[112:115], v[168:171], v[186:189], 0
	v_mfma_f32_16x16x32_bf16 v[100:103], v[144:147], v[198:201], 0
	v_mfma_f32_16x16x32_bf16 v[96:99], v[168:171], v[198:201], 0
	v_mfma_f32_16x16x32_bf16 v[84:87], v[144:147], v[206:209], 0
	v_mfma_f32_16x16x32_bf16 v[80:83], v[168:171], v[206:209], 0
	v_mfma_f32_16x16x32_bf16 v[68:71], v[144:147], v[214:217], 0
	v_mfma_f32_16x16x32_bf16 v[64:67], v[168:171], v[214:217], 0
	v_mfma_f32_16x16x32_bf16 v[116:119], v[148:151], v[190:193], v[116:119]
	v_mfma_f32_16x16x32_bf16 v[112:115], v[172:175], v[190:193], v[112:115]
	v_mfma_f32_16x16x32_bf16 v[100:103], v[148:151], v[202:205], v[100:103]
	v_mfma_f32_16x16x32_bf16 v[96:99], v[172:175], v[202:205], v[96:99]
	v_mfma_f32_16x16x32_bf16 v[84:87], v[148:151], v[210:213], v[84:87]
	v_mfma_f32_16x16x32_bf16 v[80:83], v[172:175], v[210:213], v[80:83]
	v_mfma_f32_16x16x32_bf16 v[68:71], v[148:151], v[218:221], v[68:71]
	v_mfma_f32_16x16x32_bf16 v[64:67], v[172:175], v[218:221], v[64:67]
	s_barrier
	s_setprio 0
	s_add_i32 s50, s43, s34
	v_lshl_add_u64 v[176:177], s[28:29], 0, v[154:155]
	s_mov_b32 m0, s50
	ds_read_b128 v[186:189], v183 offset:16384
	ds_read_b128 v[190:193], v183 offset:17408
	ds_read_b128 v[198:201], v183 offset:18432
	ds_read_b128 v[202:205], v183 offset:19456
	ds_read_b128 v[206:209], v183 offset:20480
	ds_read_b128 v[210:213], v183 offset:21504
	ds_read_b128 v[214:217], v183 offset:22528
	ds_read_b128 v[218:221], v183 offset:23552
	global_load_lds_dwordx4 v[176:177], off
	s_add_i32 m0, s50, 0x2000
	s_add_u32 s50, s28, 0x80000
	v_lshl_add_u64 v[194:195], s[28:29], 0, v[158:159]
	s_addc_u32 s51, s29, 0
	s_add_i32 s52, s44, s34
	global_load_lds_dwordx4 v[194:195], off
	v_lshl_add_u64 v[222:223], s[50:51], 0, v[154:155]
	s_mov_b32 m0, s52
	v_lshl_add_u64 v[224:225], s[30:31], 0, v[156:157]
	global_load_lds_dwordx4 v[222:223], off
	s_add_i32 m0, s52, 0x2000
	v_lshl_add_u64 v[222:223], s[50:51], 0, v[158:159]
	global_load_lds_dwordx4 v[222:223], off
	s_mov_b32 m0, s35
	v_lshl_add_u64 v[222:223], s[30:31], 0, v[152:153]
	global_load_lds_dwordx4 v[222:223], off
	s_mov_b32 m0, s33
	s_nop 0
	global_load_lds_dwordx4 v[224:225], off
	s_waitcnt lgkmcnt(0)
	s_setprio 1
	s_barrier
; #define PG8_STAGE(bufoff, gbase, voff) do { _Pragma("unroll") for (int _i = 0; _i < 2; ++_i) \
;         __builtin_amdgcn_global_load_lds((const unsigned*)((const char*)(gbase) + (voff)[_i]), (PG8_LAS unsigned*)(lds + (bufoff) + ldsw + _i * 8192), 16, 0, 0); } while (0)
; #define PG8_LDA(dst, b, h) do { _Pragma("unroll") for (int m = 0; m < 4; ++m) _Pragma("unroll") for (int k = 0; k < 2; ++k) dst[m][k] = *(const PG8_LAS bf16x8*)(lds + PG8_SA(b, h) + aoff + m * 2048 + k * 1024); } while (0)
; #define PG8_LDB(dst, b, h) do { _Pragma("unroll") for (int n = 0; n < 2; ++n) _Pragma("unroll") for (int k = 0; k < 2; ++k) dst[n][k] = *(const PG8_LAS bf16x8*)(lds + PG8_SB(b, h) + boff + n * 2048 + k * 1024); } while (0)
; #define PG8_MMA(ai, bj, At, Bt) do { __builtin_amdgcn_s_setprio(1); _Pragma("unroll") for (int m = 0; m < 4; ++m) _Pragma("unroll") for (int n = 0; n < 2; ++n) _Pragma("unroll") for (int k = 0; k < 2; ++k) \
;         acc[ai][bj][m][n] = __builtin_amdgcn_mfma_f32_16x16x32_bf16(Bt[n][k], At[m][k], acc[ai][bj][m][n], 0, 0, 0); __builtin_amdgcn_s_setprio(0); } while (0)
; #define PG8_WAIT_V(n) asm volatile("s_waitcnt vmcnt(" #n ")" ::: "memory")
; #define PG8_WAIT_L(n) asm volatile("s_waitcnt lgkmcnt(" #n ")" ::: "memory")
; #define PG8_BAR __builtin_amdgcn_s_barrier()
; #define PG8_SCHED __builtin_amdgcn_sched_barrier(0)
; template <class Epi, class Sched, bool ALIGN_EPI = false, bool SP2 = false>
; __device__ __forceinline__ void gemm_phase(PG8_LAS unsigned char* lds, const Gemm g, const Sched& S, const Epi& E) {
;     ...
;             PG8_WAIT_V(8); PG8_WAIT_L(0); PG8_BAR; PG8_MMA(1, 0, At, B0); PG8_MMA(1, 1, At, B1); PG8_BAR; PG8_SCHED;
;             PG8_LDB(B0, 1, 0); PG8_LDB(B1, 1, 1); PG8_SCHED; PG8_LDA(At, 1, 0); PG8_STAGE(PG8_SA(0, 1), a2 + hstep, voffA);
;             PG8_WAIT_V(8); PG8_WAIT_L(0); PG8_BAR; PG8_MMA(0, 0, At, B0); PG8_MMA(0, 1, At, B1); PG8_BAR; PG8_SCHED;
	v_mfma_f32_16x16x32_bf16 v[56:59], v[128:131], v[186:189], 0
	v_mfma_f32_16x16x32_bf16 v[60:63], v[136:139], v[186:189], 0
	v_mfma_f32_16x16x32_bf16 v[40:43], v[128:131], v[198:201], 0
	v_mfma_f32_16x16x32_bf16 v[44:47], v[136:139], v[198:201], 0
	v_mfma_f32_16x16x32_bf16 v[24:27], v[128:131], v[206:209], 0
	v_mfma_f32_16x16x32_bf16 v[28:31], v[136:139], v[206:209], 0
	v_mfma_f32_16x16x32_bf16 v[8:11], v[128:131], v[214:217], 0
	v_mfma_f32_16x16x32_bf16 v[12:15], v[136:139], v[214:217], 0
	v_mfma_f32_16x16x32_bf16 v[56:59], v[132:135], v[190:193], v[56:59]
	v_mfma_f32_16x16x32_bf16 v[60:63], v[140:143], v[190:193], v[60:63]
	v_mfma_f32_16x16x32_bf16 v[40:43], v[132:135], v[202:205], v[40:43]
	v_mfma_f32_16x16x32_bf16 v[44:47], v[140:143], v[202:205], v[44:47]
	v_mfma_f32_16x16x32_bf16 v[24:27], v[132:135], v[210:213], v[24:27]
	v_mfma_f32_16x16x32_bf16 v[28:31], v[140:143], v[210:213], v[28:31]
	v_mfma_f32_16x16x32_bf16 v[8:11], v[132:135], v[218:221], v[8:11]
	v_mfma_f32_16x16x32_bf16 v[12:15], v[140:143], v[218:221], v[12:15]
	v_mfma_f32_16x16x32_bf16 v[52:55], v[144:147], v[186:189], 0
	v_mfma_f32_16x16x32_bf16 v[48:51], v[168:171], v[186:189], 0
	v_mfma_f32_16x16x32_bf16 v[36:39], v[144:147], v[198:201], 0
	v_mfma_f32_16x16x32_bf16 v[32:35], v[168:171], v[198:201], 0
	v_mfma_f32_16x16x32_bf16 v[20:23], v[144:147], v[206:209], 0
	v_mfma_f32_16x16x32_bf16 v[16:19], v[168:171], v[206:209], 0
	v_mfma_f32_16x16x32_bf16 v[4:7], v[144:147], v[214:217], 0
	v_mfma_f32_16x16x32_bf16 v[0:3], v[168:171], v[214:217], 0
	v_mfma_f32_16x16x32_bf16 v[52:55], v[148:151], v[190:193], v[52:55]
	v_mfma_f32_16x16x32_bf16 v[48:51], v[172:175], v[190:193], v[48:51]
	v_mfma_f32_16x16x32_bf16 v[36:39], v[148:151], v[202:205], v[36:39]
	v_mfma_f32_16x16x32_bf16 v[32:35], v[172:175], v[202:205], v[32:35]
	v_mfma_f32_16x16x32_bf16 v[20:23], v[148:151], v[210:213], v[20:23]
	v_mfma_f32_16x16x32_bf16 v[16:19], v[172:175], v[210:213], v[16:19]
	v_mfma_f32_16x16x32_bf16 v[4:7], v[148:151], v[218:221], v[4:7]
	v_mfma_f32_16x16x32_bf16 v[0:3], v[172:175], v[218:221], v[0:3]
	s_barrier
	s_setprio 0
	s_add_i32 s50, 0, 0x18000
	s_add_i32 s51, 0, 0x1c000
	v_add_u32_e32 v140, s50, v179
	v_add_u32_e32 v172, s51, v179
	ds_read_b128 v[128:131], v140
	ds_read_b128 v[132:135], v140 offset:1024
	ds_read_b128 v[136:139], v140 offset:2048
	ds_read_b128 v[140:143], v140 offset:3072
	ds_read_b128 v[144:147], v172
	ds_read_b128 v[148:151], v172 offset:1024
	ds_read_b128 v[168:171], v172 offset:2048
	ds_read_b128 v[172:175], v172 offset:3072
	s_add_u32 s30, s30, 0x80000
	s_addc_u32 s31, s31, 0
	s_mov_b32 m0, s36
	v_lshl_add_u64 v[226:227], s[30:31], 0, v[152:153]
	ds_read_b128 v[186:189], v183 offset:32768
	ds_read_b128 v[190:193], v183 offset:33792
	ds_read_b128 v[198:201], v183 offset:34816
	ds_read_b128 v[202:205], v183 offset:35840
	ds_read_b128 v[206:209], v183 offset:36864
	ds_read_b128 v[210:213], v183 offset:37888
	ds_read_b128 v[214:217], v183 offset:38912
	ds_read_b128 v[218:221], v183 offset:39936
	global_load_lds_dwordx4 v[226:227], off
	s_mov_b32 m0, s37
	v_lshl_add_u64 v[226:227], s[30:31], 0, v[156:157]
	global_load_lds_dwordx4 v[226:227], off
	s_waitcnt vmcnt(8) lgkmcnt(0)
	s_setprio 1
	s_barrier
	v_mfma_f32_16x16x32_bf16 v[124:127], v[128:131], v[186:189], v[124:127]
	v_mfma_f32_16x16x32_bf16 v[120:123], v[136:139], v[186:189], v[120:123]
	v_mfma_f32_16x16x32_bf16 v[104:107], v[128:131], v[198:201], v[104:107]
	v_mfma_f32_16x16x32_bf16 v[108:111], v[136:139], v[198:201], v[108:111]
	v_mfma_f32_16x16x32_bf16 v[88:91], v[128:131], v[206:209], v[88:91]
	v_mfma_f32_16x16x32_bf16 v[92:95], v[136:139], v[206:209], v[92:95]
	v_mfma_f32_16x16x32_bf16 v[72:75], v[128:131], v[214:217], v[72:75]
	v_mfma_f32_16x16x32_bf16 v[76:79], v[136:139], v[214:217], v[76:79]
	v_mfma_f32_16x16x32_bf16 v[124:127], v[132:135], v[190:193], v[124:127]
	v_mfma_f32_16x16x32_bf16 v[120:123], v[140:143], v[190:193], v[120:123]
	v_mfma_f32_16x16x32_bf16 v[104:107], v[132:135], v[202:205], v[104:107]
	v_mfma_f32_16x16x32_bf16 v[108:111], v[140:143], v[202:205], v[108:111]
	v_mfma_f32_16x16x32_bf16 v[88:91], v[132:135], v[210:213], v[88:91]
	v_mfma_f32_16x16x32_bf16 v[92:95], v[140:143], v[210:213], v[92:95]
	v_mfma_f32_16x16x32_bf16 v[72:75], v[132:135], v[218:221], v[72:75]
	v_mfma_f32_16x16x32_bf16 v[76:79], v[140:143], v[218:221], v[76:79]
	v_mfma_f32_16x16x32_bf16 v[116:119], v[144:147], v[186:189], v[116:119]
	v_mfma_f32_16x16x32_bf16 v[112:115], v[168:171], v[186:189], v[112:115]
	v_mfma_f32_16x16x32_bf16 v[100:103], v[144:147], v[198:201], v[100:103]
	v_mfma_f32_16x16x32_bf16 v[96:99], v[168:171], v[198:201], v[96:99]
	v_mfma_f32_16x16x32_bf16 v[84:87], v[144:147], v[206:209], v[84:87]
	v_mfma_f32_16x16x32_bf16 v[80:83], v[168:171], v[206:209], v[80:83]
	v_mfma_f32_16x16x32_bf16 v[68:71], v[144:147], v[214:217], v[68:71]
	v_mfma_f32_16x16x32_bf16 v[64:67], v[168:171], v[214:217], v[64:67]
	v_mfma_f32_16x16x32_bf16 v[116:119], v[148:151], v[190:193], v[116:119]
	v_mfma_f32_16x16x32_bf16 v[112:115], v[172:175], v[190:193], v[112:115]
	v_mfma_f32_16x16x32_bf16 v[100:103], v[148:151], v[202:205], v[100:103]
	v_mfma_f32_16x16x32_bf16 v[96:99], v[172:175], v[202:205], v[96:99]
	v_mfma_f32_16x16x32_bf16 v[84:87], v[148:151], v[210:213], v[84:87]
	v_mfma_f32_16x16x32_bf16 v[80:83], v[172:175], v[210:213], v[80:83]
	v_mfma_f32_16x16x32_bf16 v[68:71], v[148:151], v[218:221], v[68:71]
	v_mfma_f32_16x16x32_bf16 v[64:67], v[172:175], v[218:221], v[64:67]
	s_barrier
; #define PG8_STAGE(bufoff, gbase, voff) do { _Pragma("unroll") for (int _i = 0; _i < 2; ++_i) \
;         __builtin_amdgcn_global_load_lds((const unsigned*)((const char*)(gbase) + (voff)[_i]), (PG8_LAS unsigned*)(lds + (bufoff) + ldsw + _i * 8192), 16, 0, 0); } while (0)
; #define PG8_LDA(dst, b, h) do { _Pragma("unroll") for (int m = 0; m < 4; ++m) _Pragma("unroll") for (int k = 0; k < 2; ++k) dst[m][k] = *(const PG8_LAS bf16x8*)(lds + PG8_SA(b, h) + aoff + m * 2048 + k * 1024); } while (0)
; #define PG8_LDB(dst, b, h) do { _Pragma("unroll") for (int n = 0; n < 2; ++n) _Pragma("unroll") for (int k = 0; k < 2; ++k) dst[n][k] = *(const PG8_LAS bf16x8*)(lds + PG8_SB(b, h) + boff + n * 2048 + k * 1024); } while (0)
; template <class Epi, class Sched, bool ALIGN_EPI = false, bool SP2 = false>
; __device__ __forceinline__ void gemm_phase(PG8_LAS unsigned char* lds, const Gemm g, const Sched& S, const Epi& E) {
;     ...
;         for (int t = 0; t < nt; t += 2) {
;             const bool last = (t == nt - 2);
;             const char* a1 = cA + (size_t)(t + 1) * kstep;
;             const char* a2 = last ? nA : cA + (size_t)(t + 2) * kstep; const char* b2 = last ? nB : cB + (size_t)(t + 2) * kstep;
;             const char* a3 = a2 + kstep; const char* b3 = b2 + kstep;
;             if (last && has_next) S.a_ready(nxt);
;             if constexpr (SP2) {
;             PG8_LDB(B0, 0, 0); PG8_LDB(B1, 0, 1); PG8_SCHED; PG8_LDA(At, 0, 0); PG8_STAGE(PG8_SA(1, 1), a1 + hstep, voffA);
;             PG8_WAIT_V(8); PG8_WAIT_L(0); PG8_BAR; PG8_MMA(0, 0, At, B0); PG8_MMA(0, 1, At, B1); PG8_BAR; PG8_SCHED;
;             PG8_LDA(At, 0, 1); PG8_STAGE(PG8_SB(0, 0), b2, voffB); PG8_STAGE(PG8_SB(0, 1), b2 + hstep, voffB); PG8_STAGE(PG8_SA(0, 0), a2, voffA);
;             PG8_WAIT_V(8); PG8_WAIT_L(0); PG8_BAR; PG8_MMA(1, 0, At, B0); PG8_MMA(1, 1, At, B1); PG8_BAR; PG8_SCHED;
;             PG8_LDB(B0, 1, 0); PG8_LDB(B1, 1, 1); PG8_SCHED; PG8_LDA(At, 1, 0); PG8_STAGE(PG8_SA(0, 1), a2 + hstep, voffA);
;             PG8_WAIT_V(8); PG8_WAIT_L(0); PG8_BAR; PG8_MMA(0, 0, At, B0); PG8_MMA(0, 1, At, B1); PG8_BAR; PG8_SCHED;
;             PG8_LDA(At, 1, 1); PG8_STAGE(PG8_SB(1, 0), b3, voffB); PG8_STAGE(PG8_SB(1, 1), b3 + hstep, voffB); PG8_STAGE(PG8_SA(1, 0), a3, voffA);
;             PG8_WAIT_V(8); PG8_WAIT_L(0); PG8_BAR; PG8_MMA(1, 0, At, B0); PG8_MMA(1, 1, At, B1); PG8_BAR; PG8_SCHED;
	s_setprio 0
	s_add_i32 s30, s50, s34
	v_lshl_add_u64 v[176:177], v[176:177], 0, s[12:13]
	s_mov_b32 m0, s30
	ds_read_b128 v[186:189], v183 offset:49152
	ds_read_b128 v[190:193], v183 offset:50176
	ds_read_b128 v[198:201], v183 offset:51200
	ds_read_b128 v[202:205], v183 offset:52224
	ds_read_b128 v[206:209], v183 offset:53248
	ds_read_b128 v[210:213], v183 offset:54272
	ds_read_b128 v[214:217], v183 offset:55296
	ds_read_b128 v[218:221], v183 offset:56320
	global_load_lds_dwordx4 v[176:177], off
	s_add_i32 m0, s30, 0x2000
	s_add_u32 s28, s28, 0x80080
	v_lshl_add_u64 v[176:177], v[194:195], 0, s[12:13]
	s_addc_u32 s29, s29, 0
	s_add_i32 s30, s51, s34
	global_load_lds_dwordx4 v[176:177], off
	s_mov_b32 m0, s30
	v_lshl_add_u64 v[176:177], s[28:29], 0, v[154:155]
	global_load_lds_dwordx4 v[176:177], off
	s_add_i32 m0, s30, 0x2000
	v_lshl_add_u64 v[176:177], s[28:29], 0, v[158:159]
	global_load_lds_dwordx4 v[176:177], off
	s_mov_b32 m0, s39
	v_lshl_add_u64 v[176:177], v[222:223], 0, s[12:13]
	global_load_lds_dwordx4 v[176:177], off
	s_mov_b32 m0, s40
	v_lshl_add_u64 v[176:177], v[224:225], 0, s[12:13]
	global_load_lds_dwordx4 v[176:177], off
	s_waitcnt vmcnt(8) lgkmcnt(0)
	s_setprio 1
	s_barrier
	v_mfma_f32_16x16x32_bf16 v[56:59], v[128:131], v[186:189], v[56:59]
	v_mfma_f32_16x16x32_bf16 v[60:63], v[136:139], v[186:189], v[60:63]
	v_mfma_f32_16x16x32_bf16 v[40:43], v[128:131], v[198:201], v[40:43]
	v_mfma_f32_16x16x32_bf16 v[44:47], v[136:139], v[198:201], v[44:47]
	v_mfma_f32_16x16x32_bf16 v[24:27], v[128:131], v[206:209], v[24:27]
	v_mfma_f32_16x16x32_bf16 v[28:31], v[136:139], v[206:209], v[28:31]
	v_mfma_f32_16x16x32_bf16 v[8:11], v[128:131], v[214:217], v[8:11]
	v_mfma_f32_16x16x32_bf16 v[12:15], v[136:139], v[214:217], v[12:15]
	v_mfma_f32_16x16x32_bf16 v[56:59], v[132:135], v[190:193], v[56:59]
	v_mfma_f32_16x16x32_bf16 v[60:63], v[140:143], v[190:193], v[60:63]
	v_mfma_f32_16x16x32_bf16 v[40:43], v[132:135], v[202:205], v[40:43]
	v_mfma_f32_16x16x32_bf16 v[44:47], v[140:143], v[202:205], v[44:47]
	v_mfma_f32_16x16x32_bf16 v[24:27], v[132:135], v[210:213], v[24:27]
	v_mfma_f32_16x16x32_bf16 v[28:31], v[140:143], v[210:213], v[28:31]
	v_mfma_f32_16x16x32_bf16 v[8:11], v[132:135], v[218:221], v[8:11]
	v_mfma_f32_16x16x32_bf16 v[12:15], v[140:143], v[218:221], v[12:15]
	v_mfma_f32_16x16x32_bf16 v[52:55], v[144:147], v[186:189], v[52:55]
	v_mfma_f32_16x16x32_bf16 v[48:51], v[168:171], v[186:189], v[48:51]
	v_mfma_f32_16x16x32_bf16 v[36:39], v[144:147], v[198:201], v[36:39]
	v_mfma_f32_16x16x32_bf16 v[32:35], v[168:171], v[198:201], v[32:35]
	v_mfma_f32_16x16x32_bf16 v[20:23], v[144:147], v[206:209], v[20:23]
	v_mfma_f32_16x16x32_bf16 v[16:19], v[168:171], v[206:209], v[16:19]
	v_mfma_f32_16x16x32_bf16 v[4:7], v[144:147], v[214:217], v[4:7]
	v_mfma_f32_16x16x32_bf16 v[0:3], v[168:171], v[214:217], v[0:3]
	v_mfma_f32_16x16x32_bf16 v[52:55], v[148:151], v[190:193], v[52:55]
	v_mfma_f32_16x16x32_bf16 v[48:51], v[172:175], v[190:193], v[48:51]
	v_mfma_f32_16x16x32_bf16 v[36:39], v[148:151], v[202:205], v[36:39]
	v_mfma_f32_16x16x32_bf16 v[32:35], v[172:175], v[202:205], v[32:35]
	v_mfma_f32_16x16x32_bf16 v[20:23], v[148:151], v[210:213], v[20:23]
	v_mfma_f32_16x16x32_bf16 v[16:19], v[172:175], v[210:213], v[16:19]
	v_mfma_f32_16x16x32_bf16 v[4:7], v[148:151], v[218:221], v[4:7]
	v_mfma_f32_16x16x32_bf16 v[0:3], v[172:175], v[218:221], v[0:3]
	s_barrier
	s_setprio 0
	s_add_i32 s49, s49, 2
	s_add_u32 s26, s26, 0x100
	s_addc_u32 s27, s27, 0
	s_add_u32 s47, s47, 0x100
	s_addc_u32 s48, s48, 0
.LBB0_1180:
	ds_read_b128 v[128:131], v181
	ds_read_b128 v[132:135], v181 offset:1024
	ds_read_b128 v[136:139], v181 offset:2048
	ds_read_b128 v[140:143], v181 offset:3072
	ds_read_b128 v[144:147], v182
	ds_read_b128 v[148:151], v182 offset:1024
	ds_read_b128 v[168:171], v182 offset:2048
	ds_read_b128 v[172:175], v182 offset:3072
	s_add_u32 s28, s26, 0xfff80080
	s_addc_u32 s29, s27, -1
	s_cmp_eq_u32 s49, 28
	s_cselect_b32 s31, s7, s29
	s_cselect_b32 s30, s21, s28
	s_cselect_b32 s29, s19, s48
	s_cselect_b32 s28, s46, s47
	v_lshl_add_u64 v[176:177], s[26:27], 0, v[160:161]
	s_add_i32 m0, s35, 0xc000
	ds_read_b128 v[186:189], v183
	ds_read_b128 v[190:193], v183 offset:1024
	ds_read_b128 v[198:201], v183 offset:2048
	ds_read_b128 v[202:205], v183 offset:3072
	ds_read_b128 v[206:209], v183 offset:4096
	ds_read_b128 v[210:213], v183 offset:5120
	ds_read_b128 v[214:217], v183 offset:6144
	ds_read_b128 v[218:221], v183 offset:7168
	global_load_lds_dwordx4 v[176:177], off
	s_add_i32 m0, s35, 0xe000
	v_lshl_add_u64 v[176:177], s[26:27], 0, v[162:163]
	global_load_lds_dwordx4 v[176:177], off
	s_waitcnt vmcnt(8) lgkmcnt(0)
	s_setprio 1
	s_barrier
; #define PG8_STAGE(bufoff, gbase, voff) do { _Pragma("unroll") for (int _i = 0; _i < 2; ++_i) \
;         __builtin_amdgcn_global_load_lds((const unsigned*)((const char*)(gbase) + (voff)[_i]), (PG8_LAS unsigned*)(lds + (bufoff) + ldsw + _i * 8192), 16, 0, 0); } while (0)
; #define PG8_LDA(dst, b, h) do { _Pragma("unroll") for (int m = 0; m < 4; ++m) _Pragma("unroll") for (int k = 0; k < 2; ++k) dst[m][k] = *(const PG8_LAS bf16x8*)(lds + PG8_SA(b, h) + aoff + m * 2048 + k * 1024); } while (0)
; #define PG8_LDB(dst, b, h) do { _Pragma("unroll") for (int n = 0; n < 2; ++n) _Pragma("unroll") for (int k = 0; k < 2; ++k) dst[n][k] = *(const PG8_LAS bf16x8*)(lds + PG8_SB(b, h) + boff + n * 2048 + k * 1024); } while (0)
; #define PG8_MMA(ai, bj, At, Bt) do { __builtin_amdgcn_s_setprio(1); _Pragma("unroll") for (int m = 0; m < 4; ++m) _Pragma("unroll") for (int n = 0; n < 2; ++n) _Pragma("unroll") for (int k = 0; k < 2; ++k) \
;         acc[ai][bj][m][n] = __builtin_amdgcn_mfma_f32_16x16x32_bf16(Bt[n][k], At[m][k], acc[ai][bj][m][n], 0, 0, 0); __builtin_amdgcn_s_setprio(0); } while (0)
; #define PG8_WAIT_V(n) asm volatile("s_waitcnt vmcnt(" #n ")" ::: "memory")
; #define PG8_WAIT_L(n) asm volatile("s_waitcnt lgkmcnt(" #n ")" ::: "memory")
; #define PG8_BAR __builtin_amdgcn_s_barrier()
; #define PG8_SCHED __builtin_amdgcn_sched_barrier(0)
; template <class Epi, class Sched, bool ALIGN_EPI = false, bool SP2 = false>
; __device__ __forceinline__ void gemm_phase(PG8_LAS unsigned char* lds, const Gemm g, const Sched& S, const Epi& E) {
;     ...
;             PG8_LDB(B0, 0, 0); PG8_LDB(B1, 0, 1); PG8_SCHED; PG8_LDA(At, 0, 0); PG8_STAGE(PG8_SA(1, 1), a1 + hstep, voffA);
;             PG8_WAIT_V(8); PG8_WAIT_L(0); PG8_BAR; PG8_MMA(0, 0, At, B0); PG8_MMA(0, 1, At, B1); PG8_BAR; PG8_SCHED;
;             PG8_LDA(At, 0, 1); PG8_STAGE(PG8_SB(0, 0), b2, voffB); PG8_STAGE(PG8_SB(0, 1), b2 + hstep, voffB); PG8_STAGE(PG8_SA(0, 0), a2, voffA);
;             PG8_WAIT_V(8); PG8_WAIT_L(0); PG8_BAR; PG8_MMA(1, 0, At, B0); PG8_MMA(1, 1, At, B1); PG8_BAR; PG8_SCHED;
	v_mfma_f32_16x16x32_bf16 v[124:127], v[128:131], v[186:189], v[124:127]
	v_mfma_f32_16x16x32_bf16 v[120:123], v[136:139], v[186:189], v[120:123]
	v_mfma_f32_16x16x32_bf16 v[104:107], v[128:131], v[198:201], v[104:107]
	v_mfma_f32_16x16x32_bf16 v[108:111], v[136:139], v[198:201], v[108:111]
	v_mfma_f32_16x16x32_bf16 v[88:91], v[128:131], v[206:209], v[88:91]
	v_mfma_f32_16x16x32_bf16 v[92:95], v[136:139], v[206:209], v[92:95]
	v_mfma_f32_16x16x32_bf16 v[72:75], v[128:131], v[214:217], v[72:75]
	v_mfma_f32_16x16x32_bf16 v[76:79], v[136:139], v[214:217], v[76:79]
	v_mfma_f32_16x16x32_bf16 v[124:127], v[132:135], v[190:193], v[124:127]
	v_mfma_f32_16x16x32_bf16 v[120:123], v[140:143], v[190:193], v[120:123]
	v_mfma_f32_16x16x32_bf16 v[104:107], v[132:135], v[202:205], v[104:107]
	v_mfma_f32_16x16x32_bf16 v[108:111], v[140:143], v[202:205], v[108:111]
	v_mfma_f32_16x16x32_bf16 v[88:91], v[132:135], v[210:213], v[88:91]
	v_mfma_f32_16x16x32_bf16 v[92:95], v[140:143], v[210:213], v[92:95]
	v_mfma_f32_16x16x32_bf16 v[72:75], v[132:135], v[218:221], v[72:75]
	v_mfma_f32_16x16x32_bf16 v[76:79], v[140:143], v[218:221], v[76:79]
	v_mfma_f32_16x16x32_bf16 v[116:119], v[144:147], v[186:189], v[116:119]
	v_mfma_f32_16x16x32_bf16 v[112:115], v[168:171], v[186:189], v[112:115]
	v_mfma_f32_16x16x32_bf16 v[100:103], v[144:147], v[198:201], v[100:103]
	v_mfma_f32_16x16x32_bf16 v[96:99], v[168:171], v[198:201], v[96:99]
	v_mfma_f32_16x16x32_bf16 v[84:87], v[144:147], v[206:209], v[84:87]
	v_mfma_f32_16x16x32_bf16 v[80:83], v[168:171], v[206:209], v[80:83]
	v_mfma_f32_16x16x32_bf16 v[68:71], v[144:147], v[214:217], v[68:71]
	v_mfma_f32_16x16x32_bf16 v[64:67], v[168:171], v[214:217], v[64:67]
	v_mfma_f32_16x16x32_bf16 v[116:119], v[148:151], v[190:193], v[116:119]
	v_mfma_f32_16x16x32_bf16 v[112:115], v[172:175], v[190:193], v[112:115]
	v_mfma_f32_16x16x32_bf16 v[100:103], v[148:151], v[202:205], v[100:103]
	v_mfma_f32_16x16x32_bf16 v[96:99], v[172:175], v[202:205], v[96:99]
	v_mfma_f32_16x16x32_bf16 v[84:87], v[148:151], v[210:213], v[84:87]
	v_mfma_f32_16x16x32_bf16 v[80:83], v[172:175], v[210:213], v[80:83]
	v_mfma_f32_16x16x32_bf16 v[68:71], v[148:151], v[218:221], v[68:71]
	v_mfma_f32_16x16x32_bf16 v[64:67], v[172:175], v[218:221], v[64:67]
	s_barrier
	s_setprio 0
	s_add_i32 s50, s43, s34
	v_lshl_add_u64 v[176:177], s[28:29], 0, v[154:155]
	s_mov_b32 m0, s50
	ds_read_b128 v[186:189], v183 offset:16384
	ds_read_b128 v[190:193], v183 offset:17408
	ds_read_b128 v[198:201], v183 offset:18432
	ds_read_b128 v[202:205], v183 offset:19456
	ds_read_b128 v[206:209], v183 offset:20480
	ds_read_b128 v[210:213], v183 offset:21504
	ds_read_b128 v[214:217], v183 offset:22528
	ds_read_b128 v[218:221], v183 offset:23552
	global_load_lds_dwordx4 v[176:177], off
	s_add_i32 m0, s50, 0x2000
	s_add_u32 s50, s28, 0x80000
	v_lshl_add_u64 v[194:195], s[28:29], 0, v[158:159]
	s_addc_u32 s51, s29, 0
	s_add_i32 s52, s44, s34
	global_load_lds_dwordx4 v[194:195], off
	v_lshl_add_u64 v[222:223], s[50:51], 0, v[154:155]
	s_mov_b32 m0, s52
	v_lshl_add_u64 v[224:225], s[30:31], 0, v[156:157]
	global_load_lds_dwordx4 v[222:223], off
	s_add_i32 m0, s52, 0x2000
	v_lshl_add_u64 v[222:223], s[50:51], 0, v[158:159]
	global_load_lds_dwordx4 v[222:223], off
	s_mov_b32 m0, s35
	v_lshl_add_u64 v[222:223], s[30:31], 0, v[152:153]
	global_load_lds_dwordx4 v[222:223], off
	s_mov_b32 m0, s33
	s_nop 0
	global_load_lds_dwordx4 v[224:225], off
	s_waitcnt vmcnt(8) lgkmcnt(0)
	s_setprio 1
	s_barrier
	v_mfma_f32_16x16x32_bf16 v[56:59], v[128:131], v[186:189], v[56:59]
	v_mfma_f32_16x16x32_bf16 v[60:63], v[136:139], v[186:189], v[60:63]
	v_mfma_f32_16x16x32_bf16 v[40:43], v[128:131], v[198:201], v[40:43]
	v_mfma_f32_16x16x32_bf16 v[44:47], v[136:139], v[198:201], v[44:47]
	v_mfma_f32_16x16x32_bf16 v[24:27], v[128:131], v[206:209], v[24:27]
	v_mfma_f32_16x16x32_bf16 v[28:31], v[136:139], v[206:209], v[28:31]
	v_mfma_f32_16x16x32_bf16 v[8:11], v[128:131], v[214:217], v[8:11]
	v_mfma_f32_16x16x32_bf16 v[12:15], v[136:139], v[214:217], v[12:15]
	v_mfma_f32_16x16x32_bf16 v[56:59], v[132:135], v[190:193], v[56:59]
	v_mfma_f32_16x16x32_bf16 v[60:63], v[140:143], v[190:193], v[60:63]
	v_mfma_f32_16x16x32_bf16 v[40:43], v[132:135], v[202:205], v[40:43]
	v_mfma_f32_16x16x32_bf16 v[44:47], v[140:143], v[202:205], v[44:47]
	v_mfma_f32_16x16x32_bf16 v[24:27], v[132:135], v[210:213], v[24:27]
	v_mfma_f32_16x16x32_bf16 v[28:31], v[140:143], v[210:213], v[28:31]
	v_mfma_f32_16x16x32_bf16 v[8:11], v[132:135], v[218:221], v[8:11]
	v_mfma_f32_16x16x32_bf16 v[12:15], v[140:143], v[218:221], v[12:15]
	v_mfma_f32_16x16x32_bf16 v[52:55], v[144:147], v[186:189], v[52:55]
	v_mfma_f32_16x16x32_bf16 v[48:51], v[168:171], v[186:189], v[48:51]
	v_mfma_f32_16x16x32_bf16 v[36:39], v[144:147], v[198:201], v[36:39]
	v_mfma_f32_16x16x32_bf16 v[32:35], v[168:171], v[198:201], v[32:35]
	v_mfma_f32_16x16x32_bf16 v[20:23], v[144:147], v[206:209], v[20:23]
	v_mfma_f32_16x16x32_bf16 v[16:19], v[168:171], v[206:209], v[16:19]
	v_mfma_f32_16x16x32_bf16 v[4:7], v[144:147], v[214:217], v[4:7]
	v_mfma_f32_16x16x32_bf16 v[0:3], v[168:171], v[214:217], v[0:3]
	v_mfma_f32_16x16x32_bf16 v[52:55], v[148:151], v[190:193], v[52:55]
	v_mfma_f32_16x16x32_bf16 v[48:51], v[172:175], v[190:193], v[48:51]
	v_mfma_f32_16x16x32_bf16 v[36:39], v[148:151], v[202:205], v[36:39]
	v_mfma_f32_16x16x32_bf16 v[32:35], v[172:175], v[202:205], v[32:35]
	v_mfma_f32_16x16x32_bf16 v[20:23], v[148:151], v[210:213], v[20:23]
	v_mfma_f32_16x16x32_bf16 v[16:19], v[172:175], v[210:213], v[16:19]
	v_mfma_f32_16x16x32_bf16 v[4:7], v[148:151], v[218:221], v[4:7]
	v_mfma_f32_16x16x32_bf16 v[0:3], v[172:175], v[218:221], v[0:3]
	s_barrier
; #define PG8_STAGE(bufoff, gbase, voff) do { _Pragma("unroll") for (int _i = 0; _i < 2; ++_i) \
;         __builtin_amdgcn_global_load_lds((const unsigned*)((const char*)(gbase) + (voff)[_i]), (PG8_LAS unsigned*)(lds + (bufoff) + ldsw + _i * 8192), 16, 0, 0); } while (0)
; #define PG8_LDA(dst, b, h) do { _Pragma("unroll") for (int m = 0; m < 4; ++m) _Pragma("unroll") for (int k = 0; k < 2; ++k) dst[m][k] = *(const PG8_LAS bf16x8*)(lds + PG8_SA(b, h) + aoff + m * 2048 + k * 1024); } while (0)
; #define PG8_LDB(dst, b, h) do { _Pragma("unroll") for (int n = 0; n < 2; ++n) _Pragma("unroll") for (int k = 0; k < 2; ++k) dst[n][k] = *(const PG8_LAS bf16x8*)(lds + PG8_SB(b, h) + boff + n * 2048 + k * 1024); } while (0)
; #define PG8_MMA(ai, bj, At, Bt) do { __builtin_amdgcn_s_setprio(1); _Pragma("unroll") for (int m = 0; m < 4; ++m) _Pragma("unroll") for (int n = 0; n < 2; ++n) _Pragma("unroll") for (int k = 0; k < 2; ++k) \
;         acc[ai][bj][m][n] = __builtin_amdgcn_mfma_f32_16x16x32_bf16(Bt[n][k], At[m][k], acc[ai][bj][m][n], 0, 0, 0); __builtin_amdgcn_s_setprio(0); } while (0)
; #define PG8_WAIT_V(n) asm volatile("s_waitcnt vmcnt(" #n ")" ::: "memory")
; #define PG8_WAIT_L(n) asm volatile("s_waitcnt lgkmcnt(" #n ")" ::: "memory")
; #define PG8_BAR __builtin_amdgcn_s_barrier()
; #define PG8_SCHED __builtin_amdgcn_sched_barrier(0)
; template <class Epi, class Sched, bool ALIGN_EPI = false, bool SP2 = false>
; __device__ __forceinline__ void gemm_phase(PG8_LAS unsigned char* lds, const Gemm g, const Sched& S, const Epi& E) {
;     ...
;             PG8_LDB(B0, 1, 0); PG8_LDB(B1, 1, 1); PG8_SCHED; PG8_LDA(At, 1, 0); PG8_STAGE(PG8_SA(0, 1), a2 + hstep, voffA);
;             PG8_WAIT_V(8); PG8_WAIT_L(0); PG8_BAR; PG8_MMA(0, 0, At, B0); PG8_MMA(0, 1, At, B1); PG8_BAR; PG8_SCHED;
	s_setprio 0
	s_add_i32 s50, 0, 0x18000
	s_add_i32 s51, 0, 0x1c000
	v_add_u32_e32 v140, s50, v179
	v_add_u32_e32 v172, s51, v179
	ds_read_b128 v[128:131], v140
	ds_read_b128 v[132:135], v140 offset:1024
	ds_read_b128 v[136:139], v140 offset:2048
	ds_read_b128 v[140:143], v140 offset:3072
	ds_read_b128 v[144:147], v172
	ds_read_b128 v[148:151], v172 offset:1024
	ds_read_b128 v[168:171], v172 offset:2048
	ds_read_b128 v[172:175], v172 offset:3072
	s_add_u32 s30, s30, 0x80000
	s_addc_u32 s31, s31, 0
	s_mov_b32 m0, s36
	v_lshl_add_u64 v[226:227], s[30:31], 0, v[152:153]
	ds_read_b128 v[186:189], v183 offset:32768
	ds_read_b128 v[190:193], v183 offset:33792
	ds_read_b128 v[198:201], v183 offset:34816
	ds_read_b128 v[202:205], v183 offset:35840
	ds_read_b128 v[206:209], v183 offset:36864
	ds_read_b128 v[210:213], v183 offset:37888
	ds_read_b128 v[214:217], v183 offset:38912
	ds_read_b128 v[218:221], v183 offset:39936
	global_load_lds_dwordx4 v[226:227], off
	s_mov_b32 m0, s37
	v_lshl_add_u64 v[226:227], s[30:31], 0, v[156:157]
	global_load_lds_dwordx4 v[226:227], off
	s_waitcnt vmcnt(8) lgkmcnt(0)
	s_setprio 1
	s_barrier
	v_mfma_f32_16x16x32_bf16 v[124:127], v[128:131], v[186:189], v[124:127]
	v_mfma_f32_16x16x32_bf16 v[120:123], v[136:139], v[186:189], v[120:123]
	v_mfma_f32_16x16x32_bf16 v[104:107], v[128:131], v[198:201], v[104:107]
	v_mfma_f32_16x16x32_bf16 v[108:111], v[136:139], v[198:201], v[108:111]
	v_mfma_f32_16x16x32_bf16 v[88:91], v[128:131], v[206:209], v[88:91]
	v_mfma_f32_16x16x32_bf16 v[92:95], v[136:139], v[206:209], v[92:95]
	v_mfma_f32_16x16x32_bf16 v[72:75], v[128:131], v[214:217], v[72:75]
	v_mfma_f32_16x16x32_bf16 v[76:79], v[136:139], v[214:217], v[76:79]
	v_mfma_f32_16x16x32_bf16 v[124:127], v[132:135], v[190:193], v[124:127]
	v_mfma_f32_16x16x32_bf16 v[120:123], v[140:143], v[190:193], v[120:123]
	v_mfma_f32_16x16x32_bf16 v[104:107], v[132:135], v[202:205], v[104:107]
	v_mfma_f32_16x16x32_bf16 v[108:111], v[140:143], v[202:205], v[108:111]
	v_mfma_f32_16x16x32_bf16 v[88:91], v[132:135], v[210:213], v[88:91]
	v_mfma_f32_16x16x32_bf16 v[92:95], v[140:143], v[210:213], v[92:95]
	v_mfma_f32_16x16x32_bf16 v[72:75], v[132:135], v[218:221], v[72:75]
	v_mfma_f32_16x16x32_bf16 v[76:79], v[140:143], v[218:221], v[76:79]
	v_mfma_f32_16x16x32_bf16 v[116:119], v[144:147], v[186:189], v[116:119]
	v_mfma_f32_16x16x32_bf16 v[112:115], v[168:171], v[186:189], v[112:115]
	v_mfma_f32_16x16x32_bf16 v[100:103], v[144:147], v[198:201], v[100:103]
	v_mfma_f32_16x16x32_bf16 v[96:99], v[168:171], v[198:201], v[96:99]
	v_mfma_f32_16x16x32_bf16 v[84:87], v[144:147], v[206:209], v[84:87]
	v_mfma_f32_16x16x32_bf16 v[80:83], v[168:171], v[206:209], v[80:83]
	v_mfma_f32_16x16x32_bf16 v[68:71], v[144:147], v[214:217], v[68:71]
	v_mfma_f32_16x16x32_bf16 v[64:67], v[168:171], v[214:217], v[64:67]
	v_mfma_f32_16x16x32_bf16 v[116:119], v[148:151], v[190:193], v[116:119]
	v_mfma_f32_16x16x32_bf16 v[112:115], v[172:175], v[190:193], v[112:115]
	v_mfma_f32_16x16x32_bf16 v[100:103], v[148:151], v[202:205], v[100:103]
	v_mfma_f32_16x16x32_bf16 v[96:99], v[172:175], v[202:205], v[96:99]
	v_mfma_f32_16x16x32_bf16 v[84:87], v[148:151], v[210:213], v[84:87]
	v_mfma_f32_16x16x32_bf16 v[80:83], v[172:175], v[210:213], v[80:83]
	v_mfma_f32_16x16x32_bf16 v[68:71], v[148:151], v[218:221], v[68:71]
	v_mfma_f32_16x16x32_bf16 v[64:67], v[172:175], v[218:221], v[64:67]
	s_barrier
; #define PG8_STAGE(bufoff, gbase, voff) do { _Pragma("unroll") for (int _i = 0; _i < 2; ++_i) \
;         __builtin_amdgcn_global_load_lds((const unsigned*)((const char*)(gbase) + (voff)[_i]), (PG8_LAS unsigned*)(lds + (bufoff) + ldsw + _i * 8192), 16, 0, 0); } while (0)
; #define PG8_LDA(dst, b, h) do { _Pragma("unroll") for (int m = 0; m < 4; ++m) _Pragma("unroll") for (int k = 0; k < 2; ++k) dst[m][k] = *(const PG8_LAS bf16x8*)(lds + PG8_SA(b, h) + aoff + m * 2048 + k * 1024); } while (0)
; #define PG8_MMA(ai, bj, At, Bt) do { __builtin_amdgcn_s_setprio(1); _Pragma("unroll") for (int m = 0; m < 4; ++m) _Pragma("unroll") for (int n = 0; n < 2; ++n) _Pragma("unroll") for (int k = 0; k < 2; ++k) \
;         acc[ai][bj][m][n] = __builtin_amdgcn_mfma_f32_16x16x32_bf16(Bt[n][k], At[m][k], acc[ai][bj][m][n], 0, 0, 0); __builtin_amdgcn_s_setprio(0); } while (0)
; #define PG8_WAIT_V(n) asm volatile("s_waitcnt vmcnt(" #n ")" ::: "memory")
; #define PG8_WAIT_L(n) asm volatile("s_waitcnt lgkmcnt(" #n ")" ::: "memory")
; #define PG8_BAR __builtin_amdgcn_s_barrier()
; #define PG8_SCHED __builtin_amdgcn_sched_barrier(0)
; template <class Epi, class Sched, bool ALIGN_EPI = false, bool SP2 = false>
; __device__ __forceinline__ void gemm_phase(PG8_LAS unsigned char* lds, const Gemm g, const Sched& S, const Epi& E) {
;     ...
;             PG8_LDA(At, 1, 1); PG8_STAGE(PG8_SB(1, 0), b3, voffB); PG8_STAGE(PG8_SB(1, 1), b3 + hstep, voffB); PG8_STAGE(PG8_SA(1, 0), a3, voffA);
;             PG8_WAIT_V(8); PG8_WAIT_L(0); PG8_BAR; PG8_MMA(1, 0, At, B0); PG8_MMA(1, 1, At, B1); PG8_BAR; PG8_SCHED;
;     ...
;         if constexpr (ALIGN_EPI) { if (wr == 0) PG8_BAR; }
	s_setprio 0
	s_add_i32 s30, s50, s34
	v_lshl_add_u64 v[176:177], v[176:177], 0, s[12:13]
	s_mov_b32 m0, s30
	ds_read_b128 v[186:189], v183 offset:49152
	ds_read_b128 v[190:193], v183 offset:50176
	ds_read_b128 v[198:201], v183 offset:51200
	ds_read_b128 v[202:205], v183 offset:52224
	ds_read_b128 v[206:209], v183 offset:53248
	ds_read_b128 v[210:213], v183 offset:54272
	ds_read_b128 v[214:217], v183 offset:55296
	ds_read_b128 v[218:221], v183 offset:56320
	global_load_lds_dwordx4 v[176:177], off
	s_add_i32 m0, s30, 0x2000
	s_add_u32 s28, s28, 0x80080
	v_lshl_add_u64 v[176:177], v[194:195], 0, s[12:13]
	s_addc_u32 s29, s29, 0
	s_add_i32 s30, s51, s34
	global_load_lds_dwordx4 v[176:177], off
	s_mov_b32 m0, s30
	v_lshl_add_u64 v[176:177], s[28:29], 0, v[154:155]
	global_load_lds_dwordx4 v[176:177], off
	s_add_i32 m0, s30, 0x2000
	v_lshl_add_u64 v[176:177], s[28:29], 0, v[158:159]
	global_load_lds_dwordx4 v[176:177], off
	s_mov_b32 m0, s39
	v_lshl_add_u64 v[176:177], v[222:223], 0, s[12:13]
	global_load_lds_dwordx4 v[176:177], off
	s_mov_b32 m0, s40
	v_lshl_add_u64 v[176:177], v[224:225], 0, s[12:13]
	global_load_lds_dwordx4 v[176:177], off
	s_waitcnt vmcnt(8) lgkmcnt(0)
	s_setprio 1
	s_barrier
	v_mfma_f32_16x16x32_bf16 v[56:59], v[128:131], v[186:189], v[56:59]
	v_mfma_f32_16x16x32_bf16 v[60:63], v[136:139], v[186:189], v[60:63]
	v_mfma_f32_16x16x32_bf16 v[40:43], v[128:131], v[198:201], v[40:43]
	v_mfma_f32_16x16x32_bf16 v[44:47], v[136:139], v[198:201], v[44:47]
	v_mfma_f32_16x16x32_bf16 v[24:27], v[128:131], v[206:209], v[24:27]
	v_mfma_f32_16x16x32_bf16 v[28:31], v[136:139], v[206:209], v[28:31]
	v_mfma_f32_16x16x32_bf16 v[8:11], v[128:131], v[214:217], v[8:11]
	v_mfma_f32_16x16x32_bf16 v[12:15], v[136:139], v[214:217], v[12:15]
	v_mfma_f32_16x16x32_bf16 v[56:59], v[132:135], v[190:193], v[56:59]
	v_mfma_f32_16x16x32_bf16 v[60:63], v[140:143], v[190:193], v[60:63]
	v_mfma_f32_16x16x32_bf16 v[40:43], v[132:135], v[202:205], v[40:43]
	v_mfma_f32_16x16x32_bf16 v[44:47], v[140:143], v[202:205], v[44:47]
	v_mfma_f32_16x16x32_bf16 v[24:27], v[132:135], v[210:213], v[24:27]
	v_mfma_f32_16x16x32_bf16 v[28:31], v[140:143], v[210:213], v[28:31]
	v_mfma_f32_16x16x32_bf16 v[8:11], v[132:135], v[218:221], v[8:11]
	v_mfma_f32_16x16x32_bf16 v[12:15], v[140:143], v[218:221], v[12:15]
	v_mfma_f32_16x16x32_bf16 v[52:55], v[144:147], v[186:189], v[52:55]
	v_mfma_f32_16x16x32_bf16 v[48:51], v[168:171], v[186:189], v[48:51]
	v_mfma_f32_16x16x32_bf16 v[36:39], v[144:147], v[198:201], v[36:39]
	v_mfma_f32_16x16x32_bf16 v[32:35], v[168:171], v[198:201], v[32:35]
	v_mfma_f32_16x16x32_bf16 v[20:23], v[144:147], v[206:209], v[20:23]
	v_mfma_f32_16x16x32_bf16 v[16:19], v[168:171], v[206:209], v[16:19]
	v_mfma_f32_16x16x32_bf16 v[4:7], v[144:147], v[214:217], v[4:7]
	v_mfma_f32_16x16x32_bf16 v[0:3], v[168:171], v[214:217], v[0:3]
	v_mfma_f32_16x16x32_bf16 v[52:55], v[148:151], v[190:193], v[52:55]
	v_mfma_f32_16x16x32_bf16 v[48:51], v[172:175], v[190:193], v[48:51]
	v_mfma_f32_16x16x32_bf16 v[36:39], v[148:151], v[202:205], v[36:39]
	v_mfma_f32_16x16x32_bf16 v[32:35], v[172:175], v[202:205], v[32:35]
	v_mfma_f32_16x16x32_bf16 v[20:23], v[148:151], v[210:213], v[20:23]
	v_mfma_f32_16x16x32_bf16 v[16:19], v[172:175], v[210:213], v[16:19]
	v_mfma_f32_16x16x32_bf16 v[4:7], v[148:151], v[218:221], v[4:7]
	v_mfma_f32_16x16x32_bf16 v[0:3], v[172:175], v[218:221], v[0:3]
	s_barrier
	s_setprio 0
	s_add_i32 s49, s49, 2
	s_add_u32 s26, s26, 0x100
	s_addc_u32 s27, s27, 0
	s_add_u32 s47, s47, 0x100
	s_addc_u32 s48, s48, 0
	s_cmp_gt_u32 s49, 29
	s_cbranch_scc0 .LBB0_1180
	s_and_b64 vcc, exec, s[14:15]
	s_cbranch_vccz .LBB0_1183
	s_barrier

; #define PG8_STAGE(bufoff, gbase, voff) do { _Pragma("unroll") for (int _i = 0; _i < 2; ++_i) \
;         __builtin_amdgcn_global_load_lds((const unsigned*)((const char*)(gbase) + (voff)[_i]), (PG8_LAS unsigned*)(lds + (bufoff) + ldsw + _i * 8192), 16, 0, 0); } while (0)
; #define PG8_LDA(dst, b, h) do { _Pragma("unroll") for (int m = 0; m < 4; ++m) _Pragma("unroll") for (int k = 0; k < 2; ++k) dst[m][k] = *(const PG8_LAS bf16x8*)(lds + PG8_SA(b, h) + aoff + m * 2048 + k * 1024); } while (0)
; #define PG8_LDB(dst, b, h) do { _Pragma("unroll") for (int n = 0; n < 2; ++n) _Pragma("unroll") for (int k = 0; k < 2; ++k) dst[n][k] = *(const PG8_LAS bf16x8*)(lds + PG8_SB(b, h) + boff + n * 2048 + k * 1024); } while (0)
; #define PG8_WAIT_V(n) asm volatile("s_waitcnt vmcnt(" #n ")" ::: "memory")
; #define PG8_WAIT_L(n) asm volatile("s_waitcnt lgkmcnt(" #n ")" ::: "memory")
; #define PG8_BAR __builtin_amdgcn_s_barrier()
; #define PG8_SCHED __builtin_amdgcn_sched_barrier(0)
; template <class Epi, class Sched, bool ALIGN_EPI = false, bool SP2 = false>
; __device__ __forceinline__ void gemm_phase(PG8_LAS unsigned char* lds, const Gemm g, const Sched& S, const Epi& E) {
;     ...
;         const bool has_next = S.next(ui + 1, nxt);
;         const char* nA = has_next ? (const char*)g.A + (size_t)nxt.pm * tstep : cA; const char* nB = has_next ? (const char*)g.Bt + (size_t)nxt.pn * tstep : cB;
;         for (int t = 0; t < nt; t += 2) {
;             const bool last = (t == nt - 2);
;             const char* a1 = cA + (size_t)(t + 1) * kstep;
;             const char* a2 = last ? nA : cA + (size_t)(t + 2) * kstep; const char* b2 = last ? nB : cB + (size_t)(t + 2) * kstep;
;             const char* a3 = a2 + kstep; const char* b3 = b2 + kstep;
;             if (last && has_next) S.a_ready(nxt);
;             if constexpr (SP2) {
;             PG8_LDB(B0, 0, 0); PG8_LDB(B1, 0, 1); PG8_SCHED; PG8_LDA(At, 0, 0); PG8_STAGE(PG8_SA(1, 1), a1 + hstep, voffA);
;             PG8_WAIT_V(8); PG8_WAIT_L(0); PG8_BAR; PG8_MMA(0, 0, At, B0); PG8_MMA(0, 1, At, B1); PG8_BAR; PG8_SCHED;
;             PG8_LDA(At, 0, 1); PG8_STAGE(PG8_SB(0, 0), b2, voffB); PG8_STAGE(PG8_SB(0, 1), b2 + hstep, voffB); PG8_STAGE(PG8_SA(0, 0), a2, voffA);
;             PG8_WAIT_V(8); PG8_WAIT_L(0); PG8_BAR; PG8_MMA(1, 0, At, B0); PG8_MMA(1, 1, At, B1); PG8_BAR; PG8_SCHED;
.LBB0_1372:
	s_ashr_i32 s29, s28, 31
	s_lshl_b64 s[34:35], s[28:29], 20
	s_add_u32 s34, s74, s34
	s_addc_u32 s35, s75, s35
	s_and_b64 s[36:37], s[30:31], exec
	s_cselect_b32 s29, s35, s9
	s_cselect_b32 s39, s34, s8
	s_ashr_i32 s27, s26, 31
	s_lshl_b64 s[36:37], s[26:27], 20
	v_readlane_b32 s44, v254, 22
	v_readlane_b32 s45, v254, 23
	s_add_u32 s36, s44, s36
	s_addc_u32 s37, s45, s37
	s_and_b64 s[44:45], s[30:31], exec
	s_cselect_b32 s27, s37, s43
	s_cselect_b32 s41, s36, s42
	s_add_u32 s8, s8, 0x80080
	s_addc_u32 s9, s9, 0
	s_add_u32 s48, s42, 0x100
	s_addc_u32 s49, s43, 0
	s_mov_b32 s66, -2
	ds_read_b128 v[108:111], v173
	ds_read_b128 v[112:115], v173 offset:1024
	ds_read_b128 v[116:119], v173 offset:2048
	ds_read_b128 v[120:123], v173 offset:3072
	ds_read_b128 v[178:181], v175
	ds_read_b128 v[182:185], v175 offset:1024
	ds_read_b128 v[186:189], v175 offset:2048
	ds_read_b128 v[190:193], v175 offset:3072
	s_add_u32 s42, s8, 0xfff80080
	s_addc_u32 s43, s9, -1
	s_cmp_eq_u32 s66, 28
	s_cselect_b32 s45, s29, s43
	s_cselect_b32 s44, s39, s42
	s_cselect_b32 s43, s27, s49
	s_cselect_b32 s42, s41, s48
	v_lshl_add_u64 v[160:161], s[8:9], 0, v[154:155]
	s_add_i32 m0, s50, 0xc000
	ds_read_b128 v[198:201], v177
	ds_read_b128 v[202:205], v177 offset:1024
	ds_read_b128 v[206:209], v177 offset:2048
	ds_read_b128 v[210:213], v177 offset:3072
	ds_read_b128 v[214:217], v177 offset:4096
	ds_read_b128 v[218:221], v177 offset:5120
	ds_read_b128 v[222:225], v177 offset:6144
	ds_read_b128 v[226:229], v177 offset:7168
	global_load_lds_dwordx4 v[160:161], off
	s_add_i32 m0, s50, 0xe000
	v_lshl_add_u64 v[160:161], s[8:9], 0, v[156:157]
	global_load_lds_dwordx4 v[160:161], off
	s_waitcnt lgkmcnt(0)
	s_setprio 1
	s_barrier
	v_mfma_f32_16x16x32_bf16 v[140:143], v[108:111], v[198:201], 0
	v_mfma_f32_16x16x32_bf16 v[136:139], v[116:119], v[198:201], 0
	v_mfma_f32_16x16x32_bf16 v[100:103], v[108:111], v[206:209], 0
	v_mfma_f32_16x16x32_bf16 v[124:127], v[116:119], v[206:209], 0
	v_mfma_f32_16x16x32_bf16 v[84:87], v[108:111], v[214:217], 0
	v_mfma_f32_16x16x32_bf16 v[92:95], v[116:119], v[214:217], 0
	v_mfma_f32_16x16x32_bf16 v[68:71], v[108:111], v[222:225], 0
	v_mfma_f32_16x16x32_bf16 v[76:79], v[116:119], v[222:225], 0
	v_mfma_f32_16x16x32_bf16 v[140:143], v[112:115], v[202:205], v[140:143]
	v_mfma_f32_16x16x32_bf16 v[136:139], v[120:123], v[202:205], v[136:139]
	v_mfma_f32_16x16x32_bf16 v[100:103], v[112:115], v[210:213], v[100:103]
	v_mfma_f32_16x16x32_bf16 v[124:127], v[120:123], v[210:213], v[124:127]
	v_mfma_f32_16x16x32_bf16 v[84:87], v[112:115], v[218:221], v[84:87]
	v_mfma_f32_16x16x32_bf16 v[92:95], v[120:123], v[218:221], v[92:95]
	v_mfma_f32_16x16x32_bf16 v[68:71], v[112:115], v[226:229], v[68:71]
	v_mfma_f32_16x16x32_bf16 v[76:79], v[120:123], v[226:229], v[76:79]
	v_mfma_f32_16x16x32_bf16 v[128:131], v[178:181], v[198:201], 0
	v_mfma_f32_16x16x32_bf16 v[132:135], v[186:189], v[198:201], 0
	v_mfma_f32_16x16x32_bf16 v[104:107], v[178:181], v[206:209], 0
	v_mfma_f32_16x16x32_bf16 v[96:99], v[186:189], v[206:209], 0
	v_mfma_f32_16x16x32_bf16 v[88:91], v[178:181], v[214:217], 0
	v_mfma_f32_16x16x32_bf16 v[80:83], v[186:189], v[214:217], 0
	v_mfma_f32_16x16x32_bf16 v[72:75], v[178:181], v[222:225], 0
	v_mfma_f32_16x16x32_bf16 v[64:67], v[186:189], v[222:225], 0
	v_mfma_f32_16x16x32_bf16 v[128:131], v[182:185], v[202:205], v[128:131]
	v_mfma_f32_16x16x32_bf16 v[132:135], v[190:193], v[202:205], v[132:135]
	v_mfma_f32_16x16x32_bf16 v[104:107], v[182:185], v[210:213], v[104:107]
	v_mfma_f32_16x16x32_bf16 v[96:99], v[190:193], v[210:213], v[96:99]
	v_mfma_f32_16x16x32_bf16 v[88:91], v[182:185], v[218:221], v[88:91]
	v_mfma_f32_16x16x32_bf16 v[80:83], v[190:193], v[218:221], v[80:83]
	v_mfma_f32_16x16x32_bf16 v[72:75], v[182:185], v[226:229], v[72:75]
	v_mfma_f32_16x16x32_bf16 v[64:67], v[190:193], v[226:229], v[64:67]
	s_barrier
	s_setprio 0
	s_add_i32 s67, s62, s47
	v_lshl_add_u64 v[160:161], s[42:43], 0, v[144:145]
	s_mov_b32 m0, s67
	ds_read_b128 v[198:201], v177 offset:16384
	ds_read_b128 v[202:205], v177 offset:17408
	ds_read_b128 v[206:209], v177 offset:18432
	ds_read_b128 v[210:213], v177 offset:19456
	ds_read_b128 v[214:217], v177 offset:20480
	ds_read_b128 v[218:221], v177 offset:21504
	ds_read_b128 v[222:225], v177 offset:22528
	ds_read_b128 v[226:229], v177 offset:23552
	global_load_lds_dwordx4 v[160:161], off
	s_add_i32 m0, s67, 0x2000
	s_add_u32 s68, s42, 0x80000
	v_lshl_add_u64 v[164:165], s[42:43], 0, v[146:147]
	s_addc_u32 s69, s43, 0
	s_add_i32 s67, s63, s47
	global_load_lds_dwordx4 v[164:165], off
	v_lshl_add_u64 v[170:171], s[68:69], 0, v[144:145]
	s_mov_b32 m0, s67
	v_lshl_add_u64 v[194:195], s[44:45], 0, v[146:147]
	global_load_lds_dwordx4 v[170:171], off
	s_add_i32 m0, s67, 0x2000
	v_lshl_add_u64 v[170:171], s[68:69], 0, v[146:147]
	global_load_lds_dwordx4 v[170:171], off
	s_mov_b32 m0, s50
	v_lshl_add_u64 v[170:171], s[44:45], 0, v[144:145]
	global_load_lds_dwordx4 v[170:171], off
	s_mov_b32 m0, s51
	s_nop 0
	global_load_lds_dwordx4 v[194:195], off
	s_waitcnt lgkmcnt(0)
	s_setprio 1
	s_barrier
; #define PG8_STAGE(bufoff, gbase, voff) do { _Pragma("unroll") for (int _i = 0; _i < 2; ++_i) \
;         __builtin_amdgcn_global_load_lds((const unsigned*)((const char*)(gbase) + (voff)[_i]), (PG8_LAS unsigned*)(lds + (bufoff) + ldsw + _i * 8192), 16, 0, 0); } while (0)
; #define PG8_LDA(dst, b, h) do { _Pragma("unroll") for (int m = 0; m < 4; ++m) _Pragma("unroll") for (int k = 0; k < 2; ++k) dst[m][k] = *(const PG8_LAS bf16x8*)(lds + PG8_SA(b, h) + aoff + m * 2048 + k * 1024); } while (0)
; #define PG8_LDB(dst, b, h) do { _Pragma("unroll") for (int n = 0; n < 2; ++n) _Pragma("unroll") for (int k = 0; k < 2; ++k) dst[n][k] = *(const PG8_LAS bf16x8*)(lds + PG8_SB(b, h) + boff + n * 2048 + k * 1024); } while (0)
; #define PG8_MMA(ai, bj, At, Bt) do { __builtin_amdgcn_s_setprio(1); _Pragma("unroll") for (int m = 0; m < 4; ++m) _Pragma("unroll") for (int n = 0; n < 2; ++n) _Pragma("unroll") for (int k = 0; k < 2; ++k) \
;         acc[ai][bj][m][n] = __builtin_amdgcn_mfma_f32_16x16x32_bf16(Bt[n][k], At[m][k], acc[ai][bj][m][n], 0, 0, 0); __builtin_amdgcn_s_setprio(0); } while (0)
; #define PG8_WAIT_V(n) asm volatile("s_waitcnt vmcnt(" #n ")" ::: "memory")
; #define PG8_WAIT_L(n) asm volatile("s_waitcnt lgkmcnt(" #n ")" ::: "memory")
; #define PG8_BAR __builtin_amdgcn_s_barrier()
; #define PG8_SCHED __builtin_amdgcn_sched_barrier(0)
; template <class Epi, class Sched, bool ALIGN_EPI = false, bool SP2 = false>
; __device__ __forceinline__ void gemm_phase(PG8_LAS unsigned char* lds, const Gemm g, const Sched& S, const Epi& E) {
;     ...
;             PG8_WAIT_V(8); PG8_WAIT_L(0); PG8_BAR; PG8_MMA(1, 0, At, B0); PG8_MMA(1, 1, At, B1); PG8_BAR; PG8_SCHED;
;             PG8_LDB(B0, 1, 0); PG8_LDB(B1, 1, 1); PG8_SCHED; PG8_LDA(At, 1, 0); PG8_STAGE(PG8_SA(0, 1), a2 + hstep, voffA);
;             PG8_WAIT_V(8); PG8_WAIT_L(0); PG8_BAR; PG8_MMA(0, 0, At, B0); PG8_MMA(0, 1, At, B1); PG8_BAR; PG8_SCHED;
	v_mfma_f32_16x16x32_bf16 v[60:63], v[108:111], v[198:201], 0
	v_mfma_f32_16x16x32_bf16 v[56:59], v[116:119], v[198:201], 0
	v_mfma_f32_16x16x32_bf16 v[36:39], v[108:111], v[206:209], 0
	v_mfma_f32_16x16x32_bf16 v[44:47], v[116:119], v[206:209], 0
	v_mfma_f32_16x16x32_bf16 v[20:23], v[108:111], v[214:217], 0
	v_mfma_f32_16x16x32_bf16 v[28:31], v[116:119], v[214:217], 0
	v_mfma_f32_16x16x32_bf16 v[4:7], v[108:111], v[222:225], 0
	v_mfma_f32_16x16x32_bf16 v[12:15], v[116:119], v[222:225], 0
	v_mfma_f32_16x16x32_bf16 v[60:63], v[112:115], v[202:205], v[60:63]
	v_mfma_f32_16x16x32_bf16 v[56:59], v[120:123], v[202:205], v[56:59]
	v_mfma_f32_16x16x32_bf16 v[36:39], v[112:115], v[210:213], v[36:39]
	v_mfma_f32_16x16x32_bf16 v[44:47], v[120:123], v[210:213], v[44:47]
	v_mfma_f32_16x16x32_bf16 v[20:23], v[112:115], v[218:221], v[20:23]
	v_mfma_f32_16x16x32_bf16 v[28:31], v[120:123], v[218:221], v[28:31]
	v_mfma_f32_16x16x32_bf16 v[4:7], v[112:115], v[226:229], v[4:7]
	v_mfma_f32_16x16x32_bf16 v[12:15], v[120:123], v[226:229], v[12:15]
	v_mfma_f32_16x16x32_bf16 v[48:51], v[178:181], v[198:201], 0
	v_mfma_f32_16x16x32_bf16 v[52:55], v[186:189], v[198:201], 0
	v_mfma_f32_16x16x32_bf16 v[40:43], v[178:181], v[206:209], 0
	v_mfma_f32_16x16x32_bf16 v[32:35], v[186:189], v[206:209], 0
	v_mfma_f32_16x16x32_bf16 v[24:27], v[178:181], v[214:217], 0
	v_mfma_f32_16x16x32_bf16 v[16:19], v[186:189], v[214:217], 0
	v_mfma_f32_16x16x32_bf16 v[8:11], v[178:181], v[222:225], 0
	v_mfma_f32_16x16x32_bf16 v[0:3], v[186:189], v[222:225], 0
	v_mfma_f32_16x16x32_bf16 v[48:51], v[182:185], v[202:205], v[48:51]
	v_mfma_f32_16x16x32_bf16 v[52:55], v[190:193], v[202:205], v[52:55]
	v_mfma_f32_16x16x32_bf16 v[40:43], v[182:185], v[210:213], v[40:43]
	v_mfma_f32_16x16x32_bf16 v[32:35], v[190:193], v[210:213], v[32:35]
	v_mfma_f32_16x16x32_bf16 v[24:27], v[182:185], v[218:221], v[24:27]
	v_mfma_f32_16x16x32_bf16 v[16:19], v[190:193], v[218:221], v[16:19]
	v_mfma_f32_16x16x32_bf16 v[8:11], v[182:185], v[226:229], v[8:11]
	v_mfma_f32_16x16x32_bf16 v[0:3], v[190:193], v[226:229], v[0:3]
	s_barrier
	s_setprio 0
	s_add_i32 s67, 0, 0x18000
	s_add_i32 s68, 0, 0x1c000
	v_add_u32_e32 v120, s67, v167
	v_add_u32_e32 v162, s68, v167
	ds_read_b128 v[108:111], v120
	ds_read_b128 v[112:115], v120 offset:1024
	ds_read_b128 v[116:119], v120 offset:2048
	ds_read_b128 v[120:123], v120 offset:3072
	ds_read_b128 v[178:181], v162
	ds_read_b128 v[182:185], v162 offset:1024
	ds_read_b128 v[186:189], v162 offset:2048
	ds_read_b128 v[190:193], v162 offset:3072
	s_add_u32 s44, s44, 0x80000
	s_addc_u32 s45, s45, 0
	s_mov_b32 m0, s52
	v_lshl_add_u64 v[230:231], s[44:45], 0, v[144:145]
	ds_read_b128 v[198:201], v177 offset:32768
	ds_read_b128 v[202:205], v177 offset:33792
	ds_read_b128 v[206:209], v177 offset:34816
	ds_read_b128 v[210:213], v177 offset:35840
	ds_read_b128 v[214:217], v177 offset:36864
	ds_read_b128 v[218:221], v177 offset:37888
	ds_read_b128 v[222:225], v177 offset:38912
	ds_read_b128 v[226:229], v177 offset:39936
	global_load_lds_dwordx4 v[230:231], off
	s_mov_b32 m0, s53
	v_lshl_add_u64 v[230:231], s[44:45], 0, v[146:147]
	global_load_lds_dwordx4 v[230:231], off
	s_waitcnt vmcnt(8) lgkmcnt(0)
	s_setprio 1
	s_barrier
	v_mfma_f32_16x16x32_bf16 v[140:143], v[108:111], v[198:201], v[140:143]
	v_mfma_f32_16x16x32_bf16 v[136:139], v[116:119], v[198:201], v[136:139]
	v_mfma_f32_16x16x32_bf16 v[100:103], v[108:111], v[206:209], v[100:103]
	v_mfma_f32_16x16x32_bf16 v[124:127], v[116:119], v[206:209], v[124:127]
	v_mfma_f32_16x16x32_bf16 v[84:87], v[108:111], v[214:217], v[84:87]
	v_mfma_f32_16x16x32_bf16 v[92:95], v[116:119], v[214:217], v[92:95]
	v_mfma_f32_16x16x32_bf16 v[68:71], v[108:111], v[222:225], v[68:71]
	v_mfma_f32_16x16x32_bf16 v[76:79], v[116:119], v[222:225], v[76:79]
	v_mfma_f32_16x16x32_bf16 v[140:143], v[112:115], v[202:205], v[140:143]
	v_mfma_f32_16x16x32_bf16 v[136:139], v[120:123], v[202:205], v[136:139]
	v_mfma_f32_16x16x32_bf16 v[100:103], v[112:115], v[210:213], v[100:103]
	v_mfma_f32_16x16x32_bf16 v[124:127], v[120:123], v[210:213], v[124:127]
	v_mfma_f32_16x16x32_bf16 v[84:87], v[112:115], v[218:221], v[84:87]
	v_mfma_f32_16x16x32_bf16 v[92:95], v[120:123], v[218:221], v[92:95]
	v_mfma_f32_16x16x32_bf16 v[68:71], v[112:115], v[226:229], v[68:71]
	v_mfma_f32_16x16x32_bf16 v[76:79], v[120:123], v[226:229], v[76:79]
	v_mfma_f32_16x16x32_bf16 v[128:131], v[178:181], v[198:201], v[128:131]
	v_mfma_f32_16x16x32_bf16 v[132:135], v[186:189], v[198:201], v[132:135]
	v_mfma_f32_16x16x32_bf16 v[104:107], v[178:181], v[206:209], v[104:107]
	v_mfma_f32_16x16x32_bf16 v[96:99], v[186:189], v[206:209], v[96:99]
	v_mfma_f32_16x16x32_bf16 v[88:91], v[178:181], v[214:217], v[88:91]
	v_mfma_f32_16x16x32_bf16 v[80:83], v[186:189], v[214:217], v[80:83]
	v_mfma_f32_16x16x32_bf16 v[72:75], v[178:181], v[222:225], v[72:75]
	v_mfma_f32_16x16x32_bf16 v[64:67], v[186:189], v[222:225], v[64:67]
	v_mfma_f32_16x16x32_bf16 v[128:131], v[182:185], v[202:205], v[128:131]
	v_mfma_f32_16x16x32_bf16 v[132:135], v[190:193], v[202:205], v[132:135]
	v_mfma_f32_16x16x32_bf16 v[104:107], v[182:185], v[210:213], v[104:107]
	v_mfma_f32_16x16x32_bf16 v[96:99], v[190:193], v[210:213], v[96:99]
	v_mfma_f32_16x16x32_bf16 v[88:91], v[182:185], v[218:221], v[88:91]
	v_mfma_f32_16x16x32_bf16 v[80:83], v[190:193], v[218:221], v[80:83]
	v_mfma_f32_16x16x32_bf16 v[72:75], v[182:185], v[226:229], v[72:75]
	v_mfma_f32_16x16x32_bf16 v[64:67], v[190:193], v[226:229], v[64:67]
	s_barrier
; #define PG8_STAGE(bufoff, gbase, voff) do { _Pragma("unroll") for (int _i = 0; _i < 2; ++_i) \
;         __builtin_amdgcn_global_load_lds((const unsigned*)((const char*)(gbase) + (voff)[_i]), (PG8_LAS unsigned*)(lds + (bufoff) + ldsw + _i * 8192), 16, 0, 0); } while (0)
; #define PG8_LDA(dst, b, h) do { _Pragma("unroll") for (int m = 0; m < 4; ++m) _Pragma("unroll") for (int k = 0; k < 2; ++k) dst[m][k] = *(const PG8_LAS bf16x8*)(lds + PG8_SA(b, h) + aoff + m * 2048 + k * 1024); } while (0)
; #define PG8_LDB(dst, b, h) do { _Pragma("unroll") for (int n = 0; n < 2; ++n) _Pragma("unroll") for (int k = 0; k < 2; ++k) dst[n][k] = *(const PG8_LAS bf16x8*)(lds + PG8_SB(b, h) + boff + n * 2048 + k * 1024); } while (0)
; template <class Epi, class Sched, bool ALIGN_EPI = false, bool SP2 = false>
; __device__ __forceinline__ void gemm_phase(PG8_LAS unsigned char* lds, const Gemm g, const Sched& S, const Epi& E) {
;     ...
;         for (int t = 0; t < nt; t += 2) {
;             const bool last = (t == nt - 2);
;             const char* a1 = cA + (size_t)(t + 1) * kstep;
;             const char* a2 = last ? nA : cA + (size_t)(t + 2) * kstep; const char* b2 = last ? nB : cB + (size_t)(t + 2) * kstep;
;             const char* a3 = a2 + kstep; const char* b3 = b2 + kstep;
;             if (last && has_next) S.a_ready(nxt);
;             if constexpr (SP2) {
;             PG8_LDB(B0, 0, 0); PG8_LDB(B1, 0, 1); PG8_SCHED; PG8_LDA(At, 0, 0); PG8_STAGE(PG8_SA(1, 1), a1 + hstep, voffA);
;             PG8_WAIT_V(8); PG8_WAIT_L(0); PG8_BAR; PG8_MMA(0, 0, At, B0); PG8_MMA(0, 1, At, B1); PG8_BAR; PG8_SCHED;
;             PG8_LDA(At, 0, 1); PG8_STAGE(PG8_SB(0, 0), b2, voffB); PG8_STAGE(PG8_SB(0, 1), b2 + hstep, voffB); PG8_STAGE(PG8_SA(0, 0), a2, voffA);
;             PG8_WAIT_V(8); PG8_WAIT_L(0); PG8_BAR; PG8_MMA(1, 0, At, B0); PG8_MMA(1, 1, At, B1); PG8_BAR; PG8_SCHED;
;             PG8_LDB(B0, 1, 0); PG8_LDB(B1, 1, 1); PG8_SCHED; PG8_LDA(At, 1, 0); PG8_STAGE(PG8_SA(0, 1), a2 + hstep, voffA);
;             PG8_WAIT_V(8); PG8_WAIT_L(0); PG8_BAR; PG8_MMA(0, 0, At, B0); PG8_MMA(0, 1, At, B1); PG8_BAR; PG8_SCHED;
;             PG8_LDA(At, 1, 1); PG8_STAGE(PG8_SB(1, 0), b3, voffB); PG8_STAGE(PG8_SB(1, 1), b3 + hstep, voffB); PG8_STAGE(PG8_SA(1, 0), a3, voffA);
;             PG8_WAIT_V(8); PG8_WAIT_L(0); PG8_BAR; PG8_MMA(1, 0, At, B0); PG8_MMA(1, 1, At, B1); PG8_BAR; PG8_SCHED;
	s_setprio 0
	s_add_i32 s44, s67, s47
	v_lshl_add_u64 v[160:161], v[160:161], 0, s[16:17]
	s_mov_b32 m0, s44
	ds_read_b128 v[198:201], v177 offset:49152
	ds_read_b128 v[202:205], v177 offset:50176
	ds_read_b128 v[206:209], v177 offset:51200
	ds_read_b128 v[210:213], v177 offset:52224
	ds_read_b128 v[214:217], v177 offset:53248
	ds_read_b128 v[218:221], v177 offset:54272
	ds_read_b128 v[222:225], v177 offset:55296
	ds_read_b128 v[226:229], v177 offset:56320
	global_load_lds_dwordx4 v[160:161], off
	s_add_i32 m0, s44, 0x2000
	s_add_u32 s42, s42, 0x80080
	v_lshl_add_u64 v[160:161], v[164:165], 0, s[16:17]
	s_addc_u32 s43, s43, 0
	s_add_i32 s44, s68, s47
	global_load_lds_dwordx4 v[160:161], off
	s_mov_b32 m0, s44
	v_lshl_add_u64 v[160:161], s[42:43], 0, v[144:145]
	global_load_lds_dwordx4 v[160:161], off
	s_add_i32 m0, s44, 0x2000
	v_lshl_add_u64 v[160:161], s[42:43], 0, v[146:147]
	global_load_lds_dwordx4 v[160:161], off
	s_mov_b32 m0, s55
	v_lshl_add_u64 v[160:161], v[170:171], 0, s[16:17]
	global_load_lds_dwordx4 v[160:161], off
	s_mov_b32 m0, s56
	v_lshl_add_u64 v[160:161], v[194:195], 0, s[16:17]
	global_load_lds_dwordx4 v[160:161], off
	s_waitcnt vmcnt(8) lgkmcnt(0)
	s_setprio 1
	s_barrier
	v_mfma_f32_16x16x32_bf16 v[60:63], v[108:111], v[198:201], v[60:63]
	v_mfma_f32_16x16x32_bf16 v[56:59], v[116:119], v[198:201], v[56:59]
	v_mfma_f32_16x16x32_bf16 v[36:39], v[108:111], v[206:209], v[36:39]
	v_mfma_f32_16x16x32_bf16 v[44:47], v[116:119], v[206:209], v[44:47]
	v_mfma_f32_16x16x32_bf16 v[20:23], v[108:111], v[214:217], v[20:23]
	v_mfma_f32_16x16x32_bf16 v[28:31], v[116:119], v[214:217], v[28:31]
	v_mfma_f32_16x16x32_bf16 v[4:7], v[108:111], v[222:225], v[4:7]
	v_mfma_f32_16x16x32_bf16 v[12:15], v[116:119], v[222:225], v[12:15]
	v_mfma_f32_16x16x32_bf16 v[60:63], v[112:115], v[202:205], v[60:63]
	v_mfma_f32_16x16x32_bf16 v[56:59], v[120:123], v[202:205], v[56:59]
	v_mfma_f32_16x16x32_bf16 v[36:39], v[112:115], v[210:213], v[36:39]
	v_mfma_f32_16x16x32_bf16 v[44:47], v[120:123], v[210:213], v[44:47]
	v_mfma_f32_16x16x32_bf16 v[20:23], v[112:115], v[218:221], v[20:23]
	v_mfma_f32_16x16x32_bf16 v[28:31], v[120:123], v[218:221], v[28:31]
	v_mfma_f32_16x16x32_bf16 v[4:7], v[112:115], v[226:229], v[4:7]
	v_mfma_f32_16x16x32_bf16 v[12:15], v[120:123], v[226:229], v[12:15]
	v_mfma_f32_16x16x32_bf16 v[48:51], v[178:181], v[198:201], v[48:51]
	v_mfma_f32_16x16x32_bf16 v[52:55], v[186:189], v[198:201], v[52:55]
	v_mfma_f32_16x16x32_bf16 v[40:43], v[178:181], v[206:209], v[40:43]
	v_mfma_f32_16x16x32_bf16 v[32:35], v[186:189], v[206:209], v[32:35]
	v_mfma_f32_16x16x32_bf16 v[24:27], v[178:181], v[214:217], v[24:27]
	v_mfma_f32_16x16x32_bf16 v[16:19], v[186:189], v[214:217], v[16:19]
	v_mfma_f32_16x16x32_bf16 v[8:11], v[178:181], v[222:225], v[8:11]
	v_mfma_f32_16x16x32_bf16 v[0:3], v[186:189], v[222:225], v[0:3]
	v_mfma_f32_16x16x32_bf16 v[48:51], v[182:185], v[202:205], v[48:51]
	v_mfma_f32_16x16x32_bf16 v[52:55], v[190:193], v[202:205], v[52:55]
	v_mfma_f32_16x16x32_bf16 v[40:43], v[182:185], v[210:213], v[40:43]
	v_mfma_f32_16x16x32_bf16 v[32:35], v[190:193], v[210:213], v[32:35]
	v_mfma_f32_16x16x32_bf16 v[24:27], v[182:185], v[218:221], v[24:27]
	v_mfma_f32_16x16x32_bf16 v[16:19], v[190:193], v[218:221], v[16:19]
	v_mfma_f32_16x16x32_bf16 v[8:11], v[182:185], v[226:229], v[8:11]
	v_mfma_f32_16x16x32_bf16 v[0:3], v[190:193], v[226:229], v[0:3]
	s_barrier
	s_setprio 0
	s_add_i32 s66, s66, 2
	s_add_u32 s8, s8, 0x100
	s_addc_u32 s9, s9, 0
	s_add_u32 s48, s48, 0x100
	s_addc_u32 s49, s49, 0
.LBB0_1373:
	ds_read_b128 v[108:111], v173
	ds_read_b128 v[112:115], v173 offset:1024
	ds_read_b128 v[116:119], v173 offset:2048
	ds_read_b128 v[120:123], v173 offset:3072
	ds_read_b128 v[178:181], v175
	ds_read_b128 v[182:185], v175 offset:1024
	ds_read_b128 v[186:189], v175 offset:2048
	ds_read_b128 v[190:193], v175 offset:3072
	s_add_u32 s42, s8, 0xfff80080
	s_addc_u32 s43, s9, -1
	s_cmp_eq_u32 s66, 28
	s_cselect_b32 s45, s29, s43
	s_cselect_b32 s44, s39, s42
	s_cselect_b32 s43, s27, s49
	s_cselect_b32 s42, s41, s48
	v_lshl_add_u64 v[160:161], s[8:9], 0, v[154:155]
	s_add_i32 m0, s50, 0xc000
	ds_read_b128 v[198:201], v177
	ds_read_b128 v[202:205], v177 offset:1024
	ds_read_b128 v[206:209], v177 offset:2048
	ds_read_b128 v[210:213], v177 offset:3072
	ds_read_b128 v[214:217], v177 offset:4096
	ds_read_b128 v[218:221], v177 offset:5120
	ds_read_b128 v[222:225], v177 offset:6144
	ds_read_b128 v[226:229], v177 offset:7168
	global_load_lds_dwordx4 v[160:161], off
	s_add_i32 m0, s50, 0xe000
	v_lshl_add_u64 v[160:161], s[8:9], 0, v[156:157]
	global_load_lds_dwordx4 v[160:161], off
	s_waitcnt vmcnt(8) lgkmcnt(0)
	s_setprio 1
	s_barrier
; #define PG8_STAGE(bufoff, gbase, voff) do { _Pragma("unroll") for (int _i = 0; _i < 2; ++_i) \
;         __builtin_amdgcn_global_load_lds((const unsigned*)((const char*)(gbase) + (voff)[_i]), (PG8_LAS unsigned*)(lds + (bufoff) + ldsw + _i * 8192), 16, 0, 0); } while (0)
; #define PG8_LDA(dst, b, h) do { _Pragma("unroll") for (int m = 0; m < 4; ++m) _Pragma("unroll") for (int k = 0; k < 2; ++k) dst[m][k] = *(const PG8_LAS bf16x8*)(lds + PG8_SA(b, h) + aoff + m * 2048 + k * 1024); } while (0)
; #define PG8_LDB(dst, b, h) do { _Pragma("unroll") for (int n = 0; n < 2; ++n) _Pragma("unroll") for (int k = 0; k < 2; ++k) dst[n][k] = *(const PG8_LAS bf16x8*)(lds + PG8_SB(b, h) + boff + n * 2048 + k * 1024); } while (0)
; #define PG8_MMA(ai, bj, At, Bt) do { __builtin_amdgcn_s_setprio(1); _Pragma("unroll") for (int m = 0; m < 4; ++m) _Pragma("unroll") for (int n = 0; n < 2; ++n) _Pragma("unroll") for (int k = 0; k < 2; ++k) \
;         acc[ai][bj][m][n] = __builtin_amdgcn_mfma_f32_16x16x32_bf16(Bt[n][k], At[m][k], acc[ai][bj][m][n], 0, 0, 0); __builtin_amdgcn_s_setprio(0); } while (0)
; #define PG8_WAIT_V(n) asm volatile("s_waitcnt vmcnt(" #n ")" ::: "memory")
; #define PG8_WAIT_L(n) asm volatile("s_waitcnt lgkmcnt(" #n ")" ::: "memory")
; #define PG8_BAR __builtin_amdgcn_s_barrier()
; #define PG8_SCHED __builtin_amdgcn_sched_barrier(0)
; template <class Epi, class Sched, bool ALIGN_EPI = false, bool SP2 = false>
; __device__ __forceinline__ void gemm_phase(PG8_LAS unsigned char* lds, const Gemm g, const Sched& S, const Epi& E) {
;     ...
;             PG8_LDB(B0, 0, 0); PG8_LDB(B1, 0, 1); PG8_SCHED; PG8_LDA(At, 0, 0); PG8_STAGE(PG8_SA(1, 1), a1 + hstep, voffA);
;             PG8_WAIT_V(8); PG8_WAIT_L(0); PG8_BAR; PG8_MMA(0, 0, At, B0); PG8_MMA(0, 1, At, B1); PG8_BAR; PG8_SCHED;
;             PG8_LDA(At, 0, 1); PG8_STAGE(PG8_SB(0, 0), b2, voffB); PG8_STAGE(PG8_SB(0, 1), b2 + hstep, voffB); PG8_STAGE(PG8_SA(0, 0), a2, voffA);
;             PG8_WAIT_V(8); PG8_WAIT_L(0); PG8_BAR; PG8_MMA(1, 0, At, B0); PG8_MMA(1, 1, At, B1); PG8_BAR; PG8_SCHED;
	v_mfma_f32_16x16x32_bf16 v[140:143], v[108:111], v[198:201], v[140:143]
	v_mfma_f32_16x16x32_bf16 v[136:139], v[116:119], v[198:201], v[136:139]
	v_mfma_f32_16x16x32_bf16 v[100:103], v[108:111], v[206:209], v[100:103]
	v_mfma_f32_16x16x32_bf16 v[124:127], v[116:119], v[206:209], v[124:127]
	v_mfma_f32_16x16x32_bf16 v[84:87], v[108:111], v[214:217], v[84:87]
	v_mfma_f32_16x16x32_bf16 v[92:95], v[116:119], v[214:217], v[92:95]
	v_mfma_f32_16x16x32_bf16 v[68:71], v[108:111], v[222:225], v[68:71]
	v_mfma_f32_16x16x32_bf16 v[76:79], v[116:119], v[222:225], v[76:79]
	v_mfma_f32_16x16x32_bf16 v[140:143], v[112:115], v[202:205], v[140:143]
	v_mfma_f32_16x16x32_bf16 v[136:139], v[120:123], v[202:205], v[136:139]
	v_mfma_f32_16x16x32_bf16 v[100:103], v[112:115], v[210:213], v[100:103]
	v_mfma_f32_16x16x32_bf16 v[124:127], v[120:123], v[210:213], v[124:127]
	v_mfma_f32_16x16x32_bf16 v[84:87], v[112:115], v[218:221], v[84:87]
	v_mfma_f32_16x16x32_bf16 v[92:95], v[120:123], v[218:221], v[92:95]
	v_mfma_f32_16x16x32_bf16 v[68:71], v[112:115], v[226:229], v[68:71]
	v_mfma_f32_16x16x32_bf16 v[76:79], v[120:123], v[226:229], v[76:79]
	v_mfma_f32_16x16x32_bf16 v[128:131], v[178:181], v[198:201], v[128:131]
	v_mfma_f32_16x16x32_bf16 v[132:135], v[186:189], v[198:201], v[132:135]
	v_mfma_f32_16x16x32_bf16 v[104:107], v[178:181], v[206:209], v[104:107]
	v_mfma_f32_16x16x32_bf16 v[96:99], v[186:189], v[206:209], v[96:99]
	v_mfma_f32_16x16x32_bf16 v[88:91], v[178:181], v[214:217], v[88:91]
	v_mfma_f32_16x16x32_bf16 v[80:83], v[186:189], v[214:217], v[80:83]
	v_mfma_f32_16x16x32_bf16 v[72:75], v[178:181], v[222:225], v[72:75]
	v_mfma_f32_16x16x32_bf16 v[64:67], v[186:189], v[222:225], v[64:67]
	v_mfma_f32_16x16x32_bf16 v[128:131], v[182:185], v[202:205], v[128:131]
	v_mfma_f32_16x16x32_bf16 v[132:135], v[190:193], v[202:205], v[132:135]
	v_mfma_f32_16x16x32_bf16 v[104:107], v[182:185], v[210:213], v[104:107]
	v_mfma_f32_16x16x32_bf16 v[96:99], v[190:193], v[210:213], v[96:99]
	v_mfma_f32_16x16x32_bf16 v[88:91], v[182:185], v[218:221], v[88:91]
	v_mfma_f32_16x16x32_bf16 v[80:83], v[190:193], v[218:221], v[80:83]
	v_mfma_f32_16x16x32_bf16 v[72:75], v[182:185], v[226:229], v[72:75]
	v_mfma_f32_16x16x32_bf16 v[64:67], v[190:193], v[226:229], v[64:67]
	s_barrier
	s_setprio 0
	s_add_i32 s67, s62, s47
	v_lshl_add_u64 v[160:161], s[42:43], 0, v[144:145]
	s_mov_b32 m0, s67
	ds_read_b128 v[198:201], v177 offset:16384
	ds_read_b128 v[202:205], v177 offset:17408
	ds_read_b128 v[206:209], v177 offset:18432
	ds_read_b128 v[210:213], v177 offset:19456
	ds_read_b128 v[214:217], v177 offset:20480
	ds_read_b128 v[218:221], v177 offset:21504
	ds_read_b128 v[222:225], v177 offset:22528
	ds_read_b128 v[226:229], v177 offset:23552
	global_load_lds_dwordx4 v[160:161], off
	s_add_i32 m0, s67, 0x2000
	s_add_u32 s68, s42, 0x80000
	v_lshl_add_u64 v[164:165], s[42:43], 0, v[146:147]
	s_addc_u32 s69, s43, 0
	s_add_i32 s67, s63, s47
	global_load_lds_dwordx4 v[164:165], off
	v_lshl_add_u64 v[170:171], s[68:69], 0, v[144:145]
	s_mov_b32 m0, s67
	v_lshl_add_u64 v[194:195], s[44:45], 0, v[146:147]
	global_load_lds_dwordx4 v[170:171], off
	s_add_i32 m0, s67, 0x2000
	v_lshl_add_u64 v[170:171], s[68:69], 0, v[146:147]
	global_load_lds_dwordx4 v[170:171], off
	s_mov_b32 m0, s50
	v_lshl_add_u64 v[170:171], s[44:45], 0, v[144:145]
	global_load_lds_dwordx4 v[170:171], off
	s_mov_b32 m0, s51
	s_nop 0
	global_load_lds_dwordx4 v[194:195], off
	s_waitcnt vmcnt(8) lgkmcnt(0)
	s_setprio 1
	s_barrier
	v_mfma_f32_16x16x32_bf16 v[60:63], v[108:111], v[198:201], v[60:63]
	v_mfma_f32_16x16x32_bf16 v[56:59], v[116:119], v[198:201], v[56:59]
	v_mfma_f32_16x16x32_bf16 v[36:39], v[108:111], v[206:209], v[36:39]
	v_mfma_f32_16x16x32_bf16 v[44:47], v[116:119], v[206:209], v[44:47]
	v_mfma_f32_16x16x32_bf16 v[20:23], v[108:111], v[214:217], v[20:23]
	v_mfma_f32_16x16x32_bf16 v[28:31], v[116:119], v[214:217], v[28:31]
	v_mfma_f32_16x16x32_bf16 v[4:7], v[108:111], v[222:225], v[4:7]
	v_mfma_f32_16x16x32_bf16 v[12:15], v[116:119], v[222:225], v[12:15]
	v_mfma_f32_16x16x32_bf16 v[60:63], v[112:115], v[202:205], v[60:63]
	v_mfma_f32_16x16x32_bf16 v[56:59], v[120:123], v[202:205], v[56:59]
	v_mfma_f32_16x16x32_bf16 v[36:39], v[112:115], v[210:213], v[36:39]
	v_mfma_f32_16x16x32_bf16 v[44:47], v[120:123], v[210:213], v[44:47]
	v_mfma_f32_16x16x32_bf16 v[20:23], v[112:115], v[218:221], v[20:23]
	v_mfma_f32_16x16x32_bf16 v[28:31], v[120:123], v[218:221], v[28:31]
	v_mfma_f32_16x16x32_bf16 v[4:7], v[112:115], v[226:229], v[4:7]
	v_mfma_f32_16x16x32_bf16 v[12:15], v[120:123], v[226:229], v[12:15]
	v_mfma_f32_16x16x32_bf16 v[48:51], v[178:181], v[198:201], v[48:51]
	v_mfma_f32_16x16x32_bf16 v[52:55], v[186:189], v[198:201], v[52:55]
	v_mfma_f32_16x16x32_bf16 v[40:43], v[178:181], v[206:209], v[40:43]
	v_mfma_f32_16x16x32_bf16 v[32:35], v[186:189], v[206:209], v[32:35]
	v_mfma_f32_16x16x32_bf16 v[24:27], v[178:181], v[214:217], v[24:27]
	v_mfma_f32_16x16x32_bf16 v[16:19], v[186:189], v[214:217], v[16:19]
	v_mfma_f32_16x16x32_bf16 v[8:11], v[178:181], v[222:225], v[8:11]
	v_mfma_f32_16x16x32_bf16 v[0:3], v[186:189], v[222:225], v[0:3]
	v_mfma_f32_16x16x32_bf16 v[48:51], v[182:185], v[202:205], v[48:51]
	v_mfma_f32_16x16x32_bf16 v[52:55], v[190:193], v[202:205], v[52:55]
	v_mfma_f32_16x16x32_bf16 v[40:43], v[182:185], v[210:213], v[40:43]
	v_mfma_f32_16x16x32_bf16 v[32:35], v[190:193], v[210:213], v[32:35]
	v_mfma_f32_16x16x32_bf16 v[24:27], v[182:185], v[218:221], v[24:27]
	v_mfma_f32_16x16x32_bf16 v[16:19], v[190:193], v[218:221], v[16:19]
	v_mfma_f32_16x16x32_bf16 v[8:11], v[182:185], v[226:229], v[8:11]
	v_mfma_f32_16x16x32_bf16 v[0:3], v[190:193], v[226:229], v[0:3]
	s_barrier
; #define PG8_STAGE(bufoff, gbase, voff) do { _Pragma("unroll") for (int _i = 0; _i < 2; ++_i) \
;         __builtin_amdgcn_global_load_lds((const unsigned*)((const char*)(gbase) + (voff)[_i]), (PG8_LAS unsigned*)(lds + (bufoff) + ldsw + _i * 8192), 16, 0, 0); } while (0)
; #define PG8_LDA(dst, b, h) do { _Pragma("unroll") for (int m = 0; m < 4; ++m) _Pragma("unroll") for (int k = 0; k < 2; ++k) dst[m][k] = *(const PG8_LAS bf16x8*)(lds + PG8_SA(b, h) + aoff + m * 2048 + k * 1024); } while (0)
; #define PG8_LDB(dst, b, h) do { _Pragma("unroll") for (int n = 0; n < 2; ++n) _Pragma("unroll") for (int k = 0; k < 2; ++k) dst[n][k] = *(const PG8_LAS bf16x8*)(lds + PG8_SB(b, h) + boff + n * 2048 + k * 1024); } while (0)
; #define PG8_MMA(ai, bj, At, Bt) do { __builtin_amdgcn_s_setprio(1); _Pragma("unroll") for (int m = 0; m < 4; ++m) _Pragma("unroll") for (int n = 0; n < 2; ++n) _Pragma("unroll") for (int k = 0; k < 2; ++k) \
;         acc[ai][bj][m][n] = __builtin_amdgcn_mfma_f32_16x16x32_bf16(Bt[n][k], At[m][k], acc[ai][bj][m][n], 0, 0, 0); __builtin_amdgcn_s_setprio(0); } while (0)
; #define PG8_WAIT_V(n) asm volatile("s_waitcnt vmcnt(" #n ")" ::: "memory")
; #define PG8_WAIT_L(n) asm volatile("s_waitcnt lgkmcnt(" #n ")" ::: "memory")
; #define PG8_BAR __builtin_amdgcn_s_barrier()
; #define PG8_SCHED __builtin_amdgcn_sched_barrier(0)
; template <class Epi, class Sched, bool ALIGN_EPI = false, bool SP2 = false>
; __device__ __forceinline__ void gemm_phase(PG8_LAS unsigned char* lds, const Gemm g, const Sched& S, const Epi& E) {
;     ...
;             PG8_LDB(B0, 1, 0); PG8_LDB(B1, 1, 1); PG8_SCHED; PG8_LDA(At, 1, 0); PG8_STAGE(PG8_SA(0, 1), a2 + hstep, voffA);
;             PG8_WAIT_V(8); PG8_WAIT_L(0); PG8_BAR; PG8_MMA(0, 0, At, B0); PG8_MMA(0, 1, At, B1); PG8_BAR; PG8_SCHED;
	s_setprio 0
	s_add_i32 s67, 0, 0x18000
	s_add_i32 s68, 0, 0x1c000
	v_add_u32_e32 v120, s67, v167
	v_add_u32_e32 v162, s68, v167
	ds_read_b128 v[108:111], v120
	ds_read_b128 v[112:115], v120 offset:1024
	ds_read_b128 v[116:119], v120 offset:2048
	ds_read_b128 v[120:123], v120 offset:3072
	ds_read_b128 v[178:181], v162
	ds_read_b128 v[182:185], v162 offset:1024
	ds_read_b128 v[186:189], v162 offset:2048
	ds_read_b128 v[190:193], v162 offset:3072
	s_add_u32 s44, s44, 0x80000
	s_addc_u32 s45, s45, 0
	s_mov_b32 m0, s52
	v_lshl_add_u64 v[230:231], s[44:45], 0, v[144:145]
	ds_read_b128 v[198:201], v177 offset:32768
	ds_read_b128 v[202:205], v177 offset:33792
	ds_read_b128 v[206:209], v177 offset:34816
	ds_read_b128 v[210:213], v177 offset:35840
	ds_read_b128 v[214:217], v177 offset:36864
	ds_read_b128 v[218:221], v177 offset:37888
	ds_read_b128 v[222:225], v177 offset:38912
	ds_read_b128 v[226:229], v177 offset:39936
	global_load_lds_dwordx4 v[230:231], off
	s_mov_b32 m0, s53
	v_lshl_add_u64 v[230:231], s[44:45], 0, v[146:147]
	global_load_lds_dwordx4 v[230:231], off
	s_waitcnt vmcnt(8) lgkmcnt(0)
	s_setprio 1
	s_barrier
	v_mfma_f32_16x16x32_bf16 v[140:143], v[108:111], v[198:201], v[140:143]
	v_mfma_f32_16x16x32_bf16 v[136:139], v[116:119], v[198:201], v[136:139]
	v_mfma_f32_16x16x32_bf16 v[100:103], v[108:111], v[206:209], v[100:103]
	v_mfma_f32_16x16x32_bf16 v[124:127], v[116:119], v[206:209], v[124:127]
	v_mfma_f32_16x16x32_bf16 v[84:87], v[108:111], v[214:217], v[84:87]
	v_mfma_f32_16x16x32_bf16 v[92:95], v[116:119], v[214:217], v[92:95]
	v_mfma_f32_16x16x32_bf16 v[68:71], v[108:111], v[222:225], v[68:71]
	v_mfma_f32_16x16x32_bf16 v[76:79], v[116:119], v[222:225], v[76:79]
	v_mfma_f32_16x16x32_bf16 v[140:143], v[112:115], v[202:205], v[140:143]
	v_mfma_f32_16x16x32_bf16 v[136:139], v[120:123], v[202:205], v[136:139]
	v_mfma_f32_16x16x32_bf16 v[100:103], v[112:115], v[210:213], v[100:103]
	v_mfma_f32_16x16x32_bf16 v[124:127], v[120:123], v[210:213], v[124:127]
	v_mfma_f32_16x16x32_bf16 v[84:87], v[112:115], v[218:221], v[84:87]
	v_mfma_f32_16x16x32_bf16 v[92:95], v[120:123], v[218:221], v[92:95]
	v_mfma_f32_16x16x32_bf16 v[68:71], v[112:115], v[226:229], v[68:71]
	v_mfma_f32_16x16x32_bf16 v[76:79], v[120:123], v[226:229], v[76:79]
	v_mfma_f32_16x16x32_bf16 v[128:131], v[178:181], v[198:201], v[128:131]
	v_mfma_f32_16x16x32_bf16 v[132:135], v[186:189], v[198:201], v[132:135]
	v_mfma_f32_16x16x32_bf16 v[104:107], v[178:181], v[206:209], v[104:107]
	v_mfma_f32_16x16x32_bf16 v[96:99], v[186:189], v[206:209], v[96:99]
	v_mfma_f32_16x16x32_bf16 v[88:91], v[178:181], v[214:217], v[88:91]
	v_mfma_f32_16x16x32_bf16 v[80:83], v[186:189], v[214:217], v[80:83]
	v_mfma_f32_16x16x32_bf16 v[72:75], v[178:181], v[222:225], v[72:75]
	v_mfma_f32_16x16x32_bf16 v[64:67], v[186:189], v[222:225], v[64:67]
	v_mfma_f32_16x16x32_bf16 v[128:131], v[182:185], v[202:205], v[128:131]
	v_mfma_f32_16x16x32_bf16 v[132:135], v[190:193], v[202:205], v[132:135]
	v_mfma_f32_16x16x32_bf16 v[104:107], v[182:185], v[210:213], v[104:107]
	v_mfma_f32_16x16x32_bf16 v[96:99], v[190:193], v[210:213], v[96:99]
	v_mfma_f32_16x16x32_bf16 v[88:91], v[182:185], v[218:221], v[88:91]
	v_mfma_f32_16x16x32_bf16 v[80:83], v[190:193], v[218:221], v[80:83]
	v_mfma_f32_16x16x32_bf16 v[72:75], v[182:185], v[226:229], v[72:75]
	v_mfma_f32_16x16x32_bf16 v[64:67], v[190:193], v[226:229], v[64:67]
	s_barrier
; #define PG8_STAGE(bufoff, gbase, voff) do { _Pragma("unroll") for (int _i = 0; _i < 2; ++_i) \
;         __builtin_amdgcn_global_load_lds((const unsigned*)((const char*)(gbase) + (voff)[_i]), (PG8_LAS unsigned*)(lds + (bufoff) + ldsw + _i * 8192), 16, 0, 0); } while (0)
; #define PG8_LDA(dst, b, h) do { _Pragma("unroll") for (int m = 0; m < 4; ++m) _Pragma("unroll") for (int k = 0; k < 2; ++k) dst[m][k] = *(const PG8_LAS bf16x8*)(lds + PG8_SA(b, h) + aoff + m * 2048 + k * 1024); } while (0)
; #define PG8_MMA(ai, bj, At, Bt) do { __builtin_amdgcn_s_setprio(1); _Pragma("unroll") for (int m = 0; m < 4; ++m) _Pragma("unroll") for (int n = 0; n < 2; ++n) _Pragma("unroll") for (int k = 0; k < 2; ++k) \
;         acc[ai][bj][m][n] = __builtin_amdgcn_mfma_f32_16x16x32_bf16(Bt[n][k], At[m][k], acc[ai][bj][m][n], 0, 0, 0); __builtin_amdgcn_s_setprio(0); } while (0)
; #define PG8_WAIT_V(n) asm volatile("s_waitcnt vmcnt(" #n ")" ::: "memory")
; #define PG8_WAIT_L(n) asm volatile("s_waitcnt lgkmcnt(" #n ")" ::: "memory")
; #define PG8_BAR __builtin_amdgcn_s_barrier()
; #define PG8_SCHED __builtin_amdgcn_sched_barrier(0)
; template <class Epi, class Sched, bool ALIGN_EPI = false, bool SP2 = false>
; __device__ __forceinline__ void gemm_phase(PG8_LAS unsigned char* lds, const Gemm g, const Sched& S, const Epi& E) {
;     ...
;             PG8_LDA(At, 1, 1); PG8_STAGE(PG8_SB(1, 0), b3, voffB); PG8_STAGE(PG8_SB(1, 1), b3 + hstep, voffB); PG8_STAGE(PG8_SA(1, 0), a3, voffA);
;             PG8_WAIT_V(8); PG8_WAIT_L(0); PG8_BAR; PG8_MMA(1, 0, At, B0); PG8_MMA(1, 1, At, B1); PG8_BAR; PG8_SCHED;
;     ...
;         }
;         if constexpr (ALIGN_EPI) { if (wr == 0) PG8_BAR; }
	s_setprio 0
	s_add_i32 s44, s67, s47
	v_lshl_add_u64 v[160:161], v[160:161], 0, s[16:17]
	s_mov_b32 m0, s44
	ds_read_b128 v[198:201], v177 offset:49152
	ds_read_b128 v[202:205], v177 offset:50176
	ds_read_b128 v[206:209], v177 offset:51200
	ds_read_b128 v[210:213], v177 offset:52224
	ds_read_b128 v[214:217], v177 offset:53248
	ds_read_b128 v[218:221], v177 offset:54272
	ds_read_b128 v[222:225], v177 offset:55296
	ds_read_b128 v[226:229], v177 offset:56320
	global_load_lds_dwordx4 v[160:161], off
	s_add_i32 m0, s44, 0x2000
	s_add_u32 s42, s42, 0x80080
	v_lshl_add_u64 v[160:161], v[164:165], 0, s[16:17]
	s_addc_u32 s43, s43, 0
	s_add_i32 s44, s68, s47
	global_load_lds_dwordx4 v[160:161], off
	s_mov_b32 m0, s44
	v_lshl_add_u64 v[160:161], s[42:43], 0, v[144:145]
	global_load_lds_dwordx4 v[160:161], off
	s_add_i32 m0, s44, 0x2000
	v_lshl_add_u64 v[160:161], s[42:43], 0, v[146:147]
	global_load_lds_dwordx4 v[160:161], off
	s_mov_b32 m0, s55
	v_lshl_add_u64 v[160:161], v[170:171], 0, s[16:17]
	global_load_lds_dwordx4 v[160:161], off
	s_mov_b32 m0, s56
	v_lshl_add_u64 v[160:161], v[194:195], 0, s[16:17]
	global_load_lds_dwordx4 v[160:161], off
	s_waitcnt vmcnt(8) lgkmcnt(0)
	s_setprio 1
	s_barrier
	v_mfma_f32_16x16x32_bf16 v[60:63], v[108:111], v[198:201], v[60:63]
	v_mfma_f32_16x16x32_bf16 v[56:59], v[116:119], v[198:201], v[56:59]
	v_mfma_f32_16x16x32_bf16 v[36:39], v[108:111], v[206:209], v[36:39]
	v_mfma_f32_16x16x32_bf16 v[44:47], v[116:119], v[206:209], v[44:47]
	v_mfma_f32_16x16x32_bf16 v[20:23], v[108:111], v[214:217], v[20:23]
	v_mfma_f32_16x16x32_bf16 v[28:31], v[116:119], v[214:217], v[28:31]
	v_mfma_f32_16x16x32_bf16 v[4:7], v[108:111], v[222:225], v[4:7]
	v_mfma_f32_16x16x32_bf16 v[12:15], v[116:119], v[222:225], v[12:15]
	v_mfma_f32_16x16x32_bf16 v[60:63], v[112:115], v[202:205], v[60:63]
	v_mfma_f32_16x16x32_bf16 v[56:59], v[120:123], v[202:205], v[56:59]
	v_mfma_f32_16x16x32_bf16 v[36:39], v[112:115], v[210:213], v[36:39]
	v_mfma_f32_16x16x32_bf16 v[44:47], v[120:123], v[210:213], v[44:47]
	v_mfma_f32_16x16x32_bf16 v[20:23], v[112:115], v[218:221], v[20:23]
	v_mfma_f32_16x16x32_bf16 v[28:31], v[120:123], v[218:221], v[28:31]
	v_mfma_f32_16x16x32_bf16 v[4:7], v[112:115], v[226:229], v[4:7]
	v_mfma_f32_16x16x32_bf16 v[12:15], v[120:123], v[226:229], v[12:15]
	v_mfma_f32_16x16x32_bf16 v[48:51], v[178:181], v[198:201], v[48:51]
	v_mfma_f32_16x16x32_bf16 v[52:55], v[186:189], v[198:201], v[52:55]
	v_mfma_f32_16x16x32_bf16 v[40:43], v[178:181], v[206:209], v[40:43]
	v_mfma_f32_16x16x32_bf16 v[32:35], v[186:189], v[206:209], v[32:35]
	v_mfma_f32_16x16x32_bf16 v[24:27], v[178:181], v[214:217], v[24:27]
	v_mfma_f32_16x16x32_bf16 v[16:19], v[186:189], v[214:217], v[16:19]
	v_mfma_f32_16x16x32_bf16 v[8:11], v[178:181], v[222:225], v[8:11]
	v_mfma_f32_16x16x32_bf16 v[0:3], v[186:189], v[222:225], v[0:3]
	v_mfma_f32_16x16x32_bf16 v[48:51], v[182:185], v[202:205], v[48:51]
	v_mfma_f32_16x16x32_bf16 v[52:55], v[190:193], v[202:205], v[52:55]
	v_mfma_f32_16x16x32_bf16 v[40:43], v[182:185], v[210:213], v[40:43]
	v_mfma_f32_16x16x32_bf16 v[32:35], v[190:193], v[210:213], v[32:35]
	v_mfma_f32_16x16x32_bf16 v[24:27], v[182:185], v[218:221], v[24:27]
	v_mfma_f32_16x16x32_bf16 v[16:19], v[190:193], v[218:221], v[16:19]
	v_mfma_f32_16x16x32_bf16 v[8:11], v[182:185], v[226:229], v[8:11]
	v_mfma_f32_16x16x32_bf16 v[0:3], v[190:193], v[226:229], v[0:3]
	s_barrier
	s_setprio 0
	s_add_i32 s66, s66, 2
	s_add_u32 s8, s8, 0x100
	s_addc_u32 s9, s9, 0
	s_add_u32 s48, s48, 0x100
	s_addc_u32 s49, s49, 0
	s_cmp_gt_u32 s66, 29
	s_cbranch_scc0 .LBB0_1373
	s_and_b64 vcc, exec, s[18:19]
	s_cbranch_vccz .LBB0_1376
	s_barrier

; #define PG8_STAGE(bufoff, gbase, voff) do { _Pragma("unroll") for (int _i = 0; _i < 2; ++_i) \
;         __builtin_amdgcn_global_load_lds((const unsigned*)((const char*)(gbase) + (voff)[_i]), (PG8_LAS unsigned*)(lds + (bufoff) + ldsw + _i * 8192), 16, 0, 0); } while (0)
; #define PG8_LDA(dst, b, h) do { _Pragma("unroll") for (int m = 0; m < 4; ++m) _Pragma("unroll") for (int k = 0; k < 2; ++k) dst[m][k] = *(const PG8_LAS bf16x8*)(lds + PG8_SA(b, h) + aoff + m * 2048 + k * 1024); } while (0)
; #define PG8_LDB(dst, b, h) do { _Pragma("unroll") for (int n = 0; n < 2; ++n) _Pragma("unroll") for (int k = 0; k < 2; ++k) dst[n][k] = *(const PG8_LAS bf16x8*)(lds + PG8_SB(b, h) + boff + n * 2048 + k * 1024); } while (0)
; #define PG8_MMA(ai, bj, At, Bt) do { __builtin_amdgcn_s_setprio(1); _Pragma("unroll") for (int m = 0; m < 4; ++m) _Pragma("unroll") for (int n = 0; n < 2; ++n) _Pragma("unroll") for (int k = 0; k < 2; ++k) \
;         acc[ai][bj][m][n] = __builtin_amdgcn_mfma_f32_16x16x32_bf16(Bt[n][k], At[m][k], acc[ai][bj][m][n], 0, 0, 0); __builtin_amdgcn_s_setprio(0); } while (0)
; #define PG8_BAR __builtin_amdgcn_s_barrier()
; template <class Epi, class Sched, bool ALIGN_EPI = false, bool SP2 = false>
; __device__ __forceinline__ void gemm_phase(PG8_LAS unsigned char* lds, const Gemm g, const Sched& S, const Epi& E) {
;     ...
;         const bool has_next = S.next(ui + 1, nxt);
;         const char* nA = has_next ? (const char*)g.A + (size_t)nxt.pm * tstep : cA; const char* nB = has_next ? (const char*)g.Bt + (size_t)nxt.pn * tstep : cB;
;         for (int t = 0; t < nt; t += 2) {
;             const bool last = (t == nt - 2);
;             const char* a1 = cA + (size_t)(t + 1) * kstep;
;             const char* a2 = last ? nA : cA + (size_t)(t + 2) * kstep; const char* b2 = last ? nB : cB + (size_t)(t + 2) * kstep;
;             const char* a3 = a2 + kstep; const char* b3 = b2 + kstep;
;             if (last && has_next) S.a_ready(nxt);
;             if constexpr (SP2) {
;             PG8_LDB(B0, 0, 0); PG8_LDB(B1, 0, 1); PG8_SCHED; PG8_LDA(At, 0, 0); PG8_STAGE(PG8_SA(1, 1), a1 + hstep, voffA);
;             PG8_WAIT_V(8); PG8_WAIT_L(0); PG8_BAR; PG8_MMA(0, 0, At, B0); PG8_MMA(0, 1, At, B1); PG8_BAR; PG8_SCHED;
;             PG8_LDA(At, 0, 1); PG8_STAGE(PG8_SB(0, 0), b2, voffB); PG8_STAGE(PG8_SB(0, 1), b2 + hstep, voffB); PG8_STAGE(PG8_SA(0, 0), a2, voffA);
.LBB0_1548:
	s_ashr_i32 s13, s12, 31
	s_lshl_b64 s[14:15], s[12:13], 20
	s_add_u32 s14, s60, s14
	s_addc_u32 s15, s61, s15
	s_and_b64 s[16:17], s[0:1], exec
	s_cselect_b32 s13, s15, s21
	s_cselect_b32 s39, s14, s20
	s_ashr_i32 s11, s10, 31
	s_lshl_b64 s[16:17], s[10:11], 20
	s_add_u32 s16, s72, s16
	s_addc_u32 s17, s73, s17
	s_and_b64 s[24:25], s[0:1], exec
	s_cselect_b32 s11, s17, s23
	s_cselect_b32 s40, s16, s22
	s_add_u32 s20, s20, 0x80080
	s_addc_u32 s21, s21, 0
	s_add_u32 s41, s22, 0x100
	s_addc_u32 s42, s23, 0
	s_mov_b32 s43, -2
	ds_read_b128 v[144:147], v155
	ds_read_b128 v[148:151], v155 offset:1024
	ds_read_b128 v[158:161], v155 offset:2048
	ds_read_b128 v[162:165], v155 offset:3072
	ds_read_b128 v[166:169], v156
	ds_read_b128 v[170:173], v156 offset:1024
	ds_read_b128 v[174:177], v156 offset:2048
	ds_read_b128 v[178:181], v156 offset:3072
	s_add_u32 s22, s20, 0xfff80080
	s_addc_u32 s23, s21, -1
	s_cmp_eq_u32 s43, 28
	s_cselect_b32 s25, s13, s23
	s_cselect_b32 s24, s39, s22
	s_cselect_b32 s23, s11, s42
	s_cselect_b32 s22, s40, s41
	v_lshl_add_u64 v[214:215], s[20:21], 0, v[136:137]
	s_add_i32 m0, s19, 0xc000
	ds_read_b128 v[182:185], v157
	ds_read_b128 v[186:189], v157 offset:1024
	ds_read_b128 v[190:193], v157 offset:2048
	ds_read_b128 v[194:197], v157 offset:3072
	ds_read_b128 v[198:201], v157 offset:4096
	ds_read_b128 v[202:205], v157 offset:5120
	ds_read_b128 v[206:209], v157 offset:6144
	ds_read_b128 v[210:213], v157 offset:7168
	global_load_lds_dwordx4 v[214:215], off
	s_add_i32 m0, s19, 0xe000
	v_lshl_add_u64 v[214:215], s[20:21], 0, v[138:139]
	global_load_lds_dwordx4 v[214:215], off
	s_waitcnt lgkmcnt(0)
	s_setprio 1
	s_barrier
	v_mfma_f32_16x16x32_bf16 v[124:127], v[144:147], v[182:185], 0
	v_mfma_f32_16x16x32_bf16 v[120:123], v[158:161], v[182:185], 0
	v_mfma_f32_16x16x32_bf16 v[108:111], v[144:147], v[190:193], 0
	v_mfma_f32_16x16x32_bf16 v[104:107], v[158:161], v[190:193], 0
	v_mfma_f32_16x16x32_bf16 v[88:91], v[144:147], v[198:201], 0
	v_mfma_f32_16x16x32_bf16 v[92:95], v[158:161], v[198:201], 0
	v_mfma_f32_16x16x32_bf16 v[72:75], v[144:147], v[206:209], 0
	v_mfma_f32_16x16x32_bf16 v[76:79], v[158:161], v[206:209], 0
	v_mfma_f32_16x16x32_bf16 v[124:127], v[148:151], v[186:189], v[124:127]
	v_mfma_f32_16x16x32_bf16 v[120:123], v[162:165], v[186:189], v[120:123]
	v_mfma_f32_16x16x32_bf16 v[108:111], v[148:151], v[194:197], v[108:111]
	v_mfma_f32_16x16x32_bf16 v[104:107], v[162:165], v[194:197], v[104:107]
	v_mfma_f32_16x16x32_bf16 v[88:91], v[148:151], v[202:205], v[88:91]
	v_mfma_f32_16x16x32_bf16 v[92:95], v[162:165], v[202:205], v[92:95]
	v_mfma_f32_16x16x32_bf16 v[72:75], v[148:151], v[210:213], v[72:75]
	v_mfma_f32_16x16x32_bf16 v[76:79], v[162:165], v[210:213], v[76:79]
	v_mfma_f32_16x16x32_bf16 v[116:119], v[166:169], v[182:185], 0
	v_mfma_f32_16x16x32_bf16 v[112:115], v[174:177], v[182:185], 0
	v_mfma_f32_16x16x32_bf16 v[96:99], v[166:169], v[190:193], 0
	v_mfma_f32_16x16x32_bf16 v[100:103], v[174:177], v[190:193], 0
	v_mfma_f32_16x16x32_bf16 v[80:83], v[166:169], v[198:201], 0
	v_mfma_f32_16x16x32_bf16 v[84:87], v[174:177], v[198:201], 0
	v_mfma_f32_16x16x32_bf16 v[64:67], v[166:169], v[206:209], 0
	v_mfma_f32_16x16x32_bf16 v[68:71], v[174:177], v[206:209], 0
	v_mfma_f32_16x16x32_bf16 v[116:119], v[170:173], v[186:189], v[116:119]
	v_mfma_f32_16x16x32_bf16 v[112:115], v[178:181], v[186:189], v[112:115]
	v_mfma_f32_16x16x32_bf16 v[96:99], v[170:173], v[194:197], v[96:99]
	v_mfma_f32_16x16x32_bf16 v[100:103], v[178:181], v[194:197], v[100:103]
	v_mfma_f32_16x16x32_bf16 v[80:83], v[170:173], v[202:205], v[80:83]
	v_mfma_f32_16x16x32_bf16 v[84:87], v[178:181], v[202:205], v[84:87]
	v_mfma_f32_16x16x32_bf16 v[64:67], v[170:173], v[210:213], v[64:67]
	v_mfma_f32_16x16x32_bf16 v[68:71], v[178:181], v[210:213], v[68:71]
	s_barrier
	s_setprio 0
	s_add_i32 s44, s36, s27
	v_lshl_add_u64 v[214:215], s[22:23], 0, v[130:131]
	s_mov_b32 m0, s44
	ds_read_b128 v[182:185], v157 offset:16384
	ds_read_b128 v[186:189], v157 offset:17408
	ds_read_b128 v[190:193], v157 offset:18432
	ds_read_b128 v[194:197], v157 offset:19456
	ds_read_b128 v[198:201], v157 offset:20480
	ds_read_b128 v[202:205], v157 offset:21504
	ds_read_b128 v[206:209], v157 offset:22528
	ds_read_b128 v[210:213], v157 offset:23552
	global_load_lds_dwordx4 v[214:215], off
	s_add_i32 m0, s44, 0x2000
	s_add_u32 s44, s22, 0x80000
	v_lshl_add_u64 v[216:217], s[22:23], 0, v[134:135]
	s_addc_u32 s45, s23, 0
	s_add_i32 s46, s37, s27
	global_load_lds_dwordx4 v[216:217], off
	v_lshl_add_u64 v[218:219], s[44:45], 0, v[130:131]
	s_mov_b32 m0, s46
	v_lshl_add_u64 v[220:221], s[24:25], 0, v[132:133]
	global_load_lds_dwordx4 v[218:219], off
	s_add_i32 m0, s46, 0x2000
	v_lshl_add_u64 v[218:219], s[44:45], 0, v[134:135]
	global_load_lds_dwordx4 v[218:219], off
	s_mov_b32 m0, s19
	v_lshl_add_u64 v[218:219], s[24:25], 0, v[128:129]
	global_load_lds_dwordx4 v[218:219], off
	s_mov_b32 m0, s28
	s_nop 0
	global_load_lds_dwordx4 v[220:221], off
	s_waitcnt lgkmcnt(0)
	s_setprio 1
	s_barrier
; #define PG8_STAGE(bufoff, gbase, voff) do { _Pragma("unroll") for (int _i = 0; _i < 2; ++_i) \
;         __builtin_amdgcn_global_load_lds((const unsigned*)((const char*)(gbase) + (voff)[_i]), (PG8_LAS unsigned*)(lds + (bufoff) + ldsw + _i * 8192), 16, 0, 0); } while (0)
; #define PG8_LDA(dst, b, h) do { _Pragma("unroll") for (int m = 0; m < 4; ++m) _Pragma("unroll") for (int k = 0; k < 2; ++k) dst[m][k] = *(const PG8_LAS bf16x8*)(lds + PG8_SA(b, h) + aoff + m * 2048 + k * 1024); } while (0)
; #define PG8_LDB(dst, b, h) do { _Pragma("unroll") for (int n = 0; n < 2; ++n) _Pragma("unroll") for (int k = 0; k < 2; ++k) dst[n][k] = *(const PG8_LAS bf16x8*)(lds + PG8_SB(b, h) + boff + n * 2048 + k * 1024); } while (0)
; #define PG8_MMA(ai, bj, At, Bt) do { __builtin_amdgcn_s_setprio(1); _Pragma("unroll") for (int m = 0; m < 4; ++m) _Pragma("unroll") for (int n = 0; n < 2; ++n) _Pragma("unroll") for (int k = 0; k < 2; ++k) \
;         acc[ai][bj][m][n] = __builtin_amdgcn_mfma_f32_16x16x32_bf16(Bt[n][k], At[m][k], acc[ai][bj][m][n], 0, 0, 0); __builtin_amdgcn_s_setprio(0); } while (0)
; #define PG8_WAIT_V(n) asm volatile("s_waitcnt vmcnt(" #n ")" ::: "memory")
; #define PG8_WAIT_L(n) asm volatile("s_waitcnt lgkmcnt(" #n ")" ::: "memory")
; #define PG8_BAR __builtin_amdgcn_s_barrier()
; #define PG8_SCHED __builtin_amdgcn_sched_barrier(0)
; template <class Epi, class Sched, bool ALIGN_EPI = false, bool SP2 = false>
; __device__ __forceinline__ void gemm_phase(PG8_LAS unsigned char* lds, const Gemm g, const Sched& S, const Epi& E) {
;     ...
;             PG8_WAIT_V(8); PG8_WAIT_L(0); PG8_BAR; PG8_MMA(1, 0, At, B0); PG8_MMA(1, 1, At, B1); PG8_BAR; PG8_SCHED;
;             PG8_LDB(B0, 1, 0); PG8_LDB(B1, 1, 1); PG8_SCHED; PG8_LDA(At, 1, 0); PG8_STAGE(PG8_SA(0, 1), a2 + hstep, voffA);
;             PG8_WAIT_V(8); PG8_WAIT_L(0); PG8_BAR; PG8_MMA(0, 0, At, B0); PG8_MMA(0, 1, At, B1); PG8_BAR; PG8_SCHED;
	v_mfma_f32_16x16x32_bf16 v[56:59], v[144:147], v[182:185], 0
	v_mfma_f32_16x16x32_bf16 v[60:63], v[158:161], v[182:185], 0
	v_mfma_f32_16x16x32_bf16 v[40:43], v[144:147], v[190:193], 0
	v_mfma_f32_16x16x32_bf16 v[44:47], v[158:161], v[190:193], 0
	v_mfma_f32_16x16x32_bf16 v[24:27], v[144:147], v[198:201], 0
	v_mfma_f32_16x16x32_bf16 v[28:31], v[158:161], v[198:201], 0
	v_mfma_f32_16x16x32_bf16 v[8:11], v[144:147], v[206:209], 0
	v_mfma_f32_16x16x32_bf16 v[12:15], v[158:161], v[206:209], 0
	v_mfma_f32_16x16x32_bf16 v[56:59], v[148:151], v[186:189], v[56:59]
	v_mfma_f32_16x16x32_bf16 v[60:63], v[162:165], v[186:189], v[60:63]
	v_mfma_f32_16x16x32_bf16 v[40:43], v[148:151], v[194:197], v[40:43]
	v_mfma_f32_16x16x32_bf16 v[44:47], v[162:165], v[194:197], v[44:47]
	v_mfma_f32_16x16x32_bf16 v[24:27], v[148:151], v[202:205], v[24:27]
	v_mfma_f32_16x16x32_bf16 v[28:31], v[162:165], v[202:205], v[28:31]
	v_mfma_f32_16x16x32_bf16 v[8:11], v[148:151], v[210:213], v[8:11]
	v_mfma_f32_16x16x32_bf16 v[12:15], v[162:165], v[210:213], v[12:15]
	v_mfma_f32_16x16x32_bf16 v[48:51], v[166:169], v[182:185], 0
	v_mfma_f32_16x16x32_bf16 v[52:55], v[174:177], v[182:185], 0
	v_mfma_f32_16x16x32_bf16 v[32:35], v[166:169], v[190:193], 0
	v_mfma_f32_16x16x32_bf16 v[36:39], v[174:177], v[190:193], 0
	v_mfma_f32_16x16x32_bf16 v[16:19], v[166:169], v[198:201], 0
	v_mfma_f32_16x16x32_bf16 v[20:23], v[174:177], v[198:201], 0
	v_mfma_f32_16x16x32_bf16 v[0:3], v[166:169], v[206:209], 0
	v_mfma_f32_16x16x32_bf16 v[4:7], v[174:177], v[206:209], 0
	v_mfma_f32_16x16x32_bf16 v[48:51], v[170:173], v[186:189], v[48:51]
	v_mfma_f32_16x16x32_bf16 v[52:55], v[178:181], v[186:189], v[52:55]
	v_mfma_f32_16x16x32_bf16 v[32:35], v[170:173], v[194:197], v[32:35]
	v_mfma_f32_16x16x32_bf16 v[36:39], v[178:181], v[194:197], v[36:39]
	v_mfma_f32_16x16x32_bf16 v[16:19], v[170:173], v[202:205], v[16:19]
	v_mfma_f32_16x16x32_bf16 v[20:23], v[178:181], v[202:205], v[20:23]
	v_mfma_f32_16x16x32_bf16 v[0:3], v[170:173], v[210:213], v[0:3]
	v_mfma_f32_16x16x32_bf16 v[4:7], v[178:181], v[210:213], v[4:7]
	s_barrier
	s_setprio 0
	s_add_i32 s44, 0, 0x18000
	s_add_i32 s45, 0, 0x1c000
	v_add_u32_e32 v162, s44, v153
	v_add_u32_e32 v178, s45, v153
	ds_read_b128 v[144:147], v162
	ds_read_b128 v[148:151], v162 offset:1024
	ds_read_b128 v[158:161], v162 offset:2048
	ds_read_b128 v[162:165], v162 offset:3072
	ds_read_b128 v[166:169], v178
	ds_read_b128 v[170:173], v178 offset:1024
	ds_read_b128 v[174:177], v178 offset:2048
	ds_read_b128 v[178:181], v178 offset:3072
	s_add_u32 s24, s24, 0x80000
	s_addc_u32 s25, s25, 0
	s_mov_b32 m0, s29
	v_lshl_add_u64 v[222:223], s[24:25], 0, v[128:129]
	ds_read_b128 v[182:185], v157 offset:32768
	ds_read_b128 v[186:189], v157 offset:33792
	ds_read_b128 v[190:193], v157 offset:34816
	ds_read_b128 v[194:197], v157 offset:35840
	ds_read_b128 v[198:201], v157 offset:36864
	ds_read_b128 v[202:205], v157 offset:37888
	ds_read_b128 v[206:209], v157 offset:38912
	ds_read_b128 v[210:213], v157 offset:39936
	global_load_lds_dwordx4 v[222:223], off
	s_mov_b32 m0, s30
	v_lshl_add_u64 v[222:223], s[24:25], 0, v[132:133]
	global_load_lds_dwordx4 v[222:223], off
	s_waitcnt vmcnt(8) lgkmcnt(0)
	s_setprio 1
	s_barrier
	v_mfma_f32_16x16x32_bf16 v[124:127], v[144:147], v[182:185], v[124:127]
	v_mfma_f32_16x16x32_bf16 v[120:123], v[158:161], v[182:185], v[120:123]
	v_mfma_f32_16x16x32_bf16 v[108:111], v[144:147], v[190:193], v[108:111]
	v_mfma_f32_16x16x32_bf16 v[104:107], v[158:161], v[190:193], v[104:107]
	v_mfma_f32_16x16x32_bf16 v[88:91], v[144:147], v[198:201], v[88:91]
	v_mfma_f32_16x16x32_bf16 v[92:95], v[158:161], v[198:201], v[92:95]
	v_mfma_f32_16x16x32_bf16 v[72:75], v[144:147], v[206:209], v[72:75]
	v_mfma_f32_16x16x32_bf16 v[76:79], v[158:161], v[206:209], v[76:79]
	v_mfma_f32_16x16x32_bf16 v[124:127], v[148:151], v[186:189], v[124:127]
	v_mfma_f32_16x16x32_bf16 v[120:123], v[162:165], v[186:189], v[120:123]
	v_mfma_f32_16x16x32_bf16 v[108:111], v[148:151], v[194:197], v[108:111]
	v_mfma_f32_16x16x32_bf16 v[104:107], v[162:165], v[194:197], v[104:107]
	v_mfma_f32_16x16x32_bf16 v[88:91], v[148:151], v[202:205], v[88:91]
	v_mfma_f32_16x16x32_bf16 v[92:95], v[162:165], v[202:205], v[92:95]
	v_mfma_f32_16x16x32_bf16 v[72:75], v[148:151], v[210:213], v[72:75]
	v_mfma_f32_16x16x32_bf16 v[76:79], v[162:165], v[210:213], v[76:79]
	v_mfma_f32_16x16x32_bf16 v[116:119], v[166:169], v[182:185], v[116:119]
	v_mfma_f32_16x16x32_bf16 v[112:115], v[174:177], v[182:185], v[112:115]
	v_mfma_f32_16x16x32_bf16 v[96:99], v[166:169], v[190:193], v[96:99]
	v_mfma_f32_16x16x32_bf16 v[100:103], v[174:177], v[190:193], v[100:103]
	v_mfma_f32_16x16x32_bf16 v[80:83], v[166:169], v[198:201], v[80:83]
	v_mfma_f32_16x16x32_bf16 v[84:87], v[174:177], v[198:201], v[84:87]
	v_mfma_f32_16x16x32_bf16 v[64:67], v[166:169], v[206:209], v[64:67]
	v_mfma_f32_16x16x32_bf16 v[68:71], v[174:177], v[206:209], v[68:71]
	v_mfma_f32_16x16x32_bf16 v[116:119], v[170:173], v[186:189], v[116:119]
	v_mfma_f32_16x16x32_bf16 v[112:115], v[178:181], v[186:189], v[112:115]
	v_mfma_f32_16x16x32_bf16 v[96:99], v[170:173], v[194:197], v[96:99]
	v_mfma_f32_16x16x32_bf16 v[100:103], v[178:181], v[194:197], v[100:103]
	v_mfma_f32_16x16x32_bf16 v[80:83], v[170:173], v[202:205], v[80:83]
	v_mfma_f32_16x16x32_bf16 v[84:87], v[178:181], v[202:205], v[84:87]
	v_mfma_f32_16x16x32_bf16 v[64:67], v[170:173], v[210:213], v[64:67]
	v_mfma_f32_16x16x32_bf16 v[68:71], v[178:181], v[210:213], v[68:71]
	s_barrier
; #define PG8_STAGE(bufoff, gbase, voff) do { _Pragma("unroll") for (int _i = 0; _i < 2; ++_i) \
;         __builtin_amdgcn_global_load_lds((const unsigned*)((const char*)(gbase) + (voff)[_i]), (PG8_LAS unsigned*)(lds + (bufoff) + ldsw + _i * 8192), 16, 0, 0); } while (0)
; #define PG8_LDA(dst, b, h) do { _Pragma("unroll") for (int m = 0; m < 4; ++m) _Pragma("unroll") for (int k = 0; k < 2; ++k) dst[m][k] = *(const PG8_LAS bf16x8*)(lds + PG8_SA(b, h) + aoff + m * 2048 + k * 1024); } while (0)
; #define PG8_LDB(dst, b, h) do { _Pragma("unroll") for (int n = 0; n < 2; ++n) _Pragma("unroll") for (int k = 0; k < 2; ++k) dst[n][k] = *(const PG8_LAS bf16x8*)(lds + PG8_SB(b, h) + boff + n * 2048 + k * 1024); } while (0)
; #define PG8_MMA(ai, bj, At, Bt) do { __builtin_amdgcn_s_setprio(1); _Pragma("unroll") for (int m = 0; m < 4; ++m) _Pragma("unroll") for (int n = 0; n < 2; ++n) _Pragma("unroll") for (int k = 0; k < 2; ++k) \
;         acc[ai][bj][m][n] = __builtin_amdgcn_mfma_f32_16x16x32_bf16(Bt[n][k], At[m][k], acc[ai][bj][m][n], 0, 0, 0); __builtin_amdgcn_s_setprio(0); } while (0)
; #define PG8_WAIT_V(n) asm volatile("s_waitcnt vmcnt(" #n ")" ::: "memory")
; template <class Epi, class Sched, bool ALIGN_EPI = false, bool SP2 = false>
; __device__ __forceinline__ void gemm_phase(PG8_LAS unsigned char* lds, const Gemm g, const Sched& S, const Epi& E) {
;     ...
;             PG8_LDB(B0, 0, 0); PG8_LDB(B1, 0, 1); PG8_SCHED; PG8_LDA(At, 0, 0); PG8_STAGE(PG8_SA(1, 1), a1 + hstep, voffA);
;             PG8_WAIT_V(8); PG8_WAIT_L(0); PG8_BAR; PG8_MMA(0, 0, At, B0); PG8_MMA(0, 1, At, B1); PG8_BAR; PG8_SCHED;
;             PG8_LDA(At, 0, 1); PG8_STAGE(PG8_SB(0, 0), b2, voffB); PG8_STAGE(PG8_SB(0, 1), b2 + hstep, voffB); PG8_STAGE(PG8_SA(0, 0), a2, voffA);
;             PG8_WAIT_V(8); PG8_WAIT_L(0); PG8_BAR; PG8_MMA(1, 0, At, B0); PG8_MMA(1, 1, At, B1); PG8_BAR; PG8_SCHED;
;             PG8_LDB(B0, 1, 0); PG8_LDB(B1, 1, 1); PG8_SCHED; PG8_LDA(At, 1, 0); PG8_STAGE(PG8_SA(0, 1), a2 + hstep, voffA);
;             PG8_WAIT_V(8); PG8_WAIT_L(0); PG8_BAR; PG8_MMA(0, 0, At, B0); PG8_MMA(0, 1, At, B1); PG8_BAR; PG8_SCHED;
;             PG8_LDA(At, 1, 1); PG8_STAGE(PG8_SB(1, 0), b3, voffB); PG8_STAGE(PG8_SB(1, 1), b3 + hstep, voffB); PG8_STAGE(PG8_SA(1, 0), a3, voffA);
;             PG8_WAIT_V(8); PG8_WAIT_L(0); PG8_BAR; PG8_MMA(1, 0, At, B0); PG8_MMA(1, 1, At, B1); PG8_BAR; PG8_SCHED;
	s_setprio 0
	s_add_i32 s24, s44, s27
	v_lshl_add_u64 v[214:215], v[214:215], 0, s[4:5]
	s_mov_b32 m0, s24
	ds_read_b128 v[182:185], v157 offset:49152
	ds_read_b128 v[186:189], v157 offset:50176
	ds_read_b128 v[190:193], v157 offset:51200
	ds_read_b128 v[194:197], v157 offset:52224
	ds_read_b128 v[198:201], v157 offset:53248
	ds_read_b128 v[202:205], v157 offset:54272
	ds_read_b128 v[206:209], v157 offset:55296
	ds_read_b128 v[210:213], v157 offset:56320
	global_load_lds_dwordx4 v[214:215], off
	s_add_i32 m0, s24, 0x2000
	s_add_u32 s22, s22, 0x80080
	v_lshl_add_u64 v[214:215], v[216:217], 0, s[4:5]
	s_addc_u32 s23, s23, 0
	s_add_i32 s24, s45, s27
	global_load_lds_dwordx4 v[214:215], off
	s_mov_b32 m0, s24
	v_lshl_add_u64 v[214:215], s[22:23], 0, v[130:131]
	global_load_lds_dwordx4 v[214:215], off
	s_add_i32 m0, s24, 0x2000
	v_lshl_add_u64 v[214:215], s[22:23], 0, v[134:135]
	global_load_lds_dwordx4 v[214:215], off
	s_mov_b32 m0, s33
	v_lshl_add_u64 v[214:215], v[218:219], 0, s[4:5]
	global_load_lds_dwordx4 v[214:215], off
	s_mov_b32 m0, s34
	v_lshl_add_u64 v[214:215], v[220:221], 0, s[4:5]
	global_load_lds_dwordx4 v[214:215], off
	s_waitcnt vmcnt(8) lgkmcnt(0)
	s_setprio 1
	s_barrier
	v_mfma_f32_16x16x32_bf16 v[56:59], v[144:147], v[182:185], v[56:59]
	v_mfma_f32_16x16x32_bf16 v[60:63], v[158:161], v[182:185], v[60:63]
	v_mfma_f32_16x16x32_bf16 v[40:43], v[144:147], v[190:193], v[40:43]
	v_mfma_f32_16x16x32_bf16 v[44:47], v[158:161], v[190:193], v[44:47]
	v_mfma_f32_16x16x32_bf16 v[24:27], v[144:147], v[198:201], v[24:27]
	v_mfma_f32_16x16x32_bf16 v[28:31], v[158:161], v[198:201], v[28:31]
	v_mfma_f32_16x16x32_bf16 v[8:11], v[144:147], v[206:209], v[8:11]
	v_mfma_f32_16x16x32_bf16 v[12:15], v[158:161], v[206:209], v[12:15]
	v_mfma_f32_16x16x32_bf16 v[56:59], v[148:151], v[186:189], v[56:59]
	v_mfma_f32_16x16x32_bf16 v[60:63], v[162:165], v[186:189], v[60:63]
	v_mfma_f32_16x16x32_bf16 v[40:43], v[148:151], v[194:197], v[40:43]
	v_mfma_f32_16x16x32_bf16 v[44:47], v[162:165], v[194:197], v[44:47]
	v_mfma_f32_16x16x32_bf16 v[24:27], v[148:151], v[202:205], v[24:27]
	v_mfma_f32_16x16x32_bf16 v[28:31], v[162:165], v[202:205], v[28:31]
	v_mfma_f32_16x16x32_bf16 v[8:11], v[148:151], v[210:213], v[8:11]
	v_mfma_f32_16x16x32_bf16 v[12:15], v[162:165], v[210:213], v[12:15]
	v_mfma_f32_16x16x32_bf16 v[48:51], v[166:169], v[182:185], v[48:51]
	v_mfma_f32_16x16x32_bf16 v[52:55], v[174:177], v[182:185], v[52:55]
	v_mfma_f32_16x16x32_bf16 v[32:35], v[166:169], v[190:193], v[32:35]
	v_mfma_f32_16x16x32_bf16 v[36:39], v[174:177], v[190:193], v[36:39]
	v_mfma_f32_16x16x32_bf16 v[16:19], v[166:169], v[198:201], v[16:19]
	v_mfma_f32_16x16x32_bf16 v[20:23], v[174:177], v[198:201], v[20:23]
	v_mfma_f32_16x16x32_bf16 v[0:3], v[166:169], v[206:209], v[0:3]
	v_mfma_f32_16x16x32_bf16 v[4:7], v[174:177], v[206:209], v[4:7]
	v_mfma_f32_16x16x32_bf16 v[48:51], v[170:173], v[186:189], v[48:51]
	v_mfma_f32_16x16x32_bf16 v[52:55], v[178:181], v[186:189], v[52:55]
	v_mfma_f32_16x16x32_bf16 v[32:35], v[170:173], v[194:197], v[32:35]
	v_mfma_f32_16x16x32_bf16 v[36:39], v[178:181], v[194:197], v[36:39]
	v_mfma_f32_16x16x32_bf16 v[16:19], v[170:173], v[202:205], v[16:19]
	v_mfma_f32_16x16x32_bf16 v[20:23], v[178:181], v[202:205], v[20:23]
	v_mfma_f32_16x16x32_bf16 v[0:3], v[170:173], v[210:213], v[0:3]
	v_mfma_f32_16x16x32_bf16 v[4:7], v[178:181], v[210:213], v[4:7]
	s_barrier
	s_setprio 0
	s_add_i32 s43, s43, 2
	s_add_u32 s20, s20, 0x100
	s_addc_u32 s21, s21, 0
	s_add_u32 s41, s41, 0x100
	s_addc_u32 s42, s42, 0
.LBB0_1549:
	ds_read_b128 v[144:147], v155
	ds_read_b128 v[148:151], v155 offset:1024
	ds_read_b128 v[158:161], v155 offset:2048
	ds_read_b128 v[162:165], v155 offset:3072
	ds_read_b128 v[166:169], v156
	ds_read_b128 v[170:173], v156 offset:1024
	ds_read_b128 v[174:177], v156 offset:2048
	ds_read_b128 v[178:181], v156 offset:3072
	s_add_u32 s22, s20, 0xfff80080
	s_addc_u32 s23, s21, -1
	s_cmp_eq_u32 s43, 28
	s_cselect_b32 s25, s13, s23
	s_cselect_b32 s24, s39, s22
	s_cselect_b32 s23, s11, s42
	s_cselect_b32 s22, s40, s41
	v_lshl_add_u64 v[214:215], s[20:21], 0, v[136:137]
	s_add_i32 m0, s19, 0xc000
	ds_read_b128 v[182:185], v157
	ds_read_b128 v[186:189], v157 offset:1024
	ds_read_b128 v[190:193], v157 offset:2048
	ds_read_b128 v[194:197], v157 offset:3072
	ds_read_b128 v[198:201], v157 offset:4096
	ds_read_b128 v[202:205], v157 offset:5120
	ds_read_b128 v[206:209], v157 offset:6144
	ds_read_b128 v[210:213], v157 offset:7168
	global_load_lds_dwordx4 v[214:215], off
	s_add_i32 m0, s19, 0xe000
	v_lshl_add_u64 v[214:215], s[20:21], 0, v[138:139]
	global_load_lds_dwordx4 v[214:215], off
	s_waitcnt vmcnt(8) lgkmcnt(0)
	s_setprio 1
	s_barrier
; #define PG8_STAGE(bufoff, gbase, voff) do { _Pragma("unroll") for (int _i = 0; _i < 2; ++_i) \
;         __builtin_amdgcn_global_load_lds((const unsigned*)((const char*)(gbase) + (voff)[_i]), (PG8_LAS unsigned*)(lds + (bufoff) + ldsw + _i * 8192), 16, 0, 0); } while (0)
; #define PG8_LDA(dst, b, h) do { _Pragma("unroll") for (int m = 0; m < 4; ++m) _Pragma("unroll") for (int k = 0; k < 2; ++k) dst[m][k] = *(const PG8_LAS bf16x8*)(lds + PG8_SA(b, h) + aoff + m * 2048 + k * 1024); } while (0)
; #define PG8_MMA(ai, bj, At, Bt) do { __builtin_amdgcn_s_setprio(1); _Pragma("unroll") for (int m = 0; m < 4; ++m) _Pragma("unroll") for (int n = 0; n < 2; ++n) _Pragma("unroll") for (int k = 0; k < 2; ++k) \
;         acc[ai][bj][m][n] = __builtin_amdgcn_mfma_f32_16x16x32_bf16(Bt[n][k], At[m][k], acc[ai][bj][m][n], 0, 0, 0); __builtin_amdgcn_s_setprio(0); } while (0)
; #define PG8_WAIT_V(n) asm volatile("s_waitcnt vmcnt(" #n ")" ::: "memory")
; #define PG8_WAIT_L(n) asm volatile("s_waitcnt lgkmcnt(" #n ")" ::: "memory")
; #define PG8_BAR __builtin_amdgcn_s_barrier()
; #define PG8_SCHED __builtin_amdgcn_sched_barrier(0)
; template <class Epi, class Sched, bool ALIGN_EPI = false, bool SP2 = false>
; __device__ __forceinline__ void gemm_phase(PG8_LAS unsigned char* lds, const Gemm g, const Sched& S, const Epi& E) {
;     ...
;             PG8_WAIT_V(8); PG8_WAIT_L(0); PG8_BAR; PG8_MMA(0, 0, At, B0); PG8_MMA(0, 1, At, B1); PG8_BAR; PG8_SCHED;
;             PG8_LDA(At, 0, 1); PG8_STAGE(PG8_SB(0, 0), b2, voffB); PG8_STAGE(PG8_SB(0, 1), b2 + hstep, voffB); PG8_STAGE(PG8_SA(0, 0), a2, voffA);
;             PG8_WAIT_V(8); PG8_WAIT_L(0); PG8_BAR; PG8_MMA(1, 0, At, B0); PG8_MMA(1, 1, At, B1); PG8_BAR; PG8_SCHED;
	v_mfma_f32_16x16x32_bf16 v[124:127], v[144:147], v[182:185], v[124:127]
	v_mfma_f32_16x16x32_bf16 v[120:123], v[158:161], v[182:185], v[120:123]
	v_mfma_f32_16x16x32_bf16 v[108:111], v[144:147], v[190:193], v[108:111]
	v_mfma_f32_16x16x32_bf16 v[104:107], v[158:161], v[190:193], v[104:107]
	v_mfma_f32_16x16x32_bf16 v[88:91], v[144:147], v[198:201], v[88:91]
	v_mfma_f32_16x16x32_bf16 v[92:95], v[158:161], v[198:201], v[92:95]
	v_mfma_f32_16x16x32_bf16 v[72:75], v[144:147], v[206:209], v[72:75]
	v_mfma_f32_16x16x32_bf16 v[76:79], v[158:161], v[206:209], v[76:79]
	v_mfma_f32_16x16x32_bf16 v[124:127], v[148:151], v[186:189], v[124:127]
	v_mfma_f32_16x16x32_bf16 v[120:123], v[162:165], v[186:189], v[120:123]
	v_mfma_f32_16x16x32_bf16 v[108:111], v[148:151], v[194:197], v[108:111]
	v_mfma_f32_16x16x32_bf16 v[104:107], v[162:165], v[194:197], v[104:107]
	v_mfma_f32_16x16x32_bf16 v[88:91], v[148:151], v[202:205], v[88:91]
	v_mfma_f32_16x16x32_bf16 v[92:95], v[162:165], v[202:205], v[92:95]
	v_mfma_f32_16x16x32_bf16 v[72:75], v[148:151], v[210:213], v[72:75]
	v_mfma_f32_16x16x32_bf16 v[76:79], v[162:165], v[210:213], v[76:79]
	v_mfma_f32_16x16x32_bf16 v[116:119], v[166:169], v[182:185], v[116:119]
	v_mfma_f32_16x16x32_bf16 v[112:115], v[174:177], v[182:185], v[112:115]
	v_mfma_f32_16x16x32_bf16 v[96:99], v[166:169], v[190:193], v[96:99]
	v_mfma_f32_16x16x32_bf16 v[100:103], v[174:177], v[190:193], v[100:103]
	v_mfma_f32_16x16x32_bf16 v[80:83], v[166:169], v[198:201], v[80:83]
	v_mfma_f32_16x16x32_bf16 v[84:87], v[174:177], v[198:201], v[84:87]
	v_mfma_f32_16x16x32_bf16 v[64:67], v[166:169], v[206:209], v[64:67]
	v_mfma_f32_16x16x32_bf16 v[68:71], v[174:177], v[206:209], v[68:71]
	v_mfma_f32_16x16x32_bf16 v[116:119], v[170:173], v[186:189], v[116:119]
	v_mfma_f32_16x16x32_bf16 v[112:115], v[178:181], v[186:189], v[112:115]
	v_mfma_f32_16x16x32_bf16 v[96:99], v[170:173], v[194:197], v[96:99]
	v_mfma_f32_16x16x32_bf16 v[100:103], v[178:181], v[194:197], v[100:103]
	v_mfma_f32_16x16x32_bf16 v[80:83], v[170:173], v[202:205], v[80:83]
	v_mfma_f32_16x16x32_bf16 v[84:87], v[178:181], v[202:205], v[84:87]
	v_mfma_f32_16x16x32_bf16 v[64:67], v[170:173], v[210:213], v[64:67]
	v_mfma_f32_16x16x32_bf16 v[68:71], v[178:181], v[210:213], v[68:71]
	s_barrier
	s_setprio 0
	s_add_i32 s44, s36, s27
	v_lshl_add_u64 v[214:215], s[22:23], 0, v[130:131]
	s_mov_b32 m0, s44
	ds_read_b128 v[182:185], v157 offset:16384
	ds_read_b128 v[186:189], v157 offset:17408
	ds_read_b128 v[190:193], v157 offset:18432
	ds_read_b128 v[194:197], v157 offset:19456
	ds_read_b128 v[198:201], v157 offset:20480
	ds_read_b128 v[202:205], v157 offset:21504
	ds_read_b128 v[206:209], v157 offset:22528
	ds_read_b128 v[210:213], v157 offset:23552
	global_load_lds_dwordx4 v[214:215], off
	s_add_i32 m0, s44, 0x2000
	s_add_u32 s44, s22, 0x80000
	v_lshl_add_u64 v[216:217], s[22:23], 0, v[134:135]
	s_addc_u32 s45, s23, 0
	s_add_i32 s46, s37, s27
	global_load_lds_dwordx4 v[216:217], off
	v_lshl_add_u64 v[218:219], s[44:45], 0, v[130:131]
	s_mov_b32 m0, s46
	v_lshl_add_u64 v[220:221], s[24:25], 0, v[132:133]
	global_load_lds_dwordx4 v[218:219], off
	s_add_i32 m0, s46, 0x2000
	v_lshl_add_u64 v[218:219], s[44:45], 0, v[134:135]
	global_load_lds_dwordx4 v[218:219], off
	s_mov_b32 m0, s19
	v_lshl_add_u64 v[218:219], s[24:25], 0, v[128:129]
	global_load_lds_dwordx4 v[218:219], off
	s_mov_b32 m0, s28
	s_nop 0
	global_load_lds_dwordx4 v[220:221], off
	s_waitcnt vmcnt(8) lgkmcnt(0)
	s_setprio 1
	s_barrier
	v_mfma_f32_16x16x32_bf16 v[56:59], v[144:147], v[182:185], v[56:59]
	v_mfma_f32_16x16x32_bf16 v[60:63], v[158:161], v[182:185], v[60:63]
	v_mfma_f32_16x16x32_bf16 v[40:43], v[144:147], v[190:193], v[40:43]
	v_mfma_f32_16x16x32_bf16 v[44:47], v[158:161], v[190:193], v[44:47]
	v_mfma_f32_16x16x32_bf16 v[24:27], v[144:147], v[198:201], v[24:27]
	v_mfma_f32_16x16x32_bf16 v[28:31], v[158:161], v[198:201], v[28:31]
	v_mfma_f32_16x16x32_bf16 v[8:11], v[144:147], v[206:209], v[8:11]
	v_mfma_f32_16x16x32_bf16 v[12:15], v[158:161], v[206:209], v[12:15]
	v_mfma_f32_16x16x32_bf16 v[56:59], v[148:151], v[186:189], v[56:59]
	v_mfma_f32_16x16x32_bf16 v[60:63], v[162:165], v[186:189], v[60:63]
	v_mfma_f32_16x16x32_bf16 v[40:43], v[148:151], v[194:197], v[40:43]
	v_mfma_f32_16x16x32_bf16 v[44:47], v[162:165], v[194:197], v[44:47]
	v_mfma_f32_16x16x32_bf16 v[24:27], v[148:151], v[202:205], v[24:27]
	v_mfma_f32_16x16x32_bf16 v[28:31], v[162:165], v[202:205], v[28:31]
	v_mfma_f32_16x16x32_bf16 v[8:11], v[148:151], v[210:213], v[8:11]
	v_mfma_f32_16x16x32_bf16 v[12:15], v[162:165], v[210:213], v[12:15]
	v_mfma_f32_16x16x32_bf16 v[48:51], v[166:169], v[182:185], v[48:51]
	v_mfma_f32_16x16x32_bf16 v[52:55], v[174:177], v[182:185], v[52:55]
	v_mfma_f32_16x16x32_bf16 v[32:35], v[166:169], v[190:193], v[32:35]
	v_mfma_f32_16x16x32_bf16 v[36:39], v[174:177], v[190:193], v[36:39]
	v_mfma_f32_16x16x32_bf16 v[16:19], v[166:169], v[198:201], v[16:19]
	v_mfma_f32_16x16x32_bf16 v[20:23], v[174:177], v[198:201], v[20:23]
	v_mfma_f32_16x16x32_bf16 v[0:3], v[166:169], v[206:209], v[0:3]
	v_mfma_f32_16x16x32_bf16 v[4:7], v[174:177], v[206:209], v[4:7]
	v_mfma_f32_16x16x32_bf16 v[48:51], v[170:173], v[186:189], v[48:51]
	v_mfma_f32_16x16x32_bf16 v[52:55], v[178:181], v[186:189], v[52:55]
	v_mfma_f32_16x16x32_bf16 v[32:35], v[170:173], v[194:197], v[32:35]
	v_mfma_f32_16x16x32_bf16 v[36:39], v[178:181], v[194:197], v[36:39]
	v_mfma_f32_16x16x32_bf16 v[16:19], v[170:173], v[202:205], v[16:19]
	v_mfma_f32_16x16x32_bf16 v[20:23], v[178:181], v[202:205], v[20:23]
	v_mfma_f32_16x16x32_bf16 v[0:3], v[170:173], v[210:213], v[0:3]
	v_mfma_f32_16x16x32_bf16 v[4:7], v[178:181], v[210:213], v[4:7]
	s_barrier
; #define PG8_STAGE(bufoff, gbase, voff) do { _Pragma("unroll") for (int _i = 0; _i < 2; ++_i) \
;         __builtin_amdgcn_global_load_lds((const unsigned*)((const char*)(gbase) + (voff)[_i]), (PG8_LAS unsigned*)(lds + (bufoff) + ldsw + _i * 8192), 16, 0, 0); } while (0)
; #define PG8_LDA(dst, b, h) do { _Pragma("unroll") for (int m = 0; m < 4; ++m) _Pragma("unroll") for (int k = 0; k < 2; ++k) dst[m][k] = *(const PG8_LAS bf16x8*)(lds + PG8_SA(b, h) + aoff + m * 2048 + k * 1024); } while (0)
; #define PG8_LDB(dst, b, h) do { _Pragma("unroll") for (int n = 0; n < 2; ++n) _Pragma("unroll") for (int k = 0; k < 2; ++k) dst[n][k] = *(const PG8_LAS bf16x8*)(lds + PG8_SB(b, h) + boff + n * 2048 + k * 1024); } while (0)
; #define PG8_MMA(ai, bj, At, Bt) do { __builtin_amdgcn_s_setprio(1); _Pragma("unroll") for (int m = 0; m < 4; ++m) _Pragma("unroll") for (int n = 0; n < 2; ++n) _Pragma("unroll") for (int k = 0; k < 2; ++k) \
;         acc[ai][bj][m][n] = __builtin_amdgcn_mfma_f32_16x16x32_bf16(Bt[n][k], At[m][k], acc[ai][bj][m][n], 0, 0, 0); __builtin_amdgcn_s_setprio(0); } while (0)
; #define PG8_WAIT_V(n) asm volatile("s_waitcnt vmcnt(" #n ")" ::: "memory")
; #define PG8_WAIT_L(n) asm volatile("s_waitcnt lgkmcnt(" #n ")" ::: "memory")
; #define PG8_BAR __builtin_amdgcn_s_barrier()
; #define PG8_SCHED __builtin_amdgcn_sched_barrier(0)
; template <class Epi, class Sched, bool ALIGN_EPI = false, bool SP2 = false>
; __device__ __forceinline__ void gemm_phase(PG8_LAS unsigned char* lds, const Gemm g, const Sched& S, const Epi& E) {
;     ...
;             PG8_LDB(B0, 1, 0); PG8_LDB(B1, 1, 1); PG8_SCHED; PG8_LDA(At, 1, 0); PG8_STAGE(PG8_SA(0, 1), a2 + hstep, voffA);
;             PG8_WAIT_V(8); PG8_WAIT_L(0); PG8_BAR; PG8_MMA(0, 0, At, B0); PG8_MMA(0, 1, At, B1); PG8_BAR; PG8_SCHED;
	s_setprio 0
	s_add_i32 s44, 0, 0x18000
	s_add_i32 s45, 0, 0x1c000
	v_add_u32_e32 v162, s44, v153
	v_add_u32_e32 v178, s45, v153
	ds_read_b128 v[144:147], v162
	ds_read_b128 v[148:151], v162 offset:1024
	ds_read_b128 v[158:161], v162 offset:2048
	ds_read_b128 v[162:165], v162 offset:3072
	ds_read_b128 v[166:169], v178
	ds_read_b128 v[170:173], v178 offset:1024
	ds_read_b128 v[174:177], v178 offset:2048
	ds_read_b128 v[178:181], v178 offset:3072
	s_add_u32 s24, s24, 0x80000
	s_addc_u32 s25, s25, 0
	s_mov_b32 m0, s29
	v_lshl_add_u64 v[222:223], s[24:25], 0, v[128:129]
	ds_read_b128 v[182:185], v157 offset:32768
	ds_read_b128 v[186:189], v157 offset:33792
	ds_read_b128 v[190:193], v157 offset:34816
	ds_read_b128 v[194:197], v157 offset:35840
	ds_read_b128 v[198:201], v157 offset:36864
	ds_read_b128 v[202:205], v157 offset:37888
	ds_read_b128 v[206:209], v157 offset:38912
	ds_read_b128 v[210:213], v157 offset:39936
	global_load_lds_dwordx4 v[222:223], off
	s_mov_b32 m0, s30
	v_lshl_add_u64 v[222:223], s[24:25], 0, v[132:133]
	global_load_lds_dwordx4 v[222:223], off
	s_waitcnt vmcnt(8) lgkmcnt(0)
	s_setprio 1
	s_barrier
	v_mfma_f32_16x16x32_bf16 v[124:127], v[144:147], v[182:185], v[124:127]
	v_mfma_f32_16x16x32_bf16 v[120:123], v[158:161], v[182:185], v[120:123]
	v_mfma_f32_16x16x32_bf16 v[108:111], v[144:147], v[190:193], v[108:111]
	v_mfma_f32_16x16x32_bf16 v[104:107], v[158:161], v[190:193], v[104:107]
	v_mfma_f32_16x16x32_bf16 v[88:91], v[144:147], v[198:201], v[88:91]
	v_mfma_f32_16x16x32_bf16 v[92:95], v[158:161], v[198:201], v[92:95]
	v_mfma_f32_16x16x32_bf16 v[72:75], v[144:147], v[206:209], v[72:75]
	v_mfma_f32_16x16x32_bf16 v[76:79], v[158:161], v[206:209], v[76:79]
	v_mfma_f32_16x16x32_bf16 v[124:127], v[148:151], v[186:189], v[124:127]
	v_mfma_f32_16x16x32_bf16 v[120:123], v[162:165], v[186:189], v[120:123]
	v_mfma_f32_16x16x32_bf16 v[108:111], v[148:151], v[194:197], v[108:111]
	v_mfma_f32_16x16x32_bf16 v[104:107], v[162:165], v[194:197], v[104:107]
	v_mfma_f32_16x16x32_bf16 v[88:91], v[148:151], v[202:205], v[88:91]
	v_mfma_f32_16x16x32_bf16 v[92:95], v[162:165], v[202:205], v[92:95]
	v_mfma_f32_16x16x32_bf16 v[72:75], v[148:151], v[210:213], v[72:75]
	v_mfma_f32_16x16x32_bf16 v[76:79], v[162:165], v[210:213], v[76:79]
	v_mfma_f32_16x16x32_bf16 v[116:119], v[166:169], v[182:185], v[116:119]
	v_mfma_f32_16x16x32_bf16 v[112:115], v[174:177], v[182:185], v[112:115]
	v_mfma_f32_16x16x32_bf16 v[96:99], v[166:169], v[190:193], v[96:99]
	v_mfma_f32_16x16x32_bf16 v[100:103], v[174:177], v[190:193], v[100:103]
	v_mfma_f32_16x16x32_bf16 v[80:83], v[166:169], v[198:201], v[80:83]
	v_mfma_f32_16x16x32_bf16 v[84:87], v[174:177], v[198:201], v[84:87]
	v_mfma_f32_16x16x32_bf16 v[64:67], v[166:169], v[206:209], v[64:67]
	v_mfma_f32_16x16x32_bf16 v[68:71], v[174:177], v[206:209], v[68:71]
	v_mfma_f32_16x16x32_bf16 v[116:119], v[170:173], v[186:189], v[116:119]
	v_mfma_f32_16x16x32_bf16 v[112:115], v[178:181], v[186:189], v[112:115]
	v_mfma_f32_16x16x32_bf16 v[96:99], v[170:173], v[194:197], v[96:99]
	v_mfma_f32_16x16x32_bf16 v[100:103], v[178:181], v[194:197], v[100:103]
	v_mfma_f32_16x16x32_bf16 v[80:83], v[170:173], v[202:205], v[80:83]
	v_mfma_f32_16x16x32_bf16 v[84:87], v[178:181], v[202:205], v[84:87]
	v_mfma_f32_16x16x32_bf16 v[64:67], v[170:173], v[210:213], v[64:67]
	v_mfma_f32_16x16x32_bf16 v[68:71], v[178:181], v[210:213], v[68:71]
	s_barrier
; #define PG8_STAGE(bufoff, gbase, voff) do { _Pragma("unroll") for (int _i = 0; _i < 2; ++_i) \
;         __builtin_amdgcn_global_load_lds((const unsigned*)((const char*)(gbase) + (voff)[_i]), (PG8_LAS unsigned*)(lds + (bufoff) + ldsw + _i * 8192), 16, 0, 0); } while (0)
; #define PG8_LDA(dst, b, h) do { _Pragma("unroll") for (int m = 0; m < 4; ++m) _Pragma("unroll") for (int k = 0; k < 2; ++k) dst[m][k] = *(const PG8_LAS bf16x8*)(lds + PG8_SA(b, h) + aoff + m * 2048 + k * 1024); } while (0)
; #define PG8_MMA(ai, bj, At, Bt) do { __builtin_amdgcn_s_setprio(1); _Pragma("unroll") for (int m = 0; m < 4; ++m) _Pragma("unroll") for (int n = 0; n < 2; ++n) _Pragma("unroll") for (int k = 0; k < 2; ++k) \
;         acc[ai][bj][m][n] = __builtin_amdgcn_mfma_f32_16x16x32_bf16(Bt[n][k], At[m][k], acc[ai][bj][m][n], 0, 0, 0); __builtin_amdgcn_s_setprio(0); } while (0)
; #define PG8_WAIT_V(n) asm volatile("s_waitcnt vmcnt(" #n ")" ::: "memory")
; #define PG8_WAIT_L(n) asm volatile("s_waitcnt lgkmcnt(" #n ")" ::: "memory")
; #define PG8_BAR __builtin_amdgcn_s_barrier()
; #define PG8_SCHED __builtin_amdgcn_sched_barrier(0)
; template <class Epi, class Sched, bool ALIGN_EPI = false, bool SP2 = false>
; __device__ __forceinline__ void gemm_phase(PG8_LAS unsigned char* lds, const Gemm g, const Sched& S, const Epi& E) {
;     ...
;             PG8_LDA(At, 1, 1); PG8_STAGE(PG8_SB(1, 0), b3, voffB); PG8_STAGE(PG8_SB(1, 1), b3 + hstep, voffB); PG8_STAGE(PG8_SA(1, 0), a3, voffA);
;             PG8_WAIT_V(8); PG8_WAIT_L(0); PG8_BAR; PG8_MMA(1, 0, At, B0); PG8_MMA(1, 1, At, B1); PG8_BAR; PG8_SCHED;
;     ...
;         }
;         if constexpr (ALIGN_EPI) { if (wr == 0) PG8_BAR; }
	s_setprio 0
	s_add_i32 s24, s44, s27
	v_lshl_add_u64 v[214:215], v[214:215], 0, s[4:5]
	s_mov_b32 m0, s24
	ds_read_b128 v[182:185], v157 offset:49152
	ds_read_b128 v[186:189], v157 offset:50176
	ds_read_b128 v[190:193], v157 offset:51200
	ds_read_b128 v[194:197], v157 offset:52224
	ds_read_b128 v[198:201], v157 offset:53248
	ds_read_b128 v[202:205], v157 offset:54272
	ds_read_b128 v[206:209], v157 offset:55296
	ds_read_b128 v[210:213], v157 offset:56320
	global_load_lds_dwordx4 v[214:215], off
	s_add_i32 m0, s24, 0x2000
	s_add_u32 s22, s22, 0x80080
	v_lshl_add_u64 v[214:215], v[216:217], 0, s[4:5]
	s_addc_u32 s23, s23, 0
	s_add_i32 s24, s45, s27
	global_load_lds_dwordx4 v[214:215], off
	s_mov_b32 m0, s24
	v_lshl_add_u64 v[214:215], s[22:23], 0, v[130:131]
	global_load_lds_dwordx4 v[214:215], off
	s_add_i32 m0, s24, 0x2000
	v_lshl_add_u64 v[214:215], s[22:23], 0, v[134:135]
	global_load_lds_dwordx4 v[214:215], off
	s_mov_b32 m0, s33
	v_lshl_add_u64 v[214:215], v[218:219], 0, s[4:5]
	global_load_lds_dwordx4 v[214:215], off
	s_mov_b32 m0, s34
	v_lshl_add_u64 v[214:215], v[220:221], 0, s[4:5]
	global_load_lds_dwordx4 v[214:215], off
	s_waitcnt vmcnt(8) lgkmcnt(0)
	s_setprio 1
	s_barrier
	v_mfma_f32_16x16x32_bf16 v[56:59], v[144:147], v[182:185], v[56:59]
	v_mfma_f32_16x16x32_bf16 v[60:63], v[158:161], v[182:185], v[60:63]
	v_mfma_f32_16x16x32_bf16 v[40:43], v[144:147], v[190:193], v[40:43]
	v_mfma_f32_16x16x32_bf16 v[44:47], v[158:161], v[190:193], v[44:47]
	v_mfma_f32_16x16x32_bf16 v[24:27], v[144:147], v[198:201], v[24:27]
	v_mfma_f32_16x16x32_bf16 v[28:31], v[158:161], v[198:201], v[28:31]
	v_mfma_f32_16x16x32_bf16 v[8:11], v[144:147], v[206:209], v[8:11]
	v_mfma_f32_16x16x32_bf16 v[12:15], v[158:161], v[206:209], v[12:15]
	v_mfma_f32_16x16x32_bf16 v[56:59], v[148:151], v[186:189], v[56:59]
	v_mfma_f32_16x16x32_bf16 v[60:63], v[162:165], v[186:189], v[60:63]
	v_mfma_f32_16x16x32_bf16 v[40:43], v[148:151], v[194:197], v[40:43]
	v_mfma_f32_16x16x32_bf16 v[44:47], v[162:165], v[194:197], v[44:47]
	v_mfma_f32_16x16x32_bf16 v[24:27], v[148:151], v[202:205], v[24:27]
	v_mfma_f32_16x16x32_bf16 v[28:31], v[162:165], v[202:205], v[28:31]
	v_mfma_f32_16x16x32_bf16 v[8:11], v[148:151], v[210:213], v[8:11]
	v_mfma_f32_16x16x32_bf16 v[12:15], v[162:165], v[210:213], v[12:15]
	v_mfma_f32_16x16x32_bf16 v[48:51], v[166:169], v[182:185], v[48:51]
	v_mfma_f32_16x16x32_bf16 v[52:55], v[174:177], v[182:185], v[52:55]
	v_mfma_f32_16x16x32_bf16 v[32:35], v[166:169], v[190:193], v[32:35]
	v_mfma_f32_16x16x32_bf16 v[36:39], v[174:177], v[190:193], v[36:39]
	v_mfma_f32_16x16x32_bf16 v[16:19], v[166:169], v[198:201], v[16:19]
	v_mfma_f32_16x16x32_bf16 v[20:23], v[174:177], v[198:201], v[20:23]
	v_mfma_f32_16x16x32_bf16 v[0:3], v[166:169], v[206:209], v[0:3]
	v_mfma_f32_16x16x32_bf16 v[4:7], v[174:177], v[206:209], v[4:7]
	v_mfma_f32_16x16x32_bf16 v[48:51], v[170:173], v[186:189], v[48:51]
	v_mfma_f32_16x16x32_bf16 v[52:55], v[178:181], v[186:189], v[52:55]
	v_mfma_f32_16x16x32_bf16 v[32:35], v[170:173], v[194:197], v[32:35]
	v_mfma_f32_16x16x32_bf16 v[36:39], v[178:181], v[194:197], v[36:39]
	v_mfma_f32_16x16x32_bf16 v[16:19], v[170:173], v[202:205], v[16:19]
	v_mfma_f32_16x16x32_bf16 v[20:23], v[178:181], v[202:205], v[20:23]
	v_mfma_f32_16x16x32_bf16 v[0:3], v[170:173], v[210:213], v[0:3]
	v_mfma_f32_16x16x32_bf16 v[4:7], v[178:181], v[210:213], v[4:7]
	s_barrier
	s_setprio 0
	s_add_i32 s43, s43, 2
	s_add_u32 s20, s20, 0x100
	s_addc_u32 s21, s21, 0
	s_add_u32 s41, s41, 0x100
	s_addc_u32 s42, s42, 0
	s_cmp_gt_u32 s43, 29
	s_cbranch_scc0 .LBB0_1549
	s_and_b64 vcc, exec, s[6:7]
	s_cbranch_vccz .LBB0_1552
	s_barrier
